# nt hint also on the out-projection fast-path residual / next-operand row stores
# speedup vs baseline: 1.0071x; 1.0071x over previous
.Lfo_entry:
	s_and_b64 vcc, exec, s[28:29]
	s_cbranch_vccz .Lfo_first
	s_lshr_b32 s14, s34, 3
	s_mul_i32 s14, s14, 0x3000
	s_add_u32 s16, s86, s14
	s_addc_u32 s17, s87, 0
	s_add_u32 s16, s16, 0x2000
	s_addc_u32 s17, s17, 0
	s_add_u32 s86, s88, s14
	s_addc_u32 s87, s89, 0
	s_add_u32 s86, s86, 0x1000
	s_addc_u32 s87, s87, 0
	v_lshl_add_u32 v171, v170, 1, v96
	v_lshl_add_u32 v171, v222, 11, v171
	v_lshlrev_b32_e32 v170, 2, v170
	s_lshl_b32 s14, s34, 8
	s_add_i32 s14, s14, s81
	s_lshl_b32 s12, s14, 11
	s_add_u32 s14, s2, s12
	s_addc_u32 s15, s3, 0
	s_add_u32 s78, s78, s12
	s_addc_u32 s79, s79, 0
	s_add_u32 s22, s78, 0x4000
	s_addc_u32 s23, s79, 0
	s_mov_b64 s[2:3], s[14:15]
	s_add_u32 s18, s14, 0x4000
	s_addc_u32 s19, s15, 0
	s_mov_b64 s[12:13], s[18:19]
	s_and_b64 vcc, exec, s[40:41]
	s_cbranch_vccz .Lfo_nong
	global_load_dwordx4 v[142:145], v170, s[16:17]
	global_load_dwordx4 v[150:153], v170, s[16:17] offset:16
	global_load_dwordx4 v[138:141], v170, s[16:17] offset:128
	global_load_dwordx4 v[146:149], v170, s[16:17] offset:144
	global_load_dwordx4 v[196:199], v171, s[14:15]
	global_load_dwordx4 v[200:203], v171, s[12:13]
	s_add_u32 s14, s14, 0x8000
	s_addc_u32 s15, s15, 0
	s_add_u32 s12, s12, 0x8000
	s_addc_u32 s13, s13, 0
	global_load_dwordx4 v[204:207], v171, s[14:15]
	global_load_dwordx4 v[234:237], v171, s[12:13]
	global_load_dwordx4 v[180:183], v170, s[86:87]
	global_load_dwordx4 v[184:187], v170, s[86:87] offset:16
	global_load_dwordx4 v[188:191], v170, s[86:87] offset:128
	global_load_dwordx4 v[192:195], v170, s[86:87] offset:144
	global_load_dwordx4 v[0:3], v170, s[26:27]
	global_load_dwordx4 v[4:7], v170, s[26:27] offset:16
	global_load_dwordx4 v[238:241], v170, s[26:27] offset:128
	global_load_dwordx4 v[242:245], v170, s[26:27] offset:144
	s_waitcnt vmcnt(0)
	v_pk_add_f32 v[182:183], v[182:183], 1.0 op_sel_hi:[1,0]
	v_pk_add_f32 v[180:181], v[180:181], 1.0 op_sel_hi:[1,0]
	v_pk_add_f32 v[186:187], v[186:187], 1.0 op_sel_hi:[1,0]
	v_pk_add_f32 v[184:185], v[184:185], 1.0 op_sel_hi:[1,0]
	v_pk_add_f32 v[190:191], v[190:191], 1.0 op_sel_hi:[1,0]
	v_pk_add_f32 v[188:189], v[188:189], 1.0 op_sel_hi:[1,0]
	v_pk_add_f32 v[194:195], v[194:195], 1.0 op_sel_hi:[1,0]
	v_pk_add_f32 v[192:193], v[192:193], 1.0 op_sel_hi:[1,0]
	v_pk_mul_f32 v[182:183], v[2:3], v[182:183]
	v_pk_mul_f32 v[180:181], v[0:1], v[180:181]
	v_pk_mul_f32 v[186:187], v[6:7], v[186:187]
	v_pk_mul_f32 v[184:185], v[4:5], v[184:185]
	v_pk_mul_f32 v[190:191], v[240:241], v[190:191]
	v_pk_mul_f32 v[188:189], v[238:239], v[188:189]
	v_pk_mul_f32 v[194:195], v[244:245], v[194:195]
	v_pk_mul_f32 v[192:193], v[242:243], v[192:193]
	s_add_u32 s14, s14, 0x8000
	s_addc_u32 s15, s15, 0
	s_add_u32 s12, s12, 0x8000
	s_addc_u32 s13, s13, 0
	global_load_dwordx4 v[238:241], v171, s[14:15]
	global_load_dwordx4 v[242:245], v171, s[12:13]
	s_waitcnt vmcnt(2)
	s_mov_b64 vcc, s[6:7]
	v_cndmask_b32_dpp v0, v200, v196, vcc row_ror:8 row_mask:0xf bank_mask:0xf
	v_cndmask_b32_dpp v1, v201, v197, vcc row_ror:8 row_mask:0xf bank_mask:0xf
	v_cndmask_b32_dpp v2, v202, v198, vcc row_ror:8 row_mask:0xf bank_mask:0xf
	v_cndmask_b32_dpp v3, v203, v199, vcc row_ror:8 row_mask:0xf bank_mask:0xf
	s_not_b64 vcc, s[6:7]
	v_cndmask_b32_dpp v4, v196, v200, vcc row_ror:8 row_mask:0xf bank_mask:0xf
	v_cndmask_b32_dpp v5, v197, v201, vcc row_ror:8 row_mask:0xf bank_mask:0xf
	v_cndmask_b32_dpp v6, v198, v202, vcc row_ror:8 row_mask:0xf bank_mask:0xf
	v_cndmask_b32_dpp v7, v199, v203, vcc row_ror:8 row_mask:0xf bank_mask:0xf
	s_add_u32 s14, s14, 0x8000
	s_addc_u32 s15, s15, 0
	s_add_u32 s12, s12, 0x8000
	s_addc_u32 s13, s13, 0
	global_load_dwordx4 v[196:199], v171, s[14:15]
	global_load_dwordx4 v[200:203], v171, s[12:13]
	v_lshlrev_b32_e32 v246, 16, v0
	v_and_b32_e32 v247, 0xffff0000, v0
	v_pk_fma_f32 v[134:135], v[134:135], v[142:143], v[246:247]
	v_lshlrev_b32_e32 v248, 16, v1
	v_and_b32_e32 v249, 0xffff0000, v1
	v_pk_fma_f32 v[136:137], v[136:137], v[144:145], v[248:249]
	v_lshlrev_b32_e32 v250, 16, v2
	v_and_b32_e32 v251, 0xffff0000, v2
	v_pk_fma_f32 v[130:131], v[130:131], v[150:151], v[250:251]
	v_lshlrev_b32_e32 v208, 16, v3
	v_and_b32_e32 v209, 0xffff0000, v3
	v_pk_fma_f32 v[132:133], v[132:133], v[152:153], v[208:209]
	v_lshlrev_b32_e32 v246, 16, v4
	v_and_b32_e32 v247, 0xffff0000, v4
	v_pk_fma_f32 v[126:127], v[126:127], v[138:139], v[246:247]
	v_lshlrev_b32_e32 v248, 16, v5
	v_and_b32_e32 v249, 0xffff0000, v5
	v_pk_fma_f32 v[128:129], v[128:129], v[140:141], v[248:249]
	v_lshlrev_b32_e32 v250, 16, v6
	v_and_b32_e32 v251, 0xffff0000, v6
	v_pk_fma_f32 v[122:123], v[122:123], v[146:147], v[250:251]
	v_lshlrev_b32_e32 v208, 16, v7
	v_and_b32_e32 v209, 0xffff0000, v7
	v_pk_fma_f32 v[124:125], v[124:125], v[148:149], v[208:209]
	v_cvt_pk_bf16_f32 v0, v134, v135
	v_cvt_pk_bf16_f32 v1, v136, v137
	v_cvt_pk_bf16_f32 v2, v130, v131
	v_cvt_pk_bf16_f32 v3, v132, v133
	v_cvt_pk_bf16_f32 v4, v126, v127
	v_cvt_pk_bf16_f32 v5, v128, v129
	v_cvt_pk_bf16_f32 v6, v122, v123
	v_cvt_pk_bf16_f32 v7, v124, v125
	v_mul_f32_e32 v246, v135, v135
	v_mul_f32_e32 v248, v137, v137
	v_fmac_f32_e32 v246, v134, v134
	v_fmac_f32_e32 v248, v136, v136
	v_add_f32_e32 v246, v246, v248
	v_mul_f32_e32 v248, v131, v131
	v_fmac_f32_e32 v248, v130, v130
	v_add_f32_e32 v246, v246, v248
	v_mul_f32_e32 v248, v133, v133
	v_fmac_f32_e32 v248, v132, v132
	v_add_f32_e32 v246, v248, v246
	v_mul_f32_e32 v247, v127, v127
	v_mul_f32_e32 v248, v129, v129
	v_fmac_f32_e32 v247, v126, v126
	v_fmac_f32_e32 v248, v128, v128
	v_add_f32_e32 v247, v247, v248
	v_mul_f32_e32 v248, v123, v123
	v_fmac_f32_e32 v248, v122, v122
	v_add_f32_e32 v247, v247, v248
	v_mul_f32_e32 v248, v125, v125
	v_fmac_f32_e32 v248, v124, v124
	v_add_f32_e32 v247, v248, v247
	v_add_f32_e32 v246, v246, v247
	v_mov_b32_e32 v247, v246
	s_nop 1
	v_permlane16_swap_b32_e32 v246, v247
	s_nop 1
	v_add_f32_e32 v246, v246, v247
	v_mov_b32_e32 v247, v246
	s_nop 1
	v_permlane32_swap_b32_e32 v246, v247
	v_add_u32_e32 v248, s8, v223
	s_nop 0
	v_add_f32_e32 v246, v246, v247
	s_mov_b64 exec, s[44:45]
	ds_write_b32 v248, v246
	s_mov_b64 exec, -1
	v_pk_mul_f32 v[134:135], v[180:181], v[134:135]
	v_pk_mul_f32 v[136:137], v[182:183], v[136:137]
	v_pk_mul_f32 v[130:131], v[184:185], v[130:131]
	v_pk_mul_f32 v[132:133], v[186:187], v[132:133]
	v_pk_mul_f32 v[126:127], v[188:189], v[126:127]
	v_pk_mul_f32 v[128:129], v[190:191], v[128:129]
	v_pk_mul_f32 v[122:123], v[192:193], v[122:123]
	v_pk_mul_f32 v[124:125], v[194:195], v[124:125]
	v_cvt_pk_bf16_f32 v246, v134, v135
	v_cvt_pk_bf16_f32 v247, v136, v137
	v_cvt_pk_bf16_f32 v248, v130, v131
	v_cvt_pk_bf16_f32 v249, v132, v133
	v_cvt_pk_bf16_f32 v250, v126, v127
	v_cvt_pk_bf16_f32 v251, v128, v129
	v_cvt_pk_bf16_f32 v208, v122, v123
	v_cvt_pk_bf16_f32 v209, v124, v125
	s_nop 1
	s_mov_b64 vcc, s[6:7]
	v_cndmask_b32_dpp v134, v4, v0, vcc row_ror:8 row_mask:0xf bank_mask:0xf
	v_cndmask_b32_dpp v135, v5, v1, vcc row_ror:8 row_mask:0xf bank_mask:0xf
	v_cndmask_b32_dpp v136, v6, v2, vcc row_ror:8 row_mask:0xf bank_mask:0xf
	v_cndmask_b32_dpp v137, v7, v3, vcc row_ror:8 row_mask:0xf bank_mask:0xf
	v_cndmask_b32_dpp v126, v250, v246, vcc row_ror:8 row_mask:0xf bank_mask:0xf
	v_cndmask_b32_dpp v127, v251, v247, vcc row_ror:8 row_mask:0xf bank_mask:0xf
	v_cndmask_b32_dpp v128, v208, v248, vcc row_ror:8 row_mask:0xf bank_mask:0xf
	v_cndmask_b32_dpp v129, v209, v249, vcc row_ror:8 row_mask:0xf bank_mask:0xf
	s_not_b64 vcc, s[6:7]
	v_cndmask_b32_dpp v130, v0, v4, vcc row_ror:8 row_mask:0xf bank_mask:0xf
	v_cndmask_b32_dpp v131, v1, v5, vcc row_ror:8 row_mask:0xf bank_mask:0xf
	v_cndmask_b32_dpp v132, v2, v6, vcc row_ror:8 row_mask:0xf bank_mask:0xf
	v_cndmask_b32_dpp v133, v3, v7, vcc row_ror:8 row_mask:0xf bank_mask:0xf
	v_cndmask_b32_dpp v122, v246, v250, vcc row_ror:8 row_mask:0xf bank_mask:0xf
	v_cndmask_b32_dpp v123, v247, v251, vcc row_ror:8 row_mask:0xf bank_mask:0xf
	v_cndmask_b32_dpp v124, v248, v208, vcc row_ror:8 row_mask:0xf bank_mask:0xf
	v_cndmask_b32_dpp v125, v249, v209, vcc row_ror:8 row_mask:0xf bank_mask:0xf
	global_store_dwordx4 v171, v[134:137], s[2:3] nt
	global_store_dwordx4 v171, v[130:133], s[18:19] nt
	global_store_dwordx4 v171, v[126:129], s[78:79] nt
	global_store_dwordx4 v171, v[122:125], s[22:23] nt
	s_waitcnt vmcnt(8)
	s_mov_b64 vcc, s[6:7]
	v_cndmask_b32_dpp v0, v234, v204, vcc row_ror:8 row_mask:0xf bank_mask:0xf
	v_cndmask_b32_dpp v1, v235, v205, vcc row_ror:8 row_mask:0xf bank_mask:0xf
	v_cndmask_b32_dpp v2, v236, v206, vcc row_ror:8 row_mask:0xf bank_mask:0xf
	v_cndmask_b32_dpp v3, v237, v207, vcc row_ror:8 row_mask:0xf bank_mask:0xf
	s_not_b64 vcc, s[6:7]
	v_cndmask_b32_dpp v4, v204, v234, vcc row_ror:8 row_mask:0xf bank_mask:0xf
	v_cndmask_b32_dpp v5, v205, v235, vcc row_ror:8 row_mask:0xf bank_mask:0xf
	v_cndmask_b32_dpp v6, v206, v236, vcc row_ror:8 row_mask:0xf bank_mask:0xf
	v_cndmask_b32_dpp v7, v207, v237, vcc row_ror:8 row_mask:0xf bank_mask:0xf
	s_add_u32 s14, s14, 0x28000
	s_addc_u32 s15, s15, 0
	s_add_u32 s12, s12, 0x28000
	s_addc_u32 s13, s13, 0
	global_load_dwordx4 v[204:207], v171, s[14:15]
	global_load_dwordx4 v[234:237], v171, s[12:13]
	v_lshlrev_b32_e32 v246, 16, v0
	v_and_b32_e32 v247, 0xffff0000, v0
	v_pk_fma_f32 v[118:119], v[118:119], v[142:143], v[246:247]
	v_lshlrev_b32_e32 v248, 16, v1
	v_and_b32_e32 v249, 0xffff0000, v1
	v_pk_fma_f32 v[120:121], v[120:121], v[144:145], v[248:249]
	v_lshlrev_b32_e32 v250, 16, v2
	v_and_b32_e32 v251, 0xffff0000, v2
	v_pk_fma_f32 v[114:115], v[114:115], v[150:151], v[250:251]
	v_lshlrev_b32_e32 v208, 16, v3
	v_and_b32_e32 v209, 0xffff0000, v3
	v_pk_fma_f32 v[116:117], v[116:117], v[152:153], v[208:209]
	v_lshlrev_b32_e32 v246, 16, v4
	v_and_b32_e32 v247, 0xffff0000, v4
	v_pk_fma_f32 v[110:111], v[110:111], v[138:139], v[246:247]
	v_lshlrev_b32_e32 v248, 16, v5
	v_and_b32_e32 v249, 0xffff0000, v5
	v_pk_fma_f32 v[112:113], v[112:113], v[140:141], v[248:249]
	v_lshlrev_b32_e32 v250, 16, v6
	v_and_b32_e32 v251, 0xffff0000, v6
	v_pk_fma_f32 v[106:107], v[106:107], v[146:147], v[250:251]
	v_lshlrev_b32_e32 v208, 16, v7
	v_and_b32_e32 v209, 0xffff0000, v7
	v_pk_fma_f32 v[108:109], v[108:109], v[148:149], v[208:209]
	v_cvt_pk_bf16_f32 v0, v118, v119
	v_cvt_pk_bf16_f32 v1, v120, v121
	v_cvt_pk_bf16_f32 v2, v114, v115
	v_cvt_pk_bf16_f32 v3, v116, v117
	v_cvt_pk_bf16_f32 v4, v110, v111
	v_cvt_pk_bf16_f32 v5, v112, v113
	v_cvt_pk_bf16_f32 v6, v106, v107
	v_cvt_pk_bf16_f32 v7, v108, v109
	v_mul_f32_e32 v246, v119, v119
	v_mul_f32_e32 v248, v121, v121
	v_fmac_f32_e32 v246, v118, v118
	v_fmac_f32_e32 v248, v120, v120
	v_add_f32_e32 v246, v246, v248
	v_mul_f32_e32 v248, v115, v115
	v_fmac_f32_e32 v248, v114, v114
	v_add_f32_e32 v246, v246, v248
	v_mul_f32_e32 v248, v117, v117
	v_fmac_f32_e32 v248, v116, v116
	v_add_f32_e32 v246, v248, v246
	v_mul_f32_e32 v247, v111, v111
	v_mul_f32_e32 v248, v113, v113
	v_fmac_f32_e32 v247, v110, v110
	v_fmac_f32_e32 v248, v112, v112
	v_add_f32_e32 v247, v247, v248
	v_mul_f32_e32 v248, v107, v107
	v_fmac_f32_e32 v248, v106, v106
	v_add_f32_e32 v247, v247, v248
	v_mul_f32_e32 v248, v109, v109
	v_fmac_f32_e32 v248, v108, v108
	v_add_f32_e32 v247, v248, v247
	v_add_f32_e32 v246, v246, v247
	v_mov_b32_e32 v247, v246
	s_nop 1
	v_permlane16_swap_b32_e32 v246, v247
	s_nop 1
	v_add_f32_e32 v246, v246, v247
	v_mov_b32_e32 v247, v246
	s_nop 1
	v_permlane32_swap_b32_e32 v246, v247
	v_add_u32_e32 v248, s8, v223
	s_nop 0
	v_add_f32_e32 v246, v246, v247
	s_mov_b64 exec, s[44:45]
	ds_write_b32 v248, v246 offset:256
	s_mov_b64 exec, -1
	v_pk_mul_f32 v[118:119], v[180:181], v[118:119]
	v_pk_mul_f32 v[120:121], v[182:183], v[120:121]
	v_pk_mul_f32 v[114:115], v[184:185], v[114:115]
	v_pk_mul_f32 v[116:117], v[186:187], v[116:117]
	v_pk_mul_f32 v[110:111], v[188:189], v[110:111]
	v_pk_mul_f32 v[112:113], v[190:191], v[112:113]
	v_pk_mul_f32 v[106:107], v[192:193], v[106:107]
	v_pk_mul_f32 v[108:109], v[194:195], v[108:109]
	v_cvt_pk_bf16_f32 v246, v118, v119
	v_cvt_pk_bf16_f32 v247, v120, v121
	v_cvt_pk_bf16_f32 v248, v114, v115
	v_cvt_pk_bf16_f32 v249, v116, v117
	v_cvt_pk_bf16_f32 v250, v110, v111
	v_cvt_pk_bf16_f32 v251, v112, v113
	v_cvt_pk_bf16_f32 v208, v106, v107
	v_cvt_pk_bf16_f32 v209, v108, v109
	s_add_u32 s2, s2, 0x8000
	s_addc_u32 s3, s3, 0
	s_add_u32 s18, s18, 0x8000
	s_addc_u32 s19, s19, 0
	s_add_u32 s78, s78, 0x8000
	s_addc_u32 s79, s79, 0
	s_add_u32 s22, s22, 0x8000
	s_addc_u32 s23, s23, 0
	s_mov_b64 vcc, s[6:7]
	v_cndmask_b32_dpp v118, v4, v0, vcc row_ror:8 row_mask:0xf bank_mask:0xf
	v_cndmask_b32_dpp v119, v5, v1, vcc row_ror:8 row_mask:0xf bank_mask:0xf
	v_cndmask_b32_dpp v120, v6, v2, vcc row_ror:8 row_mask:0xf bank_mask:0xf
	v_cndmask_b32_dpp v121, v7, v3, vcc row_ror:8 row_mask:0xf bank_mask:0xf
	v_cndmask_b32_dpp v110, v250, v246, vcc row_ror:8 row_mask:0xf bank_mask:0xf
	v_cndmask_b32_dpp v111, v251, v247, vcc row_ror:8 row_mask:0xf bank_mask:0xf
	v_cndmask_b32_dpp v112, v208, v248, vcc row_ror:8 row_mask:0xf bank_mask:0xf
	v_cndmask_b32_dpp v113, v209, v249, vcc row_ror:8 row_mask:0xf bank_mask:0xf
	s_not_b64 vcc, s[6:7]
	v_cndmask_b32_dpp v114, v0, v4, vcc row_ror:8 row_mask:0xf bank_mask:0xf
	v_cndmask_b32_dpp v115, v1, v5, vcc row_ror:8 row_mask:0xf bank_mask:0xf
	v_cndmask_b32_dpp v116, v2, v6, vcc row_ror:8 row_mask:0xf bank_mask:0xf
	v_cndmask_b32_dpp v117, v3, v7, vcc row_ror:8 row_mask:0xf bank_mask:0xf
	v_cndmask_b32_dpp v106, v246, v250, vcc row_ror:8 row_mask:0xf bank_mask:0xf
	v_cndmask_b32_dpp v107, v247, v251, vcc row_ror:8 row_mask:0xf bank_mask:0xf
	v_cndmask_b32_dpp v108, v248, v208, vcc row_ror:8 row_mask:0xf bank_mask:0xf
	v_cndmask_b32_dpp v109, v249, v209, vcc row_ror:8 row_mask:0xf bank_mask:0xf
	global_store_dwordx4 v171, v[118:121], s[2:3] nt
	global_store_dwordx4 v171, v[114:117], s[18:19] nt
	global_store_dwordx4 v171, v[110:113], s[78:79] nt
	global_store_dwordx4 v171, v[106:109], s[22:23] nt
	s_waitcnt vmcnt(12)
	s_mov_b64 vcc, s[6:7]
	v_cndmask_b32_dpp v0, v242, v238, vcc row_ror:8 row_mask:0xf bank_mask:0xf
	v_cndmask_b32_dpp v1, v243, v239, vcc row_ror:8 row_mask:0xf bank_mask:0xf
	v_cndmask_b32_dpp v2, v244, v240, vcc row_ror:8 row_mask:0xf bank_mask:0xf
	v_cndmask_b32_dpp v3, v245, v241, vcc row_ror:8 row_mask:0xf bank_mask:0xf
	s_not_b64 vcc, s[6:7]
	v_cndmask_b32_dpp v4, v238, v242, vcc row_ror:8 row_mask:0xf bank_mask:0xf
	v_cndmask_b32_dpp v5, v239, v243, vcc row_ror:8 row_mask:0xf bank_mask:0xf
	v_cndmask_b32_dpp v6, v240, v244, vcc row_ror:8 row_mask:0xf bank_mask:0xf
	v_cndmask_b32_dpp v7, v241, v245, vcc row_ror:8 row_mask:0xf bank_mask:0xf
	s_add_u32 s14, s14, 0x8000
	s_addc_u32 s15, s15, 0
	s_add_u32 s12, s12, 0x8000
	s_addc_u32 s13, s13, 0
	global_load_dwordx4 v[238:241], v171, s[14:15]
	global_load_dwordx4 v[242:245], v171, s[12:13]
	v_lshlrev_b32_e32 v246, 16, v0
	v_and_b32_e32 v247, 0xffff0000, v0
	v_pk_fma_f32 v[102:103], v[102:103], v[142:143], v[246:247]
	v_lshlrev_b32_e32 v248, 16, v1
	v_and_b32_e32 v249, 0xffff0000, v1
	v_pk_fma_f32 v[104:105], v[104:105], v[144:145], v[248:249]
	v_lshlrev_b32_e32 v250, 16, v2
	v_and_b32_e32 v251, 0xffff0000, v2
	v_pk_fma_f32 v[98:99], v[98:99], v[150:151], v[250:251]
	v_lshlrev_b32_e32 v208, 16, v3
	v_and_b32_e32 v209, 0xffff0000, v3
	v_pk_fma_f32 v[100:101], v[100:101], v[152:153], v[208:209]
	v_lshlrev_b32_e32 v246, 16, v4
	v_and_b32_e32 v247, 0xffff0000, v4
	v_pk_fma_f32 v[92:93], v[92:93], v[138:139], v[246:247]
	v_lshlrev_b32_e32 v248, 16, v5
	v_and_b32_e32 v249, 0xffff0000, v5
	v_pk_fma_f32 v[94:95], v[94:95], v[140:141], v[248:249]
	v_lshlrev_b32_e32 v250, 16, v6
	v_and_b32_e32 v251, 0xffff0000, v6
	v_pk_fma_f32 v[88:89], v[88:89], v[146:147], v[250:251]
	v_lshlrev_b32_e32 v208, 16, v7
	v_and_b32_e32 v209, 0xffff0000, v7
	v_pk_fma_f32 v[90:91], v[90:91], v[148:149], v[208:209]
	v_cvt_pk_bf16_f32 v0, v102, v103
	v_cvt_pk_bf16_f32 v1, v104, v105
	v_cvt_pk_bf16_f32 v2, v98, v99
	v_cvt_pk_bf16_f32 v3, v100, v101
	v_cvt_pk_bf16_f32 v4, v92, v93
	v_cvt_pk_bf16_f32 v5, v94, v95
	v_cvt_pk_bf16_f32 v6, v88, v89
	v_cvt_pk_bf16_f32 v7, v90, v91
	v_mul_f32_e32 v246, v103, v103
	v_mul_f32_e32 v248, v105, v105
	v_fmac_f32_e32 v246, v102, v102
	v_fmac_f32_e32 v248, v104, v104
	v_add_f32_e32 v246, v246, v248
	v_mul_f32_e32 v248, v99, v99
	v_fmac_f32_e32 v248, v98, v98
	v_add_f32_e32 v246, v246, v248
	v_mul_f32_e32 v248, v101, v101
	v_fmac_f32_e32 v248, v100, v100
	v_add_f32_e32 v246, v248, v246
	v_mul_f32_e32 v247, v93, v93
	v_mul_f32_e32 v248, v95, v95
	v_fmac_f32_e32 v247, v92, v92
	v_fmac_f32_e32 v248, v94, v94
	v_add_f32_e32 v247, v247, v248
	v_mul_f32_e32 v248, v89, v89
	v_fmac_f32_e32 v248, v88, v88
	v_add_f32_e32 v247, v247, v248
	v_mul_f32_e32 v248, v91, v91
	v_fmac_f32_e32 v248, v90, v90
	v_add_f32_e32 v247, v248, v247
	v_add_f32_e32 v246, v246, v247
	v_mov_b32_e32 v247, v246
	s_nop 1
	v_permlane16_swap_b32_e32 v246, v247
	s_nop 1
	v_add_f32_e32 v246, v246, v247
	v_mov_b32_e32 v247, v246
	s_nop 1
	v_permlane32_swap_b32_e32 v246, v247
	v_add_u32_e32 v248, s8, v223
	s_nop 0
	v_add_f32_e32 v246, v246, v247
	s_mov_b64 exec, s[44:45]
	ds_write_b32 v248, v246 offset:512
	s_mov_b64 exec, -1
	v_pk_mul_f32 v[102:103], v[180:181], v[102:103]
	v_pk_mul_f32 v[104:105], v[182:183], v[104:105]
	v_pk_mul_f32 v[98:99], v[184:185], v[98:99]
	v_pk_mul_f32 v[100:101], v[186:187], v[100:101]
	v_pk_mul_f32 v[92:93], v[188:189], v[92:93]
	v_pk_mul_f32 v[94:95], v[190:191], v[94:95]
	v_pk_mul_f32 v[88:89], v[192:193], v[88:89]
	v_pk_mul_f32 v[90:91], v[194:195], v[90:91]
	v_cvt_pk_bf16_f32 v246, v102, v103
	v_cvt_pk_bf16_f32 v247, v104, v105
	v_cvt_pk_bf16_f32 v248, v98, v99
	v_cvt_pk_bf16_f32 v249, v100, v101
	v_cvt_pk_bf16_f32 v250, v92, v93
	v_cvt_pk_bf16_f32 v251, v94, v95
	v_cvt_pk_bf16_f32 v208, v88, v89
	v_cvt_pk_bf16_f32 v209, v90, v91
	s_add_u32 s2, s2, 0x8000
	s_addc_u32 s3, s3, 0
	s_add_u32 s18, s18, 0x8000
	s_addc_u32 s19, s19, 0
	s_add_u32 s78, s78, 0x8000
	s_addc_u32 s79, s79, 0
	s_add_u32 s22, s22, 0x8000
	s_addc_u32 s23, s23, 0
	s_mov_b64 vcc, s[6:7]
	v_cndmask_b32_dpp v102, v4, v0, vcc row_ror:8 row_mask:0xf bank_mask:0xf
	v_cndmask_b32_dpp v103, v5, v1, vcc row_ror:8 row_mask:0xf bank_mask:0xf
	v_cndmask_b32_dpp v104, v6, v2, vcc row_ror:8 row_mask:0xf bank_mask:0xf
	v_cndmask_b32_dpp v105, v7, v3, vcc row_ror:8 row_mask:0xf bank_mask:0xf
	v_cndmask_b32_dpp v92, v250, v246, vcc row_ror:8 row_mask:0xf bank_mask:0xf
	v_cndmask_b32_dpp v93, v251, v247, vcc row_ror:8 row_mask:0xf bank_mask:0xf
	v_cndmask_b32_dpp v94, v208, v248, vcc row_ror:8 row_mask:0xf bank_mask:0xf
	v_cndmask_b32_dpp v95, v209, v249, vcc row_ror:8 row_mask:0xf bank_mask:0xf
	s_not_b64 vcc, s[6:7]
	v_cndmask_b32_dpp v98, v0, v4, vcc row_ror:8 row_mask:0xf bank_mask:0xf
	v_cndmask_b32_dpp v99, v1, v5, vcc row_ror:8 row_mask:0xf bank_mask:0xf
	v_cndmask_b32_dpp v100, v2, v6, vcc row_ror:8 row_mask:0xf bank_mask:0xf
	v_cndmask_b32_dpp v101, v3, v7, vcc row_ror:8 row_mask:0xf bank_mask:0xf
	v_cndmask_b32_dpp v88, v246, v250, vcc row_ror:8 row_mask:0xf bank_mask:0xf
	v_cndmask_b32_dpp v89, v247, v251, vcc row_ror:8 row_mask:0xf bank_mask:0xf
	v_cndmask_b32_dpp v90, v248, v208, vcc row_ror:8 row_mask:0xf bank_mask:0xf
	v_cndmask_b32_dpp v91, v249, v209, vcc row_ror:8 row_mask:0xf bank_mask:0xf
	global_store_dwordx4 v171, v[102:105], s[2:3] nt
	global_store_dwordx4 v171, v[98:101], s[18:19] nt
	global_store_dwordx4 v171, v[92:95], s[78:79] nt
	global_store_dwordx4 v171, v[88:91], s[22:23] nt
	s_waitcnt vmcnt(16)
	s_mov_b64 vcc, s[6:7]
	v_cndmask_b32_dpp v0, v200, v196, vcc row_ror:8 row_mask:0xf bank_mask:0xf
	v_cndmask_b32_dpp v1, v201, v197, vcc row_ror:8 row_mask:0xf bank_mask:0xf
	v_cndmask_b32_dpp v2, v202, v198, vcc row_ror:8 row_mask:0xf bank_mask:0xf
	v_cndmask_b32_dpp v3, v203, v199, vcc row_ror:8 row_mask:0xf bank_mask:0xf
	s_not_b64 vcc, s[6:7]
	v_cndmask_b32_dpp v4, v196, v200, vcc row_ror:8 row_mask:0xf bank_mask:0xf
	v_cndmask_b32_dpp v5, v197, v201, vcc row_ror:8 row_mask:0xf bank_mask:0xf
	v_cndmask_b32_dpp v6, v198, v202, vcc row_ror:8 row_mask:0xf bank_mask:0xf
	v_cndmask_b32_dpp v7, v199, v203, vcc row_ror:8 row_mask:0xf bank_mask:0xf
	s_add_u32 s14, s14, 0x8000
	s_addc_u32 s15, s15, 0
	s_add_u32 s12, s12, 0x8000
	s_addc_u32 s13, s13, 0
	global_load_dwordx4 v[196:199], v171, s[14:15]
	global_load_dwordx4 v[200:203], v171, s[12:13]
	v_lshlrev_b32_e32 v246, 16, v0
	v_and_b32_e32 v247, 0xffff0000, v0
	v_pk_fma_f32 v[84:85], v[84:85], v[142:143], v[246:247]
	v_lshlrev_b32_e32 v248, 16, v1
	v_and_b32_e32 v249, 0xffff0000, v1
	v_pk_fma_f32 v[86:87], v[86:87], v[144:145], v[248:249]
	v_lshlrev_b32_e32 v250, 16, v2
	v_and_b32_e32 v251, 0xffff0000, v2
	v_pk_fma_f32 v[80:81], v[80:81], v[150:151], v[250:251]
	v_lshlrev_b32_e32 v208, 16, v3
	v_and_b32_e32 v209, 0xffff0000, v3
	v_pk_fma_f32 v[82:83], v[82:83], v[152:153], v[208:209]
	v_lshlrev_b32_e32 v246, 16, v4
	v_and_b32_e32 v247, 0xffff0000, v4
	v_pk_fma_f32 v[76:77], v[76:77], v[138:139], v[246:247]
	v_lshlrev_b32_e32 v248, 16, v5
	v_and_b32_e32 v249, 0xffff0000, v5
	v_pk_fma_f32 v[78:79], v[78:79], v[140:141], v[248:249]
	v_lshlrev_b32_e32 v250, 16, v6
	v_and_b32_e32 v251, 0xffff0000, v6
	v_pk_fma_f32 v[72:73], v[72:73], v[146:147], v[250:251]
	v_lshlrev_b32_e32 v208, 16, v7
	v_and_b32_e32 v209, 0xffff0000, v7
	v_pk_fma_f32 v[74:75], v[74:75], v[148:149], v[208:209]
	v_cvt_pk_bf16_f32 v0, v84, v85
	v_cvt_pk_bf16_f32 v1, v86, v87
	v_cvt_pk_bf16_f32 v2, v80, v81
	v_cvt_pk_bf16_f32 v3, v82, v83
	v_cvt_pk_bf16_f32 v4, v76, v77
	v_cvt_pk_bf16_f32 v5, v78, v79
	v_cvt_pk_bf16_f32 v6, v72, v73
	v_cvt_pk_bf16_f32 v7, v74, v75
	v_mul_f32_e32 v246, v85, v85
	v_mul_f32_e32 v248, v87, v87
	v_fmac_f32_e32 v246, v84, v84
	v_fmac_f32_e32 v248, v86, v86
	v_add_f32_e32 v246, v246, v248
	v_mul_f32_e32 v248, v81, v81
	v_fmac_f32_e32 v248, v80, v80
	v_add_f32_e32 v246, v246, v248
	v_mul_f32_e32 v248, v83, v83
	v_fmac_f32_e32 v248, v82, v82
	v_add_f32_e32 v246, v248, v246
	v_mul_f32_e32 v247, v77, v77
	v_mul_f32_e32 v248, v79, v79
	v_fmac_f32_e32 v247, v76, v76
	v_fmac_f32_e32 v248, v78, v78
	v_add_f32_e32 v247, v247, v248
	v_mul_f32_e32 v248, v73, v73
	v_fmac_f32_e32 v248, v72, v72
	v_add_f32_e32 v247, v247, v248
	v_mul_f32_e32 v248, v75, v75
	v_fmac_f32_e32 v248, v74, v74
	v_add_f32_e32 v247, v248, v247
	v_add_f32_e32 v246, v246, v247
	v_mov_b32_e32 v247, v246
	s_nop 1
	v_permlane16_swap_b32_e32 v246, v247
	s_nop 1
	v_add_f32_e32 v246, v246, v247
	v_mov_b32_e32 v247, v246
	s_nop 1
	v_permlane32_swap_b32_e32 v246, v247
	v_add_u32_e32 v248, s8, v223
	s_nop 0
	v_add_f32_e32 v246, v246, v247
	s_mov_b64 exec, s[44:45]
	ds_write_b32 v248, v246 offset:768
	s_mov_b64 exec, -1
	v_pk_mul_f32 v[84:85], v[180:181], v[84:85]
	v_pk_mul_f32 v[86:87], v[182:183], v[86:87]
	v_pk_mul_f32 v[80:81], v[184:185], v[80:81]
	v_pk_mul_f32 v[82:83], v[186:187], v[82:83]
	v_pk_mul_f32 v[76:77], v[188:189], v[76:77]
	v_pk_mul_f32 v[78:79], v[190:191], v[78:79]
	v_pk_mul_f32 v[72:73], v[192:193], v[72:73]
	v_pk_mul_f32 v[74:75], v[194:195], v[74:75]
	v_cvt_pk_bf16_f32 v246, v84, v85
	v_cvt_pk_bf16_f32 v247, v86, v87
	v_cvt_pk_bf16_f32 v248, v80, v81
	v_cvt_pk_bf16_f32 v249, v82, v83
	v_cvt_pk_bf16_f32 v250, v76, v77
	v_cvt_pk_bf16_f32 v251, v78, v79
	v_cvt_pk_bf16_f32 v208, v72, v73
	v_cvt_pk_bf16_f32 v209, v74, v75
	s_add_u32 s2, s2, 0x8000
	s_addc_u32 s3, s3, 0
	s_add_u32 s18, s18, 0x8000
	s_addc_u32 s19, s19, 0
	s_add_u32 s78, s78, 0x8000
	s_addc_u32 s79, s79, 0
	s_add_u32 s22, s22, 0x8000
	s_addc_u32 s23, s23, 0
	s_mov_b64 vcc, s[6:7]
	v_cndmask_b32_dpp v84, v4, v0, vcc row_ror:8 row_mask:0xf bank_mask:0xf
	v_cndmask_b32_dpp v85, v5, v1, vcc row_ror:8 row_mask:0xf bank_mask:0xf
	v_cndmask_b32_dpp v86, v6, v2, vcc row_ror:8 row_mask:0xf bank_mask:0xf
	v_cndmask_b32_dpp v87, v7, v3, vcc row_ror:8 row_mask:0xf bank_mask:0xf
	v_cndmask_b32_dpp v76, v250, v246, vcc row_ror:8 row_mask:0xf bank_mask:0xf
	v_cndmask_b32_dpp v77, v251, v247, vcc row_ror:8 row_mask:0xf bank_mask:0xf
	v_cndmask_b32_dpp v78, v208, v248, vcc row_ror:8 row_mask:0xf bank_mask:0xf
	v_cndmask_b32_dpp v79, v209, v249, vcc row_ror:8 row_mask:0xf bank_mask:0xf
	s_not_b64 vcc, s[6:7]
	v_cndmask_b32_dpp v80, v0, v4, vcc row_ror:8 row_mask:0xf bank_mask:0xf
	v_cndmask_b32_dpp v81, v1, v5, vcc row_ror:8 row_mask:0xf bank_mask:0xf
	v_cndmask_b32_dpp v82, v2, v6, vcc row_ror:8 row_mask:0xf bank_mask:0xf
	v_cndmask_b32_dpp v83, v3, v7, vcc row_ror:8 row_mask:0xf bank_mask:0xf
	v_cndmask_b32_dpp v72, v246, v250, vcc row_ror:8 row_mask:0xf bank_mask:0xf
	v_cndmask_b32_dpp v73, v247, v251, vcc row_ror:8 row_mask:0xf bank_mask:0xf
	v_cndmask_b32_dpp v74, v248, v208, vcc row_ror:8 row_mask:0xf bank_mask:0xf
	v_cndmask_b32_dpp v75, v249, v209, vcc row_ror:8 row_mask:0xf bank_mask:0xf
	global_store_dwordx4 v171, v[84:87], s[2:3] nt
	global_store_dwordx4 v171, v[80:83], s[18:19] nt
	global_store_dwordx4 v171, v[76:79], s[78:79] nt
	global_store_dwordx4 v171, v[72:75], s[22:23] nt
	s_waitcnt vmcnt(16)
	s_mov_b64 vcc, s[6:7]
	v_cndmask_b32_dpp v0, v234, v204, vcc row_ror:8 row_mask:0xf bank_mask:0xf
	v_cndmask_b32_dpp v1, v235, v205, vcc row_ror:8 row_mask:0xf bank_mask:0xf
	v_cndmask_b32_dpp v2, v236, v206, vcc row_ror:8 row_mask:0xf bank_mask:0xf
	v_cndmask_b32_dpp v3, v237, v207, vcc row_ror:8 row_mask:0xf bank_mask:0xf
	s_not_b64 vcc, s[6:7]
	v_cndmask_b32_dpp v4, v204, v234, vcc row_ror:8 row_mask:0xf bank_mask:0xf
	v_cndmask_b32_dpp v5, v205, v235, vcc row_ror:8 row_mask:0xf bank_mask:0xf
	v_cndmask_b32_dpp v6, v206, v236, vcc row_ror:8 row_mask:0xf bank_mask:0xf
	v_cndmask_b32_dpp v7, v207, v237, vcc row_ror:8 row_mask:0xf bank_mask:0xf
	s_add_u32 s14, s14, 0x8000
	s_addc_u32 s15, s15, 0
	s_add_u32 s12, s12, 0x8000
	s_addc_u32 s13, s13, 0
	global_load_dwordx4 v[204:207], v171, s[14:15]
	global_load_dwordx4 v[234:237], v171, s[12:13]
	v_lshlrev_b32_e32 v246, 16, v0
	v_and_b32_e32 v247, 0xffff0000, v0
	v_pk_fma_f32 v[68:69], v[68:69], v[142:143], v[246:247]
	v_lshlrev_b32_e32 v248, 16, v1
	v_and_b32_e32 v249, 0xffff0000, v1
	v_pk_fma_f32 v[70:71], v[70:71], v[144:145], v[248:249]
	v_lshlrev_b32_e32 v250, 16, v2
	v_and_b32_e32 v251, 0xffff0000, v2
	v_pk_fma_f32 v[64:65], v[64:65], v[150:151], v[250:251]
	v_lshlrev_b32_e32 v208, 16, v3
	v_and_b32_e32 v209, 0xffff0000, v3
	v_pk_fma_f32 v[66:67], v[66:67], v[152:153], v[208:209]
	v_lshlrev_b32_e32 v246, 16, v4
	v_and_b32_e32 v247, 0xffff0000, v4
	v_pk_fma_f32 v[60:61], v[60:61], v[138:139], v[246:247]
	v_lshlrev_b32_e32 v248, 16, v5
	v_and_b32_e32 v249, 0xffff0000, v5
	v_pk_fma_f32 v[62:63], v[62:63], v[140:141], v[248:249]
	v_lshlrev_b32_e32 v250, 16, v6
	v_and_b32_e32 v251, 0xffff0000, v6
	v_pk_fma_f32 v[56:57], v[56:57], v[146:147], v[250:251]
	v_lshlrev_b32_e32 v208, 16, v7
	v_and_b32_e32 v209, 0xffff0000, v7
	v_pk_fma_f32 v[58:59], v[58:59], v[148:149], v[208:209]
	v_cvt_pk_bf16_f32 v0, v68, v69
	v_cvt_pk_bf16_f32 v1, v70, v71
	v_cvt_pk_bf16_f32 v2, v64, v65
	v_cvt_pk_bf16_f32 v3, v66, v67
	v_cvt_pk_bf16_f32 v4, v60, v61
	v_cvt_pk_bf16_f32 v5, v62, v63
	v_cvt_pk_bf16_f32 v6, v56, v57
	v_cvt_pk_bf16_f32 v7, v58, v59
	v_mul_f32_e32 v246, v69, v69
	v_mul_f32_e32 v248, v71, v71
	v_fmac_f32_e32 v246, v68, v68
	v_fmac_f32_e32 v248, v70, v70
	v_add_f32_e32 v246, v246, v248
	v_mul_f32_e32 v248, v65, v65
	v_fmac_f32_e32 v248, v64, v64
	v_add_f32_e32 v246, v246, v248
	v_mul_f32_e32 v248, v67, v67
	v_fmac_f32_e32 v248, v66, v66
	v_add_f32_e32 v246, v248, v246
	v_mul_f32_e32 v247, v61, v61
	v_mul_f32_e32 v248, v63, v63
	v_fmac_f32_e32 v247, v60, v60
	v_fmac_f32_e32 v248, v62, v62
	v_add_f32_e32 v247, v247, v248
	v_mul_f32_e32 v248, v57, v57
	v_fmac_f32_e32 v248, v56, v56
	v_add_f32_e32 v247, v247, v248
	v_mul_f32_e32 v248, v59, v59
	v_fmac_f32_e32 v248, v58, v58
	v_add_f32_e32 v247, v248, v247
	v_add_f32_e32 v246, v246, v247
	v_mov_b32_e32 v247, v246
	s_nop 1
	v_permlane16_swap_b32_e32 v246, v247
	s_nop 1
	v_add_f32_e32 v246, v246, v247
	v_mov_b32_e32 v247, v246
	s_nop 1
	v_permlane32_swap_b32_e32 v246, v247
	v_add_u32_e32 v248, s8, v223
	s_nop 0
	v_add_f32_e32 v246, v246, v247
	s_mov_b64 exec, s[44:45]
	ds_write_b32 v248, v246 offset:2048
	s_mov_b64 exec, -1
	v_pk_mul_f32 v[68:69], v[180:181], v[68:69]
	v_pk_mul_f32 v[70:71], v[182:183], v[70:71]
	v_pk_mul_f32 v[64:65], v[184:185], v[64:65]
	v_pk_mul_f32 v[66:67], v[186:187], v[66:67]
	v_pk_mul_f32 v[60:61], v[188:189], v[60:61]
	v_pk_mul_f32 v[62:63], v[190:191], v[62:63]
	v_pk_mul_f32 v[56:57], v[192:193], v[56:57]
	v_pk_mul_f32 v[58:59], v[194:195], v[58:59]
	v_cvt_pk_bf16_f32 v246, v68, v69
	v_cvt_pk_bf16_f32 v247, v70, v71
	v_cvt_pk_bf16_f32 v248, v64, v65
	v_cvt_pk_bf16_f32 v249, v66, v67
	v_cvt_pk_bf16_f32 v250, v60, v61
	v_cvt_pk_bf16_f32 v251, v62, v63
	v_cvt_pk_bf16_f32 v208, v56, v57
	v_cvt_pk_bf16_f32 v209, v58, v59
	s_add_u32 s2, s2, 0x28000
	s_addc_u32 s3, s3, 0
	s_add_u32 s18, s18, 0x28000
	s_addc_u32 s19, s19, 0
	s_add_u32 s78, s78, 0x28000
	s_addc_u32 s79, s79, 0
	s_add_u32 s22, s22, 0x28000
	s_addc_u32 s23, s23, 0
	s_mov_b64 vcc, s[6:7]
	v_cndmask_b32_dpp v68, v4, v0, vcc row_ror:8 row_mask:0xf bank_mask:0xf
	v_cndmask_b32_dpp v69, v5, v1, vcc row_ror:8 row_mask:0xf bank_mask:0xf
	v_cndmask_b32_dpp v70, v6, v2, vcc row_ror:8 row_mask:0xf bank_mask:0xf
	v_cndmask_b32_dpp v71, v7, v3, vcc row_ror:8 row_mask:0xf bank_mask:0xf
	v_cndmask_b32_dpp v60, v250, v246, vcc row_ror:8 row_mask:0xf bank_mask:0xf
	v_cndmask_b32_dpp v61, v251, v247, vcc row_ror:8 row_mask:0xf bank_mask:0xf
	v_cndmask_b32_dpp v62, v208, v248, vcc row_ror:8 row_mask:0xf bank_mask:0xf
	v_cndmask_b32_dpp v63, v209, v249, vcc row_ror:8 row_mask:0xf bank_mask:0xf
	s_not_b64 vcc, s[6:7]
	v_cndmask_b32_dpp v64, v0, v4, vcc row_ror:8 row_mask:0xf bank_mask:0xf
	v_cndmask_b32_dpp v65, v1, v5, vcc row_ror:8 row_mask:0xf bank_mask:0xf
	v_cndmask_b32_dpp v66, v2, v6, vcc row_ror:8 row_mask:0xf bank_mask:0xf
	v_cndmask_b32_dpp v67, v3, v7, vcc row_ror:8 row_mask:0xf bank_mask:0xf
	v_cndmask_b32_dpp v56, v246, v250, vcc row_ror:8 row_mask:0xf bank_mask:0xf
	v_cndmask_b32_dpp v57, v247, v251, vcc row_ror:8 row_mask:0xf bank_mask:0xf
	v_cndmask_b32_dpp v58, v248, v208, vcc row_ror:8 row_mask:0xf bank_mask:0xf
	v_cndmask_b32_dpp v59, v249, v209, vcc row_ror:8 row_mask:0xf bank_mask:0xf
	global_store_dwordx4 v171, v[68:71], s[2:3] nt
	global_store_dwordx4 v171, v[64:67], s[18:19] nt
	global_store_dwordx4 v171, v[60:63], s[78:79] nt
	global_store_dwordx4 v171, v[56:59], s[22:23] nt
	s_waitcnt vmcnt(16)
	s_mov_b64 vcc, s[6:7]
	v_cndmask_b32_dpp v0, v242, v238, vcc row_ror:8 row_mask:0xf bank_mask:0xf
	v_cndmask_b32_dpp v1, v243, v239, vcc row_ror:8 row_mask:0xf bank_mask:0xf
	v_cndmask_b32_dpp v2, v244, v240, vcc row_ror:8 row_mask:0xf bank_mask:0xf
	v_cndmask_b32_dpp v3, v245, v241, vcc row_ror:8 row_mask:0xf bank_mask:0xf
	s_not_b64 vcc, s[6:7]
	v_cndmask_b32_dpp v4, v238, v242, vcc row_ror:8 row_mask:0xf bank_mask:0xf
	v_cndmask_b32_dpp v5, v239, v243, vcc row_ror:8 row_mask:0xf bank_mask:0xf
	v_cndmask_b32_dpp v6, v240, v244, vcc row_ror:8 row_mask:0xf bank_mask:0xf
	v_cndmask_b32_dpp v7, v241, v245, vcc row_ror:8 row_mask:0xf bank_mask:0xf
	v_lshlrev_b32_e32 v246, 16, v0
	v_and_b32_e32 v247, 0xffff0000, v0
	v_pk_fma_f32 v[52:53], v[52:53], v[142:143], v[246:247]
	v_lshlrev_b32_e32 v248, 16, v1
	v_and_b32_e32 v249, 0xffff0000, v1
	v_pk_fma_f32 v[54:55], v[54:55], v[144:145], v[248:249]
	v_lshlrev_b32_e32 v250, 16, v2
	v_and_b32_e32 v251, 0xffff0000, v2
	v_pk_fma_f32 v[48:49], v[48:49], v[150:151], v[250:251]
	v_lshlrev_b32_e32 v208, 16, v3
	v_and_b32_e32 v209, 0xffff0000, v3
	v_pk_fma_f32 v[50:51], v[50:51], v[152:153], v[208:209]
	v_lshlrev_b32_e32 v246, 16, v4
	v_and_b32_e32 v247, 0xffff0000, v4
	v_pk_fma_f32 v[44:45], v[44:45], v[138:139], v[246:247]
	v_lshlrev_b32_e32 v248, 16, v5
	v_and_b32_e32 v249, 0xffff0000, v5
	v_pk_fma_f32 v[46:47], v[46:47], v[140:141], v[248:249]
	v_lshlrev_b32_e32 v250, 16, v6
	v_and_b32_e32 v251, 0xffff0000, v6
	v_pk_fma_f32 v[40:41], v[40:41], v[146:147], v[250:251]
	v_lshlrev_b32_e32 v208, 16, v7
	v_and_b32_e32 v209, 0xffff0000, v7
	v_pk_fma_f32 v[42:43], v[42:43], v[148:149], v[208:209]
	v_cvt_pk_bf16_f32 v0, v52, v53
	v_cvt_pk_bf16_f32 v1, v54, v55
	v_cvt_pk_bf16_f32 v2, v48, v49
	v_cvt_pk_bf16_f32 v3, v50, v51
	v_cvt_pk_bf16_f32 v4, v44, v45
	v_cvt_pk_bf16_f32 v5, v46, v47
	v_cvt_pk_bf16_f32 v6, v40, v41
	v_cvt_pk_bf16_f32 v7, v42, v43
	v_mul_f32_e32 v246, v53, v53
	v_mul_f32_e32 v248, v55, v55
	v_fmac_f32_e32 v246, v52, v52
	v_fmac_f32_e32 v248, v54, v54
	v_add_f32_e32 v246, v246, v248
	v_mul_f32_e32 v248, v49, v49
	v_fmac_f32_e32 v248, v48, v48
	v_add_f32_e32 v246, v246, v248
	v_mul_f32_e32 v248, v51, v51
	v_fmac_f32_e32 v248, v50, v50
	v_add_f32_e32 v246, v248, v246
	v_mul_f32_e32 v247, v45, v45
	v_mul_f32_e32 v248, v47, v47
	v_fmac_f32_e32 v247, v44, v44
	v_fmac_f32_e32 v248, v46, v46
	v_add_f32_e32 v247, v247, v248
	v_mul_f32_e32 v248, v41, v41
	v_fmac_f32_e32 v248, v40, v40
	v_add_f32_e32 v247, v247, v248
	v_mul_f32_e32 v248, v43, v43
	v_fmac_f32_e32 v248, v42, v42
	v_add_f32_e32 v247, v248, v247
	v_add_f32_e32 v246, v246, v247
	v_mov_b32_e32 v247, v246
	s_nop 1
	v_permlane16_swap_b32_e32 v246, v247
	s_nop 1
	v_add_f32_e32 v246, v246, v247
	v_mov_b32_e32 v247, v246
	s_nop 1
	v_permlane32_swap_b32_e32 v246, v247
	v_add_u32_e32 v248, s8, v223
	s_nop 0
	v_add_f32_e32 v246, v246, v247
	s_mov_b64 exec, s[44:45]
	ds_write_b32 v248, v246 offset:2304
	s_mov_b64 exec, -1
	v_pk_mul_f32 v[52:53], v[180:181], v[52:53]
	v_pk_mul_f32 v[54:55], v[182:183], v[54:55]
	v_pk_mul_f32 v[48:49], v[184:185], v[48:49]
	v_pk_mul_f32 v[50:51], v[186:187], v[50:51]
	v_pk_mul_f32 v[44:45], v[188:189], v[44:45]
	v_pk_mul_f32 v[46:47], v[190:191], v[46:47]
	v_pk_mul_f32 v[40:41], v[192:193], v[40:41]
	v_pk_mul_f32 v[42:43], v[194:195], v[42:43]
	v_cvt_pk_bf16_f32 v246, v52, v53
	v_cvt_pk_bf16_f32 v247, v54, v55
	v_cvt_pk_bf16_f32 v248, v48, v49
	v_cvt_pk_bf16_f32 v249, v50, v51
	v_cvt_pk_bf16_f32 v250, v44, v45
	v_cvt_pk_bf16_f32 v251, v46, v47
	v_cvt_pk_bf16_f32 v208, v40, v41
	v_cvt_pk_bf16_f32 v209, v42, v43
	s_add_u32 s2, s2, 0x8000
	s_addc_u32 s3, s3, 0
	s_add_u32 s18, s18, 0x8000
	s_addc_u32 s19, s19, 0
	s_add_u32 s78, s78, 0x8000
	s_addc_u32 s79, s79, 0
	s_add_u32 s22, s22, 0x8000
	s_addc_u32 s23, s23, 0
	s_mov_b64 vcc, s[6:7]
	v_cndmask_b32_dpp v52, v4, v0, vcc row_ror:8 row_mask:0xf bank_mask:0xf
	v_cndmask_b32_dpp v53, v5, v1, vcc row_ror:8 row_mask:0xf bank_mask:0xf
	v_cndmask_b32_dpp v54, v6, v2, vcc row_ror:8 row_mask:0xf bank_mask:0xf
	v_cndmask_b32_dpp v55, v7, v3, vcc row_ror:8 row_mask:0xf bank_mask:0xf
	v_cndmask_b32_dpp v44, v250, v246, vcc row_ror:8 row_mask:0xf bank_mask:0xf
	v_cndmask_b32_dpp v45, v251, v247, vcc row_ror:8 row_mask:0xf bank_mask:0xf
	v_cndmask_b32_dpp v46, v208, v248, vcc row_ror:8 row_mask:0xf bank_mask:0xf
	v_cndmask_b32_dpp v47, v209, v249, vcc row_ror:8 row_mask:0xf bank_mask:0xf
	s_not_b64 vcc, s[6:7]
	v_cndmask_b32_dpp v48, v0, v4, vcc row_ror:8 row_mask:0xf bank_mask:0xf
	v_cndmask_b32_dpp v49, v1, v5, vcc row_ror:8 row_mask:0xf bank_mask:0xf
	v_cndmask_b32_dpp v50, v2, v6, vcc row_ror:8 row_mask:0xf bank_mask:0xf
	v_cndmask_b32_dpp v51, v3, v7, vcc row_ror:8 row_mask:0xf bank_mask:0xf
	v_cndmask_b32_dpp v40, v246, v250, vcc row_ror:8 row_mask:0xf bank_mask:0xf
	v_cndmask_b32_dpp v41, v247, v251, vcc row_ror:8 row_mask:0xf bank_mask:0xf
	v_cndmask_b32_dpp v42, v248, v208, vcc row_ror:8 row_mask:0xf bank_mask:0xf
	v_cndmask_b32_dpp v43, v249, v209, vcc row_ror:8 row_mask:0xf bank_mask:0xf
	global_store_dwordx4 v171, v[52:55], s[2:3] nt
	global_store_dwordx4 v171, v[48:51], s[18:19] nt
	global_store_dwordx4 v171, v[44:47], s[78:79] nt
	global_store_dwordx4 v171, v[40:43], s[22:23] nt
	s_waitcnt vmcnt(14)
	s_mov_b64 vcc, s[6:7]
	v_cndmask_b32_dpp v0, v200, v196, vcc row_ror:8 row_mask:0xf bank_mask:0xf
	v_cndmask_b32_dpp v1, v201, v197, vcc row_ror:8 row_mask:0xf bank_mask:0xf
	v_cndmask_b32_dpp v2, v202, v198, vcc row_ror:8 row_mask:0xf bank_mask:0xf
	v_cndmask_b32_dpp v3, v203, v199, vcc row_ror:8 row_mask:0xf bank_mask:0xf
	s_not_b64 vcc, s[6:7]
	v_cndmask_b32_dpp v4, v196, v200, vcc row_ror:8 row_mask:0xf bank_mask:0xf
	v_cndmask_b32_dpp v5, v197, v201, vcc row_ror:8 row_mask:0xf bank_mask:0xf
	v_cndmask_b32_dpp v6, v198, v202, vcc row_ror:8 row_mask:0xf bank_mask:0xf
	v_cndmask_b32_dpp v7, v199, v203, vcc row_ror:8 row_mask:0xf bank_mask:0xf
	v_lshlrev_b32_e32 v246, 16, v0
	v_and_b32_e32 v247, 0xffff0000, v0
	v_pk_fma_f32 v[36:37], v[36:37], v[142:143], v[246:247]
	v_lshlrev_b32_e32 v248, 16, v1
	v_and_b32_e32 v249, 0xffff0000, v1
	v_pk_fma_f32 v[38:39], v[38:39], v[144:145], v[248:249]
	v_lshlrev_b32_e32 v250, 16, v2
	v_and_b32_e32 v251, 0xffff0000, v2
	v_pk_fma_f32 v[32:33], v[32:33], v[150:151], v[250:251]
	v_lshlrev_b32_e32 v208, 16, v3
	v_and_b32_e32 v209, 0xffff0000, v3
	v_pk_fma_f32 v[34:35], v[34:35], v[152:153], v[208:209]
	v_lshlrev_b32_e32 v246, 16, v4
	v_and_b32_e32 v247, 0xffff0000, v4
	v_pk_fma_f32 v[28:29], v[28:29], v[138:139], v[246:247]
	v_lshlrev_b32_e32 v248, 16, v5
	v_and_b32_e32 v249, 0xffff0000, v5
	v_pk_fma_f32 v[30:31], v[30:31], v[140:141], v[248:249]
	v_lshlrev_b32_e32 v250, 16, v6
	v_and_b32_e32 v251, 0xffff0000, v6
	v_pk_fma_f32 v[24:25], v[24:25], v[146:147], v[250:251]
	v_lshlrev_b32_e32 v208, 16, v7
	v_and_b32_e32 v209, 0xffff0000, v7
	v_pk_fma_f32 v[26:27], v[26:27], v[148:149], v[208:209]
	v_cvt_pk_bf16_f32 v0, v36, v37
	v_cvt_pk_bf16_f32 v1, v38, v39
	v_cvt_pk_bf16_f32 v2, v32, v33
	v_cvt_pk_bf16_f32 v3, v34, v35
	v_cvt_pk_bf16_f32 v4, v28, v29
	v_cvt_pk_bf16_f32 v5, v30, v31
	v_cvt_pk_bf16_f32 v6, v24, v25
	v_cvt_pk_bf16_f32 v7, v26, v27
	v_mul_f32_e32 v246, v37, v37
	v_mul_f32_e32 v248, v39, v39
	v_fmac_f32_e32 v246, v36, v36
	v_fmac_f32_e32 v248, v38, v38
	v_add_f32_e32 v246, v246, v248
	v_mul_f32_e32 v248, v33, v33
	v_fmac_f32_e32 v248, v32, v32
	v_add_f32_e32 v246, v246, v248
	v_mul_f32_e32 v248, v35, v35
	v_fmac_f32_e32 v248, v34, v34
	v_add_f32_e32 v246, v248, v246
	v_mul_f32_e32 v247, v29, v29
	v_mul_f32_e32 v248, v31, v31
	v_fmac_f32_e32 v247, v28, v28
	v_fmac_f32_e32 v248, v30, v30
	v_add_f32_e32 v247, v247, v248
	v_mul_f32_e32 v248, v25, v25
	v_fmac_f32_e32 v248, v24, v24
	v_add_f32_e32 v247, v247, v248
	v_mul_f32_e32 v248, v27, v27
	v_fmac_f32_e32 v248, v26, v26
	v_add_f32_e32 v247, v248, v247
	v_add_f32_e32 v246, v246, v247
	v_mov_b32_e32 v247, v246
	s_nop 1
	v_permlane16_swap_b32_e32 v246, v247
	s_nop 1
	v_add_f32_e32 v246, v246, v247
	v_mov_b32_e32 v247, v246
	s_nop 1
	v_permlane32_swap_b32_e32 v246, v247
	v_add_u32_e32 v248, s8, v223
	s_nop 0
	v_add_f32_e32 v246, v246, v247
	s_mov_b64 exec, s[44:45]
	ds_write_b32 v248, v246 offset:2560
	s_mov_b64 exec, -1
	v_pk_mul_f32 v[36:37], v[180:181], v[36:37]
	v_pk_mul_f32 v[38:39], v[182:183], v[38:39]
	v_pk_mul_f32 v[32:33], v[184:185], v[32:33]
	v_pk_mul_f32 v[34:35], v[186:187], v[34:35]
	v_pk_mul_f32 v[28:29], v[188:189], v[28:29]
	v_pk_mul_f32 v[30:31], v[190:191], v[30:31]
	v_pk_mul_f32 v[24:25], v[192:193], v[24:25]
	v_pk_mul_f32 v[26:27], v[194:195], v[26:27]
	v_cvt_pk_bf16_f32 v246, v36, v37
	v_cvt_pk_bf16_f32 v247, v38, v39
	v_cvt_pk_bf16_f32 v248, v32, v33
	v_cvt_pk_bf16_f32 v249, v34, v35
	v_cvt_pk_bf16_f32 v250, v28, v29
	v_cvt_pk_bf16_f32 v251, v30, v31
	v_cvt_pk_bf16_f32 v208, v24, v25
	v_cvt_pk_bf16_f32 v209, v26, v27
	s_add_u32 s2, s2, 0x8000
	s_addc_u32 s3, s3, 0
	s_add_u32 s18, s18, 0x8000
	s_addc_u32 s19, s19, 0
	s_add_u32 s78, s78, 0x8000
	s_addc_u32 s79, s79, 0
	s_add_u32 s22, s22, 0x8000
	s_addc_u32 s23, s23, 0
	s_mov_b64 vcc, s[6:7]
	v_cndmask_b32_dpp v36, v4, v0, vcc row_ror:8 row_mask:0xf bank_mask:0xf
	v_cndmask_b32_dpp v37, v5, v1, vcc row_ror:8 row_mask:0xf bank_mask:0xf
	v_cndmask_b32_dpp v38, v6, v2, vcc row_ror:8 row_mask:0xf bank_mask:0xf
	v_cndmask_b32_dpp v39, v7, v3, vcc row_ror:8 row_mask:0xf bank_mask:0xf
	v_cndmask_b32_dpp v28, v250, v246, vcc row_ror:8 row_mask:0xf bank_mask:0xf
	v_cndmask_b32_dpp v29, v251, v247, vcc row_ror:8 row_mask:0xf bank_mask:0xf
	v_cndmask_b32_dpp v30, v208, v248, vcc row_ror:8 row_mask:0xf bank_mask:0xf
	v_cndmask_b32_dpp v31, v209, v249, vcc row_ror:8 row_mask:0xf bank_mask:0xf
	s_not_b64 vcc, s[6:7]
	v_cndmask_b32_dpp v32, v0, v4, vcc row_ror:8 row_mask:0xf bank_mask:0xf
	v_cndmask_b32_dpp v33, v1, v5, vcc row_ror:8 row_mask:0xf bank_mask:0xf
	v_cndmask_b32_dpp v34, v2, v6, vcc row_ror:8 row_mask:0xf bank_mask:0xf
	v_cndmask_b32_dpp v35, v3, v7, vcc row_ror:8 row_mask:0xf bank_mask:0xf
	v_cndmask_b32_dpp v24, v246, v250, vcc row_ror:8 row_mask:0xf bank_mask:0xf
	v_cndmask_b32_dpp v25, v247, v251, vcc row_ror:8 row_mask:0xf bank_mask:0xf
	v_cndmask_b32_dpp v26, v248, v208, vcc row_ror:8 row_mask:0xf bank_mask:0xf
	v_cndmask_b32_dpp v27, v249, v209, vcc row_ror:8 row_mask:0xf bank_mask:0xf
	global_store_dwordx4 v171, v[36:39], s[2:3] nt
	global_store_dwordx4 v171, v[32:35], s[18:19] nt
	global_store_dwordx4 v171, v[28:31], s[78:79] nt
	global_store_dwordx4 v171, v[24:27], s[22:23] nt
	s_waitcnt vmcnt(12)
	s_mov_b64 vcc, s[6:7]
	v_cndmask_b32_dpp v0, v234, v204, vcc row_ror:8 row_mask:0xf bank_mask:0xf
	v_cndmask_b32_dpp v1, v235, v205, vcc row_ror:8 row_mask:0xf bank_mask:0xf
	v_cndmask_b32_dpp v2, v236, v206, vcc row_ror:8 row_mask:0xf bank_mask:0xf
	v_cndmask_b32_dpp v3, v237, v207, vcc row_ror:8 row_mask:0xf bank_mask:0xf
	s_not_b64 vcc, s[6:7]
	v_cndmask_b32_dpp v4, v204, v234, vcc row_ror:8 row_mask:0xf bank_mask:0xf
	v_cndmask_b32_dpp v5, v205, v235, vcc row_ror:8 row_mask:0xf bank_mask:0xf
	v_cndmask_b32_dpp v6, v206, v236, vcc row_ror:8 row_mask:0xf bank_mask:0xf
	v_cndmask_b32_dpp v7, v207, v237, vcc row_ror:8 row_mask:0xf bank_mask:0xf
	v_lshlrev_b32_e32 v246, 16, v0
	v_and_b32_e32 v247, 0xffff0000, v0
	v_pk_fma_f32 v[20:21], v[20:21], v[142:143], v[246:247]
	v_lshlrev_b32_e32 v248, 16, v1
	v_and_b32_e32 v249, 0xffff0000, v1
	v_pk_fma_f32 v[22:23], v[22:23], v[144:145], v[248:249]
	v_lshlrev_b32_e32 v250, 16, v2
	v_and_b32_e32 v251, 0xffff0000, v2
	v_pk_fma_f32 v[16:17], v[16:17], v[150:151], v[250:251]
	v_lshlrev_b32_e32 v208, 16, v3
	v_and_b32_e32 v209, 0xffff0000, v3
	v_pk_fma_f32 v[18:19], v[18:19], v[152:153], v[208:209]
	v_lshlrev_b32_e32 v246, 16, v4
	v_and_b32_e32 v247, 0xffff0000, v4
	v_pk_fma_f32 v[12:13], v[12:13], v[138:139], v[246:247]
	v_lshlrev_b32_e32 v248, 16, v5
	v_and_b32_e32 v249, 0xffff0000, v5
	v_pk_fma_f32 v[14:15], v[14:15], v[140:141], v[248:249]
	v_lshlrev_b32_e32 v250, 16, v6
	v_and_b32_e32 v251, 0xffff0000, v6
	v_pk_fma_f32 v[8:9], v[8:9], v[146:147], v[250:251]
	v_lshlrev_b32_e32 v208, 16, v7
	v_and_b32_e32 v209, 0xffff0000, v7
	v_pk_fma_f32 v[10:11], v[10:11], v[148:149], v[208:209]
	v_cvt_pk_bf16_f32 v0, v20, v21
	v_cvt_pk_bf16_f32 v1, v22, v23
	v_cvt_pk_bf16_f32 v2, v16, v17
	v_cvt_pk_bf16_f32 v3, v18, v19
	v_cvt_pk_bf16_f32 v4, v12, v13
	v_cvt_pk_bf16_f32 v5, v14, v15
	v_cvt_pk_bf16_f32 v6, v8, v9
	v_cvt_pk_bf16_f32 v7, v10, v11
	v_mul_f32_e32 v246, v21, v21
	v_mul_f32_e32 v248, v23, v23
	v_fmac_f32_e32 v246, v20, v20
	v_fmac_f32_e32 v248, v22, v22
	v_add_f32_e32 v246, v246, v248
	v_mul_f32_e32 v248, v17, v17
	v_fmac_f32_e32 v248, v16, v16
	v_add_f32_e32 v246, v246, v248
	v_mul_f32_e32 v248, v19, v19
	v_fmac_f32_e32 v248, v18, v18
	v_add_f32_e32 v246, v248, v246
	v_mul_f32_e32 v247, v13, v13
	v_mul_f32_e32 v248, v15, v15
	v_fmac_f32_e32 v247, v12, v12
	v_fmac_f32_e32 v248, v14, v14
	v_add_f32_e32 v247, v247, v248
	v_mul_f32_e32 v248, v9, v9
	v_fmac_f32_e32 v248, v8, v8
	v_add_f32_e32 v247, v247, v248
	v_mul_f32_e32 v248, v11, v11
	v_fmac_f32_e32 v248, v10, v10
	v_add_f32_e32 v247, v248, v247
	v_add_f32_e32 v246, v246, v247
	v_mov_b32_e32 v247, v246
	s_nop 1
	v_permlane16_swap_b32_e32 v246, v247
	s_nop 1
	v_add_f32_e32 v246, v246, v247
	v_mov_b32_e32 v247, v246
	s_nop 1
	v_permlane32_swap_b32_e32 v246, v247
	v_add_u32_e32 v248, s8, v223
	s_nop 0
	v_add_f32_e32 v246, v246, v247
	s_mov_b64 exec, s[44:45]
	ds_write_b32 v248, v246 offset:2816
	s_mov_b64 exec, -1
	v_pk_mul_f32 v[20:21], v[180:181], v[20:21]
	v_pk_mul_f32 v[22:23], v[182:183], v[22:23]
	v_pk_mul_f32 v[16:17], v[184:185], v[16:17]
	v_pk_mul_f32 v[18:19], v[186:187], v[18:19]
	v_pk_mul_f32 v[12:13], v[188:189], v[12:13]
	v_pk_mul_f32 v[14:15], v[190:191], v[14:15]
	v_pk_mul_f32 v[8:9], v[192:193], v[8:9]
	v_pk_mul_f32 v[10:11], v[194:195], v[10:11]
	v_cvt_pk_bf16_f32 v246, v20, v21
	v_cvt_pk_bf16_f32 v247, v22, v23
	v_cvt_pk_bf16_f32 v248, v16, v17
	v_cvt_pk_bf16_f32 v249, v18, v19
	v_cvt_pk_bf16_f32 v250, v12, v13
	v_cvt_pk_bf16_f32 v251, v14, v15
	v_cvt_pk_bf16_f32 v208, v8, v9
	v_cvt_pk_bf16_f32 v209, v10, v11
	s_add_u32 s2, s2, 0x8000
	s_addc_u32 s3, s3, 0
	s_add_u32 s18, s18, 0x8000
	s_addc_u32 s19, s19, 0
	s_add_u32 s78, s78, 0x8000
	s_addc_u32 s79, s79, 0
	s_add_u32 s22, s22, 0x8000
	s_addc_u32 s23, s23, 0
	s_mov_b64 vcc, s[6:7]
	v_cndmask_b32_dpp v20, v4, v0, vcc row_ror:8 row_mask:0xf bank_mask:0xf
	v_cndmask_b32_dpp v21, v5, v1, vcc row_ror:8 row_mask:0xf bank_mask:0xf
	v_cndmask_b32_dpp v22, v6, v2, vcc row_ror:8 row_mask:0xf bank_mask:0xf
	v_cndmask_b32_dpp v23, v7, v3, vcc row_ror:8 row_mask:0xf bank_mask:0xf
	v_cndmask_b32_dpp v12, v250, v246, vcc row_ror:8 row_mask:0xf bank_mask:0xf
	v_cndmask_b32_dpp v13, v251, v247, vcc row_ror:8 row_mask:0xf bank_mask:0xf
	v_cndmask_b32_dpp v14, v208, v248, vcc row_ror:8 row_mask:0xf bank_mask:0xf
	v_cndmask_b32_dpp v15, v209, v249, vcc row_ror:8 row_mask:0xf bank_mask:0xf
	s_not_b64 vcc, s[6:7]
	v_cndmask_b32_dpp v16, v0, v4, vcc row_ror:8 row_mask:0xf bank_mask:0xf
	v_cndmask_b32_dpp v17, v1, v5, vcc row_ror:8 row_mask:0xf bank_mask:0xf
	v_cndmask_b32_dpp v18, v2, v6, vcc row_ror:8 row_mask:0xf bank_mask:0xf
	v_cndmask_b32_dpp v19, v3, v7, vcc row_ror:8 row_mask:0xf bank_mask:0xf
	v_cndmask_b32_dpp v8, v246, v250, vcc row_ror:8 row_mask:0xf bank_mask:0xf
	v_cndmask_b32_dpp v9, v247, v251, vcc row_ror:8 row_mask:0xf bank_mask:0xf
	v_cndmask_b32_dpp v10, v248, v208, vcc row_ror:8 row_mask:0xf bank_mask:0xf
	v_cndmask_b32_dpp v11, v249, v209, vcc row_ror:8 row_mask:0xf bank_mask:0xf
	global_store_dwordx4 v171, v[20:23], s[2:3] nt
	global_store_dwordx4 v171, v[16:19], s[18:19] nt
	global_store_dwordx4 v171, v[12:15], s[78:79] nt
	global_store_dwordx4 v171, v[8:11], s[22:23] nt
	s_mov_b32 s100, 1
	s_branch .LBB0_714
.Lfo_nong:
	global_load_dwordx4 v[142:145], v170, s[16:17]
	global_load_dwordx4 v[150:153], v170, s[16:17] offset:16
	global_load_dwordx4 v[138:141], v170, s[16:17] offset:128
	global_load_dwordx4 v[146:149], v170, s[16:17] offset:144
	global_load_dwordx4 v[196:199], v171, s[14:15]
	global_load_dwordx4 v[200:203], v171, s[12:13]
	s_add_u32 s14, s14, 0x8000
	s_addc_u32 s15, s15, 0
	s_add_u32 s12, s12, 0x8000
	s_addc_u32 s13, s13, 0
	global_load_dwordx4 v[204:207], v171, s[14:15]
	global_load_dwordx4 v[234:237], v171, s[12:13]
	s_add_u32 s14, s14, 0x8000
	s_addc_u32 s15, s15, 0
	s_add_u32 s12, s12, 0x8000
	s_addc_u32 s13, s13, 0
	global_load_dwordx4 v[238:241], v171, s[14:15]
	global_load_dwordx4 v[242:245], v171, s[12:13]
	s_waitcnt vmcnt(4)
	s_mov_b64 vcc, s[6:7]
	v_cndmask_b32_dpp v0, v200, v196, vcc row_ror:8 row_mask:0xf bank_mask:0xf
	v_cndmask_b32_dpp v1, v201, v197, vcc row_ror:8 row_mask:0xf bank_mask:0xf
	v_cndmask_b32_dpp v2, v202, v198, vcc row_ror:8 row_mask:0xf bank_mask:0xf
	v_cndmask_b32_dpp v3, v203, v199, vcc row_ror:8 row_mask:0xf bank_mask:0xf
	s_not_b64 vcc, s[6:7]
	v_cndmask_b32_dpp v4, v196, v200, vcc row_ror:8 row_mask:0xf bank_mask:0xf
	v_cndmask_b32_dpp v5, v197, v201, vcc row_ror:8 row_mask:0xf bank_mask:0xf
	v_cndmask_b32_dpp v6, v198, v202, vcc row_ror:8 row_mask:0xf bank_mask:0xf
	v_cndmask_b32_dpp v7, v199, v203, vcc row_ror:8 row_mask:0xf bank_mask:0xf
	s_add_u32 s14, s14, 0x8000
	s_addc_u32 s15, s15, 0
	s_add_u32 s12, s12, 0x8000
	s_addc_u32 s13, s13, 0
	global_load_dwordx4 v[196:199], v171, s[14:15]
	global_load_dwordx4 v[200:203], v171, s[12:13]
	v_lshlrev_b32_e32 v246, 16, v0
	v_and_b32_e32 v247, 0xffff0000, v0
	v_pk_fma_f32 v[134:135], v[134:135], v[142:143], v[246:247]
	v_lshlrev_b32_e32 v248, 16, v1
	v_and_b32_e32 v249, 0xffff0000, v1
	v_pk_fma_f32 v[136:137], v[136:137], v[144:145], v[248:249]
	v_lshlrev_b32_e32 v250, 16, v2
	v_and_b32_e32 v251, 0xffff0000, v2
	v_pk_fma_f32 v[130:131], v[130:131], v[150:151], v[250:251]
	v_lshlrev_b32_e32 v208, 16, v3
	v_and_b32_e32 v209, 0xffff0000, v3
	v_pk_fma_f32 v[132:133], v[132:133], v[152:153], v[208:209]
	v_lshlrev_b32_e32 v246, 16, v4
	v_and_b32_e32 v247, 0xffff0000, v4
	v_pk_fma_f32 v[126:127], v[126:127], v[138:139], v[246:247]
	v_lshlrev_b32_e32 v248, 16, v5
	v_and_b32_e32 v249, 0xffff0000, v5
	v_pk_fma_f32 v[128:129], v[128:129], v[140:141], v[248:249]
	v_lshlrev_b32_e32 v250, 16, v6
	v_and_b32_e32 v251, 0xffff0000, v6
	v_pk_fma_f32 v[122:123], v[122:123], v[146:147], v[250:251]
	v_lshlrev_b32_e32 v208, 16, v7
	v_and_b32_e32 v209, 0xffff0000, v7
	v_pk_fma_f32 v[124:125], v[124:125], v[148:149], v[208:209]
	v_cvt_pk_bf16_f32 v0, v134, v135
	v_cvt_pk_bf16_f32 v1, v136, v137
	v_cvt_pk_bf16_f32 v2, v130, v131
	v_cvt_pk_bf16_f32 v3, v132, v133
	v_cvt_pk_bf16_f32 v4, v126, v127
	v_cvt_pk_bf16_f32 v5, v128, v129
	v_cvt_pk_bf16_f32 v6, v122, v123
	v_cvt_pk_bf16_f32 v7, v124, v125
	v_mul_f32_e32 v246, v135, v135
	v_mul_f32_e32 v248, v137, v137
	v_fmac_f32_e32 v246, v134, v134
	v_fmac_f32_e32 v248, v136, v136
	v_add_f32_e32 v246, v246, v248
	v_mul_f32_e32 v248, v131, v131
	v_fmac_f32_e32 v248, v130, v130
	v_add_f32_e32 v246, v246, v248
	v_mul_f32_e32 v248, v133, v133
	v_fmac_f32_e32 v248, v132, v132
	v_add_f32_e32 v246, v248, v246
	v_mul_f32_e32 v247, v127, v127
	v_mul_f32_e32 v248, v129, v129
	v_fmac_f32_e32 v247, v126, v126
	v_fmac_f32_e32 v248, v128, v128
	v_add_f32_e32 v247, v247, v248
	v_mul_f32_e32 v248, v123, v123
	v_fmac_f32_e32 v248, v122, v122
	v_add_f32_e32 v247, v247, v248
	v_mul_f32_e32 v248, v125, v125
	v_fmac_f32_e32 v248, v124, v124
	v_add_f32_e32 v247, v248, v247
	v_add_f32_e32 v246, v246, v247
	v_mov_b32_e32 v247, v246
	s_nop 1
	v_permlane16_swap_b32_e32 v246, v247
	s_nop 1
	v_add_f32_e32 v246, v246, v247
	v_mov_b32_e32 v247, v246
	s_nop 1
	v_permlane32_swap_b32_e32 v246, v247
	v_add_u32_e32 v248, s8, v223
	s_nop 0
	v_add_f32_e32 v246, v246, v247
	s_mov_b64 exec, s[44:45]
	ds_write_b32 v248, v246
	s_mov_b64 exec, -1
	s_nop 1
	s_mov_b64 vcc, s[6:7]
	v_cndmask_b32_dpp v134, v4, v0, vcc row_ror:8 row_mask:0xf bank_mask:0xf
	v_cndmask_b32_dpp v135, v5, v1, vcc row_ror:8 row_mask:0xf bank_mask:0xf
	v_cndmask_b32_dpp v136, v6, v2, vcc row_ror:8 row_mask:0xf bank_mask:0xf
	v_cndmask_b32_dpp v137, v7, v3, vcc row_ror:8 row_mask:0xf bank_mask:0xf
	s_not_b64 vcc, s[6:7]
	v_cndmask_b32_dpp v130, v0, v4, vcc row_ror:8 row_mask:0xf bank_mask:0xf
	v_cndmask_b32_dpp v131, v1, v5, vcc row_ror:8 row_mask:0xf bank_mask:0xf
	v_cndmask_b32_dpp v132, v2, v6, vcc row_ror:8 row_mask:0xf bank_mask:0xf
	v_cndmask_b32_dpp v133, v3, v7, vcc row_ror:8 row_mask:0xf bank_mask:0xf
	global_store_dwordx4 v171, v[134:137], s[2:3] nt
	global_store_dwordx4 v171, v[130:133], s[18:19] nt
	s_waitcnt vmcnt(6)
	s_mov_b64 vcc, s[6:7]
	v_cndmask_b32_dpp v0, v234, v204, vcc row_ror:8 row_mask:0xf bank_mask:0xf
	v_cndmask_b32_dpp v1, v235, v205, vcc row_ror:8 row_mask:0xf bank_mask:0xf
	v_cndmask_b32_dpp v2, v236, v206, vcc row_ror:8 row_mask:0xf bank_mask:0xf
	v_cndmask_b32_dpp v3, v237, v207, vcc row_ror:8 row_mask:0xf bank_mask:0xf
	s_not_b64 vcc, s[6:7]
	v_cndmask_b32_dpp v4, v204, v234, vcc row_ror:8 row_mask:0xf bank_mask:0xf
	v_cndmask_b32_dpp v5, v205, v235, vcc row_ror:8 row_mask:0xf bank_mask:0xf
	v_cndmask_b32_dpp v6, v206, v236, vcc row_ror:8 row_mask:0xf bank_mask:0xf
	v_cndmask_b32_dpp v7, v207, v237, vcc row_ror:8 row_mask:0xf bank_mask:0xf
	s_add_u32 s14, s14, 0x28000
	s_addc_u32 s15, s15, 0
	s_add_u32 s12, s12, 0x28000
	s_addc_u32 s13, s13, 0
	global_load_dwordx4 v[204:207], v171, s[14:15]
	global_load_dwordx4 v[234:237], v171, s[12:13]
	v_lshlrev_b32_e32 v246, 16, v0
	v_and_b32_e32 v247, 0xffff0000, v0
	v_pk_fma_f32 v[118:119], v[118:119], v[142:143], v[246:247]
	v_lshlrev_b32_e32 v248, 16, v1
	v_and_b32_e32 v249, 0xffff0000, v1
	v_pk_fma_f32 v[120:121], v[120:121], v[144:145], v[248:249]
	v_lshlrev_b32_e32 v250, 16, v2
	v_and_b32_e32 v251, 0xffff0000, v2
	v_pk_fma_f32 v[114:115], v[114:115], v[150:151], v[250:251]
	v_lshlrev_b32_e32 v208, 16, v3
	v_and_b32_e32 v209, 0xffff0000, v3
	v_pk_fma_f32 v[116:117], v[116:117], v[152:153], v[208:209]
	v_lshlrev_b32_e32 v246, 16, v4
	v_and_b32_e32 v247, 0xffff0000, v4
	v_pk_fma_f32 v[110:111], v[110:111], v[138:139], v[246:247]
	v_lshlrev_b32_e32 v248, 16, v5
	v_and_b32_e32 v249, 0xffff0000, v5
	v_pk_fma_f32 v[112:113], v[112:113], v[140:141], v[248:249]
	v_lshlrev_b32_e32 v250, 16, v6
	v_and_b32_e32 v251, 0xffff0000, v6
	v_pk_fma_f32 v[106:107], v[106:107], v[146:147], v[250:251]
	v_lshlrev_b32_e32 v208, 16, v7
	v_and_b32_e32 v209, 0xffff0000, v7
	v_pk_fma_f32 v[108:109], v[108:109], v[148:149], v[208:209]
	v_cvt_pk_bf16_f32 v0, v118, v119
	v_cvt_pk_bf16_f32 v1, v120, v121
	v_cvt_pk_bf16_f32 v2, v114, v115
	v_cvt_pk_bf16_f32 v3, v116, v117
	v_cvt_pk_bf16_f32 v4, v110, v111
	v_cvt_pk_bf16_f32 v5, v112, v113
	v_cvt_pk_bf16_f32 v6, v106, v107
	v_cvt_pk_bf16_f32 v7, v108, v109
	v_mul_f32_e32 v246, v119, v119
	v_mul_f32_e32 v248, v121, v121
	v_fmac_f32_e32 v246, v118, v118
	v_fmac_f32_e32 v248, v120, v120
	v_add_f32_e32 v246, v246, v248
	v_mul_f32_e32 v248, v115, v115
	v_fmac_f32_e32 v248, v114, v114
	v_add_f32_e32 v246, v246, v248
	v_mul_f32_e32 v248, v117, v117
	v_fmac_f32_e32 v248, v116, v116
	v_add_f32_e32 v246, v248, v246
	v_mul_f32_e32 v247, v111, v111
	v_mul_f32_e32 v248, v113, v113
	v_fmac_f32_e32 v247, v110, v110
	v_fmac_f32_e32 v248, v112, v112
	v_add_f32_e32 v247, v247, v248
	v_mul_f32_e32 v248, v107, v107
	v_fmac_f32_e32 v248, v106, v106
	v_add_f32_e32 v247, v247, v248
	v_mul_f32_e32 v248, v109, v109
	v_fmac_f32_e32 v248, v108, v108
	v_add_f32_e32 v247, v248, v247
	v_add_f32_e32 v246, v246, v247
	v_mov_b32_e32 v247, v246
	s_nop 1
	v_permlane16_swap_b32_e32 v246, v247
	s_nop 1
	v_add_f32_e32 v246, v246, v247
	v_mov_b32_e32 v247, v246
	s_nop 1
	v_permlane32_swap_b32_e32 v246, v247
	v_add_u32_e32 v248, s8, v223
	s_nop 0
	v_add_f32_e32 v246, v246, v247
	s_mov_b64 exec, s[44:45]
	ds_write_b32 v248, v246 offset:256
	s_mov_b64 exec, -1
	s_add_u32 s2, s2, 0x8000
	s_addc_u32 s3, s3, 0
	s_add_u32 s18, s18, 0x8000
	s_addc_u32 s19, s19, 0
	s_mov_b64 vcc, s[6:7]
	v_cndmask_b32_dpp v118, v4, v0, vcc row_ror:8 row_mask:0xf bank_mask:0xf
	v_cndmask_b32_dpp v119, v5, v1, vcc row_ror:8 row_mask:0xf bank_mask:0xf
	v_cndmask_b32_dpp v120, v6, v2, vcc row_ror:8 row_mask:0xf bank_mask:0xf
	v_cndmask_b32_dpp v121, v7, v3, vcc row_ror:8 row_mask:0xf bank_mask:0xf
	s_not_b64 vcc, s[6:7]
	v_cndmask_b32_dpp v114, v0, v4, vcc row_ror:8 row_mask:0xf bank_mask:0xf
	v_cndmask_b32_dpp v115, v1, v5, vcc row_ror:8 row_mask:0xf bank_mask:0xf
	v_cndmask_b32_dpp v116, v2, v6, vcc row_ror:8 row_mask:0xf bank_mask:0xf
	v_cndmask_b32_dpp v117, v3, v7, vcc row_ror:8 row_mask:0xf bank_mask:0xf
	global_store_dwordx4 v171, v[118:121], s[2:3] nt
	global_store_dwordx4 v171, v[114:117], s[18:19] nt
	s_waitcnt vmcnt(8)
	s_mov_b64 vcc, s[6:7]
	v_cndmask_b32_dpp v0, v242, v238, vcc row_ror:8 row_mask:0xf bank_mask:0xf
	v_cndmask_b32_dpp v1, v243, v239, vcc row_ror:8 row_mask:0xf bank_mask:0xf
	v_cndmask_b32_dpp v2, v244, v240, vcc row_ror:8 row_mask:0xf bank_mask:0xf
	v_cndmask_b32_dpp v3, v245, v241, vcc row_ror:8 row_mask:0xf bank_mask:0xf
	s_not_b64 vcc, s[6:7]
	v_cndmask_b32_dpp v4, v238, v242, vcc row_ror:8 row_mask:0xf bank_mask:0xf
	v_cndmask_b32_dpp v5, v239, v243, vcc row_ror:8 row_mask:0xf bank_mask:0xf
	v_cndmask_b32_dpp v6, v240, v244, vcc row_ror:8 row_mask:0xf bank_mask:0xf
	v_cndmask_b32_dpp v7, v241, v245, vcc row_ror:8 row_mask:0xf bank_mask:0xf
	s_add_u32 s14, s14, 0x8000
	s_addc_u32 s15, s15, 0
	s_add_u32 s12, s12, 0x8000
	s_addc_u32 s13, s13, 0
	global_load_dwordx4 v[238:241], v171, s[14:15]
	global_load_dwordx4 v[242:245], v171, s[12:13]
	v_lshlrev_b32_e32 v246, 16, v0
	v_and_b32_e32 v247, 0xffff0000, v0
	v_pk_fma_f32 v[102:103], v[102:103], v[142:143], v[246:247]
	v_lshlrev_b32_e32 v248, 16, v1
	v_and_b32_e32 v249, 0xffff0000, v1
	v_pk_fma_f32 v[104:105], v[104:105], v[144:145], v[248:249]
	v_lshlrev_b32_e32 v250, 16, v2
	v_and_b32_e32 v251, 0xffff0000, v2
	v_pk_fma_f32 v[98:99], v[98:99], v[150:151], v[250:251]
	v_lshlrev_b32_e32 v208, 16, v3
	v_and_b32_e32 v209, 0xffff0000, v3
	v_pk_fma_f32 v[100:101], v[100:101], v[152:153], v[208:209]
	v_lshlrev_b32_e32 v246, 16, v4
	v_and_b32_e32 v247, 0xffff0000, v4
	v_pk_fma_f32 v[92:93], v[92:93], v[138:139], v[246:247]
	v_lshlrev_b32_e32 v248, 16, v5
	v_and_b32_e32 v249, 0xffff0000, v5
	v_pk_fma_f32 v[94:95], v[94:95], v[140:141], v[248:249]
	v_lshlrev_b32_e32 v250, 16, v6
	v_and_b32_e32 v251, 0xffff0000, v6
	v_pk_fma_f32 v[88:89], v[88:89], v[146:147], v[250:251]
	v_lshlrev_b32_e32 v208, 16, v7
	v_and_b32_e32 v209, 0xffff0000, v7
	v_pk_fma_f32 v[90:91], v[90:91], v[148:149], v[208:209]
	v_cvt_pk_bf16_f32 v0, v102, v103
	v_cvt_pk_bf16_f32 v1, v104, v105
	v_cvt_pk_bf16_f32 v2, v98, v99
	v_cvt_pk_bf16_f32 v3, v100, v101
	v_cvt_pk_bf16_f32 v4, v92, v93
	v_cvt_pk_bf16_f32 v5, v94, v95
	v_cvt_pk_bf16_f32 v6, v88, v89
	v_cvt_pk_bf16_f32 v7, v90, v91
	v_mul_f32_e32 v246, v103, v103
	v_mul_f32_e32 v248, v105, v105
	v_fmac_f32_e32 v246, v102, v102
	v_fmac_f32_e32 v248, v104, v104
	v_add_f32_e32 v246, v246, v248
	v_mul_f32_e32 v248, v99, v99
	v_fmac_f32_e32 v248, v98, v98
	v_add_f32_e32 v246, v246, v248
	v_mul_f32_e32 v248, v101, v101
	v_fmac_f32_e32 v248, v100, v100
	v_add_f32_e32 v246, v248, v246
	v_mul_f32_e32 v247, v93, v93
	v_mul_f32_e32 v248, v95, v95
	v_fmac_f32_e32 v247, v92, v92
	v_fmac_f32_e32 v248, v94, v94
	v_add_f32_e32 v247, v247, v248
	v_mul_f32_e32 v248, v89, v89
	v_fmac_f32_e32 v248, v88, v88
	v_add_f32_e32 v247, v247, v248
	v_mul_f32_e32 v248, v91, v91
	v_fmac_f32_e32 v248, v90, v90
	v_add_f32_e32 v247, v248, v247
	v_add_f32_e32 v246, v246, v247
	v_mov_b32_e32 v247, v246
	s_nop 1
	v_permlane16_swap_b32_e32 v246, v247
	s_nop 1
	v_add_f32_e32 v246, v246, v247
	v_mov_b32_e32 v247, v246
	s_nop 1
	v_permlane32_swap_b32_e32 v246, v247
	v_add_u32_e32 v248, s8, v223
	s_nop 0
	v_add_f32_e32 v246, v246, v247
	s_mov_b64 exec, s[44:45]
	ds_write_b32 v248, v246 offset:512
	s_mov_b64 exec, -1
	s_add_u32 s2, s2, 0x8000
	s_addc_u32 s3, s3, 0
	s_add_u32 s18, s18, 0x8000
	s_addc_u32 s19, s19, 0
	s_mov_b64 vcc, s[6:7]
	v_cndmask_b32_dpp v102, v4, v0, vcc row_ror:8 row_mask:0xf bank_mask:0xf
	v_cndmask_b32_dpp v103, v5, v1, vcc row_ror:8 row_mask:0xf bank_mask:0xf
	v_cndmask_b32_dpp v104, v6, v2, vcc row_ror:8 row_mask:0xf bank_mask:0xf
	v_cndmask_b32_dpp v105, v7, v3, vcc row_ror:8 row_mask:0xf bank_mask:0xf
	s_not_b64 vcc, s[6:7]
	v_cndmask_b32_dpp v98, v0, v4, vcc row_ror:8 row_mask:0xf bank_mask:0xf
	v_cndmask_b32_dpp v99, v1, v5, vcc row_ror:8 row_mask:0xf bank_mask:0xf
	v_cndmask_b32_dpp v100, v2, v6, vcc row_ror:8 row_mask:0xf bank_mask:0xf
	v_cndmask_b32_dpp v101, v3, v7, vcc row_ror:8 row_mask:0xf bank_mask:0xf
	global_store_dwordx4 v171, v[102:105], s[2:3] nt
	global_store_dwordx4 v171, v[98:101], s[18:19] nt
	s_waitcnt vmcnt(10)
	s_mov_b64 vcc, s[6:7]
	v_cndmask_b32_dpp v0, v200, v196, vcc row_ror:8 row_mask:0xf bank_mask:0xf
	v_cndmask_b32_dpp v1, v201, v197, vcc row_ror:8 row_mask:0xf bank_mask:0xf
	v_cndmask_b32_dpp v2, v202, v198, vcc row_ror:8 row_mask:0xf bank_mask:0xf
	v_cndmask_b32_dpp v3, v203, v199, vcc row_ror:8 row_mask:0xf bank_mask:0xf
	s_not_b64 vcc, s[6:7]
	v_cndmask_b32_dpp v4, v196, v200, vcc row_ror:8 row_mask:0xf bank_mask:0xf
	v_cndmask_b32_dpp v5, v197, v201, vcc row_ror:8 row_mask:0xf bank_mask:0xf
	v_cndmask_b32_dpp v6, v198, v202, vcc row_ror:8 row_mask:0xf bank_mask:0xf
	v_cndmask_b32_dpp v7, v199, v203, vcc row_ror:8 row_mask:0xf bank_mask:0xf
	s_add_u32 s14, s14, 0x8000
	s_addc_u32 s15, s15, 0
	s_add_u32 s12, s12, 0x8000
	s_addc_u32 s13, s13, 0
	global_load_dwordx4 v[196:199], v171, s[14:15]
	global_load_dwordx4 v[200:203], v171, s[12:13]
	v_lshlrev_b32_e32 v246, 16, v0
	v_and_b32_e32 v247, 0xffff0000, v0
	v_pk_fma_f32 v[84:85], v[84:85], v[142:143], v[246:247]
	v_lshlrev_b32_e32 v248, 16, v1
	v_and_b32_e32 v249, 0xffff0000, v1
	v_pk_fma_f32 v[86:87], v[86:87], v[144:145], v[248:249]
	v_lshlrev_b32_e32 v250, 16, v2
	v_and_b32_e32 v251, 0xffff0000, v2
	v_pk_fma_f32 v[80:81], v[80:81], v[150:151], v[250:251]
	v_lshlrev_b32_e32 v208, 16, v3
	v_and_b32_e32 v209, 0xffff0000, v3
	v_pk_fma_f32 v[82:83], v[82:83], v[152:153], v[208:209]
	v_lshlrev_b32_e32 v246, 16, v4
	v_and_b32_e32 v247, 0xffff0000, v4
	v_pk_fma_f32 v[76:77], v[76:77], v[138:139], v[246:247]
	v_lshlrev_b32_e32 v248, 16, v5
	v_and_b32_e32 v249, 0xffff0000, v5
	v_pk_fma_f32 v[78:79], v[78:79], v[140:141], v[248:249]
	v_lshlrev_b32_e32 v250, 16, v6
	v_and_b32_e32 v251, 0xffff0000, v6
	v_pk_fma_f32 v[72:73], v[72:73], v[146:147], v[250:251]
	v_lshlrev_b32_e32 v208, 16, v7
	v_and_b32_e32 v209, 0xffff0000, v7
	v_pk_fma_f32 v[74:75], v[74:75], v[148:149], v[208:209]
	v_cvt_pk_bf16_f32 v0, v84, v85
	v_cvt_pk_bf16_f32 v1, v86, v87
	v_cvt_pk_bf16_f32 v2, v80, v81
	v_cvt_pk_bf16_f32 v3, v82, v83
	v_cvt_pk_bf16_f32 v4, v76, v77
	v_cvt_pk_bf16_f32 v5, v78, v79
	v_cvt_pk_bf16_f32 v6, v72, v73
	v_cvt_pk_bf16_f32 v7, v74, v75
	v_mul_f32_e32 v246, v85, v85
	v_mul_f32_e32 v248, v87, v87
	v_fmac_f32_e32 v246, v84, v84
	v_fmac_f32_e32 v248, v86, v86
	v_add_f32_e32 v246, v246, v248
	v_mul_f32_e32 v248, v81, v81
	v_fmac_f32_e32 v248, v80, v80
	v_add_f32_e32 v246, v246, v248
	v_mul_f32_e32 v248, v83, v83
	v_fmac_f32_e32 v248, v82, v82
	v_add_f32_e32 v246, v248, v246
	v_mul_f32_e32 v247, v77, v77
	v_mul_f32_e32 v248, v79, v79
	v_fmac_f32_e32 v247, v76, v76
	v_fmac_f32_e32 v248, v78, v78
	v_add_f32_e32 v247, v247, v248
	v_mul_f32_e32 v248, v73, v73
	v_fmac_f32_e32 v248, v72, v72
	v_add_f32_e32 v247, v247, v248
	v_mul_f32_e32 v248, v75, v75
	v_fmac_f32_e32 v248, v74, v74
	v_add_f32_e32 v247, v248, v247
	v_add_f32_e32 v246, v246, v247
	v_mov_b32_e32 v247, v246
	s_nop 1
	v_permlane16_swap_b32_e32 v246, v247
	s_nop 1
	v_add_f32_e32 v246, v246, v247
	v_mov_b32_e32 v247, v246
	s_nop 1
	v_permlane32_swap_b32_e32 v246, v247
	v_add_u32_e32 v248, s8, v223
	s_nop 0
	v_add_f32_e32 v246, v246, v247
	s_mov_b64 exec, s[44:45]
	ds_write_b32 v248, v246 offset:768
	s_mov_b64 exec, -1
	s_add_u32 s2, s2, 0x8000
	s_addc_u32 s3, s3, 0
	s_add_u32 s18, s18, 0x8000
	s_addc_u32 s19, s19, 0
	s_mov_b64 vcc, s[6:7]
	v_cndmask_b32_dpp v84, v4, v0, vcc row_ror:8 row_mask:0xf bank_mask:0xf
	v_cndmask_b32_dpp v85, v5, v1, vcc row_ror:8 row_mask:0xf bank_mask:0xf
	v_cndmask_b32_dpp v86, v6, v2, vcc row_ror:8 row_mask:0xf bank_mask:0xf
	v_cndmask_b32_dpp v87, v7, v3, vcc row_ror:8 row_mask:0xf bank_mask:0xf
	s_not_b64 vcc, s[6:7]
	v_cndmask_b32_dpp v80, v0, v4, vcc row_ror:8 row_mask:0xf bank_mask:0xf
	v_cndmask_b32_dpp v81, v1, v5, vcc row_ror:8 row_mask:0xf bank_mask:0xf
	v_cndmask_b32_dpp v82, v2, v6, vcc row_ror:8 row_mask:0xf bank_mask:0xf
	v_cndmask_b32_dpp v83, v3, v7, vcc row_ror:8 row_mask:0xf bank_mask:0xf
	global_store_dwordx4 v171, v[84:87], s[2:3] nt
	global_store_dwordx4 v171, v[80:83], s[18:19] nt
	s_waitcnt vmcnt(10)
	s_mov_b64 vcc, s[6:7]
	v_cndmask_b32_dpp v0, v234, v204, vcc row_ror:8 row_mask:0xf bank_mask:0xf
	v_cndmask_b32_dpp v1, v235, v205, vcc row_ror:8 row_mask:0xf bank_mask:0xf
	v_cndmask_b32_dpp v2, v236, v206, vcc row_ror:8 row_mask:0xf bank_mask:0xf
	v_cndmask_b32_dpp v3, v237, v207, vcc row_ror:8 row_mask:0xf bank_mask:0xf
	s_not_b64 vcc, s[6:7]
	v_cndmask_b32_dpp v4, v204, v234, vcc row_ror:8 row_mask:0xf bank_mask:0xf
	v_cndmask_b32_dpp v5, v205, v235, vcc row_ror:8 row_mask:0xf bank_mask:0xf
	v_cndmask_b32_dpp v6, v206, v236, vcc row_ror:8 row_mask:0xf bank_mask:0xf
	v_cndmask_b32_dpp v7, v207, v237, vcc row_ror:8 row_mask:0xf bank_mask:0xf
	s_add_u32 s14, s14, 0x8000
	s_addc_u32 s15, s15, 0
	s_add_u32 s12, s12, 0x8000
	s_addc_u32 s13, s13, 0
	global_load_dwordx4 v[204:207], v171, s[14:15]
	global_load_dwordx4 v[234:237], v171, s[12:13]
	v_lshlrev_b32_e32 v246, 16, v0
	v_and_b32_e32 v247, 0xffff0000, v0
	v_pk_fma_f32 v[68:69], v[68:69], v[142:143], v[246:247]
	v_lshlrev_b32_e32 v248, 16, v1
	v_and_b32_e32 v249, 0xffff0000, v1
	v_pk_fma_f32 v[70:71], v[70:71], v[144:145], v[248:249]
	v_lshlrev_b32_e32 v250, 16, v2
	v_and_b32_e32 v251, 0xffff0000, v2
	v_pk_fma_f32 v[64:65], v[64:65], v[150:151], v[250:251]
	v_lshlrev_b32_e32 v208, 16, v3
	v_and_b32_e32 v209, 0xffff0000, v3
	v_pk_fma_f32 v[66:67], v[66:67], v[152:153], v[208:209]
	v_lshlrev_b32_e32 v246, 16, v4
	v_and_b32_e32 v247, 0xffff0000, v4
	v_pk_fma_f32 v[60:61], v[60:61], v[138:139], v[246:247]
	v_lshlrev_b32_e32 v248, 16, v5
	v_and_b32_e32 v249, 0xffff0000, v5
	v_pk_fma_f32 v[62:63], v[62:63], v[140:141], v[248:249]
	v_lshlrev_b32_e32 v250, 16, v6
	v_and_b32_e32 v251, 0xffff0000, v6
	v_pk_fma_f32 v[56:57], v[56:57], v[146:147], v[250:251]
	v_lshlrev_b32_e32 v208, 16, v7
	v_and_b32_e32 v209, 0xffff0000, v7
	v_pk_fma_f32 v[58:59], v[58:59], v[148:149], v[208:209]
	v_cvt_pk_bf16_f32 v0, v68, v69
	v_cvt_pk_bf16_f32 v1, v70, v71
	v_cvt_pk_bf16_f32 v2, v64, v65
	v_cvt_pk_bf16_f32 v3, v66, v67
	v_cvt_pk_bf16_f32 v4, v60, v61
	v_cvt_pk_bf16_f32 v5, v62, v63
	v_cvt_pk_bf16_f32 v6, v56, v57
	v_cvt_pk_bf16_f32 v7, v58, v59
	v_mul_f32_e32 v246, v69, v69
	v_mul_f32_e32 v248, v71, v71
	v_fmac_f32_e32 v246, v68, v68
	v_fmac_f32_e32 v248, v70, v70
	v_add_f32_e32 v246, v246, v248
	v_mul_f32_e32 v248, v65, v65
	v_fmac_f32_e32 v248, v64, v64
	v_add_f32_e32 v246, v246, v248
	v_mul_f32_e32 v248, v67, v67
	v_fmac_f32_e32 v248, v66, v66
	v_add_f32_e32 v246, v248, v246
	v_mul_f32_e32 v247, v61, v61
	v_mul_f32_e32 v248, v63, v63
	v_fmac_f32_e32 v247, v60, v60
	v_fmac_f32_e32 v248, v62, v62
	v_add_f32_e32 v247, v247, v248
	v_mul_f32_e32 v248, v57, v57
	v_fmac_f32_e32 v248, v56, v56
	v_add_f32_e32 v247, v247, v248
	v_mul_f32_e32 v248, v59, v59
	v_fmac_f32_e32 v248, v58, v58
	v_add_f32_e32 v247, v248, v247
	v_add_f32_e32 v246, v246, v247
	v_mov_b32_e32 v247, v246
	s_nop 1
	v_permlane16_swap_b32_e32 v246, v247
	s_nop 1
	v_add_f32_e32 v246, v246, v247
	v_mov_b32_e32 v247, v246
	s_nop 1
	v_permlane32_swap_b32_e32 v246, v247
	v_add_u32_e32 v248, s8, v223
	s_nop 0
	v_add_f32_e32 v246, v246, v247
	s_mov_b64 exec, s[44:45]
	ds_write_b32 v248, v246 offset:2048
	s_mov_b64 exec, -1
	s_add_u32 s2, s2, 0x28000
	s_addc_u32 s3, s3, 0
	s_add_u32 s18, s18, 0x28000
	s_addc_u32 s19, s19, 0
	s_mov_b64 vcc, s[6:7]
	v_cndmask_b32_dpp v68, v4, v0, vcc row_ror:8 row_mask:0xf bank_mask:0xf
	v_cndmask_b32_dpp v69, v5, v1, vcc row_ror:8 row_mask:0xf bank_mask:0xf
	v_cndmask_b32_dpp v70, v6, v2, vcc row_ror:8 row_mask:0xf bank_mask:0xf
	v_cndmask_b32_dpp v71, v7, v3, vcc row_ror:8 row_mask:0xf bank_mask:0xf
	s_not_b64 vcc, s[6:7]
	v_cndmask_b32_dpp v64, v0, v4, vcc row_ror:8 row_mask:0xf bank_mask:0xf
	v_cndmask_b32_dpp v65, v1, v5, vcc row_ror:8 row_mask:0xf bank_mask:0xf
	v_cndmask_b32_dpp v66, v2, v6, vcc row_ror:8 row_mask:0xf bank_mask:0xf
	v_cndmask_b32_dpp v67, v3, v7, vcc row_ror:8 row_mask:0xf bank_mask:0xf
	global_store_dwordx4 v171, v[68:71], s[2:3] nt
	global_store_dwordx4 v171, v[64:67], s[18:19] nt
	s_waitcnt vmcnt(10)
	s_mov_b64 vcc, s[6:7]
	v_cndmask_b32_dpp v0, v242, v238, vcc row_ror:8 row_mask:0xf bank_mask:0xf
	v_cndmask_b32_dpp v1, v243, v239, vcc row_ror:8 row_mask:0xf bank_mask:0xf
	v_cndmask_b32_dpp v2, v244, v240, vcc row_ror:8 row_mask:0xf bank_mask:0xf
	v_cndmask_b32_dpp v3, v245, v241, vcc row_ror:8 row_mask:0xf bank_mask:0xf
	s_not_b64 vcc, s[6:7]
	v_cndmask_b32_dpp v4, v238, v242, vcc row_ror:8 row_mask:0xf bank_mask:0xf
	v_cndmask_b32_dpp v5, v239, v243, vcc row_ror:8 row_mask:0xf bank_mask:0xf
	v_cndmask_b32_dpp v6, v240, v244, vcc row_ror:8 row_mask:0xf bank_mask:0xf
	v_cndmask_b32_dpp v7, v241, v245, vcc row_ror:8 row_mask:0xf bank_mask:0xf
	v_lshlrev_b32_e32 v246, 16, v0
	v_and_b32_e32 v247, 0xffff0000, v0
	v_pk_fma_f32 v[52:53], v[52:53], v[142:143], v[246:247]
	v_lshlrev_b32_e32 v248, 16, v1
	v_and_b32_e32 v249, 0xffff0000, v1
	v_pk_fma_f32 v[54:55], v[54:55], v[144:145], v[248:249]
	v_lshlrev_b32_e32 v250, 16, v2
	v_and_b32_e32 v251, 0xffff0000, v2
	v_pk_fma_f32 v[48:49], v[48:49], v[150:151], v[250:251]
	v_lshlrev_b32_e32 v208, 16, v3
	v_and_b32_e32 v209, 0xffff0000, v3
	v_pk_fma_f32 v[50:51], v[50:51], v[152:153], v[208:209]
	v_lshlrev_b32_e32 v246, 16, v4
	v_and_b32_e32 v247, 0xffff0000, v4
	v_pk_fma_f32 v[44:45], v[44:45], v[138:139], v[246:247]
	v_lshlrev_b32_e32 v248, 16, v5
	v_and_b32_e32 v249, 0xffff0000, v5
	v_pk_fma_f32 v[46:47], v[46:47], v[140:141], v[248:249]
	v_lshlrev_b32_e32 v250, 16, v6
	v_and_b32_e32 v251, 0xffff0000, v6
	v_pk_fma_f32 v[40:41], v[40:41], v[146:147], v[250:251]
	v_lshlrev_b32_e32 v208, 16, v7
	v_and_b32_e32 v209, 0xffff0000, v7
	v_pk_fma_f32 v[42:43], v[42:43], v[148:149], v[208:209]
	v_cvt_pk_bf16_f32 v0, v52, v53
	v_cvt_pk_bf16_f32 v1, v54, v55
	v_cvt_pk_bf16_f32 v2, v48, v49
	v_cvt_pk_bf16_f32 v3, v50, v51
	v_cvt_pk_bf16_f32 v4, v44, v45
	v_cvt_pk_bf16_f32 v5, v46, v47
	v_cvt_pk_bf16_f32 v6, v40, v41
	v_cvt_pk_bf16_f32 v7, v42, v43
	v_mul_f32_e32 v246, v53, v53
	v_mul_f32_e32 v248, v55, v55
	v_fmac_f32_e32 v246, v52, v52
	v_fmac_f32_e32 v248, v54, v54
	v_add_f32_e32 v246, v246, v248
	v_mul_f32_e32 v248, v49, v49
	v_fmac_f32_e32 v248, v48, v48
	v_add_f32_e32 v246, v246, v248
	v_mul_f32_e32 v248, v51, v51
	v_fmac_f32_e32 v248, v50, v50
	v_add_f32_e32 v246, v248, v246
	v_mul_f32_e32 v247, v45, v45
	v_mul_f32_e32 v248, v47, v47
	v_fmac_f32_e32 v247, v44, v44
	v_fmac_f32_e32 v248, v46, v46
	v_add_f32_e32 v247, v247, v248
	v_mul_f32_e32 v248, v41, v41
	v_fmac_f32_e32 v248, v40, v40
	v_add_f32_e32 v247, v247, v248
	v_mul_f32_e32 v248, v43, v43
	v_fmac_f32_e32 v248, v42, v42
	v_add_f32_e32 v247, v248, v247
	v_add_f32_e32 v246, v246, v247
	v_mov_b32_e32 v247, v246
	s_nop 1
	v_permlane16_swap_b32_e32 v246, v247
	s_nop 1
	v_add_f32_e32 v246, v246, v247
	v_mov_b32_e32 v247, v246
	s_nop 1
	v_permlane32_swap_b32_e32 v246, v247
	v_add_u32_e32 v248, s8, v223
	s_nop 0
	v_add_f32_e32 v246, v246, v247
	s_mov_b64 exec, s[44:45]
	ds_write_b32 v248, v246 offset:2304
	s_mov_b64 exec, -1
	s_add_u32 s2, s2, 0x8000
	s_addc_u32 s3, s3, 0
	s_add_u32 s18, s18, 0x8000
	s_addc_u32 s19, s19, 0
	s_mov_b64 vcc, s[6:7]
	v_cndmask_b32_dpp v52, v4, v0, vcc row_ror:8 row_mask:0xf bank_mask:0xf
	v_cndmask_b32_dpp v53, v5, v1, vcc row_ror:8 row_mask:0xf bank_mask:0xf
	v_cndmask_b32_dpp v54, v6, v2, vcc row_ror:8 row_mask:0xf bank_mask:0xf
	v_cndmask_b32_dpp v55, v7, v3, vcc row_ror:8 row_mask:0xf bank_mask:0xf
	s_not_b64 vcc, s[6:7]
	v_cndmask_b32_dpp v48, v0, v4, vcc row_ror:8 row_mask:0xf bank_mask:0xf
	v_cndmask_b32_dpp v49, v1, v5, vcc row_ror:8 row_mask:0xf bank_mask:0xf
	v_cndmask_b32_dpp v50, v2, v6, vcc row_ror:8 row_mask:0xf bank_mask:0xf
	v_cndmask_b32_dpp v51, v3, v7, vcc row_ror:8 row_mask:0xf bank_mask:0xf
	global_store_dwordx4 v171, v[52:55], s[2:3] nt
	global_store_dwordx4 v171, v[48:51], s[18:19] nt
	s_waitcnt vmcnt(8)
	s_mov_b64 vcc, s[6:7]
	v_cndmask_b32_dpp v0, v200, v196, vcc row_ror:8 row_mask:0xf bank_mask:0xf
	v_cndmask_b32_dpp v1, v201, v197, vcc row_ror:8 row_mask:0xf bank_mask:0xf
	v_cndmask_b32_dpp v2, v202, v198, vcc row_ror:8 row_mask:0xf bank_mask:0xf
	v_cndmask_b32_dpp v3, v203, v199, vcc row_ror:8 row_mask:0xf bank_mask:0xf
	s_not_b64 vcc, s[6:7]
	v_cndmask_b32_dpp v4, v196, v200, vcc row_ror:8 row_mask:0xf bank_mask:0xf
	v_cndmask_b32_dpp v5, v197, v201, vcc row_ror:8 row_mask:0xf bank_mask:0xf
	v_cndmask_b32_dpp v6, v198, v202, vcc row_ror:8 row_mask:0xf bank_mask:0xf
	v_cndmask_b32_dpp v7, v199, v203, vcc row_ror:8 row_mask:0xf bank_mask:0xf
	v_lshlrev_b32_e32 v246, 16, v0
	v_and_b32_e32 v247, 0xffff0000, v0
	v_pk_fma_f32 v[36:37], v[36:37], v[142:143], v[246:247]
	v_lshlrev_b32_e32 v248, 16, v1
	v_and_b32_e32 v249, 0xffff0000, v1
	v_pk_fma_f32 v[38:39], v[38:39], v[144:145], v[248:249]
	v_lshlrev_b32_e32 v250, 16, v2
	v_and_b32_e32 v251, 0xffff0000, v2
	v_pk_fma_f32 v[32:33], v[32:33], v[150:151], v[250:251]
	v_lshlrev_b32_e32 v208, 16, v3
	v_and_b32_e32 v209, 0xffff0000, v3
	v_pk_fma_f32 v[34:35], v[34:35], v[152:153], v[208:209]
	v_lshlrev_b32_e32 v246, 16, v4
	v_and_b32_e32 v247, 0xffff0000, v4
	v_pk_fma_f32 v[28:29], v[28:29], v[138:139], v[246:247]
	v_lshlrev_b32_e32 v248, 16, v5
	v_and_b32_e32 v249, 0xffff0000, v5
	v_pk_fma_f32 v[30:31], v[30:31], v[140:141], v[248:249]
	v_lshlrev_b32_e32 v250, 16, v6
	v_and_b32_e32 v251, 0xffff0000, v6
	v_pk_fma_f32 v[24:25], v[24:25], v[146:147], v[250:251]
	v_lshlrev_b32_e32 v208, 16, v7
	v_and_b32_e32 v209, 0xffff0000, v7
	v_pk_fma_f32 v[26:27], v[26:27], v[148:149], v[208:209]
	v_cvt_pk_bf16_f32 v0, v36, v37
	v_cvt_pk_bf16_f32 v1, v38, v39
	v_cvt_pk_bf16_f32 v2, v32, v33
	v_cvt_pk_bf16_f32 v3, v34, v35
	v_cvt_pk_bf16_f32 v4, v28, v29
	v_cvt_pk_bf16_f32 v5, v30, v31
	v_cvt_pk_bf16_f32 v6, v24, v25
	v_cvt_pk_bf16_f32 v7, v26, v27
	v_mul_f32_e32 v246, v37, v37
	v_mul_f32_e32 v248, v39, v39
	v_fmac_f32_e32 v246, v36, v36
	v_fmac_f32_e32 v248, v38, v38
	v_add_f32_e32 v246, v246, v248
	v_mul_f32_e32 v248, v33, v33
	v_fmac_f32_e32 v248, v32, v32
	v_add_f32_e32 v246, v246, v248
	v_mul_f32_e32 v248, v35, v35
	v_fmac_f32_e32 v248, v34, v34
	v_add_f32_e32 v246, v248, v246
	v_mul_f32_e32 v247, v29, v29
	v_mul_f32_e32 v248, v31, v31
	v_fmac_f32_e32 v247, v28, v28
	v_fmac_f32_e32 v248, v30, v30
	v_add_f32_e32 v247, v247, v248
	v_mul_f32_e32 v248, v25, v25
	v_fmac_f32_e32 v248, v24, v24
	v_add_f32_e32 v247, v247, v248
	v_mul_f32_e32 v248, v27, v27
	v_fmac_f32_e32 v248, v26, v26
	v_add_f32_e32 v247, v248, v247
	v_add_f32_e32 v246, v246, v247
	v_mov_b32_e32 v247, v246
	s_nop 1
	v_permlane16_swap_b32_e32 v246, v247
	s_nop 1
	v_add_f32_e32 v246, v246, v247
	v_mov_b32_e32 v247, v246
	s_nop 1
	v_permlane32_swap_b32_e32 v246, v247
	v_add_u32_e32 v248, s8, v223
	s_nop 0
	v_add_f32_e32 v246, v246, v247
	s_mov_b64 exec, s[44:45]
	ds_write_b32 v248, v246 offset:2560
	s_mov_b64 exec, -1
	s_add_u32 s2, s2, 0x8000
	s_addc_u32 s3, s3, 0
	s_add_u32 s18, s18, 0x8000
	s_addc_u32 s19, s19, 0
	s_mov_b64 vcc, s[6:7]
	v_cndmask_b32_dpp v36, v4, v0, vcc row_ror:8 row_mask:0xf bank_mask:0xf
	v_cndmask_b32_dpp v37, v5, v1, vcc row_ror:8 row_mask:0xf bank_mask:0xf
	v_cndmask_b32_dpp v38, v6, v2, vcc row_ror:8 row_mask:0xf bank_mask:0xf
	v_cndmask_b32_dpp v39, v7, v3, vcc row_ror:8 row_mask:0xf bank_mask:0xf
	s_not_b64 vcc, s[6:7]
	v_cndmask_b32_dpp v32, v0, v4, vcc row_ror:8 row_mask:0xf bank_mask:0xf
	v_cndmask_b32_dpp v33, v1, v5, vcc row_ror:8 row_mask:0xf bank_mask:0xf
	v_cndmask_b32_dpp v34, v2, v6, vcc row_ror:8 row_mask:0xf bank_mask:0xf
	v_cndmask_b32_dpp v35, v3, v7, vcc row_ror:8 row_mask:0xf bank_mask:0xf
	global_store_dwordx4 v171, v[36:39], s[2:3] nt
	global_store_dwordx4 v171, v[32:35], s[18:19] nt
	s_waitcnt vmcnt(6)
	s_mov_b64 vcc, s[6:7]
	v_cndmask_b32_dpp v0, v234, v204, vcc row_ror:8 row_mask:0xf bank_mask:0xf
	v_cndmask_b32_dpp v1, v235, v205, vcc row_ror:8 row_mask:0xf bank_mask:0xf
	v_cndmask_b32_dpp v2, v236, v206, vcc row_ror:8 row_mask:0xf bank_mask:0xf
	v_cndmask_b32_dpp v3, v237, v207, vcc row_ror:8 row_mask:0xf bank_mask:0xf
	s_not_b64 vcc, s[6:7]
	v_cndmask_b32_dpp v4, v204, v234, vcc row_ror:8 row_mask:0xf bank_mask:0xf
	v_cndmask_b32_dpp v5, v205, v235, vcc row_ror:8 row_mask:0xf bank_mask:0xf
	v_cndmask_b32_dpp v6, v206, v236, vcc row_ror:8 row_mask:0xf bank_mask:0xf
	v_cndmask_b32_dpp v7, v207, v237, vcc row_ror:8 row_mask:0xf bank_mask:0xf
	v_lshlrev_b32_e32 v246, 16, v0
	v_and_b32_e32 v247, 0xffff0000, v0
	v_pk_fma_f32 v[20:21], v[20:21], v[142:143], v[246:247]
	v_lshlrev_b32_e32 v248, 16, v1
	v_and_b32_e32 v249, 0xffff0000, v1
	v_pk_fma_f32 v[22:23], v[22:23], v[144:145], v[248:249]
	v_lshlrev_b32_e32 v250, 16, v2
	v_and_b32_e32 v251, 0xffff0000, v2
	v_pk_fma_f32 v[16:17], v[16:17], v[150:151], v[250:251]
	v_lshlrev_b32_e32 v208, 16, v3
	v_and_b32_e32 v209, 0xffff0000, v3
	v_pk_fma_f32 v[18:19], v[18:19], v[152:153], v[208:209]
	v_lshlrev_b32_e32 v246, 16, v4
	v_and_b32_e32 v247, 0xffff0000, v4
	v_pk_fma_f32 v[12:13], v[12:13], v[138:139], v[246:247]
	v_lshlrev_b32_e32 v248, 16, v5
	v_and_b32_e32 v249, 0xffff0000, v5
	v_pk_fma_f32 v[14:15], v[14:15], v[140:141], v[248:249]
	v_lshlrev_b32_e32 v250, 16, v6
	v_and_b32_e32 v251, 0xffff0000, v6
	v_pk_fma_f32 v[8:9], v[8:9], v[146:147], v[250:251]
	v_lshlrev_b32_e32 v208, 16, v7
	v_and_b32_e32 v209, 0xffff0000, v7
	v_pk_fma_f32 v[10:11], v[10:11], v[148:149], v[208:209]
	v_cvt_pk_bf16_f32 v0, v20, v21
	v_cvt_pk_bf16_f32 v1, v22, v23
	v_cvt_pk_bf16_f32 v2, v16, v17
	v_cvt_pk_bf16_f32 v3, v18, v19
	v_cvt_pk_bf16_f32 v4, v12, v13
	v_cvt_pk_bf16_f32 v5, v14, v15
	v_cvt_pk_bf16_f32 v6, v8, v9
	v_cvt_pk_bf16_f32 v7, v10, v11
	v_mul_f32_e32 v246, v21, v21
	v_mul_f32_e32 v248, v23, v23
	v_fmac_f32_e32 v246, v20, v20
	v_fmac_f32_e32 v248, v22, v22
	v_add_f32_e32 v246, v246, v248
	v_mul_f32_e32 v248, v17, v17
	v_fmac_f32_e32 v248, v16, v16
	v_add_f32_e32 v246, v246, v248
	v_mul_f32_e32 v248, v19, v19
	v_fmac_f32_e32 v248, v18, v18
	v_add_f32_e32 v246, v248, v246
	v_mul_f32_e32 v247, v13, v13
	v_mul_f32_e32 v248, v15, v15
	v_fmac_f32_e32 v247, v12, v12
	v_fmac_f32_e32 v248, v14, v14
	v_add_f32_e32 v247, v247, v248
	v_mul_f32_e32 v248, v9, v9
	v_fmac_f32_e32 v248, v8, v8
	v_add_f32_e32 v247, v247, v248
	v_mul_f32_e32 v248, v11, v11
	v_fmac_f32_e32 v248, v10, v10
	v_add_f32_e32 v247, v248, v247
	v_add_f32_e32 v246, v246, v247
	v_mov_b32_e32 v247, v246
	s_nop 1
	v_permlane16_swap_b32_e32 v246, v247
	s_nop 1
	v_add_f32_e32 v246, v246, v247
	v_mov_b32_e32 v247, v246
	s_nop 1
	v_permlane32_swap_b32_e32 v246, v247
	v_add_u32_e32 v248, s8, v223
	s_nop 0
	v_add_f32_e32 v246, v246, v247
	s_mov_b64 exec, s[44:45]
	ds_write_b32 v248, v246 offset:2816
	s_mov_b64 exec, -1
	s_add_u32 s2, s2, 0x8000
	s_addc_u32 s3, s3, 0
	s_add_u32 s18, s18, 0x8000
	s_addc_u32 s19, s19, 0
	s_mov_b64 vcc, s[6:7]
	v_cndmask_b32_dpp v20, v4, v0, vcc row_ror:8 row_mask:0xf bank_mask:0xf
	v_cndmask_b32_dpp v21, v5, v1, vcc row_ror:8 row_mask:0xf bank_mask:0xf
	v_cndmask_b32_dpp v22, v6, v2, vcc row_ror:8 row_mask:0xf bank_mask:0xf
	v_cndmask_b32_dpp v23, v7, v3, vcc row_ror:8 row_mask:0xf bank_mask:0xf
	s_not_b64 vcc, s[6:7]
	v_cndmask_b32_dpp v16, v0, v4, vcc row_ror:8 row_mask:0xf bank_mask:0xf
	v_cndmask_b32_dpp v17, v1, v5, vcc row_ror:8 row_mask:0xf bank_mask:0xf
	v_cndmask_b32_dpp v18, v2, v6, vcc row_ror:8 row_mask:0xf bank_mask:0xf
	v_cndmask_b32_dpp v19, v3, v7, vcc row_ror:8 row_mask:0xf bank_mask:0xf
	global_store_dwordx4 v171, v[20:23], s[2:3] nt
	global_store_dwordx4 v171, v[16:19], s[18:19] nt
	s_mov_b32 s100, 1
	s_branch .LBB0_714
.Lfo_first:
	s_lshr_b32 s14, s34, 3
	s_mul_i32 s14, s14, 0x3000
	s_add_u32 s16, s86, s14
	s_addc_u32 s17, s87, 0
	s_add_u32 s16, s16, 0x2000
	s_addc_u32 s17, s17, 0
	s_add_u32 s86, s88, s14
	s_addc_u32 s87, s89, 0
	s_add_u32 s86, s86, 0x1000
	s_addc_u32 s87, s87, 0
	v_lshl_add_u32 v171, v170, 1, v96
	v_lshl_add_u32 v171, v222, 11, v171
	v_lshlrev_b32_e32 v170, 2, v170
	s_lshl_b32 s14, s34, 8
	s_add_i32 s14, s14, s81
	s_mov_b64 s[12:13], s[18:19]
	s_lshl_b32 s31, s14, 12
	s_lshl_b32 s14, s14, 11
	s_add_u32 s2, s2, s14
	s_addc_u32 s3, s3, 0
	s_add_u32 s78, s78, s14
	s_addc_u32 s79, s79, 0
	s_add_u32 s22, s78, 0x4000
	s_addc_u32 s23, s79, 0
	s_add_u32 s18, s2, 0x4000
	s_addc_u32 s19, s3, 0
	s_add_u32 s14, s12, s31
	s_addc_u32 s15, s13, 0
	global_load_dwordx4 v[142:145], v170, s[16:17]
	global_load_dwordx4 v[150:153], v170, s[16:17] offset:16
	global_load_dwordx4 v[138:141], v170, s[16:17] offset:128
	global_load_dwordx4 v[146:149], v170, s[16:17] offset:144
	v_lshl_add_u32 v96, v163, 12, v170
	global_load_dwordx4 v[196:199], v96, s[14:15]
	global_load_dwordx4 v[200:203], v96, s[14:15] offset:16
	global_load_dwordx4 v[204:207], v96, s[14:15] offset:128
	global_load_dwordx4 v[234:237], v96, s[14:15] offset:144
	global_load_dwordx4 v[180:183], v170, s[86:87]
	global_load_dwordx4 v[184:187], v170, s[86:87] offset:16
	global_load_dwordx4 v[188:191], v170, s[86:87] offset:128
	global_load_dwordx4 v[192:195], v170, s[86:87] offset:144
	global_load_dwordx4 v[238:241], v170, s[26:27]
	global_load_dwordx4 v[242:245], v170, s[26:27] offset:16
	global_load_dwordx4 v[246:249], v170, s[26:27] offset:128
	global_load_dwordx4 v[4:7], v170, s[26:27] offset:144
	s_waitcnt vmcnt(0)
	v_pk_add_f32 v[182:183], v[182:183], 1.0 op_sel_hi:[1,0]
	v_pk_add_f32 v[180:181], v[180:181], 1.0 op_sel_hi:[1,0]
	v_pk_add_f32 v[186:187], v[186:187], 1.0 op_sel_hi:[1,0]
	v_pk_add_f32 v[184:185], v[184:185], 1.0 op_sel_hi:[1,0]
	v_pk_add_f32 v[190:191], v[190:191], 1.0 op_sel_hi:[1,0]
	v_pk_add_f32 v[188:189], v[188:189], 1.0 op_sel_hi:[1,0]
	v_pk_add_f32 v[194:195], v[194:195], 1.0 op_sel_hi:[1,0]
	v_pk_add_f32 v[192:193], v[192:193], 1.0 op_sel_hi:[1,0]
	v_pk_mul_f32 v[182:183], v[240:241], v[182:183]
	v_pk_mul_f32 v[180:181], v[238:239], v[180:181]
	v_pk_mul_f32 v[186:187], v[244:245], v[186:187]
	v_pk_mul_f32 v[184:185], v[242:243], v[184:185]
	v_pk_mul_f32 v[190:191], v[248:249], v[190:191]
	v_pk_mul_f32 v[188:189], v[246:247], v[188:189]
	v_pk_mul_f32 v[194:195], v[6:7], v[194:195]
	v_pk_mul_f32 v[192:193], v[4:5], v[192:193]
	s_add_u32 s14, s14, 0x10000
	s_addc_u32 s15, s15, 0
	global_load_dwordx4 v[238:241], v96, s[14:15]
	global_load_dwordx4 v[242:245], v96, s[14:15] offset:16
	v_pk_fma_f32 v[134:135], v[134:135], v[142:143], v[196:197]
	v_pk_fma_f32 v[136:137], v[136:137], v[144:145], v[198:199]
	v_pk_fma_f32 v[130:131], v[130:131], v[150:151], v[200:201]
	v_pk_fma_f32 v[132:133], v[132:133], v[152:153], v[202:203]
	v_pk_fma_f32 v[126:127], v[126:127], v[138:139], v[204:205]
	v_pk_fma_f32 v[128:129], v[128:129], v[140:141], v[206:207]
	v_pk_fma_f32 v[122:123], v[122:123], v[146:147], v[234:235]
	v_pk_fma_f32 v[124:125], v[124:125], v[148:149], v[236:237]
	global_load_dwordx4 v[196:199], v96, s[14:15] offset:128
	global_load_dwordx4 v[200:203], v96, s[14:15] offset:144
	s_add_u32 s14, s14, 0x10000
	s_addc_u32 s15, s15, 0
	global_load_dwordx4 v[204:207], v96, s[14:15]
	global_load_dwordx4 v[234:237], v96, s[14:15] offset:16
	v_cvt_pk_bf16_f32 v0, v134, v135
	v_cvt_pk_bf16_f32 v1, v136, v137
	v_cvt_pk_bf16_f32 v2, v130, v131
	v_cvt_pk_bf16_f32 v3, v132, v133
	v_cvt_pk_bf16_f32 v4, v126, v127
	v_cvt_pk_bf16_f32 v5, v128, v129
	v_cvt_pk_bf16_f32 v6, v122, v123
	v_cvt_pk_bf16_f32 v7, v124, v125
	v_mul_f32_e32 v246, v135, v135
	v_mul_f32_e32 v248, v137, v137
	v_fmac_f32_e32 v246, v134, v134
	v_fmac_f32_e32 v248, v136, v136
	v_add_f32_e32 v246, v246, v248
	v_mul_f32_e32 v248, v131, v131
	v_fmac_f32_e32 v248, v130, v130
	v_add_f32_e32 v246, v246, v248
	v_mul_f32_e32 v248, v133, v133
	v_fmac_f32_e32 v248, v132, v132
	v_add_f32_e32 v246, v248, v246
	v_mul_f32_e32 v247, v127, v127
	v_mul_f32_e32 v248, v129, v129
	v_fmac_f32_e32 v247, v126, v126
	v_fmac_f32_e32 v248, v128, v128
	v_add_f32_e32 v247, v247, v248
	v_mul_f32_e32 v248, v123, v123
	v_fmac_f32_e32 v248, v122, v122
	v_add_f32_e32 v247, v247, v248
	v_mul_f32_e32 v248, v125, v125
	v_fmac_f32_e32 v248, v124, v124
	v_add_f32_e32 v247, v248, v247
	v_add_f32_e32 v246, v246, v247
	v_mov_b32_e32 v247, v246
	s_nop 1
	v_permlane16_swap_b32_e32 v246, v247
	s_nop 1
	v_add_f32_e32 v246, v246, v247
	v_mov_b32_e32 v247, v246
	s_nop 1
	v_permlane32_swap_b32_e32 v246, v247
	v_add_u32_e32 v248, s8, v223
	s_nop 0
	v_add_f32_e32 v246, v246, v247
	s_mov_b64 exec, s[44:45]
	ds_write_b32 v248, v246
	s_mov_b64 exec, -1
	v_pk_mul_f32 v[134:135], v[180:181], v[134:135]
	v_pk_mul_f32 v[136:137], v[182:183], v[136:137]
	v_pk_mul_f32 v[130:131], v[184:185], v[130:131]
	v_pk_mul_f32 v[132:133], v[186:187], v[132:133]
	v_pk_mul_f32 v[126:127], v[188:189], v[126:127]
	v_pk_mul_f32 v[128:129], v[190:191], v[128:129]
	v_pk_mul_f32 v[122:123], v[192:193], v[122:123]
	v_pk_mul_f32 v[124:125], v[194:195], v[124:125]
	v_cvt_pk_bf16_f32 v246, v134, v135
	v_cvt_pk_bf16_f32 v247, v136, v137
	v_cvt_pk_bf16_f32 v248, v130, v131
	v_cvt_pk_bf16_f32 v249, v132, v133
	v_cvt_pk_bf16_f32 v250, v126, v127
	v_cvt_pk_bf16_f32 v251, v128, v129
	v_cvt_pk_bf16_f32 v208, v122, v123
	v_cvt_pk_bf16_f32 v209, v124, v125
	s_nop 1
	s_mov_b64 vcc, s[6:7]
	v_cndmask_b32_dpp v134, v4, v0, vcc row_ror:8 row_mask:0xf bank_mask:0xf
	v_cndmask_b32_dpp v135, v5, v1, vcc row_ror:8 row_mask:0xf bank_mask:0xf
	v_cndmask_b32_dpp v136, v6, v2, vcc row_ror:8 row_mask:0xf bank_mask:0xf
	v_cndmask_b32_dpp v137, v7, v3, vcc row_ror:8 row_mask:0xf bank_mask:0xf
	v_cndmask_b32_dpp v126, v250, v246, vcc row_ror:8 row_mask:0xf bank_mask:0xf
	v_cndmask_b32_dpp v127, v251, v247, vcc row_ror:8 row_mask:0xf bank_mask:0xf
	v_cndmask_b32_dpp v128, v208, v248, vcc row_ror:8 row_mask:0xf bank_mask:0xf
	v_cndmask_b32_dpp v129, v209, v249, vcc row_ror:8 row_mask:0xf bank_mask:0xf
	s_not_b64 vcc, s[6:7]
	v_cndmask_b32_dpp v130, v0, v4, vcc row_ror:8 row_mask:0xf bank_mask:0xf
	v_cndmask_b32_dpp v131, v1, v5, vcc row_ror:8 row_mask:0xf bank_mask:0xf
	v_cndmask_b32_dpp v132, v2, v6, vcc row_ror:8 row_mask:0xf bank_mask:0xf
	v_cndmask_b32_dpp v133, v3, v7, vcc row_ror:8 row_mask:0xf bank_mask:0xf
	v_cndmask_b32_dpp v122, v246, v250, vcc row_ror:8 row_mask:0xf bank_mask:0xf
	v_cndmask_b32_dpp v123, v247, v251, vcc row_ror:8 row_mask:0xf bank_mask:0xf
	v_cndmask_b32_dpp v124, v248, v208, vcc row_ror:8 row_mask:0xf bank_mask:0xf
	v_cndmask_b32_dpp v125, v249, v209, vcc row_ror:8 row_mask:0xf bank_mask:0xf
	global_store_dwordx4 v171, v[134:137], s[2:3] nt
	global_store_dwordx4 v171, v[130:133], s[18:19] nt
	global_store_dwordx4 v171, v[126:129], s[78:79] nt
	global_store_dwordx4 v171, v[122:125], s[22:23] nt
	s_waitcnt vmcnt(6)
	v_pk_fma_f32 v[118:119], v[118:119], v[142:143], v[238:239]
	v_pk_fma_f32 v[120:121], v[120:121], v[144:145], v[240:241]
	v_pk_fma_f32 v[114:115], v[114:115], v[150:151], v[242:243]
	v_pk_fma_f32 v[116:117], v[116:117], v[152:153], v[244:245]
	v_pk_fma_f32 v[110:111], v[110:111], v[138:139], v[196:197]
	v_pk_fma_f32 v[112:113], v[112:113], v[140:141], v[198:199]
	v_pk_fma_f32 v[106:107], v[106:107], v[146:147], v[200:201]
	v_pk_fma_f32 v[108:109], v[108:109], v[148:149], v[202:203]
	global_load_dwordx4 v[238:241], v96, s[14:15] offset:128
	global_load_dwordx4 v[242:245], v96, s[14:15] offset:144
	s_add_u32 s14, s14, 0x10000
	s_addc_u32 s15, s15, 0
	global_load_dwordx4 v[196:199], v96, s[14:15]
	global_load_dwordx4 v[200:203], v96, s[14:15] offset:16
	v_cvt_pk_bf16_f32 v0, v118, v119
	v_cvt_pk_bf16_f32 v1, v120, v121
	v_cvt_pk_bf16_f32 v2, v114, v115
	v_cvt_pk_bf16_f32 v3, v116, v117
	v_cvt_pk_bf16_f32 v4, v110, v111
	v_cvt_pk_bf16_f32 v5, v112, v113
	v_cvt_pk_bf16_f32 v6, v106, v107
	v_cvt_pk_bf16_f32 v7, v108, v109
	v_mul_f32_e32 v246, v119, v119
	v_mul_f32_e32 v248, v121, v121
	v_fmac_f32_e32 v246, v118, v118
	v_fmac_f32_e32 v248, v120, v120
	v_add_f32_e32 v246, v246, v248
	v_mul_f32_e32 v248, v115, v115
	v_fmac_f32_e32 v248, v114, v114
	v_add_f32_e32 v246, v246, v248
	v_mul_f32_e32 v248, v117, v117
	v_fmac_f32_e32 v248, v116, v116
	v_add_f32_e32 v246, v248, v246
	v_mul_f32_e32 v247, v111, v111
	v_mul_f32_e32 v248, v113, v113
	v_fmac_f32_e32 v247, v110, v110
	v_fmac_f32_e32 v248, v112, v112
	v_add_f32_e32 v247, v247, v248
	v_mul_f32_e32 v248, v107, v107
	v_fmac_f32_e32 v248, v106, v106
	v_add_f32_e32 v247, v247, v248
	v_mul_f32_e32 v248, v109, v109
	v_fmac_f32_e32 v248, v108, v108
	v_add_f32_e32 v247, v248, v247
	v_add_f32_e32 v246, v246, v247
	v_mov_b32_e32 v247, v246
	s_nop 1
	v_permlane16_swap_b32_e32 v246, v247
	s_nop 1
	v_add_f32_e32 v246, v246, v247
	v_mov_b32_e32 v247, v246
	s_nop 1
	v_permlane32_swap_b32_e32 v246, v247
	v_add_u32_e32 v248, s8, v223
	s_nop 0
	v_add_f32_e32 v246, v246, v247
	s_mov_b64 exec, s[44:45]
	ds_write_b32 v248, v246 offset:256
	s_mov_b64 exec, -1
	v_pk_mul_f32 v[118:119], v[180:181], v[118:119]
	v_pk_mul_f32 v[120:121], v[182:183], v[120:121]
	v_pk_mul_f32 v[114:115], v[184:185], v[114:115]
	v_pk_mul_f32 v[116:117], v[186:187], v[116:117]
	v_pk_mul_f32 v[110:111], v[188:189], v[110:111]
	v_pk_mul_f32 v[112:113], v[190:191], v[112:113]
	v_pk_mul_f32 v[106:107], v[192:193], v[106:107]
	v_pk_mul_f32 v[108:109], v[194:195], v[108:109]
	v_cvt_pk_bf16_f32 v246, v118, v119
	v_cvt_pk_bf16_f32 v247, v120, v121
	v_cvt_pk_bf16_f32 v248, v114, v115
	v_cvt_pk_bf16_f32 v249, v116, v117
	v_cvt_pk_bf16_f32 v250, v110, v111
	v_cvt_pk_bf16_f32 v251, v112, v113
	v_cvt_pk_bf16_f32 v208, v106, v107
	v_cvt_pk_bf16_f32 v209, v108, v109
	s_add_u32 s2, s2, 0x8000
	s_addc_u32 s3, s3, 0
	s_add_u32 s18, s18, 0x8000
	s_addc_u32 s19, s19, 0
	s_add_u32 s78, s78, 0x8000
	s_addc_u32 s79, s79, 0
	s_add_u32 s22, s22, 0x8000
	s_addc_u32 s23, s23, 0
	s_mov_b64 vcc, s[6:7]
	v_cndmask_b32_dpp v118, v4, v0, vcc row_ror:8 row_mask:0xf bank_mask:0xf
	v_cndmask_b32_dpp v119, v5, v1, vcc row_ror:8 row_mask:0xf bank_mask:0xf
	v_cndmask_b32_dpp v120, v6, v2, vcc row_ror:8 row_mask:0xf bank_mask:0xf
	v_cndmask_b32_dpp v121, v7, v3, vcc row_ror:8 row_mask:0xf bank_mask:0xf
	v_cndmask_b32_dpp v110, v250, v246, vcc row_ror:8 row_mask:0xf bank_mask:0xf
	v_cndmask_b32_dpp v111, v251, v247, vcc row_ror:8 row_mask:0xf bank_mask:0xf
	v_cndmask_b32_dpp v112, v208, v248, vcc row_ror:8 row_mask:0xf bank_mask:0xf
	v_cndmask_b32_dpp v113, v209, v249, vcc row_ror:8 row_mask:0xf bank_mask:0xf
	s_not_b64 vcc, s[6:7]
	v_cndmask_b32_dpp v114, v0, v4, vcc row_ror:8 row_mask:0xf bank_mask:0xf
	v_cndmask_b32_dpp v115, v1, v5, vcc row_ror:8 row_mask:0xf bank_mask:0xf
	v_cndmask_b32_dpp v116, v2, v6, vcc row_ror:8 row_mask:0xf bank_mask:0xf
	v_cndmask_b32_dpp v117, v3, v7, vcc row_ror:8 row_mask:0xf bank_mask:0xf
	v_cndmask_b32_dpp v106, v246, v250, vcc row_ror:8 row_mask:0xf bank_mask:0xf
	v_cndmask_b32_dpp v107, v247, v251, vcc row_ror:8 row_mask:0xf bank_mask:0xf
	v_cndmask_b32_dpp v108, v248, v208, vcc row_ror:8 row_mask:0xf bank_mask:0xf
	v_cndmask_b32_dpp v109, v249, v209, vcc row_ror:8 row_mask:0xf bank_mask:0xf
	global_store_dwordx4 v171, v[118:121], s[2:3] nt
	global_store_dwordx4 v171, v[114:117], s[18:19] nt
	global_store_dwordx4 v171, v[110:113], s[78:79] nt
	global_store_dwordx4 v171, v[106:109], s[22:23] nt
	s_waitcnt vmcnt(6)
	v_pk_fma_f32 v[102:103], v[102:103], v[142:143], v[204:205]
	v_pk_fma_f32 v[104:105], v[104:105], v[144:145], v[206:207]
	v_pk_fma_f32 v[98:99], v[98:99], v[150:151], v[234:235]
	v_pk_fma_f32 v[100:101], v[100:101], v[152:153], v[236:237]
	v_pk_fma_f32 v[92:93], v[92:93], v[138:139], v[238:239]
	v_pk_fma_f32 v[94:95], v[94:95], v[140:141], v[240:241]
	v_pk_fma_f32 v[88:89], v[88:89], v[146:147], v[242:243]
	v_pk_fma_f32 v[90:91], v[90:91], v[148:149], v[244:245]
	global_load_dwordx4 v[204:207], v96, s[14:15] offset:128
	global_load_dwordx4 v[234:237], v96, s[14:15] offset:144
	s_add_u32 s14, s14, 0x50000
	s_addc_u32 s15, s15, 0
	global_load_dwordx4 v[238:241], v96, s[14:15]
	global_load_dwordx4 v[242:245], v96, s[14:15] offset:16
	v_cvt_pk_bf16_f32 v0, v102, v103
	v_cvt_pk_bf16_f32 v1, v104, v105
	v_cvt_pk_bf16_f32 v2, v98, v99
	v_cvt_pk_bf16_f32 v3, v100, v101
	v_cvt_pk_bf16_f32 v4, v92, v93
	v_cvt_pk_bf16_f32 v5, v94, v95
	v_cvt_pk_bf16_f32 v6, v88, v89
	v_cvt_pk_bf16_f32 v7, v90, v91
	v_mul_f32_e32 v246, v103, v103
	v_mul_f32_e32 v248, v105, v105
	v_fmac_f32_e32 v246, v102, v102
	v_fmac_f32_e32 v248, v104, v104
	v_add_f32_e32 v246, v246, v248
	v_mul_f32_e32 v248, v99, v99
	v_fmac_f32_e32 v248, v98, v98
	v_add_f32_e32 v246, v246, v248
	v_mul_f32_e32 v248, v101, v101
	v_fmac_f32_e32 v248, v100, v100
	v_add_f32_e32 v246, v248, v246
	v_mul_f32_e32 v247, v93, v93
	v_mul_f32_e32 v248, v95, v95
	v_fmac_f32_e32 v247, v92, v92
	v_fmac_f32_e32 v248, v94, v94
	v_add_f32_e32 v247, v247, v248
	v_mul_f32_e32 v248, v89, v89
	v_fmac_f32_e32 v248, v88, v88
	v_add_f32_e32 v247, v247, v248
	v_mul_f32_e32 v248, v91, v91
	v_fmac_f32_e32 v248, v90, v90
	v_add_f32_e32 v247, v248, v247
	v_add_f32_e32 v246, v246, v247
	v_mov_b32_e32 v247, v246
	s_nop 1
	v_permlane16_swap_b32_e32 v246, v247
	s_nop 1
	v_add_f32_e32 v246, v246, v247
	v_mov_b32_e32 v247, v246
	s_nop 1
	v_permlane32_swap_b32_e32 v246, v247
	v_add_u32_e32 v248, s8, v223
	s_nop 0
	v_add_f32_e32 v246, v246, v247
	s_mov_b64 exec, s[44:45]
	ds_write_b32 v248, v246 offset:512
	s_mov_b64 exec, -1
	v_pk_mul_f32 v[102:103], v[180:181], v[102:103]
	v_pk_mul_f32 v[104:105], v[182:183], v[104:105]
	v_pk_mul_f32 v[98:99], v[184:185], v[98:99]
	v_pk_mul_f32 v[100:101], v[186:187], v[100:101]
	v_pk_mul_f32 v[92:93], v[188:189], v[92:93]
	v_pk_mul_f32 v[94:95], v[190:191], v[94:95]
	v_pk_mul_f32 v[88:89], v[192:193], v[88:89]
	v_pk_mul_f32 v[90:91], v[194:195], v[90:91]
	v_cvt_pk_bf16_f32 v246, v102, v103
	v_cvt_pk_bf16_f32 v247, v104, v105
	v_cvt_pk_bf16_f32 v248, v98, v99
	v_cvt_pk_bf16_f32 v249, v100, v101
	v_cvt_pk_bf16_f32 v250, v92, v93
	v_cvt_pk_bf16_f32 v251, v94, v95
	v_cvt_pk_bf16_f32 v208, v88, v89
	v_cvt_pk_bf16_f32 v209, v90, v91
	s_add_u32 s2, s2, 0x8000
	s_addc_u32 s3, s3, 0
	s_add_u32 s18, s18, 0x8000
	s_addc_u32 s19, s19, 0
	s_add_u32 s78, s78, 0x8000
	s_addc_u32 s79, s79, 0
	s_add_u32 s22, s22, 0x8000
	s_addc_u32 s23, s23, 0
	s_mov_b64 vcc, s[6:7]
	v_cndmask_b32_dpp v102, v4, v0, vcc row_ror:8 row_mask:0xf bank_mask:0xf
	v_cndmask_b32_dpp v103, v5, v1, vcc row_ror:8 row_mask:0xf bank_mask:0xf
	v_cndmask_b32_dpp v104, v6, v2, vcc row_ror:8 row_mask:0xf bank_mask:0xf
	v_cndmask_b32_dpp v105, v7, v3, vcc row_ror:8 row_mask:0xf bank_mask:0xf
	v_cndmask_b32_dpp v92, v250, v246, vcc row_ror:8 row_mask:0xf bank_mask:0xf
	v_cndmask_b32_dpp v93, v251, v247, vcc row_ror:8 row_mask:0xf bank_mask:0xf
	v_cndmask_b32_dpp v94, v208, v248, vcc row_ror:8 row_mask:0xf bank_mask:0xf
	v_cndmask_b32_dpp v95, v209, v249, vcc row_ror:8 row_mask:0xf bank_mask:0xf
	s_not_b64 vcc, s[6:7]
	v_cndmask_b32_dpp v98, v0, v4, vcc row_ror:8 row_mask:0xf bank_mask:0xf
	v_cndmask_b32_dpp v99, v1, v5, vcc row_ror:8 row_mask:0xf bank_mask:0xf
	v_cndmask_b32_dpp v100, v2, v6, vcc row_ror:8 row_mask:0xf bank_mask:0xf
	v_cndmask_b32_dpp v101, v3, v7, vcc row_ror:8 row_mask:0xf bank_mask:0xf
	v_cndmask_b32_dpp v88, v246, v250, vcc row_ror:8 row_mask:0xf bank_mask:0xf
	v_cndmask_b32_dpp v89, v247, v251, vcc row_ror:8 row_mask:0xf bank_mask:0xf
	v_cndmask_b32_dpp v90, v248, v208, vcc row_ror:8 row_mask:0xf bank_mask:0xf
	v_cndmask_b32_dpp v91, v249, v209, vcc row_ror:8 row_mask:0xf bank_mask:0xf
	global_store_dwordx4 v171, v[102:105], s[2:3] nt
	global_store_dwordx4 v171, v[98:101], s[18:19] nt
	global_store_dwordx4 v171, v[92:95], s[78:79] nt
	global_store_dwordx4 v171, v[88:91], s[22:23] nt
	s_waitcnt vmcnt(6)
	v_pk_fma_f32 v[84:85], v[84:85], v[142:143], v[196:197]
	v_pk_fma_f32 v[86:87], v[86:87], v[144:145], v[198:199]
	v_pk_fma_f32 v[80:81], v[80:81], v[150:151], v[200:201]
	v_pk_fma_f32 v[82:83], v[82:83], v[152:153], v[202:203]
	v_pk_fma_f32 v[76:77], v[76:77], v[138:139], v[204:205]
	v_pk_fma_f32 v[78:79], v[78:79], v[140:141], v[206:207]
	v_pk_fma_f32 v[72:73], v[72:73], v[146:147], v[234:235]
	v_pk_fma_f32 v[74:75], v[74:75], v[148:149], v[236:237]
	global_load_dwordx4 v[196:199], v96, s[14:15] offset:128
	global_load_dwordx4 v[200:203], v96, s[14:15] offset:144
	s_add_u32 s14, s14, 0x10000
	s_addc_u32 s15, s15, 0
	global_load_dwordx4 v[204:207], v96, s[14:15]
	global_load_dwordx4 v[234:237], v96, s[14:15] offset:16
	v_cvt_pk_bf16_f32 v0, v84, v85
	v_cvt_pk_bf16_f32 v1, v86, v87
	v_cvt_pk_bf16_f32 v2, v80, v81
	v_cvt_pk_bf16_f32 v3, v82, v83
	v_cvt_pk_bf16_f32 v4, v76, v77
	v_cvt_pk_bf16_f32 v5, v78, v79
	v_cvt_pk_bf16_f32 v6, v72, v73
	v_cvt_pk_bf16_f32 v7, v74, v75
	v_mul_f32_e32 v246, v85, v85
	v_mul_f32_e32 v248, v87, v87
	v_fmac_f32_e32 v246, v84, v84
	v_fmac_f32_e32 v248, v86, v86
	v_add_f32_e32 v246, v246, v248
	v_mul_f32_e32 v248, v81, v81
	v_fmac_f32_e32 v248, v80, v80
	v_add_f32_e32 v246, v246, v248
	v_mul_f32_e32 v248, v83, v83
	v_fmac_f32_e32 v248, v82, v82
	v_add_f32_e32 v246, v248, v246
	v_mul_f32_e32 v247, v77, v77
	v_mul_f32_e32 v248, v79, v79
	v_fmac_f32_e32 v247, v76, v76
	v_fmac_f32_e32 v248, v78, v78
	v_add_f32_e32 v247, v247, v248
	v_mul_f32_e32 v248, v73, v73
	v_fmac_f32_e32 v248, v72, v72
	v_add_f32_e32 v247, v247, v248
	v_mul_f32_e32 v248, v75, v75
	v_fmac_f32_e32 v248, v74, v74
	v_add_f32_e32 v247, v248, v247
	v_add_f32_e32 v246, v246, v247
	v_mov_b32_e32 v247, v246
	s_nop 1
	v_permlane16_swap_b32_e32 v246, v247
	s_nop 1
	v_add_f32_e32 v246, v246, v247
	v_mov_b32_e32 v247, v246
	s_nop 1
	v_permlane32_swap_b32_e32 v246, v247
	v_add_u32_e32 v248, s8, v223
	s_nop 0
	v_add_f32_e32 v246, v246, v247
	s_mov_b64 exec, s[44:45]
	ds_write_b32 v248, v246 offset:768
	s_mov_b64 exec, -1
	v_pk_mul_f32 v[84:85], v[180:181], v[84:85]
	v_pk_mul_f32 v[86:87], v[182:183], v[86:87]
	v_pk_mul_f32 v[80:81], v[184:185], v[80:81]
	v_pk_mul_f32 v[82:83], v[186:187], v[82:83]
	v_pk_mul_f32 v[76:77], v[188:189], v[76:77]
	v_pk_mul_f32 v[78:79], v[190:191], v[78:79]
	v_pk_mul_f32 v[72:73], v[192:193], v[72:73]
	v_pk_mul_f32 v[74:75], v[194:195], v[74:75]
	v_cvt_pk_bf16_f32 v246, v84, v85
	v_cvt_pk_bf16_f32 v247, v86, v87
	v_cvt_pk_bf16_f32 v248, v80, v81
	v_cvt_pk_bf16_f32 v249, v82, v83
	v_cvt_pk_bf16_f32 v250, v76, v77
	v_cvt_pk_bf16_f32 v251, v78, v79
	v_cvt_pk_bf16_f32 v208, v72, v73
	v_cvt_pk_bf16_f32 v209, v74, v75
	s_add_u32 s2, s2, 0x8000
	s_addc_u32 s3, s3, 0
	s_add_u32 s18, s18, 0x8000
	s_addc_u32 s19, s19, 0
	s_add_u32 s78, s78, 0x8000
	s_addc_u32 s79, s79, 0
	s_add_u32 s22, s22, 0x8000
	s_addc_u32 s23, s23, 0
	s_mov_b64 vcc, s[6:7]
	v_cndmask_b32_dpp v84, v4, v0, vcc row_ror:8 row_mask:0xf bank_mask:0xf
	v_cndmask_b32_dpp v85, v5, v1, vcc row_ror:8 row_mask:0xf bank_mask:0xf
	v_cndmask_b32_dpp v86, v6, v2, vcc row_ror:8 row_mask:0xf bank_mask:0xf
	v_cndmask_b32_dpp v87, v7, v3, vcc row_ror:8 row_mask:0xf bank_mask:0xf
	v_cndmask_b32_dpp v76, v250, v246, vcc row_ror:8 row_mask:0xf bank_mask:0xf
	v_cndmask_b32_dpp v77, v251, v247, vcc row_ror:8 row_mask:0xf bank_mask:0xf
	v_cndmask_b32_dpp v78, v208, v248, vcc row_ror:8 row_mask:0xf bank_mask:0xf
	v_cndmask_b32_dpp v79, v209, v249, vcc row_ror:8 row_mask:0xf bank_mask:0xf
	s_not_b64 vcc, s[6:7]
	v_cndmask_b32_dpp v80, v0, v4, vcc row_ror:8 row_mask:0xf bank_mask:0xf
	v_cndmask_b32_dpp v81, v1, v5, vcc row_ror:8 row_mask:0xf bank_mask:0xf
	v_cndmask_b32_dpp v82, v2, v6, vcc row_ror:8 row_mask:0xf bank_mask:0xf
	v_cndmask_b32_dpp v83, v3, v7, vcc row_ror:8 row_mask:0xf bank_mask:0xf
	v_cndmask_b32_dpp v72, v246, v250, vcc row_ror:8 row_mask:0xf bank_mask:0xf
	v_cndmask_b32_dpp v73, v247, v251, vcc row_ror:8 row_mask:0xf bank_mask:0xf
	v_cndmask_b32_dpp v74, v248, v208, vcc row_ror:8 row_mask:0xf bank_mask:0xf
	v_cndmask_b32_dpp v75, v249, v209, vcc row_ror:8 row_mask:0xf bank_mask:0xf
	global_store_dwordx4 v171, v[84:87], s[2:3] nt
	global_store_dwordx4 v171, v[80:83], s[18:19] nt
	global_store_dwordx4 v171, v[76:79], s[78:79] nt
	global_store_dwordx4 v171, v[72:75], s[22:23] nt
	s_waitcnt vmcnt(6)
	v_pk_fma_f32 v[68:69], v[68:69], v[142:143], v[238:239]
	v_pk_fma_f32 v[70:71], v[70:71], v[144:145], v[240:241]
	v_pk_fma_f32 v[64:65], v[64:65], v[150:151], v[242:243]
	v_pk_fma_f32 v[66:67], v[66:67], v[152:153], v[244:245]
	v_pk_fma_f32 v[60:61], v[60:61], v[138:139], v[196:197]
	v_pk_fma_f32 v[62:63], v[62:63], v[140:141], v[198:199]
	v_pk_fma_f32 v[56:57], v[56:57], v[146:147], v[200:201]
	v_pk_fma_f32 v[58:59], v[58:59], v[148:149], v[202:203]
	global_load_dwordx4 v[238:241], v96, s[14:15] offset:128
	global_load_dwordx4 v[242:245], v96, s[14:15] offset:144
	s_add_u32 s14, s14, 0x10000
	s_addc_u32 s15, s15, 0
	global_load_dwordx4 v[196:199], v96, s[14:15]
	global_load_dwordx4 v[200:203], v96, s[14:15] offset:16
	v_cvt_pk_bf16_f32 v0, v68, v69
	v_cvt_pk_bf16_f32 v1, v70, v71
	v_cvt_pk_bf16_f32 v2, v64, v65
	v_cvt_pk_bf16_f32 v3, v66, v67
	v_cvt_pk_bf16_f32 v4, v60, v61
	v_cvt_pk_bf16_f32 v5, v62, v63
	v_cvt_pk_bf16_f32 v6, v56, v57
	v_cvt_pk_bf16_f32 v7, v58, v59
	v_mul_f32_e32 v246, v69, v69
	v_mul_f32_e32 v248, v71, v71
	v_fmac_f32_e32 v246, v68, v68
	v_fmac_f32_e32 v248, v70, v70
	v_add_f32_e32 v246, v246, v248
	v_mul_f32_e32 v248, v65, v65
	v_fmac_f32_e32 v248, v64, v64
	v_add_f32_e32 v246, v246, v248
	v_mul_f32_e32 v248, v67, v67
	v_fmac_f32_e32 v248, v66, v66
	v_add_f32_e32 v246, v248, v246
	v_mul_f32_e32 v247, v61, v61
	v_mul_f32_e32 v248, v63, v63
	v_fmac_f32_e32 v247, v60, v60
	v_fmac_f32_e32 v248, v62, v62
	v_add_f32_e32 v247, v247, v248
	v_mul_f32_e32 v248, v57, v57
	v_fmac_f32_e32 v248, v56, v56
	v_add_f32_e32 v247, v247, v248
	v_mul_f32_e32 v248, v59, v59
	v_fmac_f32_e32 v248, v58, v58
	v_add_f32_e32 v247, v248, v247
	v_add_f32_e32 v246, v246, v247
	v_mov_b32_e32 v247, v246
	s_nop 1
	v_permlane16_swap_b32_e32 v246, v247
	s_nop 1
	v_add_f32_e32 v246, v246, v247
	v_mov_b32_e32 v247, v246
	s_nop 1
	v_permlane32_swap_b32_e32 v246, v247
	v_add_u32_e32 v248, s8, v223
	s_nop 0
	v_add_f32_e32 v246, v246, v247
	s_mov_b64 exec, s[44:45]
	ds_write_b32 v248, v246 offset:2048
	s_mov_b64 exec, -1
	v_pk_mul_f32 v[68:69], v[180:181], v[68:69]
	v_pk_mul_f32 v[70:71], v[182:183], v[70:71]
	v_pk_mul_f32 v[64:65], v[184:185], v[64:65]
	v_pk_mul_f32 v[66:67], v[186:187], v[66:67]
	v_pk_mul_f32 v[60:61], v[188:189], v[60:61]
	v_pk_mul_f32 v[62:63], v[190:191], v[62:63]
	v_pk_mul_f32 v[56:57], v[192:193], v[56:57]
	v_pk_mul_f32 v[58:59], v[194:195], v[58:59]
	v_cvt_pk_bf16_f32 v246, v68, v69
	v_cvt_pk_bf16_f32 v247, v70, v71
	v_cvt_pk_bf16_f32 v248, v64, v65
	v_cvt_pk_bf16_f32 v249, v66, v67
	v_cvt_pk_bf16_f32 v250, v60, v61
	v_cvt_pk_bf16_f32 v251, v62, v63
	v_cvt_pk_bf16_f32 v208, v56, v57
	v_cvt_pk_bf16_f32 v209, v58, v59
	s_add_u32 s2, s2, 0x28000
	s_addc_u32 s3, s3, 0
	s_add_u32 s18, s18, 0x28000
	s_addc_u32 s19, s19, 0
	s_add_u32 s78, s78, 0x28000
	s_addc_u32 s79, s79, 0
	s_add_u32 s22, s22, 0x28000
	s_addc_u32 s23, s23, 0
	s_mov_b64 vcc, s[6:7]
	v_cndmask_b32_dpp v68, v4, v0, vcc row_ror:8 row_mask:0xf bank_mask:0xf
	v_cndmask_b32_dpp v69, v5, v1, vcc row_ror:8 row_mask:0xf bank_mask:0xf
	v_cndmask_b32_dpp v70, v6, v2, vcc row_ror:8 row_mask:0xf bank_mask:0xf
	v_cndmask_b32_dpp v71, v7, v3, vcc row_ror:8 row_mask:0xf bank_mask:0xf
	v_cndmask_b32_dpp v60, v250, v246, vcc row_ror:8 row_mask:0xf bank_mask:0xf
	v_cndmask_b32_dpp v61, v251, v247, vcc row_ror:8 row_mask:0xf bank_mask:0xf
	v_cndmask_b32_dpp v62, v208, v248, vcc row_ror:8 row_mask:0xf bank_mask:0xf
	v_cndmask_b32_dpp v63, v209, v249, vcc row_ror:8 row_mask:0xf bank_mask:0xf
	s_not_b64 vcc, s[6:7]
	v_cndmask_b32_dpp v64, v0, v4, vcc row_ror:8 row_mask:0xf bank_mask:0xf
	v_cndmask_b32_dpp v65, v1, v5, vcc row_ror:8 row_mask:0xf bank_mask:0xf
	v_cndmask_b32_dpp v66, v2, v6, vcc row_ror:8 row_mask:0xf bank_mask:0xf
	v_cndmask_b32_dpp v67, v3, v7, vcc row_ror:8 row_mask:0xf bank_mask:0xf
	v_cndmask_b32_dpp v56, v246, v250, vcc row_ror:8 row_mask:0xf bank_mask:0xf
	v_cndmask_b32_dpp v57, v247, v251, vcc row_ror:8 row_mask:0xf bank_mask:0xf
	v_cndmask_b32_dpp v58, v248, v208, vcc row_ror:8 row_mask:0xf bank_mask:0xf
	v_cndmask_b32_dpp v59, v249, v209, vcc row_ror:8 row_mask:0xf bank_mask:0xf
	global_store_dwordx4 v171, v[68:71], s[2:3] nt
	global_store_dwordx4 v171, v[64:67], s[18:19] nt
	global_store_dwordx4 v171, v[60:63], s[78:79] nt
	global_store_dwordx4 v171, v[56:59], s[22:23] nt
	s_waitcnt vmcnt(6)
	v_pk_fma_f32 v[52:53], v[52:53], v[142:143], v[204:205]
	v_pk_fma_f32 v[54:55], v[54:55], v[144:145], v[206:207]
	v_pk_fma_f32 v[48:49], v[48:49], v[150:151], v[234:235]
	v_pk_fma_f32 v[50:51], v[50:51], v[152:153], v[236:237]
	v_pk_fma_f32 v[44:45], v[44:45], v[138:139], v[238:239]
	v_pk_fma_f32 v[46:47], v[46:47], v[140:141], v[240:241]
	v_pk_fma_f32 v[40:41], v[40:41], v[146:147], v[242:243]
	v_pk_fma_f32 v[42:43], v[42:43], v[148:149], v[244:245]
	global_load_dwordx4 v[204:207], v96, s[14:15] offset:128
	global_load_dwordx4 v[234:237], v96, s[14:15] offset:144
	s_add_u32 s14, s14, 0x10000
	s_addc_u32 s15, s15, 0
	global_load_dwordx4 v[238:241], v96, s[14:15]
	global_load_dwordx4 v[242:245], v96, s[14:15] offset:16
	v_cvt_pk_bf16_f32 v0, v52, v53
	v_cvt_pk_bf16_f32 v1, v54, v55
	v_cvt_pk_bf16_f32 v2, v48, v49
	v_cvt_pk_bf16_f32 v3, v50, v51
	v_cvt_pk_bf16_f32 v4, v44, v45
	v_cvt_pk_bf16_f32 v5, v46, v47
	v_cvt_pk_bf16_f32 v6, v40, v41
	v_cvt_pk_bf16_f32 v7, v42, v43
	v_mul_f32_e32 v246, v53, v53
	v_mul_f32_e32 v248, v55, v55
	v_fmac_f32_e32 v246, v52, v52
	v_fmac_f32_e32 v248, v54, v54
	v_add_f32_e32 v246, v246, v248
	v_mul_f32_e32 v248, v49, v49
	v_fmac_f32_e32 v248, v48, v48
	v_add_f32_e32 v246, v246, v248
	v_mul_f32_e32 v248, v51, v51
	v_fmac_f32_e32 v248, v50, v50
	v_add_f32_e32 v246, v248, v246
	v_mul_f32_e32 v247, v45, v45
	v_mul_f32_e32 v248, v47, v47
	v_fmac_f32_e32 v247, v44, v44
	v_fmac_f32_e32 v248, v46, v46
	v_add_f32_e32 v247, v247, v248
	v_mul_f32_e32 v248, v41, v41
	v_fmac_f32_e32 v248, v40, v40
	v_add_f32_e32 v247, v247, v248
	v_mul_f32_e32 v248, v43, v43
	v_fmac_f32_e32 v248, v42, v42
	v_add_f32_e32 v247, v248, v247
	v_add_f32_e32 v246, v246, v247
	v_mov_b32_e32 v247, v246
	s_nop 1
	v_permlane16_swap_b32_e32 v246, v247
	s_nop 1
	v_add_f32_e32 v246, v246, v247
	v_mov_b32_e32 v247, v246
	s_nop 1
	v_permlane32_swap_b32_e32 v246, v247
	v_add_u32_e32 v248, s8, v223
	s_nop 0
	v_add_f32_e32 v246, v246, v247
	s_mov_b64 exec, s[44:45]
	ds_write_b32 v248, v246 offset:2304
	s_mov_b64 exec, -1
	v_pk_mul_f32 v[52:53], v[180:181], v[52:53]
	v_pk_mul_f32 v[54:55], v[182:183], v[54:55]
	v_pk_mul_f32 v[48:49], v[184:185], v[48:49]
	v_pk_mul_f32 v[50:51], v[186:187], v[50:51]
	v_pk_mul_f32 v[44:45], v[188:189], v[44:45]
	v_pk_mul_f32 v[46:47], v[190:191], v[46:47]
	v_pk_mul_f32 v[40:41], v[192:193], v[40:41]
	v_pk_mul_f32 v[42:43], v[194:195], v[42:43]
	v_cvt_pk_bf16_f32 v246, v52, v53
	v_cvt_pk_bf16_f32 v247, v54, v55
	v_cvt_pk_bf16_f32 v248, v48, v49
	v_cvt_pk_bf16_f32 v249, v50, v51
	v_cvt_pk_bf16_f32 v250, v44, v45
	v_cvt_pk_bf16_f32 v251, v46, v47
	v_cvt_pk_bf16_f32 v208, v40, v41
	v_cvt_pk_bf16_f32 v209, v42, v43
	s_add_u32 s2, s2, 0x8000
	s_addc_u32 s3, s3, 0
	s_add_u32 s18, s18, 0x8000
	s_addc_u32 s19, s19, 0
	s_add_u32 s78, s78, 0x8000
	s_addc_u32 s79, s79, 0
	s_add_u32 s22, s22, 0x8000
	s_addc_u32 s23, s23, 0
	s_mov_b64 vcc, s[6:7]
	v_cndmask_b32_dpp v52, v4, v0, vcc row_ror:8 row_mask:0xf bank_mask:0xf
	v_cndmask_b32_dpp v53, v5, v1, vcc row_ror:8 row_mask:0xf bank_mask:0xf
	v_cndmask_b32_dpp v54, v6, v2, vcc row_ror:8 row_mask:0xf bank_mask:0xf
	v_cndmask_b32_dpp v55, v7, v3, vcc row_ror:8 row_mask:0xf bank_mask:0xf
	v_cndmask_b32_dpp v44, v250, v246, vcc row_ror:8 row_mask:0xf bank_mask:0xf
	v_cndmask_b32_dpp v45, v251, v247, vcc row_ror:8 row_mask:0xf bank_mask:0xf
	v_cndmask_b32_dpp v46, v208, v248, vcc row_ror:8 row_mask:0xf bank_mask:0xf
	v_cndmask_b32_dpp v47, v209, v249, vcc row_ror:8 row_mask:0xf bank_mask:0xf
	s_not_b64 vcc, s[6:7]
	v_cndmask_b32_dpp v48, v0, v4, vcc row_ror:8 row_mask:0xf bank_mask:0xf
	v_cndmask_b32_dpp v49, v1, v5, vcc row_ror:8 row_mask:0xf bank_mask:0xf
	v_cndmask_b32_dpp v50, v2, v6, vcc row_ror:8 row_mask:0xf bank_mask:0xf
	v_cndmask_b32_dpp v51, v3, v7, vcc row_ror:8 row_mask:0xf bank_mask:0xf
	v_cndmask_b32_dpp v40, v246, v250, vcc row_ror:8 row_mask:0xf bank_mask:0xf
	v_cndmask_b32_dpp v41, v247, v251, vcc row_ror:8 row_mask:0xf bank_mask:0xf
	v_cndmask_b32_dpp v42, v248, v208, vcc row_ror:8 row_mask:0xf bank_mask:0xf
	v_cndmask_b32_dpp v43, v249, v209, vcc row_ror:8 row_mask:0xf bank_mask:0xf
	global_store_dwordx4 v171, v[52:55], s[2:3] nt
	global_store_dwordx4 v171, v[48:51], s[18:19] nt
	global_store_dwordx4 v171, v[44:47], s[78:79] nt
	global_store_dwordx4 v171, v[40:43], s[22:23] nt
	s_waitcnt vmcnt(6)
	v_pk_fma_f32 v[36:37], v[36:37], v[142:143], v[196:197]
	v_pk_fma_f32 v[38:39], v[38:39], v[144:145], v[198:199]
	v_pk_fma_f32 v[32:33], v[32:33], v[150:151], v[200:201]
	v_pk_fma_f32 v[34:35], v[34:35], v[152:153], v[202:203]
	v_pk_fma_f32 v[28:29], v[28:29], v[138:139], v[204:205]
	v_pk_fma_f32 v[30:31], v[30:31], v[140:141], v[206:207]
	v_pk_fma_f32 v[24:25], v[24:25], v[146:147], v[234:235]
	v_pk_fma_f32 v[26:27], v[26:27], v[148:149], v[236:237]
	global_load_dwordx4 v[196:199], v96, s[14:15] offset:128
	global_load_dwordx4 v[200:203], v96, s[14:15] offset:144
	v_cvt_pk_bf16_f32 v0, v36, v37
	v_cvt_pk_bf16_f32 v1, v38, v39
	v_cvt_pk_bf16_f32 v2, v32, v33
	v_cvt_pk_bf16_f32 v3, v34, v35
	v_cvt_pk_bf16_f32 v4, v28, v29
	v_cvt_pk_bf16_f32 v5, v30, v31
	v_cvt_pk_bf16_f32 v6, v24, v25
	v_cvt_pk_bf16_f32 v7, v26, v27
	v_mul_f32_e32 v246, v37, v37
	v_mul_f32_e32 v248, v39, v39
	v_fmac_f32_e32 v246, v36, v36
	v_fmac_f32_e32 v248, v38, v38
	v_add_f32_e32 v246, v246, v248
	v_mul_f32_e32 v248, v33, v33
	v_fmac_f32_e32 v248, v32, v32
	v_add_f32_e32 v246, v246, v248
	v_mul_f32_e32 v248, v35, v35
	v_fmac_f32_e32 v248, v34, v34
	v_add_f32_e32 v246, v248, v246
	v_mul_f32_e32 v247, v29, v29
	v_mul_f32_e32 v248, v31, v31
	v_fmac_f32_e32 v247, v28, v28
	v_fmac_f32_e32 v248, v30, v30
	v_add_f32_e32 v247, v247, v248
	v_mul_f32_e32 v248, v25, v25
	v_fmac_f32_e32 v248, v24, v24
	v_add_f32_e32 v247, v247, v248
	v_mul_f32_e32 v248, v27, v27
	v_fmac_f32_e32 v248, v26, v26
	v_add_f32_e32 v247, v248, v247
	v_add_f32_e32 v246, v246, v247
	v_mov_b32_e32 v247, v246
	s_nop 1
	v_permlane16_swap_b32_e32 v246, v247
	s_nop 1
	v_add_f32_e32 v246, v246, v247
	v_mov_b32_e32 v247, v246
	s_nop 1
	v_permlane32_swap_b32_e32 v246, v247
	v_add_u32_e32 v248, s8, v223
	s_nop 0
	v_add_f32_e32 v246, v246, v247
	s_mov_b64 exec, s[44:45]
	ds_write_b32 v248, v246 offset:2560
	s_mov_b64 exec, -1
	v_pk_mul_f32 v[36:37], v[180:181], v[36:37]
	v_pk_mul_f32 v[38:39], v[182:183], v[38:39]
	v_pk_mul_f32 v[32:33], v[184:185], v[32:33]
	v_pk_mul_f32 v[34:35], v[186:187], v[34:35]
	v_pk_mul_f32 v[28:29], v[188:189], v[28:29]
	v_pk_mul_f32 v[30:31], v[190:191], v[30:31]
	v_pk_mul_f32 v[24:25], v[192:193], v[24:25]
	v_pk_mul_f32 v[26:27], v[194:195], v[26:27]
	v_cvt_pk_bf16_f32 v246, v36, v37
	v_cvt_pk_bf16_f32 v247, v38, v39
	v_cvt_pk_bf16_f32 v248, v32, v33
	v_cvt_pk_bf16_f32 v249, v34, v35
	v_cvt_pk_bf16_f32 v250, v28, v29
	v_cvt_pk_bf16_f32 v251, v30, v31
	v_cvt_pk_bf16_f32 v208, v24, v25
	v_cvt_pk_bf16_f32 v209, v26, v27
	s_add_u32 s2, s2, 0x8000
	s_addc_u32 s3, s3, 0
	s_add_u32 s18, s18, 0x8000
	s_addc_u32 s19, s19, 0
	s_add_u32 s78, s78, 0x8000
	s_addc_u32 s79, s79, 0
	s_add_u32 s22, s22, 0x8000
	s_addc_u32 s23, s23, 0
	s_mov_b64 vcc, s[6:7]
	v_cndmask_b32_dpp v36, v4, v0, vcc row_ror:8 row_mask:0xf bank_mask:0xf
	v_cndmask_b32_dpp v37, v5, v1, vcc row_ror:8 row_mask:0xf bank_mask:0xf
	v_cndmask_b32_dpp v38, v6, v2, vcc row_ror:8 row_mask:0xf bank_mask:0xf
	v_cndmask_b32_dpp v39, v7, v3, vcc row_ror:8 row_mask:0xf bank_mask:0xf
	v_cndmask_b32_dpp v28, v250, v246, vcc row_ror:8 row_mask:0xf bank_mask:0xf
	v_cndmask_b32_dpp v29, v251, v247, vcc row_ror:8 row_mask:0xf bank_mask:0xf
	v_cndmask_b32_dpp v30, v208, v248, vcc row_ror:8 row_mask:0xf bank_mask:0xf
	v_cndmask_b32_dpp v31, v209, v249, vcc row_ror:8 row_mask:0xf bank_mask:0xf
	s_not_b64 vcc, s[6:7]
	v_cndmask_b32_dpp v32, v0, v4, vcc row_ror:8 row_mask:0xf bank_mask:0xf
	v_cndmask_b32_dpp v33, v1, v5, vcc row_ror:8 row_mask:0xf bank_mask:0xf
	v_cndmask_b32_dpp v34, v2, v6, vcc row_ror:8 row_mask:0xf bank_mask:0xf
	v_cndmask_b32_dpp v35, v3, v7, vcc row_ror:8 row_mask:0xf bank_mask:0xf
	v_cndmask_b32_dpp v24, v246, v250, vcc row_ror:8 row_mask:0xf bank_mask:0xf
	v_cndmask_b32_dpp v25, v247, v251, vcc row_ror:8 row_mask:0xf bank_mask:0xf
	v_cndmask_b32_dpp v26, v248, v208, vcc row_ror:8 row_mask:0xf bank_mask:0xf
	v_cndmask_b32_dpp v27, v249, v209, vcc row_ror:8 row_mask:0xf bank_mask:0xf
	global_store_dwordx4 v171, v[36:39], s[2:3] nt
	global_store_dwordx4 v171, v[32:35], s[18:19] nt
	global_store_dwordx4 v171, v[28:31], s[78:79] nt
	global_store_dwordx4 v171, v[24:27], s[22:23] nt
	s_waitcnt vmcnt(4)
	v_pk_fma_f32 v[20:21], v[20:21], v[142:143], v[238:239]
	v_pk_fma_f32 v[22:23], v[22:23], v[144:145], v[240:241]
	v_pk_fma_f32 v[16:17], v[16:17], v[150:151], v[242:243]
	v_pk_fma_f32 v[18:19], v[18:19], v[152:153], v[244:245]
	v_pk_fma_f32 v[12:13], v[12:13], v[138:139], v[196:197]
	v_pk_fma_f32 v[14:15], v[14:15], v[140:141], v[198:199]
	v_pk_fma_f32 v[8:9], v[8:9], v[146:147], v[200:201]
	v_pk_fma_f32 v[10:11], v[10:11], v[148:149], v[202:203]
	v_cvt_pk_bf16_f32 v0, v20, v21
	v_cvt_pk_bf16_f32 v1, v22, v23
	v_cvt_pk_bf16_f32 v2, v16, v17
	v_cvt_pk_bf16_f32 v3, v18, v19
	v_cvt_pk_bf16_f32 v4, v12, v13
	v_cvt_pk_bf16_f32 v5, v14, v15
	v_cvt_pk_bf16_f32 v6, v8, v9
	v_cvt_pk_bf16_f32 v7, v10, v11
	v_mul_f32_e32 v246, v21, v21
	v_mul_f32_e32 v248, v23, v23
	v_fmac_f32_e32 v246, v20, v20
	v_fmac_f32_e32 v248, v22, v22
	v_add_f32_e32 v246, v246, v248
	v_mul_f32_e32 v248, v17, v17
	v_fmac_f32_e32 v248, v16, v16
	v_add_f32_e32 v246, v246, v248
	v_mul_f32_e32 v248, v19, v19
	v_fmac_f32_e32 v248, v18, v18
	v_add_f32_e32 v246, v248, v246
	v_mul_f32_e32 v247, v13, v13
	v_mul_f32_e32 v248, v15, v15
	v_fmac_f32_e32 v247, v12, v12
	v_fmac_f32_e32 v248, v14, v14
	v_add_f32_e32 v247, v247, v248
	v_mul_f32_e32 v248, v9, v9
	v_fmac_f32_e32 v248, v8, v8
	v_add_f32_e32 v247, v247, v248
	v_mul_f32_e32 v248, v11, v11
	v_fmac_f32_e32 v248, v10, v10
	v_add_f32_e32 v247, v248, v247
	v_add_f32_e32 v246, v246, v247
	v_mov_b32_e32 v247, v246
	s_nop 1
	v_permlane16_swap_b32_e32 v246, v247
	s_nop 1
	v_add_f32_e32 v246, v246, v247
	v_mov_b32_e32 v247, v246
	s_nop 1
	v_permlane32_swap_b32_e32 v246, v247
	v_add_u32_e32 v248, s8, v223
	s_nop 0
	v_add_f32_e32 v246, v246, v247
	s_mov_b64 exec, s[44:45]
	ds_write_b32 v248, v246 offset:2816
	s_mov_b64 exec, -1
	v_pk_mul_f32 v[20:21], v[180:181], v[20:21]
	v_pk_mul_f32 v[22:23], v[182:183], v[22:23]
	v_pk_mul_f32 v[16:17], v[184:185], v[16:17]
	v_pk_mul_f32 v[18:19], v[186:187], v[18:19]
	v_pk_mul_f32 v[12:13], v[188:189], v[12:13]
	v_pk_mul_f32 v[14:15], v[190:191], v[14:15]
	v_pk_mul_f32 v[8:9], v[192:193], v[8:9]
	v_pk_mul_f32 v[10:11], v[194:195], v[10:11]
	v_cvt_pk_bf16_f32 v246, v20, v21
	v_cvt_pk_bf16_f32 v247, v22, v23
	v_cvt_pk_bf16_f32 v248, v16, v17
	v_cvt_pk_bf16_f32 v249, v18, v19
	v_cvt_pk_bf16_f32 v250, v12, v13
	v_cvt_pk_bf16_f32 v251, v14, v15
	v_cvt_pk_bf16_f32 v208, v8, v9
	v_cvt_pk_bf16_f32 v209, v10, v11
	s_add_u32 s2, s2, 0x8000
	s_addc_u32 s3, s3, 0
	s_add_u32 s18, s18, 0x8000
	s_addc_u32 s19, s19, 0
	s_add_u32 s78, s78, 0x8000
	s_addc_u32 s79, s79, 0
	s_add_u32 s22, s22, 0x8000
	s_addc_u32 s23, s23, 0
	s_mov_b64 vcc, s[6:7]
	v_cndmask_b32_dpp v20, v4, v0, vcc row_ror:8 row_mask:0xf bank_mask:0xf
	v_cndmask_b32_dpp v21, v5, v1, vcc row_ror:8 row_mask:0xf bank_mask:0xf
	v_cndmask_b32_dpp v22, v6, v2, vcc row_ror:8 row_mask:0xf bank_mask:0xf
	v_cndmask_b32_dpp v23, v7, v3, vcc row_ror:8 row_mask:0xf bank_mask:0xf
	v_cndmask_b32_dpp v12, v250, v246, vcc row_ror:8 row_mask:0xf bank_mask:0xf
	v_cndmask_b32_dpp v13, v251, v247, vcc row_ror:8 row_mask:0xf bank_mask:0xf
	v_cndmask_b32_dpp v14, v208, v248, vcc row_ror:8 row_mask:0xf bank_mask:0xf
	v_cndmask_b32_dpp v15, v209, v249, vcc row_ror:8 row_mask:0xf bank_mask:0xf
	s_not_b64 vcc, s[6:7]
	v_cndmask_b32_dpp v16, v0, v4, vcc row_ror:8 row_mask:0xf bank_mask:0xf
	v_cndmask_b32_dpp v17, v1, v5, vcc row_ror:8 row_mask:0xf bank_mask:0xf
	v_cndmask_b32_dpp v18, v2, v6, vcc row_ror:8 row_mask:0xf bank_mask:0xf
	v_cndmask_b32_dpp v19, v3, v7, vcc row_ror:8 row_mask:0xf bank_mask:0xf
	v_cndmask_b32_dpp v8, v246, v250, vcc row_ror:8 row_mask:0xf bank_mask:0xf
	v_cndmask_b32_dpp v9, v247, v251, vcc row_ror:8 row_mask:0xf bank_mask:0xf
	v_cndmask_b32_dpp v10, v248, v208, vcc row_ror:8 row_mask:0xf bank_mask:0xf
	v_cndmask_b32_dpp v11, v249, v209, vcc row_ror:8 row_mask:0xf bank_mask:0xf
	global_store_dwordx4 v171, v[20:23], s[2:3] nt
	global_store_dwordx4 v171, v[16:19], s[18:19] nt
	global_store_dwordx4 v171, v[12:15], s[78:79] nt
	global_store_dwordx4 v171, v[8:11], s[22:23] nt
	s_mov_b32 s100, 1
	s_branch .LBB0_714

.Lfn_entry:
	v_add_u32_e32 v1, s71, v208
	ds_read_b128 v[186:189], v1
	ds_read_b128 v[190:193], v1 offset:256
	ds_read_b128 v[194:197], v1 offset:512
	ds_read_b128 v[198:201], v1 offset:768
	ds_read_b128 v[202:205], v1 offset:2048
	ds_read_b128 v[222:225], v1 offset:2304
	ds_read_b128 v[226:229], v1 offset:2560
	ds_read_b128 v[230:233], v1 offset:2816
	s_sub_i32 s16, s36, 0x100
	s_lshl_b32 s16, s16, 8
	s_add_i32 s16, s16, s20
	s_lshr_b32 s17, s16, 5
	s_add_i32 s18, s17, 32
	s_mul_i32 s18, s18, 0x3000
	v_readlane_b32 s19, v252, 35
	s_add_u32 s10, s12, 0x500000
	s_addc_u32 s11, s13, 0
	s_add_u32 s10, s10, s19
	s_addc_u32 s11, s11, 0
	s_add_u32 s10, s10, s18
	s_addc_u32 s11, s11, 0
	v_lshlrev_b32_e32 v3, 2, v0
	global_load_dwordx4 v[150:153], v3, s[10:11]
	global_load_dwordx4 v[146:149], v3, s[10:11] offset:16
	global_load_dwordx4 v[142:145], v3, s[10:11] offset:128
	global_load_dwordx4 v[138:141], v3, s[10:11] offset:144
	s_waitcnt lgkmcnt(0)
	v_add_f32_e32 v4, v186, v187
	v_add_f32_e32 v5, v188, v189
	v_add_f32_e32 v4, v4, v5
	v_fmamk_f32 v4, v4, 0x3a800000, v212
	v_rsq_f32_e32 v186, v4
	v_add_f32_e32 v4, v190, v191
	v_add_f32_e32 v5, v192, v193
	v_add_f32_e32 v4, v4, v5
	v_fmamk_f32 v4, v4, 0x3a800000, v212
	v_rsq_f32_e32 v187, v4
	v_add_f32_e32 v4, v194, v195
	v_add_f32_e32 v5, v196, v197
	v_add_f32_e32 v4, v4, v5
	v_fmamk_f32 v4, v4, 0x3a800000, v212
	v_rsq_f32_e32 v188, v4
	v_add_f32_e32 v4, v198, v199
	v_add_f32_e32 v5, v200, v201
	v_add_f32_e32 v4, v4, v5
	v_fmamk_f32 v4, v4, 0x3a800000, v212
	v_rsq_f32_e32 v189, v4
	v_add_f32_e32 v4, v202, v203
	v_add_f32_e32 v5, v204, v205
	v_add_f32_e32 v4, v4, v5
	v_fmamk_f32 v4, v4, 0x3a800000, v212
	v_rsq_f32_e32 v190, v4
	v_add_f32_e32 v4, v222, v223
	v_add_f32_e32 v5, v224, v225
	v_add_f32_e32 v4, v4, v5
	v_fmamk_f32 v4, v4, 0x3a800000, v212
	v_rsq_f32_e32 v191, v4
	v_add_f32_e32 v4, v226, v227
	v_add_f32_e32 v5, v228, v229
	v_add_f32_e32 v4, v4, v5
	v_fmamk_f32 v4, v4, 0x3a800000, v212
	v_rsq_f32_e32 v192, v4
	v_add_f32_e32 v4, v230, v231
	v_add_f32_e32 v5, v232, v233
	v_add_f32_e32 v4, v4, v5
	v_fmamk_f32 v4, v4, 0x3a800000, v212
	v_rsq_f32_e32 v193, v4
	v_mov_b32_e32 v226, v3
	s_add_u32 s10, s10, 0x3000
	s_addc_u32 s11, s11, 0
	global_load_dwordx4 v[194:197], v226, s[10:11]
	global_load_dwordx4 v[198:201], v226, s[10:11] offset:16
	global_load_dwordx4 v[202:205], v226, s[10:11] offset:128
	global_load_dwordx4 v[222:225], v226, s[10:11] offset:144
	v_add_u32_e32 v2, v182, v162
	v_lshlrev_b32_e32 v2, 1, v2
	v_lshlrev_b32_e32 v227, 10, v163
	v_lshl_add_u32 v227, v182, 2, v227
	v_add_u32_e32 v228, -1, v163
	v_lshlrev_b32_e32 v228, 12, v228
	v_lshl_add_u32 v228, v182, 2, v228
	s_mov_b32 s17, s42
	s_add_i32 s18, s16, 0x10000
	v_readlane_b32 s2, v252, 28
	v_readlane_b32 s3, v252, 29
	s_cmp_gt_u32 s35, 1
	s_cbranch_scc1 .Lfn_k234
	v_lshl_add_u32 v246, v207, 11, v2
	v_add_u32_e32 v247, 0x4000, v246
	s_cmp_eq_u32 s35, 0
	s_cselect_b32 s12, s4, s50
	s_cselect_b32 s13, s5, s51
	s_lshl_b32 s18, s18, 11
	s_add_u32 s12, s12, s18
	s_addc_u32 s13, s13, 0
	s_mov_b32 s16, s42
	s_cmp_eq_u32 s35, 0
	s_cbranch_scc0 .Lfn_kind1
	s_cmp_eq_u32 s42, 1.0
	s_cbranch_scc1 .Lfn_plain
	s_waitcnt vmcnt(4)
	v_mov_b32_e32 v6, v186
	v_pk_fma_f32 v[136:137], v[136:137], v[6:7], v[152:153] op_sel_hi:[1,0,1]
	v_pk_fma_f32 v[134:135], v[134:135], v[6:7], v[150:151] op_sel_hi:[1,0,1]
	v_pk_fma_f32 v[132:133], v[132:133], v[6:7], v[148:149] op_sel_hi:[1,0,1]
	v_pk_fma_f32 v[130:131], v[130:131], v[6:7], v[146:147] op_sel_hi:[1,0,1]
	v_pk_fma_f32 v[128:129], v[128:129], v[6:7], v[144:145] op_sel_hi:[1,0,1]
	v_pk_fma_f32 v[126:127], v[126:127], v[6:7], v[142:143] op_sel_hi:[1,0,1]
	v_pk_fma_f32 v[124:125], v[124:125], v[6:7], v[140:141] op_sel_hi:[1,0,1]
	v_pk_fma_f32 v[122:123], v[122:123], v[6:7], v[138:139] op_sel_hi:[1,0,1]
	v_pk_mul_f32 v[136:137], s[16:17], v[136:137]
	v_pk_mul_f32 v[134:135], s[16:17], v[134:135]
	v_pk_mul_f32 v[132:133], s[16:17], v[132:133]
	v_pk_mul_f32 v[130:131], s[16:17], v[130:131]
	v_pk_mul_f32 v[128:129], s[16:17], v[128:129]
	v_pk_mul_f32 v[126:127], s[16:17], v[126:127]
	v_pk_mul_f32 v[124:125], s[16:17], v[124:125]
	v_pk_mul_f32 v[122:123], s[16:17], v[122:123]
	v_cvt_pk_bf16_f32 v234, v134, v135
	v_cvt_pk_bf16_f32 v235, v136, v137
	v_cvt_pk_bf16_f32 v236, v130, v131
	v_cvt_pk_bf16_f32 v237, v132, v133
	v_cvt_pk_bf16_f32 v238, v126, v127
	v_cvt_pk_bf16_f32 v239, v128, v129
	v_cvt_pk_bf16_f32 v240, v122, v123
	v_cvt_pk_bf16_f32 v241, v124, v125
	s_mov_b64 vcc, s[6:7]
	v_cndmask_b32_dpp v134, v238, v234, vcc row_ror:8 row_mask:0xf bank_mask:0xf
	v_cndmask_b32_dpp v135, v239, v235, vcc row_ror:8 row_mask:0xf bank_mask:0xf
	v_cndmask_b32_dpp v136, v240, v236, vcc row_ror:8 row_mask:0xf bank_mask:0xf
	v_cndmask_b32_dpp v137, v241, v237, vcc row_ror:8 row_mask:0xf bank_mask:0xf
	s_not_b64 vcc, s[6:7]
	v_cndmask_b32_dpp v130, v234, v238, vcc row_ror:8 row_mask:0xf bank_mask:0xf
	v_cndmask_b32_dpp v131, v235, v239, vcc row_ror:8 row_mask:0xf bank_mask:0xf
	v_cndmask_b32_dpp v132, v236, v240, vcc row_ror:8 row_mask:0xf bank_mask:0xf
	v_cndmask_b32_dpp v133, v237, v241, vcc row_ror:8 row_mask:0xf bank_mask:0xf
	global_store_dwordx4 v246, v[134:137], s[12:13] nt
	global_store_dwordx4 v247, v[130:133], s[12:13] nt
	v_mov_b32_e32 v6, v187
	s_add_u32 s12, s12, 0x8000
	s_addc_u32 s13, s13, 0
	v_pk_fma_f32 v[120:121], v[120:121], v[6:7], v[152:153] op_sel_hi:[1,0,1]
	v_pk_fma_f32 v[118:119], v[118:119], v[6:7], v[150:151] op_sel_hi:[1,0,1]
	v_pk_fma_f32 v[116:117], v[116:117], v[6:7], v[148:149] op_sel_hi:[1,0,1]
	v_pk_fma_f32 v[114:115], v[114:115], v[6:7], v[146:147] op_sel_hi:[1,0,1]
	v_pk_fma_f32 v[112:113], v[112:113], v[6:7], v[144:145] op_sel_hi:[1,0,1]
	v_pk_fma_f32 v[110:111], v[110:111], v[6:7], v[142:143] op_sel_hi:[1,0,1]
	v_pk_fma_f32 v[108:109], v[108:109], v[6:7], v[140:141] op_sel_hi:[1,0,1]
	v_pk_fma_f32 v[106:107], v[106:107], v[6:7], v[138:139] op_sel_hi:[1,0,1]
	v_pk_mul_f32 v[120:121], s[16:17], v[120:121]
	v_pk_mul_f32 v[118:119], s[16:17], v[118:119]
	v_pk_mul_f32 v[116:117], s[16:17], v[116:117]
	v_pk_mul_f32 v[114:115], s[16:17], v[114:115]
	v_pk_mul_f32 v[112:113], s[16:17], v[112:113]
	v_pk_mul_f32 v[110:111], s[16:17], v[110:111]
	v_pk_mul_f32 v[108:109], s[16:17], v[108:109]
	v_pk_mul_f32 v[106:107], s[16:17], v[106:107]
	v_cvt_pk_bf16_f32 v234, v118, v119
	v_cvt_pk_bf16_f32 v235, v120, v121
	v_cvt_pk_bf16_f32 v236, v114, v115
	v_cvt_pk_bf16_f32 v237, v116, v117
	v_cvt_pk_bf16_f32 v238, v110, v111
	v_cvt_pk_bf16_f32 v239, v112, v113
	v_cvt_pk_bf16_f32 v240, v106, v107
	v_cvt_pk_bf16_f32 v241, v108, v109
	s_mov_b64 vcc, s[6:7]
	v_cndmask_b32_dpp v118, v238, v234, vcc row_ror:8 row_mask:0xf bank_mask:0xf
	v_cndmask_b32_dpp v119, v239, v235, vcc row_ror:8 row_mask:0xf bank_mask:0xf
	v_cndmask_b32_dpp v120, v240, v236, vcc row_ror:8 row_mask:0xf bank_mask:0xf
	v_cndmask_b32_dpp v121, v241, v237, vcc row_ror:8 row_mask:0xf bank_mask:0xf
	s_not_b64 vcc, s[6:7]
	v_cndmask_b32_dpp v114, v234, v238, vcc row_ror:8 row_mask:0xf bank_mask:0xf
	v_cndmask_b32_dpp v115, v235, v239, vcc row_ror:8 row_mask:0xf bank_mask:0xf
	v_cndmask_b32_dpp v116, v236, v240, vcc row_ror:8 row_mask:0xf bank_mask:0xf
	v_cndmask_b32_dpp v117, v237, v241, vcc row_ror:8 row_mask:0xf bank_mask:0xf
	global_store_dwordx4 v246, v[118:121], s[12:13] nt
	global_store_dwordx4 v247, v[114:117], s[12:13] nt
	s_add_u32 s10, s10, 0x9000
	s_addc_u32 s11, s11, 0
	global_load_dwordx4 v[150:153], v226, s[10:11]
	global_load_dwordx4 v[146:149], v226, s[10:11] offset:16
	global_load_dwordx4 v[142:145], v226, s[10:11] offset:128
	global_load_dwordx4 v[138:141], v226, s[10:11] offset:144
	s_waitcnt vmcnt(8)
	v_mov_b32_e32 v6, v188
	s_add_u32 s12, s12, 0x8000
	s_addc_u32 s13, s13, 0
	v_pk_fma_f32 v[104:105], v[104:105], v[6:7], v[196:197] op_sel_hi:[1,0,1]
	v_pk_fma_f32 v[102:103], v[102:103], v[6:7], v[194:195] op_sel_hi:[1,0,1]
	v_pk_fma_f32 v[100:101], v[100:101], v[6:7], v[200:201] op_sel_hi:[1,0,1]
	v_pk_fma_f32 v[98:99], v[98:99], v[6:7], v[198:199] op_sel_hi:[1,0,1]
	v_pk_fma_f32 v[94:95], v[94:95], v[6:7], v[204:205] op_sel_hi:[1,0,1]
	v_pk_fma_f32 v[92:93], v[92:93], v[6:7], v[202:203] op_sel_hi:[1,0,1]
	v_pk_fma_f32 v[90:91], v[90:91], v[6:7], v[224:225] op_sel_hi:[1,0,1]
	v_pk_fma_f32 v[88:89], v[88:89], v[6:7], v[222:223] op_sel_hi:[1,0,1]
	v_pk_mul_f32 v[104:105], s[16:17], v[104:105]
	v_pk_mul_f32 v[102:103], s[16:17], v[102:103]
	v_pk_mul_f32 v[100:101], s[16:17], v[100:101]
	v_pk_mul_f32 v[98:99], s[16:17], v[98:99]
	v_pk_mul_f32 v[94:95], s[16:17], v[94:95]
	v_pk_mul_f32 v[92:93], s[16:17], v[92:93]
	v_pk_mul_f32 v[90:91], s[16:17], v[90:91]
	v_pk_mul_f32 v[88:89], s[16:17], v[88:89]
	v_cvt_pk_bf16_f32 v234, v102, v103
	v_cvt_pk_bf16_f32 v235, v104, v105
	v_cvt_pk_bf16_f32 v236, v98, v99
	v_cvt_pk_bf16_f32 v237, v100, v101
	v_cvt_pk_bf16_f32 v238, v92, v93
	v_cvt_pk_bf16_f32 v239, v94, v95
	v_cvt_pk_bf16_f32 v240, v88, v89
	v_cvt_pk_bf16_f32 v241, v90, v91
	s_mov_b64 vcc, s[6:7]
	v_cndmask_b32_dpp v102, v238, v234, vcc row_ror:8 row_mask:0xf bank_mask:0xf
	v_cndmask_b32_dpp v103, v239, v235, vcc row_ror:8 row_mask:0xf bank_mask:0xf
	v_cndmask_b32_dpp v104, v240, v236, vcc row_ror:8 row_mask:0xf bank_mask:0xf
	v_cndmask_b32_dpp v105, v241, v237, vcc row_ror:8 row_mask:0xf bank_mask:0xf
	s_not_b64 vcc, s[6:7]
	v_cndmask_b32_dpp v98, v234, v238, vcc row_ror:8 row_mask:0xf bank_mask:0xf
	v_cndmask_b32_dpp v99, v235, v239, vcc row_ror:8 row_mask:0xf bank_mask:0xf
	v_cndmask_b32_dpp v100, v236, v240, vcc row_ror:8 row_mask:0xf bank_mask:0xf
	v_cndmask_b32_dpp v101, v237, v241, vcc row_ror:8 row_mask:0xf bank_mask:0xf
	global_store_dwordx4 v246, v[102:105], s[12:13] nt
	global_store_dwordx4 v247, v[98:101], s[12:13] nt
	v_mov_b32_e32 v6, v189
	s_add_u32 s12, s12, 0x8000
	s_addc_u32 s13, s13, 0
	v_pk_fma_f32 v[86:87], v[86:87], v[6:7], v[196:197] op_sel_hi:[1,0,1]
	v_pk_fma_f32 v[84:85], v[84:85], v[6:7], v[194:195] op_sel_hi:[1,0,1]
	v_pk_fma_f32 v[82:83], v[82:83], v[6:7], v[200:201] op_sel_hi:[1,0,1]
	v_pk_fma_f32 v[80:81], v[80:81], v[6:7], v[198:199] op_sel_hi:[1,0,1]
	v_pk_fma_f32 v[78:79], v[78:79], v[6:7], v[204:205] op_sel_hi:[1,0,1]
	v_pk_fma_f32 v[76:77], v[76:77], v[6:7], v[202:203] op_sel_hi:[1,0,1]
	v_pk_fma_f32 v[74:75], v[74:75], v[6:7], v[224:225] op_sel_hi:[1,0,1]
	v_pk_fma_f32 v[72:73], v[72:73], v[6:7], v[222:223] op_sel_hi:[1,0,1]
	v_pk_mul_f32 v[86:87], s[16:17], v[86:87]
	v_pk_mul_f32 v[84:85], s[16:17], v[84:85]
	v_pk_mul_f32 v[82:83], s[16:17], v[82:83]
	v_pk_mul_f32 v[80:81], s[16:17], v[80:81]
	v_pk_mul_f32 v[78:79], s[16:17], v[78:79]
	v_pk_mul_f32 v[76:77], s[16:17], v[76:77]
	v_pk_mul_f32 v[74:75], s[16:17], v[74:75]
	v_pk_mul_f32 v[72:73], s[16:17], v[72:73]
	v_cvt_pk_bf16_f32 v234, v84, v85
	v_cvt_pk_bf16_f32 v235, v86, v87
	v_cvt_pk_bf16_f32 v236, v80, v81
	v_cvt_pk_bf16_f32 v237, v82, v83
	v_cvt_pk_bf16_f32 v238, v76, v77
	v_cvt_pk_bf16_f32 v239, v78, v79
	v_cvt_pk_bf16_f32 v240, v72, v73
	v_cvt_pk_bf16_f32 v241, v74, v75
	s_mov_b64 vcc, s[6:7]
	v_cndmask_b32_dpp v84, v238, v234, vcc row_ror:8 row_mask:0xf bank_mask:0xf
	v_cndmask_b32_dpp v85, v239, v235, vcc row_ror:8 row_mask:0xf bank_mask:0xf
	v_cndmask_b32_dpp v86, v240, v236, vcc row_ror:8 row_mask:0xf bank_mask:0xf
	v_cndmask_b32_dpp v87, v241, v237, vcc row_ror:8 row_mask:0xf bank_mask:0xf
	s_not_b64 vcc, s[6:7]
	v_cndmask_b32_dpp v80, v234, v238, vcc row_ror:8 row_mask:0xf bank_mask:0xf
	v_cndmask_b32_dpp v81, v235, v239, vcc row_ror:8 row_mask:0xf bank_mask:0xf
	v_cndmask_b32_dpp v82, v236, v240, vcc row_ror:8 row_mask:0xf bank_mask:0xf
	v_cndmask_b32_dpp v83, v237, v241, vcc row_ror:8 row_mask:0xf bank_mask:0xf
	global_store_dwordx4 v246, v[84:87], s[12:13] nt
	global_store_dwordx4 v247, v[80:83], s[12:13] nt
	s_add_u32 s10, s10, 0x3000
	s_addc_u32 s11, s11, 0
	global_load_dwordx4 v[194:197], v226, s[10:11]
	global_load_dwordx4 v[198:201], v226, s[10:11] offset:16
	global_load_dwordx4 v[202:205], v226, s[10:11] offset:128
	global_load_dwordx4 v[222:225], v226, s[10:11] offset:144
	s_waitcnt vmcnt(8)
	v_mov_b32_e32 v6, v190
	s_add_u32 s12, s12, 0x28000
	s_addc_u32 s13, s13, 0
	v_pk_fma_f32 v[70:71], v[70:71], v[6:7], v[152:153] op_sel_hi:[1,0,1]
	v_pk_fma_f32 v[68:69], v[68:69], v[6:7], v[150:151] op_sel_hi:[1,0,1]
	v_pk_fma_f32 v[66:67], v[66:67], v[6:7], v[148:149] op_sel_hi:[1,0,1]
	v_pk_fma_f32 v[64:65], v[64:65], v[6:7], v[146:147] op_sel_hi:[1,0,1]
	v_pk_fma_f32 v[62:63], v[62:63], v[6:7], v[144:145] op_sel_hi:[1,0,1]
	v_pk_fma_f32 v[60:61], v[60:61], v[6:7], v[142:143] op_sel_hi:[1,0,1]
	v_pk_fma_f32 v[58:59], v[58:59], v[6:7], v[140:141] op_sel_hi:[1,0,1]
	v_pk_fma_f32 v[56:57], v[56:57], v[6:7], v[138:139] op_sel_hi:[1,0,1]
	v_pk_mul_f32 v[70:71], s[16:17], v[70:71]
	v_pk_mul_f32 v[68:69], s[16:17], v[68:69]
	v_pk_mul_f32 v[66:67], s[16:17], v[66:67]
	v_pk_mul_f32 v[64:65], s[16:17], v[64:65]
	v_pk_mul_f32 v[62:63], s[16:17], v[62:63]
	v_pk_mul_f32 v[60:61], s[16:17], v[60:61]
	v_pk_mul_f32 v[58:59], s[16:17], v[58:59]
	v_pk_mul_f32 v[56:57], s[16:17], v[56:57]
	v_cvt_pk_bf16_f32 v234, v68, v69
	v_cvt_pk_bf16_f32 v235, v70, v71
	v_cvt_pk_bf16_f32 v236, v64, v65
	v_cvt_pk_bf16_f32 v237, v66, v67
	v_cvt_pk_bf16_f32 v238, v60, v61
	v_cvt_pk_bf16_f32 v239, v62, v63
	v_cvt_pk_bf16_f32 v240, v56, v57
	v_cvt_pk_bf16_f32 v241, v58, v59
	s_mov_b64 vcc, s[6:7]
	v_cndmask_b32_dpp v68, v238, v234, vcc row_ror:8 row_mask:0xf bank_mask:0xf
	v_cndmask_b32_dpp v69, v239, v235, vcc row_ror:8 row_mask:0xf bank_mask:0xf
	v_cndmask_b32_dpp v70, v240, v236, vcc row_ror:8 row_mask:0xf bank_mask:0xf
	v_cndmask_b32_dpp v71, v241, v237, vcc row_ror:8 row_mask:0xf bank_mask:0xf
	s_not_b64 vcc, s[6:7]
	v_cndmask_b32_dpp v64, v234, v238, vcc row_ror:8 row_mask:0xf bank_mask:0xf
	v_cndmask_b32_dpp v65, v235, v239, vcc row_ror:8 row_mask:0xf bank_mask:0xf
	v_cndmask_b32_dpp v66, v236, v240, vcc row_ror:8 row_mask:0xf bank_mask:0xf
	v_cndmask_b32_dpp v67, v237, v241, vcc row_ror:8 row_mask:0xf bank_mask:0xf
	global_store_dwordx4 v246, v[68:71], s[12:13] nt
	global_store_dwordx4 v247, v[64:67], s[12:13] nt
	v_mov_b32_e32 v6, v191
	s_add_u32 s12, s12, 0x8000
	s_addc_u32 s13, s13, 0
	v_pk_fma_f32 v[54:55], v[54:55], v[6:7], v[152:153] op_sel_hi:[1,0,1]
	v_pk_fma_f32 v[52:53], v[52:53], v[6:7], v[150:151] op_sel_hi:[1,0,1]
	v_pk_fma_f32 v[50:51], v[50:51], v[6:7], v[148:149] op_sel_hi:[1,0,1]
	v_pk_fma_f32 v[48:49], v[48:49], v[6:7], v[146:147] op_sel_hi:[1,0,1]
	v_pk_fma_f32 v[46:47], v[46:47], v[6:7], v[144:145] op_sel_hi:[1,0,1]
	v_pk_fma_f32 v[44:45], v[44:45], v[6:7], v[142:143] op_sel_hi:[1,0,1]
	v_pk_fma_f32 v[42:43], v[42:43], v[6:7], v[140:141] op_sel_hi:[1,0,1]
	v_pk_fma_f32 v[40:41], v[40:41], v[6:7], v[138:139] op_sel_hi:[1,0,1]
	v_pk_mul_f32 v[54:55], s[16:17], v[54:55]
	v_pk_mul_f32 v[52:53], s[16:17], v[52:53]
	v_pk_mul_f32 v[50:51], s[16:17], v[50:51]
	v_pk_mul_f32 v[48:49], s[16:17], v[48:49]
	v_pk_mul_f32 v[46:47], s[16:17], v[46:47]
	v_pk_mul_f32 v[44:45], s[16:17], v[44:45]
	v_pk_mul_f32 v[42:43], s[16:17], v[42:43]
	v_pk_mul_f32 v[40:41], s[16:17], v[40:41]
	v_cvt_pk_bf16_f32 v234, v52, v53
	v_cvt_pk_bf16_f32 v235, v54, v55
	v_cvt_pk_bf16_f32 v236, v48, v49
	v_cvt_pk_bf16_f32 v237, v50, v51
	v_cvt_pk_bf16_f32 v238, v44, v45
	v_cvt_pk_bf16_f32 v239, v46, v47
	v_cvt_pk_bf16_f32 v240, v40, v41
	v_cvt_pk_bf16_f32 v241, v42, v43
	s_mov_b64 vcc, s[6:7]
	v_cndmask_b32_dpp v52, v238, v234, vcc row_ror:8 row_mask:0xf bank_mask:0xf
	v_cndmask_b32_dpp v53, v239, v235, vcc row_ror:8 row_mask:0xf bank_mask:0xf
	v_cndmask_b32_dpp v54, v240, v236, vcc row_ror:8 row_mask:0xf bank_mask:0xf
	v_cndmask_b32_dpp v55, v241, v237, vcc row_ror:8 row_mask:0xf bank_mask:0xf
	s_not_b64 vcc, s[6:7]
	v_cndmask_b32_dpp v48, v234, v238, vcc row_ror:8 row_mask:0xf bank_mask:0xf
	v_cndmask_b32_dpp v49, v235, v239, vcc row_ror:8 row_mask:0xf bank_mask:0xf
	v_cndmask_b32_dpp v50, v236, v240, vcc row_ror:8 row_mask:0xf bank_mask:0xf
	v_cndmask_b32_dpp v51, v237, v241, vcc row_ror:8 row_mask:0xf bank_mask:0xf
	global_store_dwordx4 v246, v[52:55], s[12:13] nt
	global_store_dwordx4 v247, v[48:51], s[12:13] nt
	s_waitcnt vmcnt(4)
	v_mov_b32_e32 v6, v192
	s_add_u32 s12, s12, 0x8000
	s_addc_u32 s13, s13, 0
	v_pk_fma_f32 v[38:39], v[38:39], v[6:7], v[196:197] op_sel_hi:[1,0,1]
	v_pk_fma_f32 v[36:37], v[36:37], v[6:7], v[194:195] op_sel_hi:[1,0,1]
	v_pk_fma_f32 v[34:35], v[34:35], v[6:7], v[200:201] op_sel_hi:[1,0,1]
	v_pk_fma_f32 v[32:33], v[32:33], v[6:7], v[198:199] op_sel_hi:[1,0,1]
	v_pk_fma_f32 v[30:31], v[30:31], v[6:7], v[204:205] op_sel_hi:[1,0,1]
	v_pk_fma_f32 v[28:29], v[28:29], v[6:7], v[202:203] op_sel_hi:[1,0,1]
	v_pk_fma_f32 v[26:27], v[26:27], v[6:7], v[224:225] op_sel_hi:[1,0,1]
	v_pk_fma_f32 v[24:25], v[24:25], v[6:7], v[222:223] op_sel_hi:[1,0,1]
	v_pk_mul_f32 v[38:39], s[16:17], v[38:39]
	v_pk_mul_f32 v[36:37], s[16:17], v[36:37]
	v_pk_mul_f32 v[34:35], s[16:17], v[34:35]
	v_pk_mul_f32 v[32:33], s[16:17], v[32:33]
	v_pk_mul_f32 v[30:31], s[16:17], v[30:31]
	v_pk_mul_f32 v[28:29], s[16:17], v[28:29]
	v_pk_mul_f32 v[26:27], s[16:17], v[26:27]
	v_pk_mul_f32 v[24:25], s[16:17], v[24:25]
	v_cvt_pk_bf16_f32 v234, v36, v37
	v_cvt_pk_bf16_f32 v235, v38, v39
	v_cvt_pk_bf16_f32 v236, v32, v33
	v_cvt_pk_bf16_f32 v237, v34, v35
	v_cvt_pk_bf16_f32 v238, v28, v29
	v_cvt_pk_bf16_f32 v239, v30, v31
	v_cvt_pk_bf16_f32 v240, v24, v25
	v_cvt_pk_bf16_f32 v241, v26, v27
	s_mov_b64 vcc, s[6:7]
	v_cndmask_b32_dpp v36, v238, v234, vcc row_ror:8 row_mask:0xf bank_mask:0xf
	v_cndmask_b32_dpp v37, v239, v235, vcc row_ror:8 row_mask:0xf bank_mask:0xf
	v_cndmask_b32_dpp v38, v240, v236, vcc row_ror:8 row_mask:0xf bank_mask:0xf
	v_cndmask_b32_dpp v39, v241, v237, vcc row_ror:8 row_mask:0xf bank_mask:0xf
	s_not_b64 vcc, s[6:7]
	v_cndmask_b32_dpp v32, v234, v238, vcc row_ror:8 row_mask:0xf bank_mask:0xf
	v_cndmask_b32_dpp v33, v235, v239, vcc row_ror:8 row_mask:0xf bank_mask:0xf
	v_cndmask_b32_dpp v34, v236, v240, vcc row_ror:8 row_mask:0xf bank_mask:0xf
	v_cndmask_b32_dpp v35, v237, v241, vcc row_ror:8 row_mask:0xf bank_mask:0xf
	global_store_dwordx4 v246, v[36:39], s[12:13] nt
	global_store_dwordx4 v247, v[32:35], s[12:13] nt
	v_mov_b32_e32 v6, v193
	s_add_u32 s12, s12, 0x8000
	s_addc_u32 s13, s13, 0
	v_pk_fma_f32 v[22:23], v[22:23], v[6:7], v[196:197] op_sel_hi:[1,0,1]
	v_pk_fma_f32 v[20:21], v[20:21], v[6:7], v[194:195] op_sel_hi:[1,0,1]
	v_pk_fma_f32 v[18:19], v[18:19], v[6:7], v[200:201] op_sel_hi:[1,0,1]
	v_pk_fma_f32 v[16:17], v[16:17], v[6:7], v[198:199] op_sel_hi:[1,0,1]
	v_pk_fma_f32 v[14:15], v[14:15], v[6:7], v[204:205] op_sel_hi:[1,0,1]
	v_pk_fma_f32 v[12:13], v[12:13], v[6:7], v[202:203] op_sel_hi:[1,0,1]
	v_pk_fma_f32 v[10:11], v[10:11], v[6:7], v[224:225] op_sel_hi:[1,0,1]
	v_pk_fma_f32 v[8:9], v[8:9], v[6:7], v[222:223] op_sel_hi:[1,0,1]
	v_pk_mul_f32 v[22:23], s[16:17], v[22:23]
	v_pk_mul_f32 v[20:21], s[16:17], v[20:21]
	v_pk_mul_f32 v[18:19], s[16:17], v[18:19]
	v_pk_mul_f32 v[16:17], s[16:17], v[16:17]
	v_pk_mul_f32 v[14:15], s[16:17], v[14:15]
	v_pk_mul_f32 v[12:13], s[16:17], v[12:13]
	v_pk_mul_f32 v[10:11], s[16:17], v[10:11]
	v_pk_mul_f32 v[8:9], s[16:17], v[8:9]
	v_cvt_pk_bf16_f32 v234, v20, v21
	v_cvt_pk_bf16_f32 v235, v22, v23
	v_cvt_pk_bf16_f32 v236, v16, v17
	v_cvt_pk_bf16_f32 v237, v18, v19
	v_cvt_pk_bf16_f32 v238, v12, v13
	v_cvt_pk_bf16_f32 v239, v14, v15
	v_cvt_pk_bf16_f32 v240, v8, v9
	v_cvt_pk_bf16_f32 v241, v10, v11
	s_mov_b64 vcc, s[6:7]
	v_cndmask_b32_dpp v20, v238, v234, vcc row_ror:8 row_mask:0xf bank_mask:0xf
	v_cndmask_b32_dpp v21, v239, v235, vcc row_ror:8 row_mask:0xf bank_mask:0xf
	v_cndmask_b32_dpp v22, v240, v236, vcc row_ror:8 row_mask:0xf bank_mask:0xf
	v_cndmask_b32_dpp v23, v241, v237, vcc row_ror:8 row_mask:0xf bank_mask:0xf
	s_not_b64 vcc, s[6:7]
	v_cndmask_b32_dpp v16, v234, v238, vcc row_ror:8 row_mask:0xf bank_mask:0xf
	v_cndmask_b32_dpp v17, v235, v239, vcc row_ror:8 row_mask:0xf bank_mask:0xf
	v_cndmask_b32_dpp v18, v236, v240, vcc row_ror:8 row_mask:0xf bank_mask:0xf
	v_cndmask_b32_dpp v19, v237, v241, vcc row_ror:8 row_mask:0xf bank_mask:0xf
	global_store_dwordx4 v246, v[20:23], s[12:13] nt
	global_store_dwordx4 v247, v[16:19], s[12:13] nt
	s_mov_b32 s100, 1
	s_branch .LBB0_1422
.Lfn_kind1:
	s_and_b64 vcc, exec, s[2:3]
	s_cbranch_vccz .Lfn_plain
	s_waitcnt vmcnt(4)
	v_mov_b32_e32 v6, v186
	v_pk_fma_f32 v[136:137], v[136:137], v[6:7], v[152:153] op_sel_hi:[1,0,1]
	v_pk_fma_f32 v[134:135], v[134:135], v[6:7], v[150:151] op_sel_hi:[1,0,1]
	v_pk_fma_f32 v[132:133], v[132:133], v[6:7], v[148:149] op_sel_hi:[1,0,1]
	v_pk_fma_f32 v[130:131], v[130:131], v[6:7], v[146:147] op_sel_hi:[1,0,1]
	v_pk_fma_f32 v[128:129], v[128:129], v[6:7], v[144:145] op_sel_hi:[1,0,1]
	v_pk_fma_f32 v[126:127], v[126:127], v[6:7], v[142:143] op_sel_hi:[1,0,1]
	v_pk_fma_f32 v[124:125], v[124:125], v[6:7], v[140:141] op_sel_hi:[1,0,1]
	v_pk_fma_f32 v[122:123], v[122:123], v[6:7], v[138:139] op_sel_hi:[1,0,1]
	v_mul_f32_e32 v0, 0xbfb8aa3b, v134
	v_mul_f32_e32 v1, 0xbfb8aa3b, v135
	v_mul_f32_e32 v2, 0xbfb8aa3b, v136
	v_mul_f32_e32 v3, 0xbfb8aa3b, v137
	v_mul_f32_e32 v242, 0xbfb8aa3b, v130
	v_mul_f32_e32 v243, 0xbfb8aa3b, v131
	v_mul_f32_e32 v244, 0xbfb8aa3b, v132
	v_mul_f32_e32 v245, 0xbfb8aa3b, v133
	v_exp_f32_e32 v0, v0
	v_exp_f32_e32 v1, v1
	v_exp_f32_e32 v2, v2
	v_exp_f32_e32 v3, v3
	v_exp_f32_e32 v242, v242
	v_exp_f32_e32 v243, v243
	v_exp_f32_e32 v244, v244
	v_exp_f32_e32 v245, v245
	v_add_f32_e32 v0, 1.0, v0
	v_add_f32_e32 v1, 1.0, v1
	v_add_f32_e32 v2, 1.0, v2
	v_add_f32_e32 v3, 1.0, v3
	v_add_f32_e32 v242, 1.0, v242
	v_add_f32_e32 v243, 1.0, v243
	v_add_f32_e32 v244, 1.0, v244
	v_add_f32_e32 v245, 1.0, v245
	v_rcp_f32_e32 v0, v0
	v_rcp_f32_e32 v1, v1
	v_rcp_f32_e32 v2, v2
	v_rcp_f32_e32 v3, v3
	v_rcp_f32_e32 v242, v242
	v_rcp_f32_e32 v243, v243
	v_rcp_f32_e32 v244, v244
	v_rcp_f32_e32 v245, v245
	v_pk_mul_f32 v[134:135], v[134:135], v[0:1]
	v_pk_mul_f32 v[136:137], v[136:137], v[2:3]
	v_pk_mul_f32 v[130:131], v[130:131], v[242:243]
	v_pk_mul_f32 v[132:133], v[132:133], v[244:245]
	v_mul_f32_e32 v0, 0xbfb8aa3b, v126
	v_mul_f32_e32 v1, 0xbfb8aa3b, v127
	v_mul_f32_e32 v2, 0xbfb8aa3b, v128
	v_mul_f32_e32 v3, 0xbfb8aa3b, v129
	v_mul_f32_e32 v242, 0xbfb8aa3b, v122
	v_mul_f32_e32 v243, 0xbfb8aa3b, v123
	v_mul_f32_e32 v244, 0xbfb8aa3b, v124
	v_mul_f32_e32 v245, 0xbfb8aa3b, v125
	v_exp_f32_e32 v0, v0
	v_exp_f32_e32 v1, v1
	v_exp_f32_e32 v2, v2
	v_exp_f32_e32 v3, v3
	v_exp_f32_e32 v242, v242
	v_exp_f32_e32 v243, v243
	v_exp_f32_e32 v244, v244
	v_exp_f32_e32 v245, v245
	v_add_f32_e32 v0, 1.0, v0
	v_add_f32_e32 v1, 1.0, v1
	v_add_f32_e32 v2, 1.0, v2
	v_add_f32_e32 v3, 1.0, v3
	v_add_f32_e32 v242, 1.0, v242
	v_add_f32_e32 v243, 1.0, v243
	v_add_f32_e32 v244, 1.0, v244
	v_add_f32_e32 v245, 1.0, v245
	v_rcp_f32_e32 v0, v0
	v_rcp_f32_e32 v1, v1
	v_rcp_f32_e32 v2, v2
	v_rcp_f32_e32 v3, v3
	v_rcp_f32_e32 v242, v242
	v_rcp_f32_e32 v243, v243
	v_rcp_f32_e32 v244, v244
	v_rcp_f32_e32 v245, v245
	v_pk_mul_f32 v[126:127], v[126:127], v[0:1]
	v_pk_mul_f32 v[128:129], v[128:129], v[2:3]
	v_pk_mul_f32 v[122:123], v[122:123], v[242:243]
	v_pk_mul_f32 v[124:125], v[124:125], v[244:245]
	v_cvt_pk_bf16_f32 v234, v134, v135
	v_cvt_pk_bf16_f32 v235, v136, v137
	v_cvt_pk_bf16_f32 v236, v130, v131
	v_cvt_pk_bf16_f32 v237, v132, v133
	v_cvt_pk_bf16_f32 v238, v126, v127
	v_cvt_pk_bf16_f32 v239, v128, v129
	v_cvt_pk_bf16_f32 v240, v122, v123
	v_cvt_pk_bf16_f32 v241, v124, v125
	s_mov_b64 vcc, s[6:7]
	v_cndmask_b32_dpp v134, v238, v234, vcc row_ror:8 row_mask:0xf bank_mask:0xf
	v_cndmask_b32_dpp v135, v239, v235, vcc row_ror:8 row_mask:0xf bank_mask:0xf
	v_cndmask_b32_dpp v136, v240, v236, vcc row_ror:8 row_mask:0xf bank_mask:0xf
	v_cndmask_b32_dpp v137, v241, v237, vcc row_ror:8 row_mask:0xf bank_mask:0xf
	s_not_b64 vcc, s[6:7]
	v_cndmask_b32_dpp v130, v234, v238, vcc row_ror:8 row_mask:0xf bank_mask:0xf
	v_cndmask_b32_dpp v131, v235, v239, vcc row_ror:8 row_mask:0xf bank_mask:0xf
	v_cndmask_b32_dpp v132, v236, v240, vcc row_ror:8 row_mask:0xf bank_mask:0xf
	v_cndmask_b32_dpp v133, v237, v241, vcc row_ror:8 row_mask:0xf bank_mask:0xf
	global_store_dwordx4 v246, v[134:137], s[12:13] nt
	global_store_dwordx4 v247, v[130:133], s[12:13] nt
	v_mov_b32_e32 v6, v187
	s_add_u32 s12, s12, 0x8000
	s_addc_u32 s13, s13, 0
	v_pk_fma_f32 v[120:121], v[120:121], v[6:7], v[152:153] op_sel_hi:[1,0,1]
	v_pk_fma_f32 v[118:119], v[118:119], v[6:7], v[150:151] op_sel_hi:[1,0,1]
	v_pk_fma_f32 v[116:117], v[116:117], v[6:7], v[148:149] op_sel_hi:[1,0,1]
	v_pk_fma_f32 v[114:115], v[114:115], v[6:7], v[146:147] op_sel_hi:[1,0,1]
	v_pk_fma_f32 v[112:113], v[112:113], v[6:7], v[144:145] op_sel_hi:[1,0,1]
	v_pk_fma_f32 v[110:111], v[110:111], v[6:7], v[142:143] op_sel_hi:[1,0,1]
	v_pk_fma_f32 v[108:109], v[108:109], v[6:7], v[140:141] op_sel_hi:[1,0,1]
	v_pk_fma_f32 v[106:107], v[106:107], v[6:7], v[138:139] op_sel_hi:[1,0,1]
	v_mul_f32_e32 v0, 0xbfb8aa3b, v118
	v_mul_f32_e32 v1, 0xbfb8aa3b, v119
	v_mul_f32_e32 v2, 0xbfb8aa3b, v120
	v_mul_f32_e32 v3, 0xbfb8aa3b, v121
	v_mul_f32_e32 v242, 0xbfb8aa3b, v114
	v_mul_f32_e32 v243, 0xbfb8aa3b, v115
	v_mul_f32_e32 v244, 0xbfb8aa3b, v116
	v_mul_f32_e32 v245, 0xbfb8aa3b, v117
	v_exp_f32_e32 v0, v0
	v_exp_f32_e32 v1, v1
	v_exp_f32_e32 v2, v2
	v_exp_f32_e32 v3, v3
	v_exp_f32_e32 v242, v242
	v_exp_f32_e32 v243, v243
	v_exp_f32_e32 v244, v244
	v_exp_f32_e32 v245, v245
	v_add_f32_e32 v0, 1.0, v0
	v_add_f32_e32 v1, 1.0, v1
	v_add_f32_e32 v2, 1.0, v2
	v_add_f32_e32 v3, 1.0, v3
	v_add_f32_e32 v242, 1.0, v242
	v_add_f32_e32 v243, 1.0, v243
	v_add_f32_e32 v244, 1.0, v244
	v_add_f32_e32 v245, 1.0, v245
	v_rcp_f32_e32 v0, v0
	v_rcp_f32_e32 v1, v1
	v_rcp_f32_e32 v2, v2
	v_rcp_f32_e32 v3, v3
	v_rcp_f32_e32 v242, v242
	v_rcp_f32_e32 v243, v243
	v_rcp_f32_e32 v244, v244
	v_rcp_f32_e32 v245, v245
	v_pk_mul_f32 v[118:119], v[118:119], v[0:1]
	v_pk_mul_f32 v[120:121], v[120:121], v[2:3]
	v_pk_mul_f32 v[114:115], v[114:115], v[242:243]
	v_pk_mul_f32 v[116:117], v[116:117], v[244:245]
	v_mul_f32_e32 v0, 0xbfb8aa3b, v110
	v_mul_f32_e32 v1, 0xbfb8aa3b, v111
	v_mul_f32_e32 v2, 0xbfb8aa3b, v112
	v_mul_f32_e32 v3, 0xbfb8aa3b, v113
	v_mul_f32_e32 v242, 0xbfb8aa3b, v106
	v_mul_f32_e32 v243, 0xbfb8aa3b, v107
	v_mul_f32_e32 v244, 0xbfb8aa3b, v108
	v_mul_f32_e32 v245, 0xbfb8aa3b, v109
	v_exp_f32_e32 v0, v0
	v_exp_f32_e32 v1, v1
	v_exp_f32_e32 v2, v2
	v_exp_f32_e32 v3, v3
	v_exp_f32_e32 v242, v242
	v_exp_f32_e32 v243, v243
	v_exp_f32_e32 v244, v244
	v_exp_f32_e32 v245, v245
	v_add_f32_e32 v0, 1.0, v0
	v_add_f32_e32 v1, 1.0, v1
	v_add_f32_e32 v2, 1.0, v2
	v_add_f32_e32 v3, 1.0, v3
	v_add_f32_e32 v242, 1.0, v242
	v_add_f32_e32 v243, 1.0, v243
	v_add_f32_e32 v244, 1.0, v244
	v_add_f32_e32 v245, 1.0, v245
	v_rcp_f32_e32 v0, v0
	v_rcp_f32_e32 v1, v1
	v_rcp_f32_e32 v2, v2
	v_rcp_f32_e32 v3, v3
	v_rcp_f32_e32 v242, v242
	v_rcp_f32_e32 v243, v243
	v_rcp_f32_e32 v244, v244
	v_rcp_f32_e32 v245, v245
	v_pk_mul_f32 v[110:111], v[110:111], v[0:1]
	v_pk_mul_f32 v[112:113], v[112:113], v[2:3]
	v_pk_mul_f32 v[106:107], v[106:107], v[242:243]
	v_pk_mul_f32 v[108:109], v[108:109], v[244:245]
	v_cvt_pk_bf16_f32 v234, v118, v119
	v_cvt_pk_bf16_f32 v235, v120, v121
	v_cvt_pk_bf16_f32 v236, v114, v115
	v_cvt_pk_bf16_f32 v237, v116, v117
	v_cvt_pk_bf16_f32 v238, v110, v111
	v_cvt_pk_bf16_f32 v239, v112, v113
	v_cvt_pk_bf16_f32 v240, v106, v107
	v_cvt_pk_bf16_f32 v241, v108, v109
	s_mov_b64 vcc, s[6:7]
	v_cndmask_b32_dpp v118, v238, v234, vcc row_ror:8 row_mask:0xf bank_mask:0xf
	v_cndmask_b32_dpp v119, v239, v235, vcc row_ror:8 row_mask:0xf bank_mask:0xf
	v_cndmask_b32_dpp v120, v240, v236, vcc row_ror:8 row_mask:0xf bank_mask:0xf
	v_cndmask_b32_dpp v121, v241, v237, vcc row_ror:8 row_mask:0xf bank_mask:0xf
	s_not_b64 vcc, s[6:7]
	v_cndmask_b32_dpp v114, v234, v238, vcc row_ror:8 row_mask:0xf bank_mask:0xf
	v_cndmask_b32_dpp v115, v235, v239, vcc row_ror:8 row_mask:0xf bank_mask:0xf
	v_cndmask_b32_dpp v116, v236, v240, vcc row_ror:8 row_mask:0xf bank_mask:0xf
	v_cndmask_b32_dpp v117, v237, v241, vcc row_ror:8 row_mask:0xf bank_mask:0xf
	global_store_dwordx4 v246, v[118:121], s[12:13] nt
	global_store_dwordx4 v247, v[114:117], s[12:13] nt
	s_add_u32 s10, s10, 0x9000
	s_addc_u32 s11, s11, 0
	global_load_dwordx4 v[150:153], v226, s[10:11]
	global_load_dwordx4 v[146:149], v226, s[10:11] offset:16
	global_load_dwordx4 v[142:145], v226, s[10:11] offset:128
	global_load_dwordx4 v[138:141], v226, s[10:11] offset:144
	s_waitcnt vmcnt(8)
	v_mov_b32_e32 v6, v188
	s_add_u32 s12, s12, 0x8000
	s_addc_u32 s13, s13, 0
	v_pk_fma_f32 v[104:105], v[104:105], v[6:7], v[196:197] op_sel_hi:[1,0,1]
	v_pk_fma_f32 v[102:103], v[102:103], v[6:7], v[194:195] op_sel_hi:[1,0,1]
	v_pk_fma_f32 v[100:101], v[100:101], v[6:7], v[200:201] op_sel_hi:[1,0,1]
	v_pk_fma_f32 v[98:99], v[98:99], v[6:7], v[198:199] op_sel_hi:[1,0,1]
	v_pk_fma_f32 v[94:95], v[94:95], v[6:7], v[204:205] op_sel_hi:[1,0,1]
	v_pk_fma_f32 v[92:93], v[92:93], v[6:7], v[202:203] op_sel_hi:[1,0,1]
	v_pk_fma_f32 v[90:91], v[90:91], v[6:7], v[224:225] op_sel_hi:[1,0,1]
	v_pk_fma_f32 v[88:89], v[88:89], v[6:7], v[222:223] op_sel_hi:[1,0,1]
	v_mul_f32_e32 v0, 0xbfb8aa3b, v102
	v_mul_f32_e32 v1, 0xbfb8aa3b, v103
	v_mul_f32_e32 v2, 0xbfb8aa3b, v104
	v_mul_f32_e32 v3, 0xbfb8aa3b, v105
	v_mul_f32_e32 v242, 0xbfb8aa3b, v98
	v_mul_f32_e32 v243, 0xbfb8aa3b, v99
	v_mul_f32_e32 v244, 0xbfb8aa3b, v100
	v_mul_f32_e32 v245, 0xbfb8aa3b, v101
	v_exp_f32_e32 v0, v0
	v_exp_f32_e32 v1, v1
	v_exp_f32_e32 v2, v2
	v_exp_f32_e32 v3, v3
	v_exp_f32_e32 v242, v242
	v_exp_f32_e32 v243, v243
	v_exp_f32_e32 v244, v244
	v_exp_f32_e32 v245, v245
	v_add_f32_e32 v0, 1.0, v0
	v_add_f32_e32 v1, 1.0, v1
	v_add_f32_e32 v2, 1.0, v2
	v_add_f32_e32 v3, 1.0, v3
	v_add_f32_e32 v242, 1.0, v242
	v_add_f32_e32 v243, 1.0, v243
	v_add_f32_e32 v244, 1.0, v244
	v_add_f32_e32 v245, 1.0, v245
	v_rcp_f32_e32 v0, v0
	v_rcp_f32_e32 v1, v1
	v_rcp_f32_e32 v2, v2
	v_rcp_f32_e32 v3, v3
	v_rcp_f32_e32 v242, v242
	v_rcp_f32_e32 v243, v243
	v_rcp_f32_e32 v244, v244
	v_rcp_f32_e32 v245, v245
	v_pk_mul_f32 v[102:103], v[102:103], v[0:1]
	v_pk_mul_f32 v[104:105], v[104:105], v[2:3]
	v_pk_mul_f32 v[98:99], v[98:99], v[242:243]
	v_pk_mul_f32 v[100:101], v[100:101], v[244:245]
	v_mul_f32_e32 v0, 0xbfb8aa3b, v92
	v_mul_f32_e32 v1, 0xbfb8aa3b, v93
	v_mul_f32_e32 v2, 0xbfb8aa3b, v94
	v_mul_f32_e32 v3, 0xbfb8aa3b, v95
	v_mul_f32_e32 v242, 0xbfb8aa3b, v88
	v_mul_f32_e32 v243, 0xbfb8aa3b, v89
	v_mul_f32_e32 v244, 0xbfb8aa3b, v90
	v_mul_f32_e32 v245, 0xbfb8aa3b, v91
	v_exp_f32_e32 v0, v0
	v_exp_f32_e32 v1, v1
	v_exp_f32_e32 v2, v2
	v_exp_f32_e32 v3, v3
	v_exp_f32_e32 v242, v242
	v_exp_f32_e32 v243, v243
	v_exp_f32_e32 v244, v244
	v_exp_f32_e32 v245, v245
	v_add_f32_e32 v0, 1.0, v0
	v_add_f32_e32 v1, 1.0, v1
	v_add_f32_e32 v2, 1.0, v2
	v_add_f32_e32 v3, 1.0, v3
	v_add_f32_e32 v242, 1.0, v242
	v_add_f32_e32 v243, 1.0, v243
	v_add_f32_e32 v244, 1.0, v244
	v_add_f32_e32 v245, 1.0, v245
	v_rcp_f32_e32 v0, v0
	v_rcp_f32_e32 v1, v1
	v_rcp_f32_e32 v2, v2
	v_rcp_f32_e32 v3, v3
	v_rcp_f32_e32 v242, v242
	v_rcp_f32_e32 v243, v243
	v_rcp_f32_e32 v244, v244
	v_rcp_f32_e32 v245, v245
	v_pk_mul_f32 v[92:93], v[92:93], v[0:1]
	v_pk_mul_f32 v[94:95], v[94:95], v[2:3]
	v_pk_mul_f32 v[88:89], v[88:89], v[242:243]
	v_pk_mul_f32 v[90:91], v[90:91], v[244:245]
	v_cvt_pk_bf16_f32 v234, v102, v103
	v_cvt_pk_bf16_f32 v235, v104, v105
	v_cvt_pk_bf16_f32 v236, v98, v99
	v_cvt_pk_bf16_f32 v237, v100, v101
	v_cvt_pk_bf16_f32 v238, v92, v93
	v_cvt_pk_bf16_f32 v239, v94, v95
	v_cvt_pk_bf16_f32 v240, v88, v89
	v_cvt_pk_bf16_f32 v241, v90, v91
	s_mov_b64 vcc, s[6:7]
	v_cndmask_b32_dpp v102, v238, v234, vcc row_ror:8 row_mask:0xf bank_mask:0xf
	v_cndmask_b32_dpp v103, v239, v235, vcc row_ror:8 row_mask:0xf bank_mask:0xf
	v_cndmask_b32_dpp v104, v240, v236, vcc row_ror:8 row_mask:0xf bank_mask:0xf
	v_cndmask_b32_dpp v105, v241, v237, vcc row_ror:8 row_mask:0xf bank_mask:0xf
	s_not_b64 vcc, s[6:7]
	v_cndmask_b32_dpp v98, v234, v238, vcc row_ror:8 row_mask:0xf bank_mask:0xf
	v_cndmask_b32_dpp v99, v235, v239, vcc row_ror:8 row_mask:0xf bank_mask:0xf
	v_cndmask_b32_dpp v100, v236, v240, vcc row_ror:8 row_mask:0xf bank_mask:0xf
	v_cndmask_b32_dpp v101, v237, v241, vcc row_ror:8 row_mask:0xf bank_mask:0xf
	global_store_dwordx4 v246, v[102:105], s[12:13] nt
	global_store_dwordx4 v247, v[98:101], s[12:13] nt
	v_mov_b32_e32 v6, v189
	s_add_u32 s12, s12, 0x8000
	s_addc_u32 s13, s13, 0
	v_pk_fma_f32 v[86:87], v[86:87], v[6:7], v[196:197] op_sel_hi:[1,0,1]
	v_pk_fma_f32 v[84:85], v[84:85], v[6:7], v[194:195] op_sel_hi:[1,0,1]
	v_pk_fma_f32 v[82:83], v[82:83], v[6:7], v[200:201] op_sel_hi:[1,0,1]
	v_pk_fma_f32 v[80:81], v[80:81], v[6:7], v[198:199] op_sel_hi:[1,0,1]
	v_pk_fma_f32 v[78:79], v[78:79], v[6:7], v[204:205] op_sel_hi:[1,0,1]
	v_pk_fma_f32 v[76:77], v[76:77], v[6:7], v[202:203] op_sel_hi:[1,0,1]
	v_pk_fma_f32 v[74:75], v[74:75], v[6:7], v[224:225] op_sel_hi:[1,0,1]
	v_pk_fma_f32 v[72:73], v[72:73], v[6:7], v[222:223] op_sel_hi:[1,0,1]
	v_mul_f32_e32 v0, 0xbfb8aa3b, v84
	v_mul_f32_e32 v1, 0xbfb8aa3b, v85
	v_mul_f32_e32 v2, 0xbfb8aa3b, v86
	v_mul_f32_e32 v3, 0xbfb8aa3b, v87
	v_mul_f32_e32 v242, 0xbfb8aa3b, v80
	v_mul_f32_e32 v243, 0xbfb8aa3b, v81
	v_mul_f32_e32 v244, 0xbfb8aa3b, v82
	v_mul_f32_e32 v245, 0xbfb8aa3b, v83
	v_exp_f32_e32 v0, v0
	v_exp_f32_e32 v1, v1
	v_exp_f32_e32 v2, v2
	v_exp_f32_e32 v3, v3
	v_exp_f32_e32 v242, v242
	v_exp_f32_e32 v243, v243
	v_exp_f32_e32 v244, v244
	v_exp_f32_e32 v245, v245
	v_add_f32_e32 v0, 1.0, v0
	v_add_f32_e32 v1, 1.0, v1
	v_add_f32_e32 v2, 1.0, v2
	v_add_f32_e32 v3, 1.0, v3
	v_add_f32_e32 v242, 1.0, v242
	v_add_f32_e32 v243, 1.0, v243
	v_add_f32_e32 v244, 1.0, v244
	v_add_f32_e32 v245, 1.0, v245
	v_rcp_f32_e32 v0, v0
	v_rcp_f32_e32 v1, v1
	v_rcp_f32_e32 v2, v2
	v_rcp_f32_e32 v3, v3
	v_rcp_f32_e32 v242, v242
	v_rcp_f32_e32 v243, v243
	v_rcp_f32_e32 v244, v244
	v_rcp_f32_e32 v245, v245
	v_pk_mul_f32 v[84:85], v[84:85], v[0:1]
	v_pk_mul_f32 v[86:87], v[86:87], v[2:3]
	v_pk_mul_f32 v[80:81], v[80:81], v[242:243]
	v_pk_mul_f32 v[82:83], v[82:83], v[244:245]
	v_mul_f32_e32 v0, 0xbfb8aa3b, v76
	v_mul_f32_e32 v1, 0xbfb8aa3b, v77
	v_mul_f32_e32 v2, 0xbfb8aa3b, v78
	v_mul_f32_e32 v3, 0xbfb8aa3b, v79
	v_mul_f32_e32 v242, 0xbfb8aa3b, v72
	v_mul_f32_e32 v243, 0xbfb8aa3b, v73
	v_mul_f32_e32 v244, 0xbfb8aa3b, v74
	v_mul_f32_e32 v245, 0xbfb8aa3b, v75
	v_exp_f32_e32 v0, v0
	v_exp_f32_e32 v1, v1
	v_exp_f32_e32 v2, v2
	v_exp_f32_e32 v3, v3
	v_exp_f32_e32 v242, v242
	v_exp_f32_e32 v243, v243
	v_exp_f32_e32 v244, v244
	v_exp_f32_e32 v245, v245
	v_add_f32_e32 v0, 1.0, v0
	v_add_f32_e32 v1, 1.0, v1
	v_add_f32_e32 v2, 1.0, v2
	v_add_f32_e32 v3, 1.0, v3
	v_add_f32_e32 v242, 1.0, v242
	v_add_f32_e32 v243, 1.0, v243
	v_add_f32_e32 v244, 1.0, v244
	v_add_f32_e32 v245, 1.0, v245
	v_rcp_f32_e32 v0, v0
	v_rcp_f32_e32 v1, v1
	v_rcp_f32_e32 v2, v2
	v_rcp_f32_e32 v3, v3
	v_rcp_f32_e32 v242, v242
	v_rcp_f32_e32 v243, v243
	v_rcp_f32_e32 v244, v244
	v_rcp_f32_e32 v245, v245
	v_pk_mul_f32 v[76:77], v[76:77], v[0:1]
	v_pk_mul_f32 v[78:79], v[78:79], v[2:3]
	v_pk_mul_f32 v[72:73], v[72:73], v[242:243]
	v_pk_mul_f32 v[74:75], v[74:75], v[244:245]
	v_cvt_pk_bf16_f32 v234, v84, v85
	v_cvt_pk_bf16_f32 v235, v86, v87
	v_cvt_pk_bf16_f32 v236, v80, v81
	v_cvt_pk_bf16_f32 v237, v82, v83
	v_cvt_pk_bf16_f32 v238, v76, v77
	v_cvt_pk_bf16_f32 v239, v78, v79
	v_cvt_pk_bf16_f32 v240, v72, v73
	v_cvt_pk_bf16_f32 v241, v74, v75
	s_mov_b64 vcc, s[6:7]
	v_cndmask_b32_dpp v84, v238, v234, vcc row_ror:8 row_mask:0xf bank_mask:0xf
	v_cndmask_b32_dpp v85, v239, v235, vcc row_ror:8 row_mask:0xf bank_mask:0xf
	v_cndmask_b32_dpp v86, v240, v236, vcc row_ror:8 row_mask:0xf bank_mask:0xf
	v_cndmask_b32_dpp v87, v241, v237, vcc row_ror:8 row_mask:0xf bank_mask:0xf
	s_not_b64 vcc, s[6:7]
	v_cndmask_b32_dpp v80, v234, v238, vcc row_ror:8 row_mask:0xf bank_mask:0xf
	v_cndmask_b32_dpp v81, v235, v239, vcc row_ror:8 row_mask:0xf bank_mask:0xf
	v_cndmask_b32_dpp v82, v236, v240, vcc row_ror:8 row_mask:0xf bank_mask:0xf
	v_cndmask_b32_dpp v83, v237, v241, vcc row_ror:8 row_mask:0xf bank_mask:0xf
	global_store_dwordx4 v246, v[84:87], s[12:13] nt
	global_store_dwordx4 v247, v[80:83], s[12:13] nt
	s_add_u32 s10, s10, 0x3000
	s_addc_u32 s11, s11, 0
	global_load_dwordx4 v[194:197], v226, s[10:11]
	global_load_dwordx4 v[198:201], v226, s[10:11] offset:16
	global_load_dwordx4 v[202:205], v226, s[10:11] offset:128
	global_load_dwordx4 v[222:225], v226, s[10:11] offset:144
	s_waitcnt vmcnt(8)
	v_mov_b32_e32 v6, v190
	s_add_u32 s12, s12, 0x28000
	s_addc_u32 s13, s13, 0
	v_pk_fma_f32 v[70:71], v[70:71], v[6:7], v[152:153] op_sel_hi:[1,0,1]
	v_pk_fma_f32 v[68:69], v[68:69], v[6:7], v[150:151] op_sel_hi:[1,0,1]
	v_pk_fma_f32 v[66:67], v[66:67], v[6:7], v[148:149] op_sel_hi:[1,0,1]
	v_pk_fma_f32 v[64:65], v[64:65], v[6:7], v[146:147] op_sel_hi:[1,0,1]
	v_pk_fma_f32 v[62:63], v[62:63], v[6:7], v[144:145] op_sel_hi:[1,0,1]
	v_pk_fma_f32 v[60:61], v[60:61], v[6:7], v[142:143] op_sel_hi:[1,0,1]
	v_pk_fma_f32 v[58:59], v[58:59], v[6:7], v[140:141] op_sel_hi:[1,0,1]
	v_pk_fma_f32 v[56:57], v[56:57], v[6:7], v[138:139] op_sel_hi:[1,0,1]
	v_mul_f32_e32 v0, 0xbfb8aa3b, v68
	v_mul_f32_e32 v1, 0xbfb8aa3b, v69
	v_mul_f32_e32 v2, 0xbfb8aa3b, v70
	v_mul_f32_e32 v3, 0xbfb8aa3b, v71
	v_mul_f32_e32 v242, 0xbfb8aa3b, v64
	v_mul_f32_e32 v243, 0xbfb8aa3b, v65
	v_mul_f32_e32 v244, 0xbfb8aa3b, v66
	v_mul_f32_e32 v245, 0xbfb8aa3b, v67
	v_exp_f32_e32 v0, v0
	v_exp_f32_e32 v1, v1
	v_exp_f32_e32 v2, v2
	v_exp_f32_e32 v3, v3
	v_exp_f32_e32 v242, v242
	v_exp_f32_e32 v243, v243
	v_exp_f32_e32 v244, v244
	v_exp_f32_e32 v245, v245
	v_add_f32_e32 v0, 1.0, v0
	v_add_f32_e32 v1, 1.0, v1
	v_add_f32_e32 v2, 1.0, v2
	v_add_f32_e32 v3, 1.0, v3
	v_add_f32_e32 v242, 1.0, v242
	v_add_f32_e32 v243, 1.0, v243
	v_add_f32_e32 v244, 1.0, v244
	v_add_f32_e32 v245, 1.0, v245
	v_rcp_f32_e32 v0, v0
	v_rcp_f32_e32 v1, v1
	v_rcp_f32_e32 v2, v2
	v_rcp_f32_e32 v3, v3
	v_rcp_f32_e32 v242, v242
	v_rcp_f32_e32 v243, v243
	v_rcp_f32_e32 v244, v244
	v_rcp_f32_e32 v245, v245
	v_pk_mul_f32 v[68:69], v[68:69], v[0:1]
	v_pk_mul_f32 v[70:71], v[70:71], v[2:3]
	v_pk_mul_f32 v[64:65], v[64:65], v[242:243]
	v_pk_mul_f32 v[66:67], v[66:67], v[244:245]
	v_mul_f32_e32 v0, 0xbfb8aa3b, v60
	v_mul_f32_e32 v1, 0xbfb8aa3b, v61
	v_mul_f32_e32 v2, 0xbfb8aa3b, v62
	v_mul_f32_e32 v3, 0xbfb8aa3b, v63
	v_mul_f32_e32 v242, 0xbfb8aa3b, v56
	v_mul_f32_e32 v243, 0xbfb8aa3b, v57
	v_mul_f32_e32 v244, 0xbfb8aa3b, v58
	v_mul_f32_e32 v245, 0xbfb8aa3b, v59
	v_exp_f32_e32 v0, v0
	v_exp_f32_e32 v1, v1
	v_exp_f32_e32 v2, v2
	v_exp_f32_e32 v3, v3
	v_exp_f32_e32 v242, v242
	v_exp_f32_e32 v243, v243
	v_exp_f32_e32 v244, v244
	v_exp_f32_e32 v245, v245
	v_add_f32_e32 v0, 1.0, v0
	v_add_f32_e32 v1, 1.0, v1
	v_add_f32_e32 v2, 1.0, v2
	v_add_f32_e32 v3, 1.0, v3
	v_add_f32_e32 v242, 1.0, v242
	v_add_f32_e32 v243, 1.0, v243
	v_add_f32_e32 v244, 1.0, v244
	v_add_f32_e32 v245, 1.0, v245
	v_rcp_f32_e32 v0, v0
	v_rcp_f32_e32 v1, v1
	v_rcp_f32_e32 v2, v2
	v_rcp_f32_e32 v3, v3
	v_rcp_f32_e32 v242, v242
	v_rcp_f32_e32 v243, v243
	v_rcp_f32_e32 v244, v244
	v_rcp_f32_e32 v245, v245
	v_pk_mul_f32 v[60:61], v[60:61], v[0:1]
	v_pk_mul_f32 v[62:63], v[62:63], v[2:3]
	v_pk_mul_f32 v[56:57], v[56:57], v[242:243]
	v_pk_mul_f32 v[58:59], v[58:59], v[244:245]
	v_cvt_pk_bf16_f32 v234, v68, v69
	v_cvt_pk_bf16_f32 v235, v70, v71
	v_cvt_pk_bf16_f32 v236, v64, v65
	v_cvt_pk_bf16_f32 v237, v66, v67
	v_cvt_pk_bf16_f32 v238, v60, v61
	v_cvt_pk_bf16_f32 v239, v62, v63
	v_cvt_pk_bf16_f32 v240, v56, v57
	v_cvt_pk_bf16_f32 v241, v58, v59
	s_mov_b64 vcc, s[6:7]
	v_cndmask_b32_dpp v68, v238, v234, vcc row_ror:8 row_mask:0xf bank_mask:0xf
	v_cndmask_b32_dpp v69, v239, v235, vcc row_ror:8 row_mask:0xf bank_mask:0xf
	v_cndmask_b32_dpp v70, v240, v236, vcc row_ror:8 row_mask:0xf bank_mask:0xf
	v_cndmask_b32_dpp v71, v241, v237, vcc row_ror:8 row_mask:0xf bank_mask:0xf
	s_not_b64 vcc, s[6:7]
	v_cndmask_b32_dpp v64, v234, v238, vcc row_ror:8 row_mask:0xf bank_mask:0xf
	v_cndmask_b32_dpp v65, v235, v239, vcc row_ror:8 row_mask:0xf bank_mask:0xf
	v_cndmask_b32_dpp v66, v236, v240, vcc row_ror:8 row_mask:0xf bank_mask:0xf
	v_cndmask_b32_dpp v67, v237, v241, vcc row_ror:8 row_mask:0xf bank_mask:0xf
	global_store_dwordx4 v246, v[68:71], s[12:13] nt
	global_store_dwordx4 v247, v[64:67], s[12:13] nt
	v_mov_b32_e32 v6, v191
	s_add_u32 s12, s12, 0x8000
	s_addc_u32 s13, s13, 0
	v_pk_fma_f32 v[54:55], v[54:55], v[6:7], v[152:153] op_sel_hi:[1,0,1]
	v_pk_fma_f32 v[52:53], v[52:53], v[6:7], v[150:151] op_sel_hi:[1,0,1]
	v_pk_fma_f32 v[50:51], v[50:51], v[6:7], v[148:149] op_sel_hi:[1,0,1]
	v_pk_fma_f32 v[48:49], v[48:49], v[6:7], v[146:147] op_sel_hi:[1,0,1]
	v_pk_fma_f32 v[46:47], v[46:47], v[6:7], v[144:145] op_sel_hi:[1,0,1]
	v_pk_fma_f32 v[44:45], v[44:45], v[6:7], v[142:143] op_sel_hi:[1,0,1]
	v_pk_fma_f32 v[42:43], v[42:43], v[6:7], v[140:141] op_sel_hi:[1,0,1]
	v_pk_fma_f32 v[40:41], v[40:41], v[6:7], v[138:139] op_sel_hi:[1,0,1]
	v_mul_f32_e32 v0, 0xbfb8aa3b, v52
	v_mul_f32_e32 v1, 0xbfb8aa3b, v53
	v_mul_f32_e32 v2, 0xbfb8aa3b, v54
	v_mul_f32_e32 v3, 0xbfb8aa3b, v55
	v_mul_f32_e32 v242, 0xbfb8aa3b, v48
	v_mul_f32_e32 v243, 0xbfb8aa3b, v49
	v_mul_f32_e32 v244, 0xbfb8aa3b, v50
	v_mul_f32_e32 v245, 0xbfb8aa3b, v51
	v_exp_f32_e32 v0, v0
	v_exp_f32_e32 v1, v1
	v_exp_f32_e32 v2, v2
	v_exp_f32_e32 v3, v3
	v_exp_f32_e32 v242, v242
	v_exp_f32_e32 v243, v243
	v_exp_f32_e32 v244, v244
	v_exp_f32_e32 v245, v245
	v_add_f32_e32 v0, 1.0, v0
	v_add_f32_e32 v1, 1.0, v1
	v_add_f32_e32 v2, 1.0, v2
	v_add_f32_e32 v3, 1.0, v3
	v_add_f32_e32 v242, 1.0, v242
	v_add_f32_e32 v243, 1.0, v243
	v_add_f32_e32 v244, 1.0, v244
	v_add_f32_e32 v245, 1.0, v245
	v_rcp_f32_e32 v0, v0
	v_rcp_f32_e32 v1, v1
	v_rcp_f32_e32 v2, v2
	v_rcp_f32_e32 v3, v3
	v_rcp_f32_e32 v242, v242
	v_rcp_f32_e32 v243, v243
	v_rcp_f32_e32 v244, v244
	v_rcp_f32_e32 v245, v245
	v_pk_mul_f32 v[52:53], v[52:53], v[0:1]
	v_pk_mul_f32 v[54:55], v[54:55], v[2:3]
	v_pk_mul_f32 v[48:49], v[48:49], v[242:243]
	v_pk_mul_f32 v[50:51], v[50:51], v[244:245]
	v_mul_f32_e32 v0, 0xbfb8aa3b, v44
	v_mul_f32_e32 v1, 0xbfb8aa3b, v45
	v_mul_f32_e32 v2, 0xbfb8aa3b, v46
	v_mul_f32_e32 v3, 0xbfb8aa3b, v47
	v_mul_f32_e32 v242, 0xbfb8aa3b, v40
	v_mul_f32_e32 v243, 0xbfb8aa3b, v41
	v_mul_f32_e32 v244, 0xbfb8aa3b, v42
	v_mul_f32_e32 v245, 0xbfb8aa3b, v43
	v_exp_f32_e32 v0, v0
	v_exp_f32_e32 v1, v1
	v_exp_f32_e32 v2, v2
	v_exp_f32_e32 v3, v3
	v_exp_f32_e32 v242, v242
	v_exp_f32_e32 v243, v243
	v_exp_f32_e32 v244, v244
	v_exp_f32_e32 v245, v245
	v_add_f32_e32 v0, 1.0, v0
	v_add_f32_e32 v1, 1.0, v1
	v_add_f32_e32 v2, 1.0, v2
	v_add_f32_e32 v3, 1.0, v3
	v_add_f32_e32 v242, 1.0, v242
	v_add_f32_e32 v243, 1.0, v243
	v_add_f32_e32 v244, 1.0, v244
	v_add_f32_e32 v245, 1.0, v245
	v_rcp_f32_e32 v0, v0
	v_rcp_f32_e32 v1, v1
	v_rcp_f32_e32 v2, v2
	v_rcp_f32_e32 v3, v3
	v_rcp_f32_e32 v242, v242
	v_rcp_f32_e32 v243, v243
	v_rcp_f32_e32 v244, v244
	v_rcp_f32_e32 v245, v245
	v_pk_mul_f32 v[44:45], v[44:45], v[0:1]
	v_pk_mul_f32 v[46:47], v[46:47], v[2:3]
	v_pk_mul_f32 v[40:41], v[40:41], v[242:243]
	v_pk_mul_f32 v[42:43], v[42:43], v[244:245]
	v_cvt_pk_bf16_f32 v234, v52, v53
	v_cvt_pk_bf16_f32 v235, v54, v55
	v_cvt_pk_bf16_f32 v236, v48, v49
	v_cvt_pk_bf16_f32 v237, v50, v51
	v_cvt_pk_bf16_f32 v238, v44, v45
	v_cvt_pk_bf16_f32 v239, v46, v47
	v_cvt_pk_bf16_f32 v240, v40, v41
	v_cvt_pk_bf16_f32 v241, v42, v43
	s_mov_b64 vcc, s[6:7]
	v_cndmask_b32_dpp v52, v238, v234, vcc row_ror:8 row_mask:0xf bank_mask:0xf
	v_cndmask_b32_dpp v53, v239, v235, vcc row_ror:8 row_mask:0xf bank_mask:0xf
	v_cndmask_b32_dpp v54, v240, v236, vcc row_ror:8 row_mask:0xf bank_mask:0xf
	v_cndmask_b32_dpp v55, v241, v237, vcc row_ror:8 row_mask:0xf bank_mask:0xf
	s_not_b64 vcc, s[6:7]
	v_cndmask_b32_dpp v48, v234, v238, vcc row_ror:8 row_mask:0xf bank_mask:0xf
	v_cndmask_b32_dpp v49, v235, v239, vcc row_ror:8 row_mask:0xf bank_mask:0xf
	v_cndmask_b32_dpp v50, v236, v240, vcc row_ror:8 row_mask:0xf bank_mask:0xf
	v_cndmask_b32_dpp v51, v237, v241, vcc row_ror:8 row_mask:0xf bank_mask:0xf
	global_store_dwordx4 v246, v[52:55], s[12:13] nt
	global_store_dwordx4 v247, v[48:51], s[12:13] nt
	s_waitcnt vmcnt(4)
	v_mov_b32_e32 v6, v192
	s_add_u32 s12, s12, 0x8000
	s_addc_u32 s13, s13, 0
	v_pk_fma_f32 v[38:39], v[38:39], v[6:7], v[196:197] op_sel_hi:[1,0,1]
	v_pk_fma_f32 v[36:37], v[36:37], v[6:7], v[194:195] op_sel_hi:[1,0,1]
	v_pk_fma_f32 v[34:35], v[34:35], v[6:7], v[200:201] op_sel_hi:[1,0,1]
	v_pk_fma_f32 v[32:33], v[32:33], v[6:7], v[198:199] op_sel_hi:[1,0,1]
	v_pk_fma_f32 v[30:31], v[30:31], v[6:7], v[204:205] op_sel_hi:[1,0,1]
	v_pk_fma_f32 v[28:29], v[28:29], v[6:7], v[202:203] op_sel_hi:[1,0,1]
	v_pk_fma_f32 v[26:27], v[26:27], v[6:7], v[224:225] op_sel_hi:[1,0,1]
	v_pk_fma_f32 v[24:25], v[24:25], v[6:7], v[222:223] op_sel_hi:[1,0,1]
	v_mul_f32_e32 v0, 0xbfb8aa3b, v36
	v_mul_f32_e32 v1, 0xbfb8aa3b, v37
	v_mul_f32_e32 v2, 0xbfb8aa3b, v38
	v_mul_f32_e32 v3, 0xbfb8aa3b, v39
	v_mul_f32_e32 v242, 0xbfb8aa3b, v32
	v_mul_f32_e32 v243, 0xbfb8aa3b, v33
	v_mul_f32_e32 v244, 0xbfb8aa3b, v34
	v_mul_f32_e32 v245, 0xbfb8aa3b, v35
	v_exp_f32_e32 v0, v0
	v_exp_f32_e32 v1, v1
	v_exp_f32_e32 v2, v2
	v_exp_f32_e32 v3, v3
	v_exp_f32_e32 v242, v242
	v_exp_f32_e32 v243, v243
	v_exp_f32_e32 v244, v244
	v_exp_f32_e32 v245, v245
	v_add_f32_e32 v0, 1.0, v0
	v_add_f32_e32 v1, 1.0, v1
	v_add_f32_e32 v2, 1.0, v2
	v_add_f32_e32 v3, 1.0, v3
	v_add_f32_e32 v242, 1.0, v242
	v_add_f32_e32 v243, 1.0, v243
	v_add_f32_e32 v244, 1.0, v244
	v_add_f32_e32 v245, 1.0, v245
	v_rcp_f32_e32 v0, v0
	v_rcp_f32_e32 v1, v1
	v_rcp_f32_e32 v2, v2
	v_rcp_f32_e32 v3, v3
	v_rcp_f32_e32 v242, v242
	v_rcp_f32_e32 v243, v243
	v_rcp_f32_e32 v244, v244
	v_rcp_f32_e32 v245, v245
	v_pk_mul_f32 v[36:37], v[36:37], v[0:1]
	v_pk_mul_f32 v[38:39], v[38:39], v[2:3]
	v_pk_mul_f32 v[32:33], v[32:33], v[242:243]
	v_pk_mul_f32 v[34:35], v[34:35], v[244:245]
	v_mul_f32_e32 v0, 0xbfb8aa3b, v28
	v_mul_f32_e32 v1, 0xbfb8aa3b, v29
	v_mul_f32_e32 v2, 0xbfb8aa3b, v30
	v_mul_f32_e32 v3, 0xbfb8aa3b, v31
	v_mul_f32_e32 v242, 0xbfb8aa3b, v24
	v_mul_f32_e32 v243, 0xbfb8aa3b, v25
	v_mul_f32_e32 v244, 0xbfb8aa3b, v26
	v_mul_f32_e32 v245, 0xbfb8aa3b, v27
	v_exp_f32_e32 v0, v0
	v_exp_f32_e32 v1, v1
	v_exp_f32_e32 v2, v2
	v_exp_f32_e32 v3, v3
	v_exp_f32_e32 v242, v242
	v_exp_f32_e32 v243, v243
	v_exp_f32_e32 v244, v244
	v_exp_f32_e32 v245, v245
	v_add_f32_e32 v0, 1.0, v0
	v_add_f32_e32 v1, 1.0, v1
	v_add_f32_e32 v2, 1.0, v2
	v_add_f32_e32 v3, 1.0, v3
	v_add_f32_e32 v242, 1.0, v242
	v_add_f32_e32 v243, 1.0, v243
	v_add_f32_e32 v244, 1.0, v244
	v_add_f32_e32 v245, 1.0, v245
	v_rcp_f32_e32 v0, v0
	v_rcp_f32_e32 v1, v1
	v_rcp_f32_e32 v2, v2
	v_rcp_f32_e32 v3, v3
	v_rcp_f32_e32 v242, v242
	v_rcp_f32_e32 v243, v243
	v_rcp_f32_e32 v244, v244
	v_rcp_f32_e32 v245, v245
	v_pk_mul_f32 v[28:29], v[28:29], v[0:1]
	v_pk_mul_f32 v[30:31], v[30:31], v[2:3]
	v_pk_mul_f32 v[24:25], v[24:25], v[242:243]
	v_pk_mul_f32 v[26:27], v[26:27], v[244:245]
	v_cvt_pk_bf16_f32 v234, v36, v37
	v_cvt_pk_bf16_f32 v235, v38, v39
	v_cvt_pk_bf16_f32 v236, v32, v33
	v_cvt_pk_bf16_f32 v237, v34, v35
	v_cvt_pk_bf16_f32 v238, v28, v29
	v_cvt_pk_bf16_f32 v239, v30, v31
	v_cvt_pk_bf16_f32 v240, v24, v25
	v_cvt_pk_bf16_f32 v241, v26, v27
	s_mov_b64 vcc, s[6:7]
	v_cndmask_b32_dpp v36, v238, v234, vcc row_ror:8 row_mask:0xf bank_mask:0xf
	v_cndmask_b32_dpp v37, v239, v235, vcc row_ror:8 row_mask:0xf bank_mask:0xf
	v_cndmask_b32_dpp v38, v240, v236, vcc row_ror:8 row_mask:0xf bank_mask:0xf
	v_cndmask_b32_dpp v39, v241, v237, vcc row_ror:8 row_mask:0xf bank_mask:0xf
	s_not_b64 vcc, s[6:7]
	v_cndmask_b32_dpp v32, v234, v238, vcc row_ror:8 row_mask:0xf bank_mask:0xf
	v_cndmask_b32_dpp v33, v235, v239, vcc row_ror:8 row_mask:0xf bank_mask:0xf
	v_cndmask_b32_dpp v34, v236, v240, vcc row_ror:8 row_mask:0xf bank_mask:0xf
	v_cndmask_b32_dpp v35, v237, v241, vcc row_ror:8 row_mask:0xf bank_mask:0xf
	global_store_dwordx4 v246, v[36:39], s[12:13] nt
	global_store_dwordx4 v247, v[32:35], s[12:13] nt
	v_mov_b32_e32 v6, v193
	s_add_u32 s12, s12, 0x8000
	s_addc_u32 s13, s13, 0
	v_pk_fma_f32 v[22:23], v[22:23], v[6:7], v[196:197] op_sel_hi:[1,0,1]
	v_pk_fma_f32 v[20:21], v[20:21], v[6:7], v[194:195] op_sel_hi:[1,0,1]
	v_pk_fma_f32 v[18:19], v[18:19], v[6:7], v[200:201] op_sel_hi:[1,0,1]
	v_pk_fma_f32 v[16:17], v[16:17], v[6:7], v[198:199] op_sel_hi:[1,0,1]
	v_pk_fma_f32 v[14:15], v[14:15], v[6:7], v[204:205] op_sel_hi:[1,0,1]
	v_pk_fma_f32 v[12:13], v[12:13], v[6:7], v[202:203] op_sel_hi:[1,0,1]
	v_pk_fma_f32 v[10:11], v[10:11], v[6:7], v[224:225] op_sel_hi:[1,0,1]
	v_pk_fma_f32 v[8:9], v[8:9], v[6:7], v[222:223] op_sel_hi:[1,0,1]
	v_mul_f32_e32 v0, 0xbfb8aa3b, v20
	v_mul_f32_e32 v1, 0xbfb8aa3b, v21
	v_mul_f32_e32 v2, 0xbfb8aa3b, v22
	v_mul_f32_e32 v3, 0xbfb8aa3b, v23
	v_mul_f32_e32 v242, 0xbfb8aa3b, v16
	v_mul_f32_e32 v243, 0xbfb8aa3b, v17
	v_mul_f32_e32 v244, 0xbfb8aa3b, v18
	v_mul_f32_e32 v245, 0xbfb8aa3b, v19
	v_exp_f32_e32 v0, v0
	v_exp_f32_e32 v1, v1
	v_exp_f32_e32 v2, v2
	v_exp_f32_e32 v3, v3
	v_exp_f32_e32 v242, v242
	v_exp_f32_e32 v243, v243
	v_exp_f32_e32 v244, v244
	v_exp_f32_e32 v245, v245
	v_add_f32_e32 v0, 1.0, v0
	v_add_f32_e32 v1, 1.0, v1
	v_add_f32_e32 v2, 1.0, v2
	v_add_f32_e32 v3, 1.0, v3
	v_add_f32_e32 v242, 1.0, v242
	v_add_f32_e32 v243, 1.0, v243
	v_add_f32_e32 v244, 1.0, v244
	v_add_f32_e32 v245, 1.0, v245
	v_rcp_f32_e32 v0, v0
	v_rcp_f32_e32 v1, v1
	v_rcp_f32_e32 v2, v2
	v_rcp_f32_e32 v3, v3
	v_rcp_f32_e32 v242, v242
	v_rcp_f32_e32 v243, v243
	v_rcp_f32_e32 v244, v244
	v_rcp_f32_e32 v245, v245
	v_pk_mul_f32 v[20:21], v[20:21], v[0:1]
	v_pk_mul_f32 v[22:23], v[22:23], v[2:3]
	v_pk_mul_f32 v[16:17], v[16:17], v[242:243]
	v_pk_mul_f32 v[18:19], v[18:19], v[244:245]
	v_mul_f32_e32 v0, 0xbfb8aa3b, v12
	v_mul_f32_e32 v1, 0xbfb8aa3b, v13
	v_mul_f32_e32 v2, 0xbfb8aa3b, v14
	v_mul_f32_e32 v3, 0xbfb8aa3b, v15
	v_mul_f32_e32 v242, 0xbfb8aa3b, v8
	v_mul_f32_e32 v243, 0xbfb8aa3b, v9
	v_mul_f32_e32 v244, 0xbfb8aa3b, v10
	v_mul_f32_e32 v245, 0xbfb8aa3b, v11
	v_exp_f32_e32 v0, v0
	v_exp_f32_e32 v1, v1
	v_exp_f32_e32 v2, v2
	v_exp_f32_e32 v3, v3
	v_exp_f32_e32 v242, v242
	v_exp_f32_e32 v243, v243
	v_exp_f32_e32 v244, v244
	v_exp_f32_e32 v245, v245
	v_add_f32_e32 v0, 1.0, v0
	v_add_f32_e32 v1, 1.0, v1
	v_add_f32_e32 v2, 1.0, v2
	v_add_f32_e32 v3, 1.0, v3
	v_add_f32_e32 v242, 1.0, v242
	v_add_f32_e32 v243, 1.0, v243
	v_add_f32_e32 v244, 1.0, v244
	v_add_f32_e32 v245, 1.0, v245
	v_rcp_f32_e32 v0, v0
	v_rcp_f32_e32 v1, v1
	v_rcp_f32_e32 v2, v2
	v_rcp_f32_e32 v3, v3
	v_rcp_f32_e32 v242, v242
	v_rcp_f32_e32 v243, v243
	v_rcp_f32_e32 v244, v244
	v_rcp_f32_e32 v245, v245
	v_pk_mul_f32 v[12:13], v[12:13], v[0:1]
	v_pk_mul_f32 v[14:15], v[14:15], v[2:3]
	v_pk_mul_f32 v[8:9], v[8:9], v[242:243]
	v_pk_mul_f32 v[10:11], v[10:11], v[244:245]
	v_cvt_pk_bf16_f32 v234, v20, v21
	v_cvt_pk_bf16_f32 v235, v22, v23
	v_cvt_pk_bf16_f32 v236, v16, v17
	v_cvt_pk_bf16_f32 v237, v18, v19
	v_cvt_pk_bf16_f32 v238, v12, v13
	v_cvt_pk_bf16_f32 v239, v14, v15
	v_cvt_pk_bf16_f32 v240, v8, v9
	v_cvt_pk_bf16_f32 v241, v10, v11
	s_mov_b64 vcc, s[6:7]
	v_cndmask_b32_dpp v20, v238, v234, vcc row_ror:8 row_mask:0xf bank_mask:0xf
	v_cndmask_b32_dpp v21, v239, v235, vcc row_ror:8 row_mask:0xf bank_mask:0xf
	v_cndmask_b32_dpp v22, v240, v236, vcc row_ror:8 row_mask:0xf bank_mask:0xf
	v_cndmask_b32_dpp v23, v241, v237, vcc row_ror:8 row_mask:0xf bank_mask:0xf
	s_not_b64 vcc, s[6:7]
	v_cndmask_b32_dpp v16, v234, v238, vcc row_ror:8 row_mask:0xf bank_mask:0xf
	v_cndmask_b32_dpp v17, v235, v239, vcc row_ror:8 row_mask:0xf bank_mask:0xf
	v_cndmask_b32_dpp v18, v236, v240, vcc row_ror:8 row_mask:0xf bank_mask:0xf
	v_cndmask_b32_dpp v19, v237, v241, vcc row_ror:8 row_mask:0xf bank_mask:0xf
	global_store_dwordx4 v246, v[20:23], s[12:13] nt
	global_store_dwordx4 v247, v[16:19], s[12:13] nt
	s_mov_b32 s100, 1
	s_branch .LBB0_1422
.Lfn_plain:
	s_waitcnt vmcnt(4)
	v_mov_b32_e32 v6, v186
	v_pk_fma_f32 v[136:137], v[136:137], v[6:7], v[152:153] op_sel_hi:[1,0,1]
	v_pk_fma_f32 v[134:135], v[134:135], v[6:7], v[150:151] op_sel_hi:[1,0,1]
	v_pk_fma_f32 v[132:133], v[132:133], v[6:7], v[148:149] op_sel_hi:[1,0,1]
	v_pk_fma_f32 v[130:131], v[130:131], v[6:7], v[146:147] op_sel_hi:[1,0,1]
	v_pk_fma_f32 v[128:129], v[128:129], v[6:7], v[144:145] op_sel_hi:[1,0,1]
	v_pk_fma_f32 v[126:127], v[126:127], v[6:7], v[142:143] op_sel_hi:[1,0,1]
	v_pk_fma_f32 v[124:125], v[124:125], v[6:7], v[140:141] op_sel_hi:[1,0,1]
	v_pk_fma_f32 v[122:123], v[122:123], v[6:7], v[138:139] op_sel_hi:[1,0,1]
	v_cvt_pk_bf16_f32 v234, v134, v135
	v_cvt_pk_bf16_f32 v235, v136, v137
	v_cvt_pk_bf16_f32 v236, v130, v131
	v_cvt_pk_bf16_f32 v237, v132, v133
	v_cvt_pk_bf16_f32 v238, v126, v127
	v_cvt_pk_bf16_f32 v239, v128, v129
	v_cvt_pk_bf16_f32 v240, v122, v123
	v_cvt_pk_bf16_f32 v241, v124, v125
	s_mov_b64 vcc, s[6:7]
	v_cndmask_b32_dpp v134, v238, v234, vcc row_ror:8 row_mask:0xf bank_mask:0xf
	v_cndmask_b32_dpp v135, v239, v235, vcc row_ror:8 row_mask:0xf bank_mask:0xf
	v_cndmask_b32_dpp v136, v240, v236, vcc row_ror:8 row_mask:0xf bank_mask:0xf
	v_cndmask_b32_dpp v137, v241, v237, vcc row_ror:8 row_mask:0xf bank_mask:0xf
	s_not_b64 vcc, s[6:7]
	v_cndmask_b32_dpp v130, v234, v238, vcc row_ror:8 row_mask:0xf bank_mask:0xf
	v_cndmask_b32_dpp v131, v235, v239, vcc row_ror:8 row_mask:0xf bank_mask:0xf
	v_cndmask_b32_dpp v132, v236, v240, vcc row_ror:8 row_mask:0xf bank_mask:0xf
	v_cndmask_b32_dpp v133, v237, v241, vcc row_ror:8 row_mask:0xf bank_mask:0xf
	global_store_dwordx4 v246, v[134:137], s[12:13] nt
	global_store_dwordx4 v247, v[130:133], s[12:13] nt
	v_mov_b32_e32 v6, v187
	s_add_u32 s12, s12, 0x8000
	s_addc_u32 s13, s13, 0
	v_pk_fma_f32 v[120:121], v[120:121], v[6:7], v[152:153] op_sel_hi:[1,0,1]
	v_pk_fma_f32 v[118:119], v[118:119], v[6:7], v[150:151] op_sel_hi:[1,0,1]
	v_pk_fma_f32 v[116:117], v[116:117], v[6:7], v[148:149] op_sel_hi:[1,0,1]
	v_pk_fma_f32 v[114:115], v[114:115], v[6:7], v[146:147] op_sel_hi:[1,0,1]
	v_pk_fma_f32 v[112:113], v[112:113], v[6:7], v[144:145] op_sel_hi:[1,0,1]
	v_pk_fma_f32 v[110:111], v[110:111], v[6:7], v[142:143] op_sel_hi:[1,0,1]
	v_pk_fma_f32 v[108:109], v[108:109], v[6:7], v[140:141] op_sel_hi:[1,0,1]
	v_pk_fma_f32 v[106:107], v[106:107], v[6:7], v[138:139] op_sel_hi:[1,0,1]
	v_cvt_pk_bf16_f32 v234, v118, v119
	v_cvt_pk_bf16_f32 v235, v120, v121
	v_cvt_pk_bf16_f32 v236, v114, v115
	v_cvt_pk_bf16_f32 v237, v116, v117
	v_cvt_pk_bf16_f32 v238, v110, v111
	v_cvt_pk_bf16_f32 v239, v112, v113
	v_cvt_pk_bf16_f32 v240, v106, v107
	v_cvt_pk_bf16_f32 v241, v108, v109
	s_mov_b64 vcc, s[6:7]
	v_cndmask_b32_dpp v118, v238, v234, vcc row_ror:8 row_mask:0xf bank_mask:0xf
	v_cndmask_b32_dpp v119, v239, v235, vcc row_ror:8 row_mask:0xf bank_mask:0xf
	v_cndmask_b32_dpp v120, v240, v236, vcc row_ror:8 row_mask:0xf bank_mask:0xf
	v_cndmask_b32_dpp v121, v241, v237, vcc row_ror:8 row_mask:0xf bank_mask:0xf
	s_not_b64 vcc, s[6:7]
	v_cndmask_b32_dpp v114, v234, v238, vcc row_ror:8 row_mask:0xf bank_mask:0xf
	v_cndmask_b32_dpp v115, v235, v239, vcc row_ror:8 row_mask:0xf bank_mask:0xf
	v_cndmask_b32_dpp v116, v236, v240, vcc row_ror:8 row_mask:0xf bank_mask:0xf
	v_cndmask_b32_dpp v117, v237, v241, vcc row_ror:8 row_mask:0xf bank_mask:0xf
	global_store_dwordx4 v246, v[118:121], s[12:13] nt
	global_store_dwordx4 v247, v[114:117], s[12:13] nt
	s_add_u32 s10, s10, 0x9000
	s_addc_u32 s11, s11, 0
	global_load_dwordx4 v[150:153], v226, s[10:11]
	global_load_dwordx4 v[146:149], v226, s[10:11] offset:16
	global_load_dwordx4 v[142:145], v226, s[10:11] offset:128
	global_load_dwordx4 v[138:141], v226, s[10:11] offset:144
	s_waitcnt vmcnt(8)
	v_mov_b32_e32 v6, v188
	s_add_u32 s12, s12, 0x8000
	s_addc_u32 s13, s13, 0
	v_pk_fma_f32 v[104:105], v[104:105], v[6:7], v[196:197] op_sel_hi:[1,0,1]
	v_pk_fma_f32 v[102:103], v[102:103], v[6:7], v[194:195] op_sel_hi:[1,0,1]
	v_pk_fma_f32 v[100:101], v[100:101], v[6:7], v[200:201] op_sel_hi:[1,0,1]
	v_pk_fma_f32 v[98:99], v[98:99], v[6:7], v[198:199] op_sel_hi:[1,0,1]
	v_pk_fma_f32 v[94:95], v[94:95], v[6:7], v[204:205] op_sel_hi:[1,0,1]
	v_pk_fma_f32 v[92:93], v[92:93], v[6:7], v[202:203] op_sel_hi:[1,0,1]
	v_pk_fma_f32 v[90:91], v[90:91], v[6:7], v[224:225] op_sel_hi:[1,0,1]
	v_pk_fma_f32 v[88:89], v[88:89], v[6:7], v[222:223] op_sel_hi:[1,0,1]
	v_cvt_pk_bf16_f32 v234, v102, v103
	v_cvt_pk_bf16_f32 v235, v104, v105
	v_cvt_pk_bf16_f32 v236, v98, v99
	v_cvt_pk_bf16_f32 v237, v100, v101
	v_cvt_pk_bf16_f32 v238, v92, v93
	v_cvt_pk_bf16_f32 v239, v94, v95
	v_cvt_pk_bf16_f32 v240, v88, v89
	v_cvt_pk_bf16_f32 v241, v90, v91
	s_mov_b64 vcc, s[6:7]
	v_cndmask_b32_dpp v102, v238, v234, vcc row_ror:8 row_mask:0xf bank_mask:0xf
	v_cndmask_b32_dpp v103, v239, v235, vcc row_ror:8 row_mask:0xf bank_mask:0xf
	v_cndmask_b32_dpp v104, v240, v236, vcc row_ror:8 row_mask:0xf bank_mask:0xf
	v_cndmask_b32_dpp v105, v241, v237, vcc row_ror:8 row_mask:0xf bank_mask:0xf
	s_not_b64 vcc, s[6:7]
	v_cndmask_b32_dpp v98, v234, v238, vcc row_ror:8 row_mask:0xf bank_mask:0xf
	v_cndmask_b32_dpp v99, v235, v239, vcc row_ror:8 row_mask:0xf bank_mask:0xf
	v_cndmask_b32_dpp v100, v236, v240, vcc row_ror:8 row_mask:0xf bank_mask:0xf
	v_cndmask_b32_dpp v101, v237, v241, vcc row_ror:8 row_mask:0xf bank_mask:0xf
	global_store_dwordx4 v246, v[102:105], s[12:13] nt
	global_store_dwordx4 v247, v[98:101], s[12:13] nt
	v_mov_b32_e32 v6, v189
	s_add_u32 s12, s12, 0x8000
	s_addc_u32 s13, s13, 0
	v_pk_fma_f32 v[86:87], v[86:87], v[6:7], v[196:197] op_sel_hi:[1,0,1]
	v_pk_fma_f32 v[84:85], v[84:85], v[6:7], v[194:195] op_sel_hi:[1,0,1]
	v_pk_fma_f32 v[82:83], v[82:83], v[6:7], v[200:201] op_sel_hi:[1,0,1]
	v_pk_fma_f32 v[80:81], v[80:81], v[6:7], v[198:199] op_sel_hi:[1,0,1]
	v_pk_fma_f32 v[78:79], v[78:79], v[6:7], v[204:205] op_sel_hi:[1,0,1]
	v_pk_fma_f32 v[76:77], v[76:77], v[6:7], v[202:203] op_sel_hi:[1,0,1]
	v_pk_fma_f32 v[74:75], v[74:75], v[6:7], v[224:225] op_sel_hi:[1,0,1]
	v_pk_fma_f32 v[72:73], v[72:73], v[6:7], v[222:223] op_sel_hi:[1,0,1]
	v_cvt_pk_bf16_f32 v234, v84, v85
	v_cvt_pk_bf16_f32 v235, v86, v87
	v_cvt_pk_bf16_f32 v236, v80, v81
	v_cvt_pk_bf16_f32 v237, v82, v83
	v_cvt_pk_bf16_f32 v238, v76, v77
	v_cvt_pk_bf16_f32 v239, v78, v79
	v_cvt_pk_bf16_f32 v240, v72, v73
	v_cvt_pk_bf16_f32 v241, v74, v75
	s_mov_b64 vcc, s[6:7]
	v_cndmask_b32_dpp v84, v238, v234, vcc row_ror:8 row_mask:0xf bank_mask:0xf
	v_cndmask_b32_dpp v85, v239, v235, vcc row_ror:8 row_mask:0xf bank_mask:0xf
	v_cndmask_b32_dpp v86, v240, v236, vcc row_ror:8 row_mask:0xf bank_mask:0xf
	v_cndmask_b32_dpp v87, v241, v237, vcc row_ror:8 row_mask:0xf bank_mask:0xf
	s_not_b64 vcc, s[6:7]
	v_cndmask_b32_dpp v80, v234, v238, vcc row_ror:8 row_mask:0xf bank_mask:0xf
	v_cndmask_b32_dpp v81, v235, v239, vcc row_ror:8 row_mask:0xf bank_mask:0xf
	v_cndmask_b32_dpp v82, v236, v240, vcc row_ror:8 row_mask:0xf bank_mask:0xf
	v_cndmask_b32_dpp v83, v237, v241, vcc row_ror:8 row_mask:0xf bank_mask:0xf
	global_store_dwordx4 v246, v[84:87], s[12:13] nt
	global_store_dwordx4 v247, v[80:83], s[12:13] nt
	s_add_u32 s10, s10, 0x3000
	s_addc_u32 s11, s11, 0
	global_load_dwordx4 v[194:197], v226, s[10:11]
	global_load_dwordx4 v[198:201], v226, s[10:11] offset:16
	global_load_dwordx4 v[202:205], v226, s[10:11] offset:128
	global_load_dwordx4 v[222:225], v226, s[10:11] offset:144
	s_waitcnt vmcnt(8)
	v_mov_b32_e32 v6, v190
	s_add_u32 s12, s12, 0x28000
	s_addc_u32 s13, s13, 0
	v_pk_fma_f32 v[70:71], v[70:71], v[6:7], v[152:153] op_sel_hi:[1,0,1]
	v_pk_fma_f32 v[68:69], v[68:69], v[6:7], v[150:151] op_sel_hi:[1,0,1]
	v_pk_fma_f32 v[66:67], v[66:67], v[6:7], v[148:149] op_sel_hi:[1,0,1]
	v_pk_fma_f32 v[64:65], v[64:65], v[6:7], v[146:147] op_sel_hi:[1,0,1]
	v_pk_fma_f32 v[62:63], v[62:63], v[6:7], v[144:145] op_sel_hi:[1,0,1]
	v_pk_fma_f32 v[60:61], v[60:61], v[6:7], v[142:143] op_sel_hi:[1,0,1]
	v_pk_fma_f32 v[58:59], v[58:59], v[6:7], v[140:141] op_sel_hi:[1,0,1]
	v_pk_fma_f32 v[56:57], v[56:57], v[6:7], v[138:139] op_sel_hi:[1,0,1]
	v_cvt_pk_bf16_f32 v234, v68, v69
	v_cvt_pk_bf16_f32 v235, v70, v71
	v_cvt_pk_bf16_f32 v236, v64, v65
	v_cvt_pk_bf16_f32 v237, v66, v67
	v_cvt_pk_bf16_f32 v238, v60, v61
	v_cvt_pk_bf16_f32 v239, v62, v63
	v_cvt_pk_bf16_f32 v240, v56, v57
	v_cvt_pk_bf16_f32 v241, v58, v59
	s_mov_b64 vcc, s[6:7]
	v_cndmask_b32_dpp v68, v238, v234, vcc row_ror:8 row_mask:0xf bank_mask:0xf
	v_cndmask_b32_dpp v69, v239, v235, vcc row_ror:8 row_mask:0xf bank_mask:0xf
	v_cndmask_b32_dpp v70, v240, v236, vcc row_ror:8 row_mask:0xf bank_mask:0xf
	v_cndmask_b32_dpp v71, v241, v237, vcc row_ror:8 row_mask:0xf bank_mask:0xf
	s_not_b64 vcc, s[6:7]
	v_cndmask_b32_dpp v64, v234, v238, vcc row_ror:8 row_mask:0xf bank_mask:0xf
	v_cndmask_b32_dpp v65, v235, v239, vcc row_ror:8 row_mask:0xf bank_mask:0xf
	v_cndmask_b32_dpp v66, v236, v240, vcc row_ror:8 row_mask:0xf bank_mask:0xf
	v_cndmask_b32_dpp v67, v237, v241, vcc row_ror:8 row_mask:0xf bank_mask:0xf
	global_store_dwordx4 v246, v[68:71], s[12:13] nt
	global_store_dwordx4 v247, v[64:67], s[12:13] nt
	v_mov_b32_e32 v6, v191
	s_add_u32 s12, s12, 0x8000
	s_addc_u32 s13, s13, 0
	v_pk_fma_f32 v[54:55], v[54:55], v[6:7], v[152:153] op_sel_hi:[1,0,1]
	v_pk_fma_f32 v[52:53], v[52:53], v[6:7], v[150:151] op_sel_hi:[1,0,1]
	v_pk_fma_f32 v[50:51], v[50:51], v[6:7], v[148:149] op_sel_hi:[1,0,1]
	v_pk_fma_f32 v[48:49], v[48:49], v[6:7], v[146:147] op_sel_hi:[1,0,1]
	v_pk_fma_f32 v[46:47], v[46:47], v[6:7], v[144:145] op_sel_hi:[1,0,1]
	v_pk_fma_f32 v[44:45], v[44:45], v[6:7], v[142:143] op_sel_hi:[1,0,1]
	v_pk_fma_f32 v[42:43], v[42:43], v[6:7], v[140:141] op_sel_hi:[1,0,1]
	v_pk_fma_f32 v[40:41], v[40:41], v[6:7], v[138:139] op_sel_hi:[1,0,1]
	v_cvt_pk_bf16_f32 v234, v52, v53
	v_cvt_pk_bf16_f32 v235, v54, v55
	v_cvt_pk_bf16_f32 v236, v48, v49
	v_cvt_pk_bf16_f32 v237, v50, v51
	v_cvt_pk_bf16_f32 v238, v44, v45
	v_cvt_pk_bf16_f32 v239, v46, v47
	v_cvt_pk_bf16_f32 v240, v40, v41
	v_cvt_pk_bf16_f32 v241, v42, v43
	s_mov_b64 vcc, s[6:7]
	v_cndmask_b32_dpp v52, v238, v234, vcc row_ror:8 row_mask:0xf bank_mask:0xf
	v_cndmask_b32_dpp v53, v239, v235, vcc row_ror:8 row_mask:0xf bank_mask:0xf
	v_cndmask_b32_dpp v54, v240, v236, vcc row_ror:8 row_mask:0xf bank_mask:0xf
	v_cndmask_b32_dpp v55, v241, v237, vcc row_ror:8 row_mask:0xf bank_mask:0xf
	s_not_b64 vcc, s[6:7]
	v_cndmask_b32_dpp v48, v234, v238, vcc row_ror:8 row_mask:0xf bank_mask:0xf
	v_cndmask_b32_dpp v49, v235, v239, vcc row_ror:8 row_mask:0xf bank_mask:0xf
	v_cndmask_b32_dpp v50, v236, v240, vcc row_ror:8 row_mask:0xf bank_mask:0xf
	v_cndmask_b32_dpp v51, v237, v241, vcc row_ror:8 row_mask:0xf bank_mask:0xf
	global_store_dwordx4 v246, v[52:55], s[12:13] nt
	global_store_dwordx4 v247, v[48:51], s[12:13] nt
	s_waitcnt vmcnt(4)
	v_mov_b32_e32 v6, v192
	s_add_u32 s12, s12, 0x8000
	s_addc_u32 s13, s13, 0
	v_pk_fma_f32 v[38:39], v[38:39], v[6:7], v[196:197] op_sel_hi:[1,0,1]
	v_pk_fma_f32 v[36:37], v[36:37], v[6:7], v[194:195] op_sel_hi:[1,0,1]
	v_pk_fma_f32 v[34:35], v[34:35], v[6:7], v[200:201] op_sel_hi:[1,0,1]
	v_pk_fma_f32 v[32:33], v[32:33], v[6:7], v[198:199] op_sel_hi:[1,0,1]
	v_pk_fma_f32 v[30:31], v[30:31], v[6:7], v[204:205] op_sel_hi:[1,0,1]
	v_pk_fma_f32 v[28:29], v[28:29], v[6:7], v[202:203] op_sel_hi:[1,0,1]
	v_pk_fma_f32 v[26:27], v[26:27], v[6:7], v[224:225] op_sel_hi:[1,0,1]
	v_pk_fma_f32 v[24:25], v[24:25], v[6:7], v[222:223] op_sel_hi:[1,0,1]
	v_cvt_pk_bf16_f32 v234, v36, v37
	v_cvt_pk_bf16_f32 v235, v38, v39
	v_cvt_pk_bf16_f32 v236, v32, v33
	v_cvt_pk_bf16_f32 v237, v34, v35
	v_cvt_pk_bf16_f32 v238, v28, v29
	v_cvt_pk_bf16_f32 v239, v30, v31
	v_cvt_pk_bf16_f32 v240, v24, v25
	v_cvt_pk_bf16_f32 v241, v26, v27
	s_mov_b64 vcc, s[6:7]
	v_cndmask_b32_dpp v36, v238, v234, vcc row_ror:8 row_mask:0xf bank_mask:0xf
	v_cndmask_b32_dpp v37, v239, v235, vcc row_ror:8 row_mask:0xf bank_mask:0xf
	v_cndmask_b32_dpp v38, v240, v236, vcc row_ror:8 row_mask:0xf bank_mask:0xf
	v_cndmask_b32_dpp v39, v241, v237, vcc row_ror:8 row_mask:0xf bank_mask:0xf
	s_not_b64 vcc, s[6:7]
	v_cndmask_b32_dpp v32, v234, v238, vcc row_ror:8 row_mask:0xf bank_mask:0xf
	v_cndmask_b32_dpp v33, v235, v239, vcc row_ror:8 row_mask:0xf bank_mask:0xf
	v_cndmask_b32_dpp v34, v236, v240, vcc row_ror:8 row_mask:0xf bank_mask:0xf
	v_cndmask_b32_dpp v35, v237, v241, vcc row_ror:8 row_mask:0xf bank_mask:0xf
	global_store_dwordx4 v246, v[36:39], s[12:13] nt
	global_store_dwordx4 v247, v[32:35], s[12:13] nt
	v_mov_b32_e32 v6, v193
	s_add_u32 s12, s12, 0x8000
	s_addc_u32 s13, s13, 0
	v_pk_fma_f32 v[22:23], v[22:23], v[6:7], v[196:197] op_sel_hi:[1,0,1]
	v_pk_fma_f32 v[20:21], v[20:21], v[6:7], v[194:195] op_sel_hi:[1,0,1]
	v_pk_fma_f32 v[18:19], v[18:19], v[6:7], v[200:201] op_sel_hi:[1,0,1]
	v_pk_fma_f32 v[16:17], v[16:17], v[6:7], v[198:199] op_sel_hi:[1,0,1]
	v_pk_fma_f32 v[14:15], v[14:15], v[6:7], v[204:205] op_sel_hi:[1,0,1]
	v_pk_fma_f32 v[12:13], v[12:13], v[6:7], v[202:203] op_sel_hi:[1,0,1]
	v_pk_fma_f32 v[10:11], v[10:11], v[6:7], v[224:225] op_sel_hi:[1,0,1]
	v_pk_fma_f32 v[8:9], v[8:9], v[6:7], v[222:223] op_sel_hi:[1,0,1]
	v_cvt_pk_bf16_f32 v234, v20, v21
	v_cvt_pk_bf16_f32 v235, v22, v23
	v_cvt_pk_bf16_f32 v236, v16, v17
	v_cvt_pk_bf16_f32 v237, v18, v19
	v_cvt_pk_bf16_f32 v238, v12, v13
	v_cvt_pk_bf16_f32 v239, v14, v15
	v_cvt_pk_bf16_f32 v240, v8, v9
	v_cvt_pk_bf16_f32 v241, v10, v11
	s_mov_b64 vcc, s[6:7]
	v_cndmask_b32_dpp v20, v238, v234, vcc row_ror:8 row_mask:0xf bank_mask:0xf
	v_cndmask_b32_dpp v21, v239, v235, vcc row_ror:8 row_mask:0xf bank_mask:0xf
	v_cndmask_b32_dpp v22, v240, v236, vcc row_ror:8 row_mask:0xf bank_mask:0xf
	v_cndmask_b32_dpp v23, v241, v237, vcc row_ror:8 row_mask:0xf bank_mask:0xf
	s_not_b64 vcc, s[6:7]
	v_cndmask_b32_dpp v16, v234, v238, vcc row_ror:8 row_mask:0xf bank_mask:0xf
	v_cndmask_b32_dpp v17, v235, v239, vcc row_ror:8 row_mask:0xf bank_mask:0xf
	v_cndmask_b32_dpp v18, v236, v240, vcc row_ror:8 row_mask:0xf bank_mask:0xf
	v_cndmask_b32_dpp v19, v237, v241, vcc row_ror:8 row_mask:0xf bank_mask:0xf
	global_store_dwordx4 v246, v[20:23], s[12:13] nt
	global_store_dwordx4 v247, v[16:19], s[12:13] nt
	s_mov_b32 s100, 1
	s_branch .LBB0_1422
.Lfn_k234:
	s_cmp_eq_u32 s35, 4
	s_cbranch_scc1 .Lfn_k4
	v_lshl_add_u32 v246, v207, 9, v2
	v_add_u32_e32 v247, 0x1000, v246
	s_cmp_eq_u32 s35, 2
	s_cselect_b32 s12, s52, s54
	s_cselect_b32 s13, s53, s55
	s_lshl_b32 s18, s18, 9
	s_add_u32 s12, s12, s18
	s_addc_u32 s13, s13, 0
	s_cmp_eq_u32 s35, 2
	s_cselect_b32 s18, s84, s65
	s_cselect_b32 s19, s85, s66
	s_lshl_b32 s2, s16, 2
	s_lshl_b32 s2, s2, 10
	s_add_u32 s84, s18, s2
	s_addc_u32 s85, s19, 0
	s_add_u32 s84, s84, 0x18000
	s_addc_u32 s85, s85, 0
	s_waitcnt vmcnt(4)
	v_mov_b32_e32 v6, v186
	v_pk_fma_f32 v[136:137], v[136:137], v[6:7], v[152:153] op_sel_hi:[1,0,1]
	v_pk_fma_f32 v[134:135], v[134:135], v[6:7], v[150:151] op_sel_hi:[1,0,1]
	v_pk_fma_f32 v[132:133], v[132:133], v[6:7], v[148:149] op_sel_hi:[1,0,1]
	v_pk_fma_f32 v[130:131], v[130:131], v[6:7], v[146:147] op_sel_hi:[1,0,1]
	v_pk_fma_f32 v[128:129], v[128:129], v[6:7], v[144:145] op_sel_hi:[1,0,1]
	v_pk_fma_f32 v[126:127], v[126:127], v[6:7], v[142:143] op_sel_hi:[1,0,1]
	v_pk_fma_f32 v[124:125], v[124:125], v[6:7], v[140:141] op_sel_hi:[1,0,1]
	v_pk_fma_f32 v[122:123], v[122:123], v[6:7], v[138:139] op_sel_hi:[1,0,1]
	s_add_u32 s18, s84, 0
	s_addc_u32 s19, s85, 0
	global_store_dwordx4 v227, v[134:137], s[18:19]
	global_store_dwordx4 v227, v[130:133], s[18:19] offset:16
	global_store_dwordx4 v227, v[126:129], s[18:19] offset:128
	global_store_dwordx4 v227, v[122:125], s[18:19] offset:144
	v_cvt_pk_bf16_f32 v234, v134, v135
	v_cvt_pk_bf16_f32 v235, v136, v137
	v_cvt_pk_bf16_f32 v236, v130, v131
	v_cvt_pk_bf16_f32 v237, v132, v133
	v_cvt_pk_bf16_f32 v238, v126, v127
	v_cvt_pk_bf16_f32 v239, v128, v129
	v_cvt_pk_bf16_f32 v240, v122, v123
	v_cvt_pk_bf16_f32 v241, v124, v125
	s_mov_b64 vcc, s[6:7]
	v_cndmask_b32_dpp v134, v238, v234, vcc row_ror:8 row_mask:0xf bank_mask:0xf
	v_cndmask_b32_dpp v135, v239, v235, vcc row_ror:8 row_mask:0xf bank_mask:0xf
	v_cndmask_b32_dpp v136, v240, v236, vcc row_ror:8 row_mask:0xf bank_mask:0xf
	v_cndmask_b32_dpp v137, v241, v237, vcc row_ror:8 row_mask:0xf bank_mask:0xf
	s_not_b64 vcc, s[6:7]
	v_cndmask_b32_dpp v130, v234, v238, vcc row_ror:8 row_mask:0xf bank_mask:0xf
	v_cndmask_b32_dpp v131, v235, v239, vcc row_ror:8 row_mask:0xf bank_mask:0xf
	v_cndmask_b32_dpp v132, v236, v240, vcc row_ror:8 row_mask:0xf bank_mask:0xf
	v_cndmask_b32_dpp v133, v237, v241, vcc row_ror:8 row_mask:0xf bank_mask:0xf
	global_store_dwordx4 v246, v[134:137], s[12:13] nt
	global_store_dwordx4 v247, v[130:133], s[12:13] nt
	v_mov_b32_e32 v6, v187
	s_add_u32 s12, s12, 0x2000
	s_addc_u32 s13, s13, 0
	v_pk_fma_f32 v[120:121], v[120:121], v[6:7], v[152:153] op_sel_hi:[1,0,1]
	v_pk_fma_f32 v[118:119], v[118:119], v[6:7], v[150:151] op_sel_hi:[1,0,1]
	v_pk_fma_f32 v[116:117], v[116:117], v[6:7], v[148:149] op_sel_hi:[1,0,1]
	v_pk_fma_f32 v[114:115], v[114:115], v[6:7], v[146:147] op_sel_hi:[1,0,1]
	v_pk_fma_f32 v[112:113], v[112:113], v[6:7], v[144:145] op_sel_hi:[1,0,1]
	v_pk_fma_f32 v[110:111], v[110:111], v[6:7], v[142:143] op_sel_hi:[1,0,1]
	v_pk_fma_f32 v[108:109], v[108:109], v[6:7], v[140:141] op_sel_hi:[1,0,1]
	v_pk_fma_f32 v[106:107], v[106:107], v[6:7], v[138:139] op_sel_hi:[1,0,1]
	s_add_u32 s18, s84, 0x4000
	s_addc_u32 s19, s85, 0
	global_store_dwordx4 v227, v[118:121], s[18:19]
	global_store_dwordx4 v227, v[114:117], s[18:19] offset:16
	global_store_dwordx4 v227, v[110:113], s[18:19] offset:128
	global_store_dwordx4 v227, v[106:109], s[18:19] offset:144
	v_cvt_pk_bf16_f32 v234, v118, v119
	v_cvt_pk_bf16_f32 v235, v120, v121
	v_cvt_pk_bf16_f32 v236, v114, v115
	v_cvt_pk_bf16_f32 v237, v116, v117
	v_cvt_pk_bf16_f32 v238, v110, v111
	v_cvt_pk_bf16_f32 v239, v112, v113
	v_cvt_pk_bf16_f32 v240, v106, v107
	v_cvt_pk_bf16_f32 v241, v108, v109
	s_mov_b64 vcc, s[6:7]
	v_cndmask_b32_dpp v118, v238, v234, vcc row_ror:8 row_mask:0xf bank_mask:0xf
	v_cndmask_b32_dpp v119, v239, v235, vcc row_ror:8 row_mask:0xf bank_mask:0xf
	v_cndmask_b32_dpp v120, v240, v236, vcc row_ror:8 row_mask:0xf bank_mask:0xf
	v_cndmask_b32_dpp v121, v241, v237, vcc row_ror:8 row_mask:0xf bank_mask:0xf
	s_not_b64 vcc, s[6:7]
	v_cndmask_b32_dpp v114, v234, v238, vcc row_ror:8 row_mask:0xf bank_mask:0xf
	v_cndmask_b32_dpp v115, v235, v239, vcc row_ror:8 row_mask:0xf bank_mask:0xf
	v_cndmask_b32_dpp v116, v236, v240, vcc row_ror:8 row_mask:0xf bank_mask:0xf
	v_cndmask_b32_dpp v117, v237, v241, vcc row_ror:8 row_mask:0xf bank_mask:0xf
	global_store_dwordx4 v246, v[118:121], s[12:13] nt
	global_store_dwordx4 v247, v[114:117], s[12:13] nt
	s_add_u32 s10, s10, 0x9000
	s_addc_u32 s11, s11, 0
	global_load_dwordx4 v[150:153], v226, s[10:11]
	global_load_dwordx4 v[146:149], v226, s[10:11] offset:16
	global_load_dwordx4 v[142:145], v226, s[10:11] offset:128
	global_load_dwordx4 v[138:141], v226, s[10:11] offset:144
	s_waitcnt vmcnt(16)
	v_mov_b32_e32 v6, v188
	s_add_u32 s12, s12, 0x2000
	s_addc_u32 s13, s13, 0
	v_pk_fma_f32 v[104:105], v[104:105], v[6:7], v[196:197] op_sel_hi:[1,0,1]
	v_pk_fma_f32 v[102:103], v[102:103], v[6:7], v[194:195] op_sel_hi:[1,0,1]
	v_pk_fma_f32 v[100:101], v[100:101], v[6:7], v[200:201] op_sel_hi:[1,0,1]
	v_pk_fma_f32 v[98:99], v[98:99], v[6:7], v[198:199] op_sel_hi:[1,0,1]
	v_pk_fma_f32 v[94:95], v[94:95], v[6:7], v[204:205] op_sel_hi:[1,0,1]
	v_pk_fma_f32 v[92:93], v[92:93], v[6:7], v[202:203] op_sel_hi:[1,0,1]
	v_pk_fma_f32 v[90:91], v[90:91], v[6:7], v[224:225] op_sel_hi:[1,0,1]
	v_pk_fma_f32 v[88:89], v[88:89], v[6:7], v[222:223] op_sel_hi:[1,0,1]
	s_add_u32 s18, s84, 0x20000
	s_addc_u32 s19, s85, 0
	global_store_dwordx4 v227, v[102:105], s[18:19]
	global_store_dwordx4 v227, v[98:101], s[18:19] offset:16
	global_store_dwordx4 v227, v[92:95], s[18:19] offset:128
	global_store_dwordx4 v227, v[88:91], s[18:19] offset:144
	v_cvt_pk_bf16_f32 v234, v102, v103
	v_cvt_pk_bf16_f32 v235, v104, v105
	v_cvt_pk_bf16_f32 v236, v98, v99
	v_cvt_pk_bf16_f32 v237, v100, v101
	v_cvt_pk_bf16_f32 v238, v92, v93
	v_cvt_pk_bf16_f32 v239, v94, v95
	v_cvt_pk_bf16_f32 v240, v88, v89
	v_cvt_pk_bf16_f32 v241, v90, v91
	s_mov_b64 vcc, s[6:7]
	v_cndmask_b32_dpp v102, v238, v234, vcc row_ror:8 row_mask:0xf bank_mask:0xf
	v_cndmask_b32_dpp v103, v239, v235, vcc row_ror:8 row_mask:0xf bank_mask:0xf
	v_cndmask_b32_dpp v104, v240, v236, vcc row_ror:8 row_mask:0xf bank_mask:0xf
	v_cndmask_b32_dpp v105, v241, v237, vcc row_ror:8 row_mask:0xf bank_mask:0xf
	s_not_b64 vcc, s[6:7]
	v_cndmask_b32_dpp v98, v234, v238, vcc row_ror:8 row_mask:0xf bank_mask:0xf
	v_cndmask_b32_dpp v99, v235, v239, vcc row_ror:8 row_mask:0xf bank_mask:0xf
	v_cndmask_b32_dpp v100, v236, v240, vcc row_ror:8 row_mask:0xf bank_mask:0xf
	v_cndmask_b32_dpp v101, v237, v241, vcc row_ror:8 row_mask:0xf bank_mask:0xf
	global_store_dwordx4 v246, v[102:105], s[12:13] nt
	global_store_dwordx4 v247, v[98:101], s[12:13] nt
	v_mov_b32_e32 v6, v189
	s_add_u32 s12, s12, 0x2000
	s_addc_u32 s13, s13, 0
	v_pk_fma_f32 v[86:87], v[86:87], v[6:7], v[196:197] op_sel_hi:[1,0,1]
	v_pk_fma_f32 v[84:85], v[84:85], v[6:7], v[194:195] op_sel_hi:[1,0,1]
	v_pk_fma_f32 v[82:83], v[82:83], v[6:7], v[200:201] op_sel_hi:[1,0,1]
	v_pk_fma_f32 v[80:81], v[80:81], v[6:7], v[198:199] op_sel_hi:[1,0,1]
	v_pk_fma_f32 v[78:79], v[78:79], v[6:7], v[204:205] op_sel_hi:[1,0,1]
	v_pk_fma_f32 v[76:77], v[76:77], v[6:7], v[202:203] op_sel_hi:[1,0,1]
	v_pk_fma_f32 v[74:75], v[74:75], v[6:7], v[224:225] op_sel_hi:[1,0,1]
	v_pk_fma_f32 v[72:73], v[72:73], v[6:7], v[222:223] op_sel_hi:[1,0,1]
	s_add_u32 s18, s84, 0x24000
	s_addc_u32 s19, s85, 0
	global_store_dwordx4 v227, v[84:87], s[18:19]
	global_store_dwordx4 v227, v[80:83], s[18:19] offset:16
	global_store_dwordx4 v227, v[76:79], s[18:19] offset:128
	global_store_dwordx4 v227, v[72:75], s[18:19] offset:144
	v_cvt_pk_bf16_f32 v234, v84, v85
	v_cvt_pk_bf16_f32 v235, v86, v87
	v_cvt_pk_bf16_f32 v236, v80, v81
	v_cvt_pk_bf16_f32 v237, v82, v83
	v_cvt_pk_bf16_f32 v238, v76, v77
	v_cvt_pk_bf16_f32 v239, v78, v79
	v_cvt_pk_bf16_f32 v240, v72, v73
	v_cvt_pk_bf16_f32 v241, v74, v75
	s_mov_b64 vcc, s[6:7]
	v_cndmask_b32_dpp v84, v238, v234, vcc row_ror:8 row_mask:0xf bank_mask:0xf
	v_cndmask_b32_dpp v85, v239, v235, vcc row_ror:8 row_mask:0xf bank_mask:0xf
	v_cndmask_b32_dpp v86, v240, v236, vcc row_ror:8 row_mask:0xf bank_mask:0xf
	v_cndmask_b32_dpp v87, v241, v237, vcc row_ror:8 row_mask:0xf bank_mask:0xf
	s_not_b64 vcc, s[6:7]
	v_cndmask_b32_dpp v80, v234, v238, vcc row_ror:8 row_mask:0xf bank_mask:0xf
	v_cndmask_b32_dpp v81, v235, v239, vcc row_ror:8 row_mask:0xf bank_mask:0xf
	v_cndmask_b32_dpp v82, v236, v240, vcc row_ror:8 row_mask:0xf bank_mask:0xf
	v_cndmask_b32_dpp v83, v237, v241, vcc row_ror:8 row_mask:0xf bank_mask:0xf
	global_store_dwordx4 v246, v[84:87], s[12:13] nt
	global_store_dwordx4 v247, v[80:83], s[12:13] nt
	s_add_u32 s10, s10, 0x3000
	s_addc_u32 s11, s11, 0
	global_load_dwordx4 v[194:197], v226, s[10:11]
	global_load_dwordx4 v[198:201], v226, s[10:11] offset:16
	global_load_dwordx4 v[202:205], v226, s[10:11] offset:128
	global_load_dwordx4 v[222:225], v226, s[10:11] offset:144
	s_waitcnt vmcnt(16)
	v_mov_b32_e32 v6, v190
	s_add_u32 s12, s12, 0xa000
	s_addc_u32 s13, s13, 0
	v_pk_fma_f32 v[70:71], v[70:71], v[6:7], v[152:153] op_sel_hi:[1,0,1]
	v_pk_fma_f32 v[68:69], v[68:69], v[6:7], v[150:151] op_sel_hi:[1,0,1]
	v_pk_fma_f32 v[66:67], v[66:67], v[6:7], v[148:149] op_sel_hi:[1,0,1]
	v_pk_fma_f32 v[64:65], v[64:65], v[6:7], v[146:147] op_sel_hi:[1,0,1]
	v_pk_fma_f32 v[62:63], v[62:63], v[6:7], v[144:145] op_sel_hi:[1,0,1]
	v_pk_fma_f32 v[60:61], v[60:61], v[6:7], v[142:143] op_sel_hi:[1,0,1]
	v_pk_fma_f32 v[58:59], v[58:59], v[6:7], v[140:141] op_sel_hi:[1,0,1]
	v_pk_fma_f32 v[56:57], v[56:57], v[6:7], v[138:139] op_sel_hi:[1,0,1]
	s_add_u32 s18, s84, 0x80000
	s_addc_u32 s19, s85, 0
	global_store_dwordx4 v227, v[68:71], s[18:19]
	global_store_dwordx4 v227, v[64:67], s[18:19] offset:16
	global_store_dwordx4 v227, v[60:63], s[18:19] offset:128
	global_store_dwordx4 v227, v[56:59], s[18:19] offset:144
	v_cvt_pk_bf16_f32 v234, v68, v69
	v_cvt_pk_bf16_f32 v235, v70, v71
	v_cvt_pk_bf16_f32 v236, v64, v65
	v_cvt_pk_bf16_f32 v237, v66, v67
	v_cvt_pk_bf16_f32 v238, v60, v61
	v_cvt_pk_bf16_f32 v239, v62, v63
	v_cvt_pk_bf16_f32 v240, v56, v57
	v_cvt_pk_bf16_f32 v241, v58, v59
	s_mov_b64 vcc, s[6:7]
	v_cndmask_b32_dpp v68, v238, v234, vcc row_ror:8 row_mask:0xf bank_mask:0xf
	v_cndmask_b32_dpp v69, v239, v235, vcc row_ror:8 row_mask:0xf bank_mask:0xf
	v_cndmask_b32_dpp v70, v240, v236, vcc row_ror:8 row_mask:0xf bank_mask:0xf
	v_cndmask_b32_dpp v71, v241, v237, vcc row_ror:8 row_mask:0xf bank_mask:0xf
	s_not_b64 vcc, s[6:7]
	v_cndmask_b32_dpp v64, v234, v238, vcc row_ror:8 row_mask:0xf bank_mask:0xf
	v_cndmask_b32_dpp v65, v235, v239, vcc row_ror:8 row_mask:0xf bank_mask:0xf
	v_cndmask_b32_dpp v66, v236, v240, vcc row_ror:8 row_mask:0xf bank_mask:0xf
	v_cndmask_b32_dpp v67, v237, v241, vcc row_ror:8 row_mask:0xf bank_mask:0xf
	global_store_dwordx4 v246, v[68:71], s[12:13] nt
	global_store_dwordx4 v247, v[64:67], s[12:13] nt
	v_mov_b32_e32 v6, v191
	s_add_u32 s12, s12, 0x2000
	s_addc_u32 s13, s13, 0
	v_pk_fma_f32 v[54:55], v[54:55], v[6:7], v[152:153] op_sel_hi:[1,0,1]
	v_pk_fma_f32 v[52:53], v[52:53], v[6:7], v[150:151] op_sel_hi:[1,0,1]
	v_pk_fma_f32 v[50:51], v[50:51], v[6:7], v[148:149] op_sel_hi:[1,0,1]
	v_pk_fma_f32 v[48:49], v[48:49], v[6:7], v[146:147] op_sel_hi:[1,0,1]
	v_pk_fma_f32 v[46:47], v[46:47], v[6:7], v[144:145] op_sel_hi:[1,0,1]
	v_pk_fma_f32 v[44:45], v[44:45], v[6:7], v[142:143] op_sel_hi:[1,0,1]
	v_pk_fma_f32 v[42:43], v[42:43], v[6:7], v[140:141] op_sel_hi:[1,0,1]
	v_pk_fma_f32 v[40:41], v[40:41], v[6:7], v[138:139] op_sel_hi:[1,0,1]
	s_add_u32 s18, s84, 0x84000
	s_addc_u32 s19, s85, 0
	global_store_dwordx4 v227, v[52:55], s[18:19]
	global_store_dwordx4 v227, v[48:51], s[18:19] offset:16
	global_store_dwordx4 v227, v[44:47], s[18:19] offset:128
	global_store_dwordx4 v227, v[40:43], s[18:19] offset:144
	v_cvt_pk_bf16_f32 v234, v52, v53
	v_cvt_pk_bf16_f32 v235, v54, v55
	v_cvt_pk_bf16_f32 v236, v48, v49
	v_cvt_pk_bf16_f32 v237, v50, v51
	v_cvt_pk_bf16_f32 v238, v44, v45
	v_cvt_pk_bf16_f32 v239, v46, v47
	v_cvt_pk_bf16_f32 v240, v40, v41
	v_cvt_pk_bf16_f32 v241, v42, v43
	s_mov_b64 vcc, s[6:7]
	v_cndmask_b32_dpp v52, v238, v234, vcc row_ror:8 row_mask:0xf bank_mask:0xf
	v_cndmask_b32_dpp v53, v239, v235, vcc row_ror:8 row_mask:0xf bank_mask:0xf
	v_cndmask_b32_dpp v54, v240, v236, vcc row_ror:8 row_mask:0xf bank_mask:0xf
	v_cndmask_b32_dpp v55, v241, v237, vcc row_ror:8 row_mask:0xf bank_mask:0xf
	s_not_b64 vcc, s[6:7]
	v_cndmask_b32_dpp v48, v234, v238, vcc row_ror:8 row_mask:0xf bank_mask:0xf
	v_cndmask_b32_dpp v49, v235, v239, vcc row_ror:8 row_mask:0xf bank_mask:0xf
	v_cndmask_b32_dpp v50, v236, v240, vcc row_ror:8 row_mask:0xf bank_mask:0xf
	v_cndmask_b32_dpp v51, v237, v241, vcc row_ror:8 row_mask:0xf bank_mask:0xf
	global_store_dwordx4 v246, v[52:55], s[12:13] nt
	global_store_dwordx4 v247, v[48:51], s[12:13] nt
	s_waitcnt vmcnt(12)
	v_mov_b32_e32 v6, v192
	s_add_u32 s12, s12, 0x2000
	s_addc_u32 s13, s13, 0
	v_pk_fma_f32 v[38:39], v[38:39], v[6:7], v[196:197] op_sel_hi:[1,0,1]
	v_pk_fma_f32 v[36:37], v[36:37], v[6:7], v[194:195] op_sel_hi:[1,0,1]
	v_pk_fma_f32 v[34:35], v[34:35], v[6:7], v[200:201] op_sel_hi:[1,0,1]
	v_pk_fma_f32 v[32:33], v[32:33], v[6:7], v[198:199] op_sel_hi:[1,0,1]
	v_pk_fma_f32 v[30:31], v[30:31], v[6:7], v[204:205] op_sel_hi:[1,0,1]
	v_pk_fma_f32 v[28:29], v[28:29], v[6:7], v[202:203] op_sel_hi:[1,0,1]
	v_pk_fma_f32 v[26:27], v[26:27], v[6:7], v[224:225] op_sel_hi:[1,0,1]
	v_pk_fma_f32 v[24:25], v[24:25], v[6:7], v[222:223] op_sel_hi:[1,0,1]
	s_add_u32 s18, s84, 0xa0000
	s_addc_u32 s19, s85, 0
	global_store_dwordx4 v227, v[36:39], s[18:19]
	global_store_dwordx4 v227, v[32:35], s[18:19] offset:16
	global_store_dwordx4 v227, v[28:31], s[18:19] offset:128
	global_store_dwordx4 v227, v[24:27], s[18:19] offset:144
	v_cvt_pk_bf16_f32 v234, v36, v37
	v_cvt_pk_bf16_f32 v235, v38, v39
	v_cvt_pk_bf16_f32 v236, v32, v33
	v_cvt_pk_bf16_f32 v237, v34, v35
	v_cvt_pk_bf16_f32 v238, v28, v29
	v_cvt_pk_bf16_f32 v239, v30, v31
	v_cvt_pk_bf16_f32 v240, v24, v25
	v_cvt_pk_bf16_f32 v241, v26, v27
	s_mov_b64 vcc, s[6:7]
	v_cndmask_b32_dpp v36, v238, v234, vcc row_ror:8 row_mask:0xf bank_mask:0xf
	v_cndmask_b32_dpp v37, v239, v235, vcc row_ror:8 row_mask:0xf bank_mask:0xf
	v_cndmask_b32_dpp v38, v240, v236, vcc row_ror:8 row_mask:0xf bank_mask:0xf
	v_cndmask_b32_dpp v39, v241, v237, vcc row_ror:8 row_mask:0xf bank_mask:0xf
	s_not_b64 vcc, s[6:7]
	v_cndmask_b32_dpp v32, v234, v238, vcc row_ror:8 row_mask:0xf bank_mask:0xf
	v_cndmask_b32_dpp v33, v235, v239, vcc row_ror:8 row_mask:0xf bank_mask:0xf
	v_cndmask_b32_dpp v34, v236, v240, vcc row_ror:8 row_mask:0xf bank_mask:0xf
	v_cndmask_b32_dpp v35, v237, v241, vcc row_ror:8 row_mask:0xf bank_mask:0xf
	global_store_dwordx4 v246, v[36:39], s[12:13] nt
	global_store_dwordx4 v247, v[32:35], s[12:13] nt
	v_mov_b32_e32 v6, v193
	s_add_u32 s12, s12, 0x2000
	s_addc_u32 s13, s13, 0
	v_pk_fma_f32 v[22:23], v[22:23], v[6:7], v[196:197] op_sel_hi:[1,0,1]
	v_pk_fma_f32 v[20:21], v[20:21], v[6:7], v[194:195] op_sel_hi:[1,0,1]
	v_pk_fma_f32 v[18:19], v[18:19], v[6:7], v[200:201] op_sel_hi:[1,0,1]
	v_pk_fma_f32 v[16:17], v[16:17], v[6:7], v[198:199] op_sel_hi:[1,0,1]
	v_pk_fma_f32 v[14:15], v[14:15], v[6:7], v[204:205] op_sel_hi:[1,0,1]
	v_pk_fma_f32 v[12:13], v[12:13], v[6:7], v[202:203] op_sel_hi:[1,0,1]
	v_pk_fma_f32 v[10:11], v[10:11], v[6:7], v[224:225] op_sel_hi:[1,0,1]
	v_pk_fma_f32 v[8:9], v[8:9], v[6:7], v[222:223] op_sel_hi:[1,0,1]
	s_add_u32 s18, s84, 0xa4000
	s_addc_u32 s19, s85, 0
	global_store_dwordx4 v227, v[20:23], s[18:19]
	global_store_dwordx4 v227, v[16:19], s[18:19] offset:16
	global_store_dwordx4 v227, v[12:15], s[18:19] offset:128
	global_store_dwordx4 v227, v[8:11], s[18:19] offset:144
	v_cvt_pk_bf16_f32 v234, v20, v21
	v_cvt_pk_bf16_f32 v235, v22, v23
	v_cvt_pk_bf16_f32 v236, v16, v17
	v_cvt_pk_bf16_f32 v237, v18, v19
	v_cvt_pk_bf16_f32 v238, v12, v13
	v_cvt_pk_bf16_f32 v239, v14, v15
	v_cvt_pk_bf16_f32 v240, v8, v9
	v_cvt_pk_bf16_f32 v241, v10, v11
	s_mov_b64 vcc, s[6:7]
	v_cndmask_b32_dpp v20, v238, v234, vcc row_ror:8 row_mask:0xf bank_mask:0xf
	v_cndmask_b32_dpp v21, v239, v235, vcc row_ror:8 row_mask:0xf bank_mask:0xf
	v_cndmask_b32_dpp v22, v240, v236, vcc row_ror:8 row_mask:0xf bank_mask:0xf
	v_cndmask_b32_dpp v23, v241, v237, vcc row_ror:8 row_mask:0xf bank_mask:0xf
	s_not_b64 vcc, s[6:7]
	v_cndmask_b32_dpp v16, v234, v238, vcc row_ror:8 row_mask:0xf bank_mask:0xf
	v_cndmask_b32_dpp v17, v235, v239, vcc row_ror:8 row_mask:0xf bank_mask:0xf
	v_cndmask_b32_dpp v18, v236, v240, vcc row_ror:8 row_mask:0xf bank_mask:0xf
	v_cndmask_b32_dpp v19, v237, v241, vcc row_ror:8 row_mask:0xf bank_mask:0xf
	global_store_dwordx4 v246, v[20:23], s[12:13] nt
	global_store_dwordx4 v247, v[16:19], s[12:13] nt
	s_mov_b32 s100, 1
	s_branch .LBB0_1422

.Lfi_entry:
	v_readlane_b32 s10, v252, 42
	v_add_u32_e32 v1, s71, v208
	s_add_i32 s10, s10, s71
	v_add_u32_e32 v0, s10, v209
	ds_read_b128 v[186:189], v1
	ds_read_b128 v[190:193], v1 offset:256
	ds_read_b128 v[194:197], v1 offset:512
	ds_read_b128 v[198:201], v1 offset:768
	ds_read_b128 v[202:205], v1 offset:2048
	ds_read_b128 v[222:225], v1 offset:2304
	ds_read_b128 v[226:229], v1 offset:2560
	ds_read_b128 v[230:233], v1 offset:2816
	ds_read_b128 v[150:153], v0 offset:4096
	ds_read_b128 v[146:149], v0 offset:4112
	ds_read_b128 v[142:145], v0 offset:4224
	ds_read_b128 v[138:141], v0 offset:4240
	s_cmp_eq_u32 s35, 0
	s_cselect_b32 s12, s4, s50
	s_cselect_b32 s13, s5, s51
	s_lshl_b32 s14, s36, 8
	s_add_i32 s14, s14, s20
	s_lshl_b32 s14, s14, 11
	s_add_u32 s12, s12, s14
	s_addc_u32 s13, s13, 0
	v_add_u32_e32 v2, v182, v162
	v_lshlrev_b32_e32 v2, 1, v2
	v_lshl_add_u32 v246, v207, 11, v2
	v_add_u32_e32 v247, 0x4000, v246
	s_mov_b32 s16, s42
	s_mov_b32 s17, s42
	v_readlane_b32 s18, v252, 28
	v_readlane_b32 s19, v252, 29
	s_waitcnt lgkmcnt(0)
	s_cmp_eq_u32 s35, 0
	s_cbranch_scc0 .Lfi_kind1
	s_cmp_eq_u32 s42, 1.0
	s_cbranch_scc1 .Lfi_plain
	v_add_f32_e32 v4, v186, v187
	v_add_f32_e32 v5, v188, v189
	v_add_f32_e32 v4, v4, v5
	v_fmamk_f32 v4, v4, 0x3a800000, v212
	v_rsq_f32_e32 v6, v4
	s_nop 1
	v_pk_fma_f32 v[136:137], v[136:137], v[6:7], v[152:153] op_sel_hi:[1,0,1]
	v_pk_fma_f32 v[134:135], v[134:135], v[6:7], v[150:151] op_sel_hi:[1,0,1]
	v_pk_fma_f32 v[132:133], v[132:133], v[6:7], v[148:149] op_sel_hi:[1,0,1]
	v_pk_fma_f32 v[130:131], v[130:131], v[6:7], v[146:147] op_sel_hi:[1,0,1]
	v_pk_fma_f32 v[128:129], v[128:129], v[6:7], v[144:145] op_sel_hi:[1,0,1]
	v_pk_fma_f32 v[126:127], v[126:127], v[6:7], v[142:143] op_sel_hi:[1,0,1]
	v_pk_fma_f32 v[124:125], v[124:125], v[6:7], v[140:141] op_sel_hi:[1,0,1]
	v_pk_fma_f32 v[122:123], v[122:123], v[6:7], v[138:139] op_sel_hi:[1,0,1]
	v_pk_mul_f32 v[136:137], s[16:17], v[136:137]
	v_pk_mul_f32 v[134:135], s[16:17], v[134:135]
	v_pk_mul_f32 v[132:133], s[16:17], v[132:133]
	v_pk_mul_f32 v[130:131], s[16:17], v[130:131]
	v_pk_mul_f32 v[128:129], s[16:17], v[128:129]
	v_pk_mul_f32 v[126:127], s[16:17], v[126:127]
	v_pk_mul_f32 v[124:125], s[16:17], v[124:125]
	v_pk_mul_f32 v[122:123], s[16:17], v[122:123]
	v_cvt_pk_bf16_f32 v234, v134, v135
	v_cvt_pk_bf16_f32 v235, v136, v137
	v_cvt_pk_bf16_f32 v236, v130, v131
	v_cvt_pk_bf16_f32 v237, v132, v133
	v_cvt_pk_bf16_f32 v238, v126, v127
	v_cvt_pk_bf16_f32 v239, v128, v129
	v_cvt_pk_bf16_f32 v240, v122, v123
	v_cvt_pk_bf16_f32 v241, v124, v125
	s_mov_b64 vcc, s[6:7]
	v_cndmask_b32_dpp v134, v238, v234, vcc row_ror:8 row_mask:0xf bank_mask:0xf
	v_cndmask_b32_dpp v135, v239, v235, vcc row_ror:8 row_mask:0xf bank_mask:0xf
	v_cndmask_b32_dpp v136, v240, v236, vcc row_ror:8 row_mask:0xf bank_mask:0xf
	v_cndmask_b32_dpp v137, v241, v237, vcc row_ror:8 row_mask:0xf bank_mask:0xf
	s_not_b64 vcc, s[6:7]
	v_cndmask_b32_dpp v130, v234, v238, vcc row_ror:8 row_mask:0xf bank_mask:0xf
	v_cndmask_b32_dpp v131, v235, v239, vcc row_ror:8 row_mask:0xf bank_mask:0xf
	v_cndmask_b32_dpp v132, v236, v240, vcc row_ror:8 row_mask:0xf bank_mask:0xf
	v_cndmask_b32_dpp v133, v237, v241, vcc row_ror:8 row_mask:0xf bank_mask:0xf
	global_store_dwordx4 v246, v[134:137], s[12:13] nt
	global_store_dwordx4 v247, v[130:133], s[12:13] nt
	v_add_f32_e32 v4, v190, v191
	v_add_f32_e32 v5, v192, v193
	v_add_f32_e32 v4, v4, v5
	v_fmamk_f32 v4, v4, 0x3a800000, v212
	v_rsq_f32_e32 v6, v4
	s_add_u32 s12, s12, 0x8000
	s_addc_u32 s13, s13, 0
	v_pk_fma_f32 v[120:121], v[120:121], v[6:7], v[152:153] op_sel_hi:[1,0,1]
	v_pk_fma_f32 v[118:119], v[118:119], v[6:7], v[150:151] op_sel_hi:[1,0,1]
	v_pk_fma_f32 v[116:117], v[116:117], v[6:7], v[148:149] op_sel_hi:[1,0,1]
	v_pk_fma_f32 v[114:115], v[114:115], v[6:7], v[146:147] op_sel_hi:[1,0,1]
	v_pk_fma_f32 v[112:113], v[112:113], v[6:7], v[144:145] op_sel_hi:[1,0,1]
	v_pk_fma_f32 v[110:111], v[110:111], v[6:7], v[142:143] op_sel_hi:[1,0,1]
	v_pk_fma_f32 v[108:109], v[108:109], v[6:7], v[140:141] op_sel_hi:[1,0,1]
	v_pk_fma_f32 v[106:107], v[106:107], v[6:7], v[138:139] op_sel_hi:[1,0,1]
	v_pk_mul_f32 v[120:121], s[16:17], v[120:121]
	v_pk_mul_f32 v[118:119], s[16:17], v[118:119]
	v_pk_mul_f32 v[116:117], s[16:17], v[116:117]
	v_pk_mul_f32 v[114:115], s[16:17], v[114:115]
	v_pk_mul_f32 v[112:113], s[16:17], v[112:113]
	v_pk_mul_f32 v[110:111], s[16:17], v[110:111]
	v_pk_mul_f32 v[108:109], s[16:17], v[108:109]
	v_pk_mul_f32 v[106:107], s[16:17], v[106:107]
	v_cvt_pk_bf16_f32 v234, v118, v119
	v_cvt_pk_bf16_f32 v235, v120, v121
	v_cvt_pk_bf16_f32 v236, v114, v115
	v_cvt_pk_bf16_f32 v237, v116, v117
	v_cvt_pk_bf16_f32 v238, v110, v111
	v_cvt_pk_bf16_f32 v239, v112, v113
	v_cvt_pk_bf16_f32 v240, v106, v107
	v_cvt_pk_bf16_f32 v241, v108, v109
	s_mov_b64 vcc, s[6:7]
	v_cndmask_b32_dpp v118, v238, v234, vcc row_ror:8 row_mask:0xf bank_mask:0xf
	v_cndmask_b32_dpp v119, v239, v235, vcc row_ror:8 row_mask:0xf bank_mask:0xf
	v_cndmask_b32_dpp v120, v240, v236, vcc row_ror:8 row_mask:0xf bank_mask:0xf
	v_cndmask_b32_dpp v121, v241, v237, vcc row_ror:8 row_mask:0xf bank_mask:0xf
	s_not_b64 vcc, s[6:7]
	v_cndmask_b32_dpp v114, v234, v238, vcc row_ror:8 row_mask:0xf bank_mask:0xf
	v_cndmask_b32_dpp v115, v235, v239, vcc row_ror:8 row_mask:0xf bank_mask:0xf
	v_cndmask_b32_dpp v116, v236, v240, vcc row_ror:8 row_mask:0xf bank_mask:0xf
	v_cndmask_b32_dpp v117, v237, v241, vcc row_ror:8 row_mask:0xf bank_mask:0xf
	global_store_dwordx4 v246, v[118:121], s[12:13] nt
	global_store_dwordx4 v247, v[114:117], s[12:13] nt
	v_add_f32_e32 v4, v194, v195
	v_add_f32_e32 v5, v196, v197
	v_add_f32_e32 v4, v4, v5
	v_fmamk_f32 v4, v4, 0x3a800000, v212
	v_rsq_f32_e32 v6, v4
	s_add_u32 s12, s12, 0x8000
	s_addc_u32 s13, s13, 0
	v_pk_fma_f32 v[104:105], v[104:105], v[6:7], v[152:153] op_sel_hi:[1,0,1]
	v_pk_fma_f32 v[102:103], v[102:103], v[6:7], v[150:151] op_sel_hi:[1,0,1]
	v_pk_fma_f32 v[100:101], v[100:101], v[6:7], v[148:149] op_sel_hi:[1,0,1]
	v_pk_fma_f32 v[98:99], v[98:99], v[6:7], v[146:147] op_sel_hi:[1,0,1]
	v_pk_fma_f32 v[94:95], v[94:95], v[6:7], v[144:145] op_sel_hi:[1,0,1]
	v_pk_fma_f32 v[92:93], v[92:93], v[6:7], v[142:143] op_sel_hi:[1,0,1]
	v_pk_fma_f32 v[90:91], v[90:91], v[6:7], v[140:141] op_sel_hi:[1,0,1]
	v_pk_fma_f32 v[88:89], v[88:89], v[6:7], v[138:139] op_sel_hi:[1,0,1]
	v_pk_mul_f32 v[104:105], s[16:17], v[104:105]
	v_pk_mul_f32 v[102:103], s[16:17], v[102:103]
	v_pk_mul_f32 v[100:101], s[16:17], v[100:101]
	v_pk_mul_f32 v[98:99], s[16:17], v[98:99]
	v_pk_mul_f32 v[94:95], s[16:17], v[94:95]
	v_pk_mul_f32 v[92:93], s[16:17], v[92:93]
	v_pk_mul_f32 v[90:91], s[16:17], v[90:91]
	v_pk_mul_f32 v[88:89], s[16:17], v[88:89]
	v_cvt_pk_bf16_f32 v234, v102, v103
	v_cvt_pk_bf16_f32 v235, v104, v105
	v_cvt_pk_bf16_f32 v236, v98, v99
	v_cvt_pk_bf16_f32 v237, v100, v101
	v_cvt_pk_bf16_f32 v238, v92, v93
	v_cvt_pk_bf16_f32 v239, v94, v95
	v_cvt_pk_bf16_f32 v240, v88, v89
	v_cvt_pk_bf16_f32 v241, v90, v91
	s_mov_b64 vcc, s[6:7]
	v_cndmask_b32_dpp v102, v238, v234, vcc row_ror:8 row_mask:0xf bank_mask:0xf
	v_cndmask_b32_dpp v103, v239, v235, vcc row_ror:8 row_mask:0xf bank_mask:0xf
	v_cndmask_b32_dpp v104, v240, v236, vcc row_ror:8 row_mask:0xf bank_mask:0xf
	v_cndmask_b32_dpp v105, v241, v237, vcc row_ror:8 row_mask:0xf bank_mask:0xf
	s_not_b64 vcc, s[6:7]
	v_cndmask_b32_dpp v98, v234, v238, vcc row_ror:8 row_mask:0xf bank_mask:0xf
	v_cndmask_b32_dpp v99, v235, v239, vcc row_ror:8 row_mask:0xf bank_mask:0xf
	v_cndmask_b32_dpp v100, v236, v240, vcc row_ror:8 row_mask:0xf bank_mask:0xf
	v_cndmask_b32_dpp v101, v237, v241, vcc row_ror:8 row_mask:0xf bank_mask:0xf
	global_store_dwordx4 v246, v[102:105], s[12:13] nt
	global_store_dwordx4 v247, v[98:101], s[12:13] nt
	v_add_f32_e32 v4, v198, v199
	v_add_f32_e32 v5, v200, v201
	v_add_f32_e32 v4, v4, v5
	v_fmamk_f32 v4, v4, 0x3a800000, v212
	v_rsq_f32_e32 v6, v4
	s_add_u32 s12, s12, 0x8000
	s_addc_u32 s13, s13, 0
	v_pk_fma_f32 v[86:87], v[86:87], v[6:7], v[152:153] op_sel_hi:[1,0,1]
	v_pk_fma_f32 v[84:85], v[84:85], v[6:7], v[150:151] op_sel_hi:[1,0,1]
	v_pk_fma_f32 v[82:83], v[82:83], v[6:7], v[148:149] op_sel_hi:[1,0,1]
	v_pk_fma_f32 v[80:81], v[80:81], v[6:7], v[146:147] op_sel_hi:[1,0,1]
	v_pk_fma_f32 v[78:79], v[78:79], v[6:7], v[144:145] op_sel_hi:[1,0,1]
	v_pk_fma_f32 v[76:77], v[76:77], v[6:7], v[142:143] op_sel_hi:[1,0,1]
	v_pk_fma_f32 v[74:75], v[74:75], v[6:7], v[140:141] op_sel_hi:[1,0,1]
	v_pk_fma_f32 v[72:73], v[72:73], v[6:7], v[138:139] op_sel_hi:[1,0,1]
	v_pk_mul_f32 v[86:87], s[16:17], v[86:87]
	v_pk_mul_f32 v[84:85], s[16:17], v[84:85]
	v_pk_mul_f32 v[82:83], s[16:17], v[82:83]
	v_pk_mul_f32 v[80:81], s[16:17], v[80:81]
	v_pk_mul_f32 v[78:79], s[16:17], v[78:79]
	v_pk_mul_f32 v[76:77], s[16:17], v[76:77]
	v_pk_mul_f32 v[74:75], s[16:17], v[74:75]
	v_pk_mul_f32 v[72:73], s[16:17], v[72:73]
	v_cvt_pk_bf16_f32 v234, v84, v85
	v_cvt_pk_bf16_f32 v235, v86, v87
	v_cvt_pk_bf16_f32 v236, v80, v81
	v_cvt_pk_bf16_f32 v237, v82, v83
	v_cvt_pk_bf16_f32 v238, v76, v77
	v_cvt_pk_bf16_f32 v239, v78, v79
	v_cvt_pk_bf16_f32 v240, v72, v73
	v_cvt_pk_bf16_f32 v241, v74, v75
	s_mov_b64 vcc, s[6:7]
	v_cndmask_b32_dpp v84, v238, v234, vcc row_ror:8 row_mask:0xf bank_mask:0xf
	v_cndmask_b32_dpp v85, v239, v235, vcc row_ror:8 row_mask:0xf bank_mask:0xf
	v_cndmask_b32_dpp v86, v240, v236, vcc row_ror:8 row_mask:0xf bank_mask:0xf
	v_cndmask_b32_dpp v87, v241, v237, vcc row_ror:8 row_mask:0xf bank_mask:0xf
	s_not_b64 vcc, s[6:7]
	v_cndmask_b32_dpp v80, v234, v238, vcc row_ror:8 row_mask:0xf bank_mask:0xf
	v_cndmask_b32_dpp v81, v235, v239, vcc row_ror:8 row_mask:0xf bank_mask:0xf
	v_cndmask_b32_dpp v82, v236, v240, vcc row_ror:8 row_mask:0xf bank_mask:0xf
	v_cndmask_b32_dpp v83, v237, v241, vcc row_ror:8 row_mask:0xf bank_mask:0xf
	global_store_dwordx4 v246, v[84:87], s[12:13] nt
	global_store_dwordx4 v247, v[80:83], s[12:13] nt
	v_add_f32_e32 v4, v202, v203
	v_add_f32_e32 v5, v204, v205
	v_add_f32_e32 v4, v4, v5
	v_fmamk_f32 v4, v4, 0x3a800000, v212
	v_rsq_f32_e32 v6, v4
	s_add_u32 s12, s12, 0x28000
	s_addc_u32 s13, s13, 0
	v_pk_fma_f32 v[70:71], v[70:71], v[6:7], v[152:153] op_sel_hi:[1,0,1]
	v_pk_fma_f32 v[68:69], v[68:69], v[6:7], v[150:151] op_sel_hi:[1,0,1]
	v_pk_fma_f32 v[66:67], v[66:67], v[6:7], v[148:149] op_sel_hi:[1,0,1]
	v_pk_fma_f32 v[64:65], v[64:65], v[6:7], v[146:147] op_sel_hi:[1,0,1]
	v_pk_fma_f32 v[62:63], v[62:63], v[6:7], v[144:145] op_sel_hi:[1,0,1]
	v_pk_fma_f32 v[60:61], v[60:61], v[6:7], v[142:143] op_sel_hi:[1,0,1]
	v_pk_fma_f32 v[58:59], v[58:59], v[6:7], v[140:141] op_sel_hi:[1,0,1]
	v_pk_fma_f32 v[56:57], v[56:57], v[6:7], v[138:139] op_sel_hi:[1,0,1]
	v_pk_mul_f32 v[70:71], s[16:17], v[70:71]
	v_pk_mul_f32 v[68:69], s[16:17], v[68:69]
	v_pk_mul_f32 v[66:67], s[16:17], v[66:67]
	v_pk_mul_f32 v[64:65], s[16:17], v[64:65]
	v_pk_mul_f32 v[62:63], s[16:17], v[62:63]
	v_pk_mul_f32 v[60:61], s[16:17], v[60:61]
	v_pk_mul_f32 v[58:59], s[16:17], v[58:59]
	v_pk_mul_f32 v[56:57], s[16:17], v[56:57]
	v_cvt_pk_bf16_f32 v234, v68, v69
	v_cvt_pk_bf16_f32 v235, v70, v71
	v_cvt_pk_bf16_f32 v236, v64, v65
	v_cvt_pk_bf16_f32 v237, v66, v67
	v_cvt_pk_bf16_f32 v238, v60, v61
	v_cvt_pk_bf16_f32 v239, v62, v63
	v_cvt_pk_bf16_f32 v240, v56, v57
	v_cvt_pk_bf16_f32 v241, v58, v59
	s_mov_b64 vcc, s[6:7]
	v_cndmask_b32_dpp v68, v238, v234, vcc row_ror:8 row_mask:0xf bank_mask:0xf
	v_cndmask_b32_dpp v69, v239, v235, vcc row_ror:8 row_mask:0xf bank_mask:0xf
	v_cndmask_b32_dpp v70, v240, v236, vcc row_ror:8 row_mask:0xf bank_mask:0xf
	v_cndmask_b32_dpp v71, v241, v237, vcc row_ror:8 row_mask:0xf bank_mask:0xf
	s_not_b64 vcc, s[6:7]
	v_cndmask_b32_dpp v64, v234, v238, vcc row_ror:8 row_mask:0xf bank_mask:0xf
	v_cndmask_b32_dpp v65, v235, v239, vcc row_ror:8 row_mask:0xf bank_mask:0xf
	v_cndmask_b32_dpp v66, v236, v240, vcc row_ror:8 row_mask:0xf bank_mask:0xf
	v_cndmask_b32_dpp v67, v237, v241, vcc row_ror:8 row_mask:0xf bank_mask:0xf
	global_store_dwordx4 v246, v[68:71], s[12:13] nt
	global_store_dwordx4 v247, v[64:67], s[12:13] nt
	v_add_f32_e32 v4, v222, v223
	v_add_f32_e32 v5, v224, v225
	v_add_f32_e32 v4, v4, v5
	v_fmamk_f32 v4, v4, 0x3a800000, v212
	v_rsq_f32_e32 v6, v4
	s_add_u32 s12, s12, 0x8000
	s_addc_u32 s13, s13, 0
	v_pk_fma_f32 v[54:55], v[54:55], v[6:7], v[152:153] op_sel_hi:[1,0,1]
	v_pk_fma_f32 v[52:53], v[52:53], v[6:7], v[150:151] op_sel_hi:[1,0,1]
	v_pk_fma_f32 v[50:51], v[50:51], v[6:7], v[148:149] op_sel_hi:[1,0,1]
	v_pk_fma_f32 v[48:49], v[48:49], v[6:7], v[146:147] op_sel_hi:[1,0,1]
	v_pk_fma_f32 v[46:47], v[46:47], v[6:7], v[144:145] op_sel_hi:[1,0,1]
	v_pk_fma_f32 v[44:45], v[44:45], v[6:7], v[142:143] op_sel_hi:[1,0,1]
	v_pk_fma_f32 v[42:43], v[42:43], v[6:7], v[140:141] op_sel_hi:[1,0,1]
	v_pk_fma_f32 v[40:41], v[40:41], v[6:7], v[138:139] op_sel_hi:[1,0,1]
	v_pk_mul_f32 v[54:55], s[16:17], v[54:55]
	v_pk_mul_f32 v[52:53], s[16:17], v[52:53]
	v_pk_mul_f32 v[50:51], s[16:17], v[50:51]
	v_pk_mul_f32 v[48:49], s[16:17], v[48:49]
	v_pk_mul_f32 v[46:47], s[16:17], v[46:47]
	v_pk_mul_f32 v[44:45], s[16:17], v[44:45]
	v_pk_mul_f32 v[42:43], s[16:17], v[42:43]
	v_pk_mul_f32 v[40:41], s[16:17], v[40:41]
	v_cvt_pk_bf16_f32 v234, v52, v53
	v_cvt_pk_bf16_f32 v235, v54, v55
	v_cvt_pk_bf16_f32 v236, v48, v49
	v_cvt_pk_bf16_f32 v237, v50, v51
	v_cvt_pk_bf16_f32 v238, v44, v45
	v_cvt_pk_bf16_f32 v239, v46, v47
	v_cvt_pk_bf16_f32 v240, v40, v41
	v_cvt_pk_bf16_f32 v241, v42, v43
	s_mov_b64 vcc, s[6:7]
	v_cndmask_b32_dpp v52, v238, v234, vcc row_ror:8 row_mask:0xf bank_mask:0xf
	v_cndmask_b32_dpp v53, v239, v235, vcc row_ror:8 row_mask:0xf bank_mask:0xf
	v_cndmask_b32_dpp v54, v240, v236, vcc row_ror:8 row_mask:0xf bank_mask:0xf
	v_cndmask_b32_dpp v55, v241, v237, vcc row_ror:8 row_mask:0xf bank_mask:0xf
	s_not_b64 vcc, s[6:7]
	v_cndmask_b32_dpp v48, v234, v238, vcc row_ror:8 row_mask:0xf bank_mask:0xf
	v_cndmask_b32_dpp v49, v235, v239, vcc row_ror:8 row_mask:0xf bank_mask:0xf
	v_cndmask_b32_dpp v50, v236, v240, vcc row_ror:8 row_mask:0xf bank_mask:0xf
	v_cndmask_b32_dpp v51, v237, v241, vcc row_ror:8 row_mask:0xf bank_mask:0xf
	global_store_dwordx4 v246, v[52:55], s[12:13] nt
	global_store_dwordx4 v247, v[48:51], s[12:13] nt
	v_add_f32_e32 v4, v226, v227
	v_add_f32_e32 v5, v228, v229
	v_add_f32_e32 v4, v4, v5
	v_fmamk_f32 v4, v4, 0x3a800000, v212
	v_rsq_f32_e32 v6, v4
	s_add_u32 s12, s12, 0x8000
	s_addc_u32 s13, s13, 0
	v_pk_fma_f32 v[38:39], v[38:39], v[6:7], v[152:153] op_sel_hi:[1,0,1]
	v_pk_fma_f32 v[36:37], v[36:37], v[6:7], v[150:151] op_sel_hi:[1,0,1]
	v_pk_fma_f32 v[34:35], v[34:35], v[6:7], v[148:149] op_sel_hi:[1,0,1]
	v_pk_fma_f32 v[32:33], v[32:33], v[6:7], v[146:147] op_sel_hi:[1,0,1]
	v_pk_fma_f32 v[30:31], v[30:31], v[6:7], v[144:145] op_sel_hi:[1,0,1]
	v_pk_fma_f32 v[28:29], v[28:29], v[6:7], v[142:143] op_sel_hi:[1,0,1]
	v_pk_fma_f32 v[26:27], v[26:27], v[6:7], v[140:141] op_sel_hi:[1,0,1]
	v_pk_fma_f32 v[24:25], v[24:25], v[6:7], v[138:139] op_sel_hi:[1,0,1]
	v_pk_mul_f32 v[38:39], s[16:17], v[38:39]
	v_pk_mul_f32 v[36:37], s[16:17], v[36:37]
	v_pk_mul_f32 v[34:35], s[16:17], v[34:35]
	v_pk_mul_f32 v[32:33], s[16:17], v[32:33]
	v_pk_mul_f32 v[30:31], s[16:17], v[30:31]
	v_pk_mul_f32 v[28:29], s[16:17], v[28:29]
	v_pk_mul_f32 v[26:27], s[16:17], v[26:27]
	v_pk_mul_f32 v[24:25], s[16:17], v[24:25]
	v_cvt_pk_bf16_f32 v234, v36, v37
	v_cvt_pk_bf16_f32 v235, v38, v39
	v_cvt_pk_bf16_f32 v236, v32, v33
	v_cvt_pk_bf16_f32 v237, v34, v35
	v_cvt_pk_bf16_f32 v238, v28, v29
	v_cvt_pk_bf16_f32 v239, v30, v31
	v_cvt_pk_bf16_f32 v240, v24, v25
	v_cvt_pk_bf16_f32 v241, v26, v27
	s_mov_b64 vcc, s[6:7]
	v_cndmask_b32_dpp v36, v238, v234, vcc row_ror:8 row_mask:0xf bank_mask:0xf
	v_cndmask_b32_dpp v37, v239, v235, vcc row_ror:8 row_mask:0xf bank_mask:0xf
	v_cndmask_b32_dpp v38, v240, v236, vcc row_ror:8 row_mask:0xf bank_mask:0xf
	v_cndmask_b32_dpp v39, v241, v237, vcc row_ror:8 row_mask:0xf bank_mask:0xf
	s_not_b64 vcc, s[6:7]
	v_cndmask_b32_dpp v32, v234, v238, vcc row_ror:8 row_mask:0xf bank_mask:0xf
	v_cndmask_b32_dpp v33, v235, v239, vcc row_ror:8 row_mask:0xf bank_mask:0xf
	v_cndmask_b32_dpp v34, v236, v240, vcc row_ror:8 row_mask:0xf bank_mask:0xf
	v_cndmask_b32_dpp v35, v237, v241, vcc row_ror:8 row_mask:0xf bank_mask:0xf
	global_store_dwordx4 v246, v[36:39], s[12:13] nt
	global_store_dwordx4 v247, v[32:35], s[12:13] nt
	v_add_f32_e32 v4, v230, v231
	v_add_f32_e32 v5, v232, v233
	v_add_f32_e32 v4, v4, v5
	v_fmamk_f32 v4, v4, 0x3a800000, v212
	v_rsq_f32_e32 v6, v4
	s_add_u32 s12, s12, 0x8000
	s_addc_u32 s13, s13, 0
	v_pk_fma_f32 v[22:23], v[22:23], v[6:7], v[152:153] op_sel_hi:[1,0,1]
	v_pk_fma_f32 v[20:21], v[20:21], v[6:7], v[150:151] op_sel_hi:[1,0,1]
	v_pk_fma_f32 v[18:19], v[18:19], v[6:7], v[148:149] op_sel_hi:[1,0,1]
	v_pk_fma_f32 v[16:17], v[16:17], v[6:7], v[146:147] op_sel_hi:[1,0,1]
	v_pk_fma_f32 v[14:15], v[14:15], v[6:7], v[144:145] op_sel_hi:[1,0,1]
	v_pk_fma_f32 v[12:13], v[12:13], v[6:7], v[142:143] op_sel_hi:[1,0,1]
	v_pk_fma_f32 v[10:11], v[10:11], v[6:7], v[140:141] op_sel_hi:[1,0,1]
	v_pk_fma_f32 v[8:9], v[8:9], v[6:7], v[138:139] op_sel_hi:[1,0,1]
	v_pk_mul_f32 v[22:23], s[16:17], v[22:23]
	v_pk_mul_f32 v[20:21], s[16:17], v[20:21]
	v_pk_mul_f32 v[18:19], s[16:17], v[18:19]
	v_pk_mul_f32 v[16:17], s[16:17], v[16:17]
	v_pk_mul_f32 v[14:15], s[16:17], v[14:15]
	v_pk_mul_f32 v[12:13], s[16:17], v[12:13]
	v_pk_mul_f32 v[10:11], s[16:17], v[10:11]
	v_pk_mul_f32 v[8:9], s[16:17], v[8:9]
	v_cvt_pk_bf16_f32 v234, v20, v21
	v_cvt_pk_bf16_f32 v235, v22, v23
	v_cvt_pk_bf16_f32 v236, v16, v17
	v_cvt_pk_bf16_f32 v237, v18, v19
	v_cvt_pk_bf16_f32 v238, v12, v13
	v_cvt_pk_bf16_f32 v239, v14, v15
	v_cvt_pk_bf16_f32 v240, v8, v9
	v_cvt_pk_bf16_f32 v241, v10, v11
	s_mov_b64 vcc, s[6:7]
	v_cndmask_b32_dpp v20, v238, v234, vcc row_ror:8 row_mask:0xf bank_mask:0xf
	v_cndmask_b32_dpp v21, v239, v235, vcc row_ror:8 row_mask:0xf bank_mask:0xf
	v_cndmask_b32_dpp v22, v240, v236, vcc row_ror:8 row_mask:0xf bank_mask:0xf
	v_cndmask_b32_dpp v23, v241, v237, vcc row_ror:8 row_mask:0xf bank_mask:0xf
	s_not_b64 vcc, s[6:7]
	v_cndmask_b32_dpp v16, v234, v238, vcc row_ror:8 row_mask:0xf bank_mask:0xf
	v_cndmask_b32_dpp v17, v235, v239, vcc row_ror:8 row_mask:0xf bank_mask:0xf
	v_cndmask_b32_dpp v18, v236, v240, vcc row_ror:8 row_mask:0xf bank_mask:0xf
	v_cndmask_b32_dpp v19, v237, v241, vcc row_ror:8 row_mask:0xf bank_mask:0xf
	global_store_dwordx4 v246, v[20:23], s[12:13] nt
	global_store_dwordx4 v247, v[16:19], s[12:13] nt
	s_mov_b32 s100, 1
	s_branch .LBB0_1422
.Lfi_kind1:
	s_and_b64 vcc, exec, s[18:19]
	s_cbranch_vccz .Lfi_plain
	v_add_f32_e32 v4, v186, v187
	v_add_f32_e32 v5, v188, v189
	v_add_f32_e32 v4, v4, v5
	v_fmamk_f32 v4, v4, 0x3a800000, v212
	v_rsq_f32_e32 v6, v4
	s_nop 1
	v_pk_fma_f32 v[136:137], v[136:137], v[6:7], v[152:153] op_sel_hi:[1,0,1]
	v_pk_fma_f32 v[134:135], v[134:135], v[6:7], v[150:151] op_sel_hi:[1,0,1]
	v_pk_fma_f32 v[132:133], v[132:133], v[6:7], v[148:149] op_sel_hi:[1,0,1]
	v_pk_fma_f32 v[130:131], v[130:131], v[6:7], v[146:147] op_sel_hi:[1,0,1]
	v_pk_fma_f32 v[128:129], v[128:129], v[6:7], v[144:145] op_sel_hi:[1,0,1]
	v_pk_fma_f32 v[126:127], v[126:127], v[6:7], v[142:143] op_sel_hi:[1,0,1]
	v_pk_fma_f32 v[124:125], v[124:125], v[6:7], v[140:141] op_sel_hi:[1,0,1]
	v_pk_fma_f32 v[122:123], v[122:123], v[6:7], v[138:139] op_sel_hi:[1,0,1]
	v_mul_f32_e32 v0, 0xbfb8aa3b, v134
	v_mul_f32_e32 v1, 0xbfb8aa3b, v135
	v_mul_f32_e32 v2, 0xbfb8aa3b, v136
	v_mul_f32_e32 v3, 0xbfb8aa3b, v137
	v_mul_f32_e32 v242, 0xbfb8aa3b, v130
	v_mul_f32_e32 v243, 0xbfb8aa3b, v131
	v_mul_f32_e32 v244, 0xbfb8aa3b, v132
	v_mul_f32_e32 v245, 0xbfb8aa3b, v133
	v_exp_f32_e32 v0, v0
	v_exp_f32_e32 v1, v1
	v_exp_f32_e32 v2, v2
	v_exp_f32_e32 v3, v3
	v_exp_f32_e32 v242, v242
	v_exp_f32_e32 v243, v243
	v_exp_f32_e32 v244, v244
	v_exp_f32_e32 v245, v245
	v_add_f32_e32 v0, 1.0, v0
	v_add_f32_e32 v1, 1.0, v1
	v_add_f32_e32 v2, 1.0, v2
	v_add_f32_e32 v3, 1.0, v3
	v_add_f32_e32 v242, 1.0, v242
	v_add_f32_e32 v243, 1.0, v243
	v_add_f32_e32 v244, 1.0, v244
	v_add_f32_e32 v245, 1.0, v245
	v_rcp_f32_e32 v0, v0
	v_rcp_f32_e32 v1, v1
	v_rcp_f32_e32 v2, v2
	v_rcp_f32_e32 v3, v3
	v_rcp_f32_e32 v242, v242
	v_rcp_f32_e32 v243, v243
	v_rcp_f32_e32 v244, v244
	v_rcp_f32_e32 v245, v245
	v_pk_mul_f32 v[134:135], v[134:135], v[0:1]
	v_pk_mul_f32 v[136:137], v[136:137], v[2:3]
	v_pk_mul_f32 v[130:131], v[130:131], v[242:243]
	v_pk_mul_f32 v[132:133], v[132:133], v[244:245]
	v_mul_f32_e32 v0, 0xbfb8aa3b, v126
	v_mul_f32_e32 v1, 0xbfb8aa3b, v127
	v_mul_f32_e32 v2, 0xbfb8aa3b, v128
	v_mul_f32_e32 v3, 0xbfb8aa3b, v129
	v_mul_f32_e32 v242, 0xbfb8aa3b, v122
	v_mul_f32_e32 v243, 0xbfb8aa3b, v123
	v_mul_f32_e32 v244, 0xbfb8aa3b, v124
	v_mul_f32_e32 v245, 0xbfb8aa3b, v125
	v_exp_f32_e32 v0, v0
	v_exp_f32_e32 v1, v1
	v_exp_f32_e32 v2, v2
	v_exp_f32_e32 v3, v3
	v_exp_f32_e32 v242, v242
	v_exp_f32_e32 v243, v243
	v_exp_f32_e32 v244, v244
	v_exp_f32_e32 v245, v245
	v_add_f32_e32 v0, 1.0, v0
	v_add_f32_e32 v1, 1.0, v1
	v_add_f32_e32 v2, 1.0, v2
	v_add_f32_e32 v3, 1.0, v3
	v_add_f32_e32 v242, 1.0, v242
	v_add_f32_e32 v243, 1.0, v243
	v_add_f32_e32 v244, 1.0, v244
	v_add_f32_e32 v245, 1.0, v245
	v_rcp_f32_e32 v0, v0
	v_rcp_f32_e32 v1, v1
	v_rcp_f32_e32 v2, v2
	v_rcp_f32_e32 v3, v3
	v_rcp_f32_e32 v242, v242
	v_rcp_f32_e32 v243, v243
	v_rcp_f32_e32 v244, v244
	v_rcp_f32_e32 v245, v245
	v_pk_mul_f32 v[126:127], v[126:127], v[0:1]
	v_pk_mul_f32 v[128:129], v[128:129], v[2:3]
	v_pk_mul_f32 v[122:123], v[122:123], v[242:243]
	v_pk_mul_f32 v[124:125], v[124:125], v[244:245]
	v_cvt_pk_bf16_f32 v234, v134, v135
	v_cvt_pk_bf16_f32 v235, v136, v137
	v_cvt_pk_bf16_f32 v236, v130, v131
	v_cvt_pk_bf16_f32 v237, v132, v133
	v_cvt_pk_bf16_f32 v238, v126, v127
	v_cvt_pk_bf16_f32 v239, v128, v129
	v_cvt_pk_bf16_f32 v240, v122, v123
	v_cvt_pk_bf16_f32 v241, v124, v125
	s_mov_b64 vcc, s[6:7]
	v_cndmask_b32_dpp v134, v238, v234, vcc row_ror:8 row_mask:0xf bank_mask:0xf
	v_cndmask_b32_dpp v135, v239, v235, vcc row_ror:8 row_mask:0xf bank_mask:0xf
	v_cndmask_b32_dpp v136, v240, v236, vcc row_ror:8 row_mask:0xf bank_mask:0xf
	v_cndmask_b32_dpp v137, v241, v237, vcc row_ror:8 row_mask:0xf bank_mask:0xf
	s_not_b64 vcc, s[6:7]
	v_cndmask_b32_dpp v130, v234, v238, vcc row_ror:8 row_mask:0xf bank_mask:0xf
	v_cndmask_b32_dpp v131, v235, v239, vcc row_ror:8 row_mask:0xf bank_mask:0xf
	v_cndmask_b32_dpp v132, v236, v240, vcc row_ror:8 row_mask:0xf bank_mask:0xf
	v_cndmask_b32_dpp v133, v237, v241, vcc row_ror:8 row_mask:0xf bank_mask:0xf
	global_store_dwordx4 v246, v[134:137], s[12:13] nt
	global_store_dwordx4 v247, v[130:133], s[12:13] nt
	v_add_f32_e32 v4, v190, v191
	v_add_f32_e32 v5, v192, v193
	v_add_f32_e32 v4, v4, v5
	v_fmamk_f32 v4, v4, 0x3a800000, v212
	v_rsq_f32_e32 v6, v4
	s_add_u32 s12, s12, 0x8000
	s_addc_u32 s13, s13, 0
	v_pk_fma_f32 v[120:121], v[120:121], v[6:7], v[152:153] op_sel_hi:[1,0,1]
	v_pk_fma_f32 v[118:119], v[118:119], v[6:7], v[150:151] op_sel_hi:[1,0,1]
	v_pk_fma_f32 v[116:117], v[116:117], v[6:7], v[148:149] op_sel_hi:[1,0,1]
	v_pk_fma_f32 v[114:115], v[114:115], v[6:7], v[146:147] op_sel_hi:[1,0,1]
	v_pk_fma_f32 v[112:113], v[112:113], v[6:7], v[144:145] op_sel_hi:[1,0,1]
	v_pk_fma_f32 v[110:111], v[110:111], v[6:7], v[142:143] op_sel_hi:[1,0,1]
	v_pk_fma_f32 v[108:109], v[108:109], v[6:7], v[140:141] op_sel_hi:[1,0,1]
	v_pk_fma_f32 v[106:107], v[106:107], v[6:7], v[138:139] op_sel_hi:[1,0,1]
	v_mul_f32_e32 v0, 0xbfb8aa3b, v118
	v_mul_f32_e32 v1, 0xbfb8aa3b, v119
	v_mul_f32_e32 v2, 0xbfb8aa3b, v120
	v_mul_f32_e32 v3, 0xbfb8aa3b, v121
	v_mul_f32_e32 v242, 0xbfb8aa3b, v114
	v_mul_f32_e32 v243, 0xbfb8aa3b, v115
	v_mul_f32_e32 v244, 0xbfb8aa3b, v116
	v_mul_f32_e32 v245, 0xbfb8aa3b, v117
	v_exp_f32_e32 v0, v0
	v_exp_f32_e32 v1, v1
	v_exp_f32_e32 v2, v2
	v_exp_f32_e32 v3, v3
	v_exp_f32_e32 v242, v242
	v_exp_f32_e32 v243, v243
	v_exp_f32_e32 v244, v244
	v_exp_f32_e32 v245, v245
	v_add_f32_e32 v0, 1.0, v0
	v_add_f32_e32 v1, 1.0, v1
	v_add_f32_e32 v2, 1.0, v2
	v_add_f32_e32 v3, 1.0, v3
	v_add_f32_e32 v242, 1.0, v242
	v_add_f32_e32 v243, 1.0, v243
	v_add_f32_e32 v244, 1.0, v244
	v_add_f32_e32 v245, 1.0, v245
	v_rcp_f32_e32 v0, v0
	v_rcp_f32_e32 v1, v1
	v_rcp_f32_e32 v2, v2
	v_rcp_f32_e32 v3, v3
	v_rcp_f32_e32 v242, v242
	v_rcp_f32_e32 v243, v243
	v_rcp_f32_e32 v244, v244
	v_rcp_f32_e32 v245, v245
	v_pk_mul_f32 v[118:119], v[118:119], v[0:1]
	v_pk_mul_f32 v[120:121], v[120:121], v[2:3]
	v_pk_mul_f32 v[114:115], v[114:115], v[242:243]
	v_pk_mul_f32 v[116:117], v[116:117], v[244:245]
	v_mul_f32_e32 v0, 0xbfb8aa3b, v110
	v_mul_f32_e32 v1, 0xbfb8aa3b, v111
	v_mul_f32_e32 v2, 0xbfb8aa3b, v112
	v_mul_f32_e32 v3, 0xbfb8aa3b, v113
	v_mul_f32_e32 v242, 0xbfb8aa3b, v106
	v_mul_f32_e32 v243, 0xbfb8aa3b, v107
	v_mul_f32_e32 v244, 0xbfb8aa3b, v108
	v_mul_f32_e32 v245, 0xbfb8aa3b, v109
	v_exp_f32_e32 v0, v0
	v_exp_f32_e32 v1, v1
	v_exp_f32_e32 v2, v2
	v_exp_f32_e32 v3, v3
	v_exp_f32_e32 v242, v242
	v_exp_f32_e32 v243, v243
	v_exp_f32_e32 v244, v244
	v_exp_f32_e32 v245, v245
	v_add_f32_e32 v0, 1.0, v0
	v_add_f32_e32 v1, 1.0, v1
	v_add_f32_e32 v2, 1.0, v2
	v_add_f32_e32 v3, 1.0, v3
	v_add_f32_e32 v242, 1.0, v242
	v_add_f32_e32 v243, 1.0, v243
	v_add_f32_e32 v244, 1.0, v244
	v_add_f32_e32 v245, 1.0, v245
	v_rcp_f32_e32 v0, v0
	v_rcp_f32_e32 v1, v1
	v_rcp_f32_e32 v2, v2
	v_rcp_f32_e32 v3, v3
	v_rcp_f32_e32 v242, v242
	v_rcp_f32_e32 v243, v243
	v_rcp_f32_e32 v244, v244
	v_rcp_f32_e32 v245, v245
	v_pk_mul_f32 v[110:111], v[110:111], v[0:1]
	v_pk_mul_f32 v[112:113], v[112:113], v[2:3]
	v_pk_mul_f32 v[106:107], v[106:107], v[242:243]
	v_pk_mul_f32 v[108:109], v[108:109], v[244:245]
	v_cvt_pk_bf16_f32 v234, v118, v119
	v_cvt_pk_bf16_f32 v235, v120, v121
	v_cvt_pk_bf16_f32 v236, v114, v115
	v_cvt_pk_bf16_f32 v237, v116, v117
	v_cvt_pk_bf16_f32 v238, v110, v111
	v_cvt_pk_bf16_f32 v239, v112, v113
	v_cvt_pk_bf16_f32 v240, v106, v107
	v_cvt_pk_bf16_f32 v241, v108, v109
	s_mov_b64 vcc, s[6:7]
	v_cndmask_b32_dpp v118, v238, v234, vcc row_ror:8 row_mask:0xf bank_mask:0xf
	v_cndmask_b32_dpp v119, v239, v235, vcc row_ror:8 row_mask:0xf bank_mask:0xf
	v_cndmask_b32_dpp v120, v240, v236, vcc row_ror:8 row_mask:0xf bank_mask:0xf
	v_cndmask_b32_dpp v121, v241, v237, vcc row_ror:8 row_mask:0xf bank_mask:0xf
	s_not_b64 vcc, s[6:7]
	v_cndmask_b32_dpp v114, v234, v238, vcc row_ror:8 row_mask:0xf bank_mask:0xf
	v_cndmask_b32_dpp v115, v235, v239, vcc row_ror:8 row_mask:0xf bank_mask:0xf
	v_cndmask_b32_dpp v116, v236, v240, vcc row_ror:8 row_mask:0xf bank_mask:0xf
	v_cndmask_b32_dpp v117, v237, v241, vcc row_ror:8 row_mask:0xf bank_mask:0xf
	global_store_dwordx4 v246, v[118:121], s[12:13] nt
	global_store_dwordx4 v247, v[114:117], s[12:13] nt
	v_add_f32_e32 v4, v194, v195
	v_add_f32_e32 v5, v196, v197
	v_add_f32_e32 v4, v4, v5
	v_fmamk_f32 v4, v4, 0x3a800000, v212
	v_rsq_f32_e32 v6, v4
	s_add_u32 s12, s12, 0x8000
	s_addc_u32 s13, s13, 0
	v_pk_fma_f32 v[104:105], v[104:105], v[6:7], v[152:153] op_sel_hi:[1,0,1]
	v_pk_fma_f32 v[102:103], v[102:103], v[6:7], v[150:151] op_sel_hi:[1,0,1]
	v_pk_fma_f32 v[100:101], v[100:101], v[6:7], v[148:149] op_sel_hi:[1,0,1]
	v_pk_fma_f32 v[98:99], v[98:99], v[6:7], v[146:147] op_sel_hi:[1,0,1]
	v_pk_fma_f32 v[94:95], v[94:95], v[6:7], v[144:145] op_sel_hi:[1,0,1]
	v_pk_fma_f32 v[92:93], v[92:93], v[6:7], v[142:143] op_sel_hi:[1,0,1]
	v_pk_fma_f32 v[90:91], v[90:91], v[6:7], v[140:141] op_sel_hi:[1,0,1]
	v_pk_fma_f32 v[88:89], v[88:89], v[6:7], v[138:139] op_sel_hi:[1,0,1]
	v_mul_f32_e32 v0, 0xbfb8aa3b, v102
	v_mul_f32_e32 v1, 0xbfb8aa3b, v103
	v_mul_f32_e32 v2, 0xbfb8aa3b, v104
	v_mul_f32_e32 v3, 0xbfb8aa3b, v105
	v_mul_f32_e32 v242, 0xbfb8aa3b, v98
	v_mul_f32_e32 v243, 0xbfb8aa3b, v99
	v_mul_f32_e32 v244, 0xbfb8aa3b, v100
	v_mul_f32_e32 v245, 0xbfb8aa3b, v101
	v_exp_f32_e32 v0, v0
	v_exp_f32_e32 v1, v1
	v_exp_f32_e32 v2, v2
	v_exp_f32_e32 v3, v3
	v_exp_f32_e32 v242, v242
	v_exp_f32_e32 v243, v243
	v_exp_f32_e32 v244, v244
	v_exp_f32_e32 v245, v245
	v_add_f32_e32 v0, 1.0, v0
	v_add_f32_e32 v1, 1.0, v1
	v_add_f32_e32 v2, 1.0, v2
	v_add_f32_e32 v3, 1.0, v3
	v_add_f32_e32 v242, 1.0, v242
	v_add_f32_e32 v243, 1.0, v243
	v_add_f32_e32 v244, 1.0, v244
	v_add_f32_e32 v245, 1.0, v245
	v_rcp_f32_e32 v0, v0
	v_rcp_f32_e32 v1, v1
	v_rcp_f32_e32 v2, v2
	v_rcp_f32_e32 v3, v3
	v_rcp_f32_e32 v242, v242
	v_rcp_f32_e32 v243, v243
	v_rcp_f32_e32 v244, v244
	v_rcp_f32_e32 v245, v245
	v_pk_mul_f32 v[102:103], v[102:103], v[0:1]
	v_pk_mul_f32 v[104:105], v[104:105], v[2:3]
	v_pk_mul_f32 v[98:99], v[98:99], v[242:243]
	v_pk_mul_f32 v[100:101], v[100:101], v[244:245]
	v_mul_f32_e32 v0, 0xbfb8aa3b, v92
	v_mul_f32_e32 v1, 0xbfb8aa3b, v93
	v_mul_f32_e32 v2, 0xbfb8aa3b, v94
	v_mul_f32_e32 v3, 0xbfb8aa3b, v95
	v_mul_f32_e32 v242, 0xbfb8aa3b, v88
	v_mul_f32_e32 v243, 0xbfb8aa3b, v89
	v_mul_f32_e32 v244, 0xbfb8aa3b, v90
	v_mul_f32_e32 v245, 0xbfb8aa3b, v91
	v_exp_f32_e32 v0, v0
	v_exp_f32_e32 v1, v1
	v_exp_f32_e32 v2, v2
	v_exp_f32_e32 v3, v3
	v_exp_f32_e32 v242, v242
	v_exp_f32_e32 v243, v243
	v_exp_f32_e32 v244, v244
	v_exp_f32_e32 v245, v245
	v_add_f32_e32 v0, 1.0, v0
	v_add_f32_e32 v1, 1.0, v1
	v_add_f32_e32 v2, 1.0, v2
	v_add_f32_e32 v3, 1.0, v3
	v_add_f32_e32 v242, 1.0, v242
	v_add_f32_e32 v243, 1.0, v243
	v_add_f32_e32 v244, 1.0, v244
	v_add_f32_e32 v245, 1.0, v245
	v_rcp_f32_e32 v0, v0
	v_rcp_f32_e32 v1, v1
	v_rcp_f32_e32 v2, v2
	v_rcp_f32_e32 v3, v3
	v_rcp_f32_e32 v242, v242
	v_rcp_f32_e32 v243, v243
	v_rcp_f32_e32 v244, v244
	v_rcp_f32_e32 v245, v245
	v_pk_mul_f32 v[92:93], v[92:93], v[0:1]
	v_pk_mul_f32 v[94:95], v[94:95], v[2:3]
	v_pk_mul_f32 v[88:89], v[88:89], v[242:243]
	v_pk_mul_f32 v[90:91], v[90:91], v[244:245]
	v_cvt_pk_bf16_f32 v234, v102, v103
	v_cvt_pk_bf16_f32 v235, v104, v105
	v_cvt_pk_bf16_f32 v236, v98, v99
	v_cvt_pk_bf16_f32 v237, v100, v101
	v_cvt_pk_bf16_f32 v238, v92, v93
	v_cvt_pk_bf16_f32 v239, v94, v95
	v_cvt_pk_bf16_f32 v240, v88, v89
	v_cvt_pk_bf16_f32 v241, v90, v91
	s_mov_b64 vcc, s[6:7]
	v_cndmask_b32_dpp v102, v238, v234, vcc row_ror:8 row_mask:0xf bank_mask:0xf
	v_cndmask_b32_dpp v103, v239, v235, vcc row_ror:8 row_mask:0xf bank_mask:0xf
	v_cndmask_b32_dpp v104, v240, v236, vcc row_ror:8 row_mask:0xf bank_mask:0xf
	v_cndmask_b32_dpp v105, v241, v237, vcc row_ror:8 row_mask:0xf bank_mask:0xf
	s_not_b64 vcc, s[6:7]
	v_cndmask_b32_dpp v98, v234, v238, vcc row_ror:8 row_mask:0xf bank_mask:0xf
	v_cndmask_b32_dpp v99, v235, v239, vcc row_ror:8 row_mask:0xf bank_mask:0xf
	v_cndmask_b32_dpp v100, v236, v240, vcc row_ror:8 row_mask:0xf bank_mask:0xf
	v_cndmask_b32_dpp v101, v237, v241, vcc row_ror:8 row_mask:0xf bank_mask:0xf
	global_store_dwordx4 v246, v[102:105], s[12:13] nt
	global_store_dwordx4 v247, v[98:101], s[12:13] nt
	v_add_f32_e32 v4, v198, v199
	v_add_f32_e32 v5, v200, v201
	v_add_f32_e32 v4, v4, v5
	v_fmamk_f32 v4, v4, 0x3a800000, v212
	v_rsq_f32_e32 v6, v4
	s_add_u32 s12, s12, 0x8000
	s_addc_u32 s13, s13, 0
	v_pk_fma_f32 v[86:87], v[86:87], v[6:7], v[152:153] op_sel_hi:[1,0,1]
	v_pk_fma_f32 v[84:85], v[84:85], v[6:7], v[150:151] op_sel_hi:[1,0,1]
	v_pk_fma_f32 v[82:83], v[82:83], v[6:7], v[148:149] op_sel_hi:[1,0,1]
	v_pk_fma_f32 v[80:81], v[80:81], v[6:7], v[146:147] op_sel_hi:[1,0,1]
	v_pk_fma_f32 v[78:79], v[78:79], v[6:7], v[144:145] op_sel_hi:[1,0,1]
	v_pk_fma_f32 v[76:77], v[76:77], v[6:7], v[142:143] op_sel_hi:[1,0,1]
	v_pk_fma_f32 v[74:75], v[74:75], v[6:7], v[140:141] op_sel_hi:[1,0,1]
	v_pk_fma_f32 v[72:73], v[72:73], v[6:7], v[138:139] op_sel_hi:[1,0,1]
	v_mul_f32_e32 v0, 0xbfb8aa3b, v84
	v_mul_f32_e32 v1, 0xbfb8aa3b, v85
	v_mul_f32_e32 v2, 0xbfb8aa3b, v86
	v_mul_f32_e32 v3, 0xbfb8aa3b, v87
	v_mul_f32_e32 v242, 0xbfb8aa3b, v80
	v_mul_f32_e32 v243, 0xbfb8aa3b, v81
	v_mul_f32_e32 v244, 0xbfb8aa3b, v82
	v_mul_f32_e32 v245, 0xbfb8aa3b, v83
	v_exp_f32_e32 v0, v0
	v_exp_f32_e32 v1, v1
	v_exp_f32_e32 v2, v2
	v_exp_f32_e32 v3, v3
	v_exp_f32_e32 v242, v242
	v_exp_f32_e32 v243, v243
	v_exp_f32_e32 v244, v244
	v_exp_f32_e32 v245, v245
	v_add_f32_e32 v0, 1.0, v0
	v_add_f32_e32 v1, 1.0, v1
	v_add_f32_e32 v2, 1.0, v2
	v_add_f32_e32 v3, 1.0, v3
	v_add_f32_e32 v242, 1.0, v242
	v_add_f32_e32 v243, 1.0, v243
	v_add_f32_e32 v244, 1.0, v244
	v_add_f32_e32 v245, 1.0, v245
	v_rcp_f32_e32 v0, v0
	v_rcp_f32_e32 v1, v1
	v_rcp_f32_e32 v2, v2
	v_rcp_f32_e32 v3, v3
	v_rcp_f32_e32 v242, v242
	v_rcp_f32_e32 v243, v243
	v_rcp_f32_e32 v244, v244
	v_rcp_f32_e32 v245, v245
	v_pk_mul_f32 v[84:85], v[84:85], v[0:1]
	v_pk_mul_f32 v[86:87], v[86:87], v[2:3]
	v_pk_mul_f32 v[80:81], v[80:81], v[242:243]
	v_pk_mul_f32 v[82:83], v[82:83], v[244:245]
	v_mul_f32_e32 v0, 0xbfb8aa3b, v76
	v_mul_f32_e32 v1, 0xbfb8aa3b, v77
	v_mul_f32_e32 v2, 0xbfb8aa3b, v78
	v_mul_f32_e32 v3, 0xbfb8aa3b, v79
	v_mul_f32_e32 v242, 0xbfb8aa3b, v72
	v_mul_f32_e32 v243, 0xbfb8aa3b, v73
	v_mul_f32_e32 v244, 0xbfb8aa3b, v74
	v_mul_f32_e32 v245, 0xbfb8aa3b, v75
	v_exp_f32_e32 v0, v0
	v_exp_f32_e32 v1, v1
	v_exp_f32_e32 v2, v2
	v_exp_f32_e32 v3, v3
	v_exp_f32_e32 v242, v242
	v_exp_f32_e32 v243, v243
	v_exp_f32_e32 v244, v244
	v_exp_f32_e32 v245, v245
	v_add_f32_e32 v0, 1.0, v0
	v_add_f32_e32 v1, 1.0, v1
	v_add_f32_e32 v2, 1.0, v2
	v_add_f32_e32 v3, 1.0, v3
	v_add_f32_e32 v242, 1.0, v242
	v_add_f32_e32 v243, 1.0, v243
	v_add_f32_e32 v244, 1.0, v244
	v_add_f32_e32 v245, 1.0, v245
	v_rcp_f32_e32 v0, v0
	v_rcp_f32_e32 v1, v1
	v_rcp_f32_e32 v2, v2
	v_rcp_f32_e32 v3, v3
	v_rcp_f32_e32 v242, v242
	v_rcp_f32_e32 v243, v243
	v_rcp_f32_e32 v244, v244
	v_rcp_f32_e32 v245, v245
	v_pk_mul_f32 v[76:77], v[76:77], v[0:1]
	v_pk_mul_f32 v[78:79], v[78:79], v[2:3]
	v_pk_mul_f32 v[72:73], v[72:73], v[242:243]
	v_pk_mul_f32 v[74:75], v[74:75], v[244:245]
	v_cvt_pk_bf16_f32 v234, v84, v85
	v_cvt_pk_bf16_f32 v235, v86, v87
	v_cvt_pk_bf16_f32 v236, v80, v81
	v_cvt_pk_bf16_f32 v237, v82, v83
	v_cvt_pk_bf16_f32 v238, v76, v77
	v_cvt_pk_bf16_f32 v239, v78, v79
	v_cvt_pk_bf16_f32 v240, v72, v73
	v_cvt_pk_bf16_f32 v241, v74, v75
	s_mov_b64 vcc, s[6:7]
	v_cndmask_b32_dpp v84, v238, v234, vcc row_ror:8 row_mask:0xf bank_mask:0xf
	v_cndmask_b32_dpp v85, v239, v235, vcc row_ror:8 row_mask:0xf bank_mask:0xf
	v_cndmask_b32_dpp v86, v240, v236, vcc row_ror:8 row_mask:0xf bank_mask:0xf
	v_cndmask_b32_dpp v87, v241, v237, vcc row_ror:8 row_mask:0xf bank_mask:0xf
	s_not_b64 vcc, s[6:7]
	v_cndmask_b32_dpp v80, v234, v238, vcc row_ror:8 row_mask:0xf bank_mask:0xf
	v_cndmask_b32_dpp v81, v235, v239, vcc row_ror:8 row_mask:0xf bank_mask:0xf
	v_cndmask_b32_dpp v82, v236, v240, vcc row_ror:8 row_mask:0xf bank_mask:0xf
	v_cndmask_b32_dpp v83, v237, v241, vcc row_ror:8 row_mask:0xf bank_mask:0xf
	global_store_dwordx4 v246, v[84:87], s[12:13] nt
	global_store_dwordx4 v247, v[80:83], s[12:13] nt
	v_add_f32_e32 v4, v202, v203
	v_add_f32_e32 v5, v204, v205
	v_add_f32_e32 v4, v4, v5
	v_fmamk_f32 v4, v4, 0x3a800000, v212
	v_rsq_f32_e32 v6, v4
	s_add_u32 s12, s12, 0x28000
	s_addc_u32 s13, s13, 0
	v_pk_fma_f32 v[70:71], v[70:71], v[6:7], v[152:153] op_sel_hi:[1,0,1]
	v_pk_fma_f32 v[68:69], v[68:69], v[6:7], v[150:151] op_sel_hi:[1,0,1]
	v_pk_fma_f32 v[66:67], v[66:67], v[6:7], v[148:149] op_sel_hi:[1,0,1]
	v_pk_fma_f32 v[64:65], v[64:65], v[6:7], v[146:147] op_sel_hi:[1,0,1]
	v_pk_fma_f32 v[62:63], v[62:63], v[6:7], v[144:145] op_sel_hi:[1,0,1]
	v_pk_fma_f32 v[60:61], v[60:61], v[6:7], v[142:143] op_sel_hi:[1,0,1]
	v_pk_fma_f32 v[58:59], v[58:59], v[6:7], v[140:141] op_sel_hi:[1,0,1]
	v_pk_fma_f32 v[56:57], v[56:57], v[6:7], v[138:139] op_sel_hi:[1,0,1]
	v_mul_f32_e32 v0, 0xbfb8aa3b, v68
	v_mul_f32_e32 v1, 0xbfb8aa3b, v69
	v_mul_f32_e32 v2, 0xbfb8aa3b, v70
	v_mul_f32_e32 v3, 0xbfb8aa3b, v71
	v_mul_f32_e32 v242, 0xbfb8aa3b, v64
	v_mul_f32_e32 v243, 0xbfb8aa3b, v65
	v_mul_f32_e32 v244, 0xbfb8aa3b, v66
	v_mul_f32_e32 v245, 0xbfb8aa3b, v67
	v_exp_f32_e32 v0, v0
	v_exp_f32_e32 v1, v1
	v_exp_f32_e32 v2, v2
	v_exp_f32_e32 v3, v3
	v_exp_f32_e32 v242, v242
	v_exp_f32_e32 v243, v243
	v_exp_f32_e32 v244, v244
	v_exp_f32_e32 v245, v245
	v_add_f32_e32 v0, 1.0, v0
	v_add_f32_e32 v1, 1.0, v1
	v_add_f32_e32 v2, 1.0, v2
	v_add_f32_e32 v3, 1.0, v3
	v_add_f32_e32 v242, 1.0, v242
	v_add_f32_e32 v243, 1.0, v243
	v_add_f32_e32 v244, 1.0, v244
	v_add_f32_e32 v245, 1.0, v245
	v_rcp_f32_e32 v0, v0
	v_rcp_f32_e32 v1, v1
	v_rcp_f32_e32 v2, v2
	v_rcp_f32_e32 v3, v3
	v_rcp_f32_e32 v242, v242
	v_rcp_f32_e32 v243, v243
	v_rcp_f32_e32 v244, v244
	v_rcp_f32_e32 v245, v245
	v_pk_mul_f32 v[68:69], v[68:69], v[0:1]
	v_pk_mul_f32 v[70:71], v[70:71], v[2:3]
	v_pk_mul_f32 v[64:65], v[64:65], v[242:243]
	v_pk_mul_f32 v[66:67], v[66:67], v[244:245]
	v_mul_f32_e32 v0, 0xbfb8aa3b, v60
	v_mul_f32_e32 v1, 0xbfb8aa3b, v61
	v_mul_f32_e32 v2, 0xbfb8aa3b, v62
	v_mul_f32_e32 v3, 0xbfb8aa3b, v63
	v_mul_f32_e32 v242, 0xbfb8aa3b, v56
	v_mul_f32_e32 v243, 0xbfb8aa3b, v57
	v_mul_f32_e32 v244, 0xbfb8aa3b, v58
	v_mul_f32_e32 v245, 0xbfb8aa3b, v59
	v_exp_f32_e32 v0, v0
	v_exp_f32_e32 v1, v1
	v_exp_f32_e32 v2, v2
	v_exp_f32_e32 v3, v3
	v_exp_f32_e32 v242, v242
	v_exp_f32_e32 v243, v243
	v_exp_f32_e32 v244, v244
	v_exp_f32_e32 v245, v245
	v_add_f32_e32 v0, 1.0, v0
	v_add_f32_e32 v1, 1.0, v1
	v_add_f32_e32 v2, 1.0, v2
	v_add_f32_e32 v3, 1.0, v3
	v_add_f32_e32 v242, 1.0, v242
	v_add_f32_e32 v243, 1.0, v243
	v_add_f32_e32 v244, 1.0, v244
	v_add_f32_e32 v245, 1.0, v245
	v_rcp_f32_e32 v0, v0
	v_rcp_f32_e32 v1, v1
	v_rcp_f32_e32 v2, v2
	v_rcp_f32_e32 v3, v3
	v_rcp_f32_e32 v242, v242
	v_rcp_f32_e32 v243, v243
	v_rcp_f32_e32 v244, v244
	v_rcp_f32_e32 v245, v245
	v_pk_mul_f32 v[60:61], v[60:61], v[0:1]
	v_pk_mul_f32 v[62:63], v[62:63], v[2:3]
	v_pk_mul_f32 v[56:57], v[56:57], v[242:243]
	v_pk_mul_f32 v[58:59], v[58:59], v[244:245]
	v_cvt_pk_bf16_f32 v234, v68, v69
	v_cvt_pk_bf16_f32 v235, v70, v71
	v_cvt_pk_bf16_f32 v236, v64, v65
	v_cvt_pk_bf16_f32 v237, v66, v67
	v_cvt_pk_bf16_f32 v238, v60, v61
	v_cvt_pk_bf16_f32 v239, v62, v63
	v_cvt_pk_bf16_f32 v240, v56, v57
	v_cvt_pk_bf16_f32 v241, v58, v59
	s_mov_b64 vcc, s[6:7]
	v_cndmask_b32_dpp v68, v238, v234, vcc row_ror:8 row_mask:0xf bank_mask:0xf
	v_cndmask_b32_dpp v69, v239, v235, vcc row_ror:8 row_mask:0xf bank_mask:0xf
	v_cndmask_b32_dpp v70, v240, v236, vcc row_ror:8 row_mask:0xf bank_mask:0xf
	v_cndmask_b32_dpp v71, v241, v237, vcc row_ror:8 row_mask:0xf bank_mask:0xf
	s_not_b64 vcc, s[6:7]
	v_cndmask_b32_dpp v64, v234, v238, vcc row_ror:8 row_mask:0xf bank_mask:0xf
	v_cndmask_b32_dpp v65, v235, v239, vcc row_ror:8 row_mask:0xf bank_mask:0xf
	v_cndmask_b32_dpp v66, v236, v240, vcc row_ror:8 row_mask:0xf bank_mask:0xf
	v_cndmask_b32_dpp v67, v237, v241, vcc row_ror:8 row_mask:0xf bank_mask:0xf
	global_store_dwordx4 v246, v[68:71], s[12:13] nt
	global_store_dwordx4 v247, v[64:67], s[12:13] nt
	v_add_f32_e32 v4, v222, v223
	v_add_f32_e32 v5, v224, v225
	v_add_f32_e32 v4, v4, v5
	v_fmamk_f32 v4, v4, 0x3a800000, v212
	v_rsq_f32_e32 v6, v4
	s_add_u32 s12, s12, 0x8000
	s_addc_u32 s13, s13, 0
	v_pk_fma_f32 v[54:55], v[54:55], v[6:7], v[152:153] op_sel_hi:[1,0,1]
	v_pk_fma_f32 v[52:53], v[52:53], v[6:7], v[150:151] op_sel_hi:[1,0,1]
	v_pk_fma_f32 v[50:51], v[50:51], v[6:7], v[148:149] op_sel_hi:[1,0,1]
	v_pk_fma_f32 v[48:49], v[48:49], v[6:7], v[146:147] op_sel_hi:[1,0,1]
	v_pk_fma_f32 v[46:47], v[46:47], v[6:7], v[144:145] op_sel_hi:[1,0,1]
	v_pk_fma_f32 v[44:45], v[44:45], v[6:7], v[142:143] op_sel_hi:[1,0,1]
	v_pk_fma_f32 v[42:43], v[42:43], v[6:7], v[140:141] op_sel_hi:[1,0,1]
	v_pk_fma_f32 v[40:41], v[40:41], v[6:7], v[138:139] op_sel_hi:[1,0,1]
	v_mul_f32_e32 v0, 0xbfb8aa3b, v52
	v_mul_f32_e32 v1, 0xbfb8aa3b, v53
	v_mul_f32_e32 v2, 0xbfb8aa3b, v54
	v_mul_f32_e32 v3, 0xbfb8aa3b, v55
	v_mul_f32_e32 v242, 0xbfb8aa3b, v48
	v_mul_f32_e32 v243, 0xbfb8aa3b, v49
	v_mul_f32_e32 v244, 0xbfb8aa3b, v50
	v_mul_f32_e32 v245, 0xbfb8aa3b, v51
	v_exp_f32_e32 v0, v0
	v_exp_f32_e32 v1, v1
	v_exp_f32_e32 v2, v2
	v_exp_f32_e32 v3, v3
	v_exp_f32_e32 v242, v242
	v_exp_f32_e32 v243, v243
	v_exp_f32_e32 v244, v244
	v_exp_f32_e32 v245, v245
	v_add_f32_e32 v0, 1.0, v0
	v_add_f32_e32 v1, 1.0, v1
	v_add_f32_e32 v2, 1.0, v2
	v_add_f32_e32 v3, 1.0, v3
	v_add_f32_e32 v242, 1.0, v242
	v_add_f32_e32 v243, 1.0, v243
	v_add_f32_e32 v244, 1.0, v244
	v_add_f32_e32 v245, 1.0, v245
	v_rcp_f32_e32 v0, v0
	v_rcp_f32_e32 v1, v1
	v_rcp_f32_e32 v2, v2
	v_rcp_f32_e32 v3, v3
	v_rcp_f32_e32 v242, v242
	v_rcp_f32_e32 v243, v243
	v_rcp_f32_e32 v244, v244
	v_rcp_f32_e32 v245, v245
	v_pk_mul_f32 v[52:53], v[52:53], v[0:1]
	v_pk_mul_f32 v[54:55], v[54:55], v[2:3]
	v_pk_mul_f32 v[48:49], v[48:49], v[242:243]
	v_pk_mul_f32 v[50:51], v[50:51], v[244:245]
	v_mul_f32_e32 v0, 0xbfb8aa3b, v44
	v_mul_f32_e32 v1, 0xbfb8aa3b, v45
	v_mul_f32_e32 v2, 0xbfb8aa3b, v46
	v_mul_f32_e32 v3, 0xbfb8aa3b, v47
	v_mul_f32_e32 v242, 0xbfb8aa3b, v40
	v_mul_f32_e32 v243, 0xbfb8aa3b, v41
	v_mul_f32_e32 v244, 0xbfb8aa3b, v42
	v_mul_f32_e32 v245, 0xbfb8aa3b, v43
	v_exp_f32_e32 v0, v0
	v_exp_f32_e32 v1, v1
	v_exp_f32_e32 v2, v2
	v_exp_f32_e32 v3, v3
	v_exp_f32_e32 v242, v242
	v_exp_f32_e32 v243, v243
	v_exp_f32_e32 v244, v244
	v_exp_f32_e32 v245, v245
	v_add_f32_e32 v0, 1.0, v0
	v_add_f32_e32 v1, 1.0, v1
	v_add_f32_e32 v2, 1.0, v2
	v_add_f32_e32 v3, 1.0, v3
	v_add_f32_e32 v242, 1.0, v242
	v_add_f32_e32 v243, 1.0, v243
	v_add_f32_e32 v244, 1.0, v244
	v_add_f32_e32 v245, 1.0, v245
	v_rcp_f32_e32 v0, v0
	v_rcp_f32_e32 v1, v1
	v_rcp_f32_e32 v2, v2
	v_rcp_f32_e32 v3, v3
	v_rcp_f32_e32 v242, v242
	v_rcp_f32_e32 v243, v243
	v_rcp_f32_e32 v244, v244
	v_rcp_f32_e32 v245, v245
	v_pk_mul_f32 v[44:45], v[44:45], v[0:1]
	v_pk_mul_f32 v[46:47], v[46:47], v[2:3]
	v_pk_mul_f32 v[40:41], v[40:41], v[242:243]
	v_pk_mul_f32 v[42:43], v[42:43], v[244:245]
	v_cvt_pk_bf16_f32 v234, v52, v53
	v_cvt_pk_bf16_f32 v235, v54, v55
	v_cvt_pk_bf16_f32 v236, v48, v49
	v_cvt_pk_bf16_f32 v237, v50, v51
	v_cvt_pk_bf16_f32 v238, v44, v45
	v_cvt_pk_bf16_f32 v239, v46, v47
	v_cvt_pk_bf16_f32 v240, v40, v41
	v_cvt_pk_bf16_f32 v241, v42, v43
	s_mov_b64 vcc, s[6:7]
	v_cndmask_b32_dpp v52, v238, v234, vcc row_ror:8 row_mask:0xf bank_mask:0xf
	v_cndmask_b32_dpp v53, v239, v235, vcc row_ror:8 row_mask:0xf bank_mask:0xf
	v_cndmask_b32_dpp v54, v240, v236, vcc row_ror:8 row_mask:0xf bank_mask:0xf
	v_cndmask_b32_dpp v55, v241, v237, vcc row_ror:8 row_mask:0xf bank_mask:0xf
	s_not_b64 vcc, s[6:7]
	v_cndmask_b32_dpp v48, v234, v238, vcc row_ror:8 row_mask:0xf bank_mask:0xf
	v_cndmask_b32_dpp v49, v235, v239, vcc row_ror:8 row_mask:0xf bank_mask:0xf
	v_cndmask_b32_dpp v50, v236, v240, vcc row_ror:8 row_mask:0xf bank_mask:0xf
	v_cndmask_b32_dpp v51, v237, v241, vcc row_ror:8 row_mask:0xf bank_mask:0xf
	global_store_dwordx4 v246, v[52:55], s[12:13] nt
	global_store_dwordx4 v247, v[48:51], s[12:13] nt
	v_add_f32_e32 v4, v226, v227
	v_add_f32_e32 v5, v228, v229
	v_add_f32_e32 v4, v4, v5
	v_fmamk_f32 v4, v4, 0x3a800000, v212
	v_rsq_f32_e32 v6, v4
	s_add_u32 s12, s12, 0x8000
	s_addc_u32 s13, s13, 0
	v_pk_fma_f32 v[38:39], v[38:39], v[6:7], v[152:153] op_sel_hi:[1,0,1]
	v_pk_fma_f32 v[36:37], v[36:37], v[6:7], v[150:151] op_sel_hi:[1,0,1]
	v_pk_fma_f32 v[34:35], v[34:35], v[6:7], v[148:149] op_sel_hi:[1,0,1]
	v_pk_fma_f32 v[32:33], v[32:33], v[6:7], v[146:147] op_sel_hi:[1,0,1]
	v_pk_fma_f32 v[30:31], v[30:31], v[6:7], v[144:145] op_sel_hi:[1,0,1]
	v_pk_fma_f32 v[28:29], v[28:29], v[6:7], v[142:143] op_sel_hi:[1,0,1]
	v_pk_fma_f32 v[26:27], v[26:27], v[6:7], v[140:141] op_sel_hi:[1,0,1]
	v_pk_fma_f32 v[24:25], v[24:25], v[6:7], v[138:139] op_sel_hi:[1,0,1]
	v_mul_f32_e32 v0, 0xbfb8aa3b, v36
	v_mul_f32_e32 v1, 0xbfb8aa3b, v37
	v_mul_f32_e32 v2, 0xbfb8aa3b, v38
	v_mul_f32_e32 v3, 0xbfb8aa3b, v39
	v_mul_f32_e32 v242, 0xbfb8aa3b, v32
	v_mul_f32_e32 v243, 0xbfb8aa3b, v33
	v_mul_f32_e32 v244, 0xbfb8aa3b, v34
	v_mul_f32_e32 v245, 0xbfb8aa3b, v35
	v_exp_f32_e32 v0, v0
	v_exp_f32_e32 v1, v1
	v_exp_f32_e32 v2, v2
	v_exp_f32_e32 v3, v3
	v_exp_f32_e32 v242, v242
	v_exp_f32_e32 v243, v243
	v_exp_f32_e32 v244, v244
	v_exp_f32_e32 v245, v245
	v_add_f32_e32 v0, 1.0, v0
	v_add_f32_e32 v1, 1.0, v1
	v_add_f32_e32 v2, 1.0, v2
	v_add_f32_e32 v3, 1.0, v3
	v_add_f32_e32 v242, 1.0, v242
	v_add_f32_e32 v243, 1.0, v243
	v_add_f32_e32 v244, 1.0, v244
	v_add_f32_e32 v245, 1.0, v245
	v_rcp_f32_e32 v0, v0
	v_rcp_f32_e32 v1, v1
	v_rcp_f32_e32 v2, v2
	v_rcp_f32_e32 v3, v3
	v_rcp_f32_e32 v242, v242
	v_rcp_f32_e32 v243, v243
	v_rcp_f32_e32 v244, v244
	v_rcp_f32_e32 v245, v245
	v_pk_mul_f32 v[36:37], v[36:37], v[0:1]
	v_pk_mul_f32 v[38:39], v[38:39], v[2:3]
	v_pk_mul_f32 v[32:33], v[32:33], v[242:243]
	v_pk_mul_f32 v[34:35], v[34:35], v[244:245]
	v_mul_f32_e32 v0, 0xbfb8aa3b, v28
	v_mul_f32_e32 v1, 0xbfb8aa3b, v29
	v_mul_f32_e32 v2, 0xbfb8aa3b, v30
	v_mul_f32_e32 v3, 0xbfb8aa3b, v31
	v_mul_f32_e32 v242, 0xbfb8aa3b, v24
	v_mul_f32_e32 v243, 0xbfb8aa3b, v25
	v_mul_f32_e32 v244, 0xbfb8aa3b, v26
	v_mul_f32_e32 v245, 0xbfb8aa3b, v27
	v_exp_f32_e32 v0, v0
	v_exp_f32_e32 v1, v1
	v_exp_f32_e32 v2, v2
	v_exp_f32_e32 v3, v3
	v_exp_f32_e32 v242, v242
	v_exp_f32_e32 v243, v243
	v_exp_f32_e32 v244, v244
	v_exp_f32_e32 v245, v245
	v_add_f32_e32 v0, 1.0, v0
	v_add_f32_e32 v1, 1.0, v1
	v_add_f32_e32 v2, 1.0, v2
	v_add_f32_e32 v3, 1.0, v3
	v_add_f32_e32 v242, 1.0, v242
	v_add_f32_e32 v243, 1.0, v243
	v_add_f32_e32 v244, 1.0, v244
	v_add_f32_e32 v245, 1.0, v245
	v_rcp_f32_e32 v0, v0
	v_rcp_f32_e32 v1, v1
	v_rcp_f32_e32 v2, v2
	v_rcp_f32_e32 v3, v3
	v_rcp_f32_e32 v242, v242
	v_rcp_f32_e32 v243, v243
	v_rcp_f32_e32 v244, v244
	v_rcp_f32_e32 v245, v245
	v_pk_mul_f32 v[28:29], v[28:29], v[0:1]
	v_pk_mul_f32 v[30:31], v[30:31], v[2:3]
	v_pk_mul_f32 v[24:25], v[24:25], v[242:243]
	v_pk_mul_f32 v[26:27], v[26:27], v[244:245]
	v_cvt_pk_bf16_f32 v234, v36, v37
	v_cvt_pk_bf16_f32 v235, v38, v39
	v_cvt_pk_bf16_f32 v236, v32, v33
	v_cvt_pk_bf16_f32 v237, v34, v35
	v_cvt_pk_bf16_f32 v238, v28, v29
	v_cvt_pk_bf16_f32 v239, v30, v31
	v_cvt_pk_bf16_f32 v240, v24, v25
	v_cvt_pk_bf16_f32 v241, v26, v27
	s_mov_b64 vcc, s[6:7]
	v_cndmask_b32_dpp v36, v238, v234, vcc row_ror:8 row_mask:0xf bank_mask:0xf
	v_cndmask_b32_dpp v37, v239, v235, vcc row_ror:8 row_mask:0xf bank_mask:0xf
	v_cndmask_b32_dpp v38, v240, v236, vcc row_ror:8 row_mask:0xf bank_mask:0xf
	v_cndmask_b32_dpp v39, v241, v237, vcc row_ror:8 row_mask:0xf bank_mask:0xf
	s_not_b64 vcc, s[6:7]
	v_cndmask_b32_dpp v32, v234, v238, vcc row_ror:8 row_mask:0xf bank_mask:0xf
	v_cndmask_b32_dpp v33, v235, v239, vcc row_ror:8 row_mask:0xf bank_mask:0xf
	v_cndmask_b32_dpp v34, v236, v240, vcc row_ror:8 row_mask:0xf bank_mask:0xf
	v_cndmask_b32_dpp v35, v237, v241, vcc row_ror:8 row_mask:0xf bank_mask:0xf
	global_store_dwordx4 v246, v[36:39], s[12:13] nt
	global_store_dwordx4 v247, v[32:35], s[12:13] nt
	v_add_f32_e32 v4, v230, v231
	v_add_f32_e32 v5, v232, v233
	v_add_f32_e32 v4, v4, v5
	v_fmamk_f32 v4, v4, 0x3a800000, v212
	v_rsq_f32_e32 v6, v4
	s_add_u32 s12, s12, 0x8000
	s_addc_u32 s13, s13, 0
	v_pk_fma_f32 v[22:23], v[22:23], v[6:7], v[152:153] op_sel_hi:[1,0,1]
	v_pk_fma_f32 v[20:21], v[20:21], v[6:7], v[150:151] op_sel_hi:[1,0,1]
	v_pk_fma_f32 v[18:19], v[18:19], v[6:7], v[148:149] op_sel_hi:[1,0,1]
	v_pk_fma_f32 v[16:17], v[16:17], v[6:7], v[146:147] op_sel_hi:[1,0,1]
	v_pk_fma_f32 v[14:15], v[14:15], v[6:7], v[144:145] op_sel_hi:[1,0,1]
	v_pk_fma_f32 v[12:13], v[12:13], v[6:7], v[142:143] op_sel_hi:[1,0,1]
	v_pk_fma_f32 v[10:11], v[10:11], v[6:7], v[140:141] op_sel_hi:[1,0,1]
	v_pk_fma_f32 v[8:9], v[8:9], v[6:7], v[138:139] op_sel_hi:[1,0,1]
	v_mul_f32_e32 v0, 0xbfb8aa3b, v20
	v_mul_f32_e32 v1, 0xbfb8aa3b, v21
	v_mul_f32_e32 v2, 0xbfb8aa3b, v22
	v_mul_f32_e32 v3, 0xbfb8aa3b, v23
	v_mul_f32_e32 v242, 0xbfb8aa3b, v16
	v_mul_f32_e32 v243, 0xbfb8aa3b, v17
	v_mul_f32_e32 v244, 0xbfb8aa3b, v18
	v_mul_f32_e32 v245, 0xbfb8aa3b, v19
	v_exp_f32_e32 v0, v0
	v_exp_f32_e32 v1, v1
	v_exp_f32_e32 v2, v2
	v_exp_f32_e32 v3, v3
	v_exp_f32_e32 v242, v242
	v_exp_f32_e32 v243, v243
	v_exp_f32_e32 v244, v244
	v_exp_f32_e32 v245, v245
	v_add_f32_e32 v0, 1.0, v0
	v_add_f32_e32 v1, 1.0, v1
	v_add_f32_e32 v2, 1.0, v2
	v_add_f32_e32 v3, 1.0, v3
	v_add_f32_e32 v242, 1.0, v242
	v_add_f32_e32 v243, 1.0, v243
	v_add_f32_e32 v244, 1.0, v244
	v_add_f32_e32 v245, 1.0, v245
	v_rcp_f32_e32 v0, v0
	v_rcp_f32_e32 v1, v1
	v_rcp_f32_e32 v2, v2
	v_rcp_f32_e32 v3, v3
	v_rcp_f32_e32 v242, v242
	v_rcp_f32_e32 v243, v243
	v_rcp_f32_e32 v244, v244
	v_rcp_f32_e32 v245, v245
	v_pk_mul_f32 v[20:21], v[20:21], v[0:1]
	v_pk_mul_f32 v[22:23], v[22:23], v[2:3]
	v_pk_mul_f32 v[16:17], v[16:17], v[242:243]
	v_pk_mul_f32 v[18:19], v[18:19], v[244:245]
	v_mul_f32_e32 v0, 0xbfb8aa3b, v12
	v_mul_f32_e32 v1, 0xbfb8aa3b, v13
	v_mul_f32_e32 v2, 0xbfb8aa3b, v14
	v_mul_f32_e32 v3, 0xbfb8aa3b, v15
	v_mul_f32_e32 v242, 0xbfb8aa3b, v8
	v_mul_f32_e32 v243, 0xbfb8aa3b, v9
	v_mul_f32_e32 v244, 0xbfb8aa3b, v10
	v_mul_f32_e32 v245, 0xbfb8aa3b, v11
	v_exp_f32_e32 v0, v0
	v_exp_f32_e32 v1, v1
	v_exp_f32_e32 v2, v2
	v_exp_f32_e32 v3, v3
	v_exp_f32_e32 v242, v242
	v_exp_f32_e32 v243, v243
	v_exp_f32_e32 v244, v244
	v_exp_f32_e32 v245, v245
	v_add_f32_e32 v0, 1.0, v0
	v_add_f32_e32 v1, 1.0, v1
	v_add_f32_e32 v2, 1.0, v2
	v_add_f32_e32 v3, 1.0, v3
	v_add_f32_e32 v242, 1.0, v242
	v_add_f32_e32 v243, 1.0, v243
	v_add_f32_e32 v244, 1.0, v244
	v_add_f32_e32 v245, 1.0, v245
	v_rcp_f32_e32 v0, v0
	v_rcp_f32_e32 v1, v1
	v_rcp_f32_e32 v2, v2
	v_rcp_f32_e32 v3, v3
	v_rcp_f32_e32 v242, v242
	v_rcp_f32_e32 v243, v243
	v_rcp_f32_e32 v244, v244
	v_rcp_f32_e32 v245, v245
	v_pk_mul_f32 v[12:13], v[12:13], v[0:1]
	v_pk_mul_f32 v[14:15], v[14:15], v[2:3]
	v_pk_mul_f32 v[8:9], v[8:9], v[242:243]
	v_pk_mul_f32 v[10:11], v[10:11], v[244:245]
	v_cvt_pk_bf16_f32 v234, v20, v21
	v_cvt_pk_bf16_f32 v235, v22, v23
	v_cvt_pk_bf16_f32 v236, v16, v17
	v_cvt_pk_bf16_f32 v237, v18, v19
	v_cvt_pk_bf16_f32 v238, v12, v13
	v_cvt_pk_bf16_f32 v239, v14, v15
	v_cvt_pk_bf16_f32 v240, v8, v9
	v_cvt_pk_bf16_f32 v241, v10, v11
	s_mov_b64 vcc, s[6:7]
	v_cndmask_b32_dpp v20, v238, v234, vcc row_ror:8 row_mask:0xf bank_mask:0xf
	v_cndmask_b32_dpp v21, v239, v235, vcc row_ror:8 row_mask:0xf bank_mask:0xf
	v_cndmask_b32_dpp v22, v240, v236, vcc row_ror:8 row_mask:0xf bank_mask:0xf
	v_cndmask_b32_dpp v23, v241, v237, vcc row_ror:8 row_mask:0xf bank_mask:0xf
	s_not_b64 vcc, s[6:7]
	v_cndmask_b32_dpp v16, v234, v238, vcc row_ror:8 row_mask:0xf bank_mask:0xf
	v_cndmask_b32_dpp v17, v235, v239, vcc row_ror:8 row_mask:0xf bank_mask:0xf
	v_cndmask_b32_dpp v18, v236, v240, vcc row_ror:8 row_mask:0xf bank_mask:0xf
	v_cndmask_b32_dpp v19, v237, v241, vcc row_ror:8 row_mask:0xf bank_mask:0xf
	global_store_dwordx4 v246, v[20:23], s[12:13] nt
	global_store_dwordx4 v247, v[16:19], s[12:13] nt
	s_mov_b32 s100, 1
	s_branch .LBB0_1422
.Lfi_plain:
	v_add_f32_e32 v4, v186, v187
	v_add_f32_e32 v5, v188, v189
	v_add_f32_e32 v4, v4, v5
	v_fmamk_f32 v4, v4, 0x3a800000, v212
	v_rsq_f32_e32 v6, v4
	s_nop 1
	v_pk_fma_f32 v[136:137], v[136:137], v[6:7], v[152:153] op_sel_hi:[1,0,1]
	v_pk_fma_f32 v[134:135], v[134:135], v[6:7], v[150:151] op_sel_hi:[1,0,1]
	v_pk_fma_f32 v[132:133], v[132:133], v[6:7], v[148:149] op_sel_hi:[1,0,1]
	v_pk_fma_f32 v[130:131], v[130:131], v[6:7], v[146:147] op_sel_hi:[1,0,1]
	v_pk_fma_f32 v[128:129], v[128:129], v[6:7], v[144:145] op_sel_hi:[1,0,1]
	v_pk_fma_f32 v[126:127], v[126:127], v[6:7], v[142:143] op_sel_hi:[1,0,1]
	v_pk_fma_f32 v[124:125], v[124:125], v[6:7], v[140:141] op_sel_hi:[1,0,1]
	v_pk_fma_f32 v[122:123], v[122:123], v[6:7], v[138:139] op_sel_hi:[1,0,1]
	v_cvt_pk_bf16_f32 v234, v134, v135
	v_cvt_pk_bf16_f32 v235, v136, v137
	v_cvt_pk_bf16_f32 v236, v130, v131
	v_cvt_pk_bf16_f32 v237, v132, v133
	v_cvt_pk_bf16_f32 v238, v126, v127
	v_cvt_pk_bf16_f32 v239, v128, v129
	v_cvt_pk_bf16_f32 v240, v122, v123
	v_cvt_pk_bf16_f32 v241, v124, v125
	s_mov_b64 vcc, s[6:7]
	v_cndmask_b32_dpp v134, v238, v234, vcc row_ror:8 row_mask:0xf bank_mask:0xf
	v_cndmask_b32_dpp v135, v239, v235, vcc row_ror:8 row_mask:0xf bank_mask:0xf
	v_cndmask_b32_dpp v136, v240, v236, vcc row_ror:8 row_mask:0xf bank_mask:0xf
	v_cndmask_b32_dpp v137, v241, v237, vcc row_ror:8 row_mask:0xf bank_mask:0xf
	s_not_b64 vcc, s[6:7]
	v_cndmask_b32_dpp v130, v234, v238, vcc row_ror:8 row_mask:0xf bank_mask:0xf
	v_cndmask_b32_dpp v131, v235, v239, vcc row_ror:8 row_mask:0xf bank_mask:0xf
	v_cndmask_b32_dpp v132, v236, v240, vcc row_ror:8 row_mask:0xf bank_mask:0xf
	v_cndmask_b32_dpp v133, v237, v241, vcc row_ror:8 row_mask:0xf bank_mask:0xf
	global_store_dwordx4 v246, v[134:137], s[12:13] nt
	global_store_dwordx4 v247, v[130:133], s[12:13] nt
	v_add_f32_e32 v4, v190, v191
	v_add_f32_e32 v5, v192, v193
	v_add_f32_e32 v4, v4, v5
	v_fmamk_f32 v4, v4, 0x3a800000, v212
	v_rsq_f32_e32 v6, v4
	s_add_u32 s12, s12, 0x8000
	s_addc_u32 s13, s13, 0
	v_pk_fma_f32 v[120:121], v[120:121], v[6:7], v[152:153] op_sel_hi:[1,0,1]
	v_pk_fma_f32 v[118:119], v[118:119], v[6:7], v[150:151] op_sel_hi:[1,0,1]
	v_pk_fma_f32 v[116:117], v[116:117], v[6:7], v[148:149] op_sel_hi:[1,0,1]
	v_pk_fma_f32 v[114:115], v[114:115], v[6:7], v[146:147] op_sel_hi:[1,0,1]
	v_pk_fma_f32 v[112:113], v[112:113], v[6:7], v[144:145] op_sel_hi:[1,0,1]
	v_pk_fma_f32 v[110:111], v[110:111], v[6:7], v[142:143] op_sel_hi:[1,0,1]
	v_pk_fma_f32 v[108:109], v[108:109], v[6:7], v[140:141] op_sel_hi:[1,0,1]
	v_pk_fma_f32 v[106:107], v[106:107], v[6:7], v[138:139] op_sel_hi:[1,0,1]
	v_cvt_pk_bf16_f32 v234, v118, v119
	v_cvt_pk_bf16_f32 v235, v120, v121
	v_cvt_pk_bf16_f32 v236, v114, v115
	v_cvt_pk_bf16_f32 v237, v116, v117
	v_cvt_pk_bf16_f32 v238, v110, v111
	v_cvt_pk_bf16_f32 v239, v112, v113
	v_cvt_pk_bf16_f32 v240, v106, v107
	v_cvt_pk_bf16_f32 v241, v108, v109
	s_mov_b64 vcc, s[6:7]
	v_cndmask_b32_dpp v118, v238, v234, vcc row_ror:8 row_mask:0xf bank_mask:0xf
	v_cndmask_b32_dpp v119, v239, v235, vcc row_ror:8 row_mask:0xf bank_mask:0xf
	v_cndmask_b32_dpp v120, v240, v236, vcc row_ror:8 row_mask:0xf bank_mask:0xf
	v_cndmask_b32_dpp v121, v241, v237, vcc row_ror:8 row_mask:0xf bank_mask:0xf
	s_not_b64 vcc, s[6:7]
	v_cndmask_b32_dpp v114, v234, v238, vcc row_ror:8 row_mask:0xf bank_mask:0xf
	v_cndmask_b32_dpp v115, v235, v239, vcc row_ror:8 row_mask:0xf bank_mask:0xf
	v_cndmask_b32_dpp v116, v236, v240, vcc row_ror:8 row_mask:0xf bank_mask:0xf
	v_cndmask_b32_dpp v117, v237, v241, vcc row_ror:8 row_mask:0xf bank_mask:0xf
	global_store_dwordx4 v246, v[118:121], s[12:13] nt
	global_store_dwordx4 v247, v[114:117], s[12:13] nt
	v_add_f32_e32 v4, v194, v195
	v_add_f32_e32 v5, v196, v197
	v_add_f32_e32 v4, v4, v5
	v_fmamk_f32 v4, v4, 0x3a800000, v212
	v_rsq_f32_e32 v6, v4
	s_add_u32 s12, s12, 0x8000
	s_addc_u32 s13, s13, 0
	v_pk_fma_f32 v[104:105], v[104:105], v[6:7], v[152:153] op_sel_hi:[1,0,1]
	v_pk_fma_f32 v[102:103], v[102:103], v[6:7], v[150:151] op_sel_hi:[1,0,1]
	v_pk_fma_f32 v[100:101], v[100:101], v[6:7], v[148:149] op_sel_hi:[1,0,1]
	v_pk_fma_f32 v[98:99], v[98:99], v[6:7], v[146:147] op_sel_hi:[1,0,1]
	v_pk_fma_f32 v[94:95], v[94:95], v[6:7], v[144:145] op_sel_hi:[1,0,1]
	v_pk_fma_f32 v[92:93], v[92:93], v[6:7], v[142:143] op_sel_hi:[1,0,1]
	v_pk_fma_f32 v[90:91], v[90:91], v[6:7], v[140:141] op_sel_hi:[1,0,1]
	v_pk_fma_f32 v[88:89], v[88:89], v[6:7], v[138:139] op_sel_hi:[1,0,1]
	v_cvt_pk_bf16_f32 v234, v102, v103
	v_cvt_pk_bf16_f32 v235, v104, v105
	v_cvt_pk_bf16_f32 v236, v98, v99
	v_cvt_pk_bf16_f32 v237, v100, v101
	v_cvt_pk_bf16_f32 v238, v92, v93
	v_cvt_pk_bf16_f32 v239, v94, v95
	v_cvt_pk_bf16_f32 v240, v88, v89
	v_cvt_pk_bf16_f32 v241, v90, v91
	s_mov_b64 vcc, s[6:7]
	v_cndmask_b32_dpp v102, v238, v234, vcc row_ror:8 row_mask:0xf bank_mask:0xf
	v_cndmask_b32_dpp v103, v239, v235, vcc row_ror:8 row_mask:0xf bank_mask:0xf
	v_cndmask_b32_dpp v104, v240, v236, vcc row_ror:8 row_mask:0xf bank_mask:0xf
	v_cndmask_b32_dpp v105, v241, v237, vcc row_ror:8 row_mask:0xf bank_mask:0xf
	s_not_b64 vcc, s[6:7]
	v_cndmask_b32_dpp v98, v234, v238, vcc row_ror:8 row_mask:0xf bank_mask:0xf
	v_cndmask_b32_dpp v99, v235, v239, vcc row_ror:8 row_mask:0xf bank_mask:0xf
	v_cndmask_b32_dpp v100, v236, v240, vcc row_ror:8 row_mask:0xf bank_mask:0xf
	v_cndmask_b32_dpp v101, v237, v241, vcc row_ror:8 row_mask:0xf bank_mask:0xf
	global_store_dwordx4 v246, v[102:105], s[12:13] nt
	global_store_dwordx4 v247, v[98:101], s[12:13] nt
	v_add_f32_e32 v4, v198, v199
	v_add_f32_e32 v5, v200, v201
	v_add_f32_e32 v4, v4, v5
	v_fmamk_f32 v4, v4, 0x3a800000, v212
	v_rsq_f32_e32 v6, v4
	s_add_u32 s12, s12, 0x8000
	s_addc_u32 s13, s13, 0
	v_pk_fma_f32 v[86:87], v[86:87], v[6:7], v[152:153] op_sel_hi:[1,0,1]
	v_pk_fma_f32 v[84:85], v[84:85], v[6:7], v[150:151] op_sel_hi:[1,0,1]
	v_pk_fma_f32 v[82:83], v[82:83], v[6:7], v[148:149] op_sel_hi:[1,0,1]
	v_pk_fma_f32 v[80:81], v[80:81], v[6:7], v[146:147] op_sel_hi:[1,0,1]
	v_pk_fma_f32 v[78:79], v[78:79], v[6:7], v[144:145] op_sel_hi:[1,0,1]
	v_pk_fma_f32 v[76:77], v[76:77], v[6:7], v[142:143] op_sel_hi:[1,0,1]
	v_pk_fma_f32 v[74:75], v[74:75], v[6:7], v[140:141] op_sel_hi:[1,0,1]
	v_pk_fma_f32 v[72:73], v[72:73], v[6:7], v[138:139] op_sel_hi:[1,0,1]
	v_cvt_pk_bf16_f32 v234, v84, v85
	v_cvt_pk_bf16_f32 v235, v86, v87
	v_cvt_pk_bf16_f32 v236, v80, v81
	v_cvt_pk_bf16_f32 v237, v82, v83
	v_cvt_pk_bf16_f32 v238, v76, v77
	v_cvt_pk_bf16_f32 v239, v78, v79
	v_cvt_pk_bf16_f32 v240, v72, v73
	v_cvt_pk_bf16_f32 v241, v74, v75
	s_mov_b64 vcc, s[6:7]
	v_cndmask_b32_dpp v84, v238, v234, vcc row_ror:8 row_mask:0xf bank_mask:0xf
	v_cndmask_b32_dpp v85, v239, v235, vcc row_ror:8 row_mask:0xf bank_mask:0xf
	v_cndmask_b32_dpp v86, v240, v236, vcc row_ror:8 row_mask:0xf bank_mask:0xf
	v_cndmask_b32_dpp v87, v241, v237, vcc row_ror:8 row_mask:0xf bank_mask:0xf
	s_not_b64 vcc, s[6:7]
	v_cndmask_b32_dpp v80, v234, v238, vcc row_ror:8 row_mask:0xf bank_mask:0xf
	v_cndmask_b32_dpp v81, v235, v239, vcc row_ror:8 row_mask:0xf bank_mask:0xf
	v_cndmask_b32_dpp v82, v236, v240, vcc row_ror:8 row_mask:0xf bank_mask:0xf
	v_cndmask_b32_dpp v83, v237, v241, vcc row_ror:8 row_mask:0xf bank_mask:0xf
	global_store_dwordx4 v246, v[84:87], s[12:13] nt
	global_store_dwordx4 v247, v[80:83], s[12:13] nt
	v_add_f32_e32 v4, v202, v203
	v_add_f32_e32 v5, v204, v205
	v_add_f32_e32 v4, v4, v5
	v_fmamk_f32 v4, v4, 0x3a800000, v212
	v_rsq_f32_e32 v6, v4
	s_add_u32 s12, s12, 0x28000
	s_addc_u32 s13, s13, 0
	v_pk_fma_f32 v[70:71], v[70:71], v[6:7], v[152:153] op_sel_hi:[1,0,1]
	v_pk_fma_f32 v[68:69], v[68:69], v[6:7], v[150:151] op_sel_hi:[1,0,1]
	v_pk_fma_f32 v[66:67], v[66:67], v[6:7], v[148:149] op_sel_hi:[1,0,1]
	v_pk_fma_f32 v[64:65], v[64:65], v[6:7], v[146:147] op_sel_hi:[1,0,1]
	v_pk_fma_f32 v[62:63], v[62:63], v[6:7], v[144:145] op_sel_hi:[1,0,1]
	v_pk_fma_f32 v[60:61], v[60:61], v[6:7], v[142:143] op_sel_hi:[1,0,1]
	v_pk_fma_f32 v[58:59], v[58:59], v[6:7], v[140:141] op_sel_hi:[1,0,1]
	v_pk_fma_f32 v[56:57], v[56:57], v[6:7], v[138:139] op_sel_hi:[1,0,1]
	v_cvt_pk_bf16_f32 v234, v68, v69
	v_cvt_pk_bf16_f32 v235, v70, v71
	v_cvt_pk_bf16_f32 v236, v64, v65
	v_cvt_pk_bf16_f32 v237, v66, v67
	v_cvt_pk_bf16_f32 v238, v60, v61
	v_cvt_pk_bf16_f32 v239, v62, v63
	v_cvt_pk_bf16_f32 v240, v56, v57
	v_cvt_pk_bf16_f32 v241, v58, v59
	s_mov_b64 vcc, s[6:7]
	v_cndmask_b32_dpp v68, v238, v234, vcc row_ror:8 row_mask:0xf bank_mask:0xf
	v_cndmask_b32_dpp v69, v239, v235, vcc row_ror:8 row_mask:0xf bank_mask:0xf
	v_cndmask_b32_dpp v70, v240, v236, vcc row_ror:8 row_mask:0xf bank_mask:0xf
	v_cndmask_b32_dpp v71, v241, v237, vcc row_ror:8 row_mask:0xf bank_mask:0xf
	s_not_b64 vcc, s[6:7]
	v_cndmask_b32_dpp v64, v234, v238, vcc row_ror:8 row_mask:0xf bank_mask:0xf
	v_cndmask_b32_dpp v65, v235, v239, vcc row_ror:8 row_mask:0xf bank_mask:0xf
	v_cndmask_b32_dpp v66, v236, v240, vcc row_ror:8 row_mask:0xf bank_mask:0xf
	v_cndmask_b32_dpp v67, v237, v241, vcc row_ror:8 row_mask:0xf bank_mask:0xf
	global_store_dwordx4 v246, v[68:71], s[12:13] nt
	global_store_dwordx4 v247, v[64:67], s[12:13] nt
	v_add_f32_e32 v4, v222, v223
	v_add_f32_e32 v5, v224, v225
	v_add_f32_e32 v4, v4, v5
	v_fmamk_f32 v4, v4, 0x3a800000, v212
	v_rsq_f32_e32 v6, v4
	s_add_u32 s12, s12, 0x8000
	s_addc_u32 s13, s13, 0
	v_pk_fma_f32 v[54:55], v[54:55], v[6:7], v[152:153] op_sel_hi:[1,0,1]
	v_pk_fma_f32 v[52:53], v[52:53], v[6:7], v[150:151] op_sel_hi:[1,0,1]
	v_pk_fma_f32 v[50:51], v[50:51], v[6:7], v[148:149] op_sel_hi:[1,0,1]
	v_pk_fma_f32 v[48:49], v[48:49], v[6:7], v[146:147] op_sel_hi:[1,0,1]
	v_pk_fma_f32 v[46:47], v[46:47], v[6:7], v[144:145] op_sel_hi:[1,0,1]
	v_pk_fma_f32 v[44:45], v[44:45], v[6:7], v[142:143] op_sel_hi:[1,0,1]
	v_pk_fma_f32 v[42:43], v[42:43], v[6:7], v[140:141] op_sel_hi:[1,0,1]
	v_pk_fma_f32 v[40:41], v[40:41], v[6:7], v[138:139] op_sel_hi:[1,0,1]
	v_cvt_pk_bf16_f32 v234, v52, v53
	v_cvt_pk_bf16_f32 v235, v54, v55
	v_cvt_pk_bf16_f32 v236, v48, v49
	v_cvt_pk_bf16_f32 v237, v50, v51
	v_cvt_pk_bf16_f32 v238, v44, v45
	v_cvt_pk_bf16_f32 v239, v46, v47
	v_cvt_pk_bf16_f32 v240, v40, v41
	v_cvt_pk_bf16_f32 v241, v42, v43
	s_mov_b64 vcc, s[6:7]
	v_cndmask_b32_dpp v52, v238, v234, vcc row_ror:8 row_mask:0xf bank_mask:0xf
	v_cndmask_b32_dpp v53, v239, v235, vcc row_ror:8 row_mask:0xf bank_mask:0xf
	v_cndmask_b32_dpp v54, v240, v236, vcc row_ror:8 row_mask:0xf bank_mask:0xf
	v_cndmask_b32_dpp v55, v241, v237, vcc row_ror:8 row_mask:0xf bank_mask:0xf
	s_not_b64 vcc, s[6:7]
	v_cndmask_b32_dpp v48, v234, v238, vcc row_ror:8 row_mask:0xf bank_mask:0xf
	v_cndmask_b32_dpp v49, v235, v239, vcc row_ror:8 row_mask:0xf bank_mask:0xf
	v_cndmask_b32_dpp v50, v236, v240, vcc row_ror:8 row_mask:0xf bank_mask:0xf
	v_cndmask_b32_dpp v51, v237, v241, vcc row_ror:8 row_mask:0xf bank_mask:0xf
	global_store_dwordx4 v246, v[52:55], s[12:13] nt
	global_store_dwordx4 v247, v[48:51], s[12:13] nt
	v_add_f32_e32 v4, v226, v227
	v_add_f32_e32 v5, v228, v229
	v_add_f32_e32 v4, v4, v5
	v_fmamk_f32 v4, v4, 0x3a800000, v212
	v_rsq_f32_e32 v6, v4
	s_add_u32 s12, s12, 0x8000
	s_addc_u32 s13, s13, 0
	v_pk_fma_f32 v[38:39], v[38:39], v[6:7], v[152:153] op_sel_hi:[1,0,1]
	v_pk_fma_f32 v[36:37], v[36:37], v[6:7], v[150:151] op_sel_hi:[1,0,1]
	v_pk_fma_f32 v[34:35], v[34:35], v[6:7], v[148:149] op_sel_hi:[1,0,1]
	v_pk_fma_f32 v[32:33], v[32:33], v[6:7], v[146:147] op_sel_hi:[1,0,1]
	v_pk_fma_f32 v[30:31], v[30:31], v[6:7], v[144:145] op_sel_hi:[1,0,1]
	v_pk_fma_f32 v[28:29], v[28:29], v[6:7], v[142:143] op_sel_hi:[1,0,1]
	v_pk_fma_f32 v[26:27], v[26:27], v[6:7], v[140:141] op_sel_hi:[1,0,1]
	v_pk_fma_f32 v[24:25], v[24:25], v[6:7], v[138:139] op_sel_hi:[1,0,1]
	v_cvt_pk_bf16_f32 v234, v36, v37
	v_cvt_pk_bf16_f32 v235, v38, v39
	v_cvt_pk_bf16_f32 v236, v32, v33
	v_cvt_pk_bf16_f32 v237, v34, v35
	v_cvt_pk_bf16_f32 v238, v28, v29
	v_cvt_pk_bf16_f32 v239, v30, v31
	v_cvt_pk_bf16_f32 v240, v24, v25
	v_cvt_pk_bf16_f32 v241, v26, v27
	s_mov_b64 vcc, s[6:7]
	v_cndmask_b32_dpp v36, v238, v234, vcc row_ror:8 row_mask:0xf bank_mask:0xf
	v_cndmask_b32_dpp v37, v239, v235, vcc row_ror:8 row_mask:0xf bank_mask:0xf
	v_cndmask_b32_dpp v38, v240, v236, vcc row_ror:8 row_mask:0xf bank_mask:0xf
	v_cndmask_b32_dpp v39, v241, v237, vcc row_ror:8 row_mask:0xf bank_mask:0xf
	s_not_b64 vcc, s[6:7]
	v_cndmask_b32_dpp v32, v234, v238, vcc row_ror:8 row_mask:0xf bank_mask:0xf
	v_cndmask_b32_dpp v33, v235, v239, vcc row_ror:8 row_mask:0xf bank_mask:0xf
	v_cndmask_b32_dpp v34, v236, v240, vcc row_ror:8 row_mask:0xf bank_mask:0xf
	v_cndmask_b32_dpp v35, v237, v241, vcc row_ror:8 row_mask:0xf bank_mask:0xf
	global_store_dwordx4 v246, v[36:39], s[12:13] nt
	global_store_dwordx4 v247, v[32:35], s[12:13] nt
	v_add_f32_e32 v4, v230, v231
	v_add_f32_e32 v5, v232, v233
	v_add_f32_e32 v4, v4, v5
	v_fmamk_f32 v4, v4, 0x3a800000, v212
	v_rsq_f32_e32 v6, v4
	s_add_u32 s12, s12, 0x8000
	s_addc_u32 s13, s13, 0
	v_pk_fma_f32 v[22:23], v[22:23], v[6:7], v[152:153] op_sel_hi:[1,0,1]
	v_pk_fma_f32 v[20:21], v[20:21], v[6:7], v[150:151] op_sel_hi:[1,0,1]
	v_pk_fma_f32 v[18:19], v[18:19], v[6:7], v[148:149] op_sel_hi:[1,0,1]
	v_pk_fma_f32 v[16:17], v[16:17], v[6:7], v[146:147] op_sel_hi:[1,0,1]
	v_pk_fma_f32 v[14:15], v[14:15], v[6:7], v[144:145] op_sel_hi:[1,0,1]
	v_pk_fma_f32 v[12:13], v[12:13], v[6:7], v[142:143] op_sel_hi:[1,0,1]
	v_pk_fma_f32 v[10:11], v[10:11], v[6:7], v[140:141] op_sel_hi:[1,0,1]
	v_pk_fma_f32 v[8:9], v[8:9], v[6:7], v[138:139] op_sel_hi:[1,0,1]
	v_cvt_pk_bf16_f32 v234, v20, v21
	v_cvt_pk_bf16_f32 v235, v22, v23
	v_cvt_pk_bf16_f32 v236, v16, v17
	v_cvt_pk_bf16_f32 v237, v18, v19
	v_cvt_pk_bf16_f32 v238, v12, v13
	v_cvt_pk_bf16_f32 v239, v14, v15
	v_cvt_pk_bf16_f32 v240, v8, v9
	v_cvt_pk_bf16_f32 v241, v10, v11
	s_mov_b64 vcc, s[6:7]
	v_cndmask_b32_dpp v20, v238, v234, vcc row_ror:8 row_mask:0xf bank_mask:0xf
	v_cndmask_b32_dpp v21, v239, v235, vcc row_ror:8 row_mask:0xf bank_mask:0xf
	v_cndmask_b32_dpp v22, v240, v236, vcc row_ror:8 row_mask:0xf bank_mask:0xf
	v_cndmask_b32_dpp v23, v241, v237, vcc row_ror:8 row_mask:0xf bank_mask:0xf
	s_not_b64 vcc, s[6:7]
	v_cndmask_b32_dpp v16, v234, v238, vcc row_ror:8 row_mask:0xf bank_mask:0xf
	v_cndmask_b32_dpp v17, v235, v239, vcc row_ror:8 row_mask:0xf bank_mask:0xf
	v_cndmask_b32_dpp v18, v236, v240, vcc row_ror:8 row_mask:0xf bank_mask:0xf
	v_cndmask_b32_dpp v19, v237, v241, vcc row_ror:8 row_mask:0xf bank_mask:0xf
	global_store_dwordx4 v246, v[20:23], s[12:13] nt
	global_store_dwordx4 v247, v[16:19], s[12:13] nt
	s_mov_b32 s100, 1
	s_branch .LBB0_1422

.Lfi_kv:
	v_readlane_b32 s10, v252, 42
	v_add_u32_e32 v1, s71, v208
	s_add_i32 s10, s10, s71
	v_add_u32_e32 v0, s10, v209
	ds_read_b128 v[186:189], v1
	ds_read_b128 v[190:193], v1 offset:256
	ds_read_b128 v[194:197], v1 offset:512
	ds_read_b128 v[198:201], v1 offset:768
	ds_read_b128 v[202:205], v1 offset:2048
	ds_read_b128 v[222:225], v1 offset:2304
	ds_read_b128 v[226:229], v1 offset:2560
	ds_read_b128 v[230:233], v1 offset:2816
	ds_read_b128 v[150:153], v0 offset:4096
	ds_read_b128 v[146:149], v0 offset:4112
	ds_read_b128 v[142:145], v0 offset:4224
	ds_read_b128 v[138:141], v0 offset:4240
	s_cmp_eq_u32 s35, 2
	s_cselect_b32 s12, s52, s54
	s_cselect_b32 s13, s53, s55
	s_cselect_b32 s18, s37, s33
	s_cselect_b32 s19, s49, s74
	s_lshl_b32 s14, s36, 8
	s_add_i32 s14, s14, s20
	s_lshl_b32 s14, s14, 9
	s_add_u32 s12, s12, s14
	s_addc_u32 s13, s13, 0
	v_add_u32_e32 v2, v182, v162
	v_lshlrev_b32_e32 v2, 1, v2
	v_lshl_add_u32 v246, v207, 9, v2
	v_add_u32_e32 v247, 0x1000, v246
	s_lshr_b32 s14, s36, 3
	s_lshl_b32 s14, s14, 7
	s_add_i32 s14, s14, s20
	s_lshl_b32 s14, s14, 10
	s_add_u32 s18, s18, s14
	s_addc_u32 s19, s19, 0
	v_lshlrev_b32_e32 v3, 10, v163
	v_lshl_add_u32 v3, v182, 2, v3
	s_and_b32 s14, s36, 7
	s_waitcnt lgkmcnt(0)
	s_cmp_eq_u32 s14, 7
	s_cbranch_scc1 .Lfi_kv_win
	v_add_f32_e32 v4, v186, v187
	v_add_f32_e32 v5, v188, v189
	v_add_f32_e32 v4, v4, v5
	v_fmamk_f32 v4, v4, 0x3a800000, v212
	v_rsq_f32_e32 v6, v4
	s_nop 1
	v_pk_fma_f32 v[136:137], v[136:137], v[6:7], v[152:153] op_sel_hi:[1,0,1]
	v_pk_fma_f32 v[134:135], v[134:135], v[6:7], v[150:151] op_sel_hi:[1,0,1]
	v_pk_fma_f32 v[132:133], v[132:133], v[6:7], v[148:149] op_sel_hi:[1,0,1]
	v_pk_fma_f32 v[130:131], v[130:131], v[6:7], v[146:147] op_sel_hi:[1,0,1]
	v_pk_fma_f32 v[128:129], v[128:129], v[6:7], v[144:145] op_sel_hi:[1,0,1]
	v_pk_fma_f32 v[126:127], v[126:127], v[6:7], v[142:143] op_sel_hi:[1,0,1]
	v_pk_fma_f32 v[124:125], v[124:125], v[6:7], v[140:141] op_sel_hi:[1,0,1]
	v_pk_fma_f32 v[122:123], v[122:123], v[6:7], v[138:139] op_sel_hi:[1,0,1]
	v_cvt_pk_bf16_f32 v234, v134, v135
	v_cvt_pk_bf16_f32 v235, v136, v137
	v_cvt_pk_bf16_f32 v236, v130, v131
	v_cvt_pk_bf16_f32 v237, v132, v133
	v_cvt_pk_bf16_f32 v238, v126, v127
	v_cvt_pk_bf16_f32 v239, v128, v129
	v_cvt_pk_bf16_f32 v240, v122, v123
	v_cvt_pk_bf16_f32 v241, v124, v125
	s_mov_b64 vcc, s[6:7]
	v_cndmask_b32_dpp v134, v238, v234, vcc row_ror:8 row_mask:0xf bank_mask:0xf
	v_cndmask_b32_dpp v135, v239, v235, vcc row_ror:8 row_mask:0xf bank_mask:0xf
	v_cndmask_b32_dpp v136, v240, v236, vcc row_ror:8 row_mask:0xf bank_mask:0xf
	v_cndmask_b32_dpp v137, v241, v237, vcc row_ror:8 row_mask:0xf bank_mask:0xf
	s_not_b64 vcc, s[6:7]
	v_cndmask_b32_dpp v130, v234, v238, vcc row_ror:8 row_mask:0xf bank_mask:0xf
	v_cndmask_b32_dpp v131, v235, v239, vcc row_ror:8 row_mask:0xf bank_mask:0xf
	v_cndmask_b32_dpp v132, v236, v240, vcc row_ror:8 row_mask:0xf bank_mask:0xf
	v_cndmask_b32_dpp v133, v237, v241, vcc row_ror:8 row_mask:0xf bank_mask:0xf
	global_store_dwordx4 v246, v[134:137], s[12:13] nt
	global_store_dwordx4 v247, v[130:133], s[12:13] nt
	v_add_f32_e32 v4, v190, v191
	v_add_f32_e32 v5, v192, v193
	v_add_f32_e32 v4, v4, v5
	v_fmamk_f32 v4, v4, 0x3a800000, v212
	v_rsq_f32_e32 v6, v4
	s_add_u32 s12, s12, 0x2000
	s_addc_u32 s13, s13, 0
	v_pk_fma_f32 v[120:121], v[120:121], v[6:7], v[152:153] op_sel_hi:[1,0,1]
	v_pk_fma_f32 v[118:119], v[118:119], v[6:7], v[150:151] op_sel_hi:[1,0,1]
	v_pk_fma_f32 v[116:117], v[116:117], v[6:7], v[148:149] op_sel_hi:[1,0,1]
	v_pk_fma_f32 v[114:115], v[114:115], v[6:7], v[146:147] op_sel_hi:[1,0,1]
	v_pk_fma_f32 v[112:113], v[112:113], v[6:7], v[144:145] op_sel_hi:[1,0,1]
	v_pk_fma_f32 v[110:111], v[110:111], v[6:7], v[142:143] op_sel_hi:[1,0,1]
	v_pk_fma_f32 v[108:109], v[108:109], v[6:7], v[140:141] op_sel_hi:[1,0,1]
	v_pk_fma_f32 v[106:107], v[106:107], v[6:7], v[138:139] op_sel_hi:[1,0,1]
	v_cvt_pk_bf16_f32 v234, v118, v119
	v_cvt_pk_bf16_f32 v235, v120, v121
	v_cvt_pk_bf16_f32 v236, v114, v115
	v_cvt_pk_bf16_f32 v237, v116, v117
	v_cvt_pk_bf16_f32 v238, v110, v111
	v_cvt_pk_bf16_f32 v239, v112, v113
	v_cvt_pk_bf16_f32 v240, v106, v107
	v_cvt_pk_bf16_f32 v241, v108, v109
	s_mov_b64 vcc, s[6:7]
	v_cndmask_b32_dpp v118, v238, v234, vcc row_ror:8 row_mask:0xf bank_mask:0xf
	v_cndmask_b32_dpp v119, v239, v235, vcc row_ror:8 row_mask:0xf bank_mask:0xf
	v_cndmask_b32_dpp v120, v240, v236, vcc row_ror:8 row_mask:0xf bank_mask:0xf
	v_cndmask_b32_dpp v121, v241, v237, vcc row_ror:8 row_mask:0xf bank_mask:0xf
	s_not_b64 vcc, s[6:7]
	v_cndmask_b32_dpp v114, v234, v238, vcc row_ror:8 row_mask:0xf bank_mask:0xf
	v_cndmask_b32_dpp v115, v235, v239, vcc row_ror:8 row_mask:0xf bank_mask:0xf
	v_cndmask_b32_dpp v116, v236, v240, vcc row_ror:8 row_mask:0xf bank_mask:0xf
	v_cndmask_b32_dpp v117, v237, v241, vcc row_ror:8 row_mask:0xf bank_mask:0xf
	global_store_dwordx4 v246, v[118:121], s[12:13] nt
	global_store_dwordx4 v247, v[114:117], s[12:13] nt
	v_add_f32_e32 v4, v194, v195
	v_add_f32_e32 v5, v196, v197
	v_add_f32_e32 v4, v4, v5
	v_fmamk_f32 v4, v4, 0x3a800000, v212
	v_rsq_f32_e32 v6, v4
	s_add_u32 s12, s12, 0x2000
	s_addc_u32 s13, s13, 0
	v_pk_fma_f32 v[104:105], v[104:105], v[6:7], v[152:153] op_sel_hi:[1,0,1]
	v_pk_fma_f32 v[102:103], v[102:103], v[6:7], v[150:151] op_sel_hi:[1,0,1]
	v_pk_fma_f32 v[100:101], v[100:101], v[6:7], v[148:149] op_sel_hi:[1,0,1]
	v_pk_fma_f32 v[98:99], v[98:99], v[6:7], v[146:147] op_sel_hi:[1,0,1]
	v_pk_fma_f32 v[94:95], v[94:95], v[6:7], v[144:145] op_sel_hi:[1,0,1]
	v_pk_fma_f32 v[92:93], v[92:93], v[6:7], v[142:143] op_sel_hi:[1,0,1]
	v_pk_fma_f32 v[90:91], v[90:91], v[6:7], v[140:141] op_sel_hi:[1,0,1]
	v_pk_fma_f32 v[88:89], v[88:89], v[6:7], v[138:139] op_sel_hi:[1,0,1]
	v_cvt_pk_bf16_f32 v234, v102, v103
	v_cvt_pk_bf16_f32 v235, v104, v105
	v_cvt_pk_bf16_f32 v236, v98, v99
	v_cvt_pk_bf16_f32 v237, v100, v101
	v_cvt_pk_bf16_f32 v238, v92, v93
	v_cvt_pk_bf16_f32 v239, v94, v95
	v_cvt_pk_bf16_f32 v240, v88, v89
	v_cvt_pk_bf16_f32 v241, v90, v91
	s_mov_b64 vcc, s[6:7]
	v_cndmask_b32_dpp v102, v238, v234, vcc row_ror:8 row_mask:0xf bank_mask:0xf
	v_cndmask_b32_dpp v103, v239, v235, vcc row_ror:8 row_mask:0xf bank_mask:0xf
	v_cndmask_b32_dpp v104, v240, v236, vcc row_ror:8 row_mask:0xf bank_mask:0xf
	v_cndmask_b32_dpp v105, v241, v237, vcc row_ror:8 row_mask:0xf bank_mask:0xf
	s_not_b64 vcc, s[6:7]
	v_cndmask_b32_dpp v98, v234, v238, vcc row_ror:8 row_mask:0xf bank_mask:0xf
	v_cndmask_b32_dpp v99, v235, v239, vcc row_ror:8 row_mask:0xf bank_mask:0xf
	v_cndmask_b32_dpp v100, v236, v240, vcc row_ror:8 row_mask:0xf bank_mask:0xf
	v_cndmask_b32_dpp v101, v237, v241, vcc row_ror:8 row_mask:0xf bank_mask:0xf
	global_store_dwordx4 v246, v[102:105], s[12:13] nt
	global_store_dwordx4 v247, v[98:101], s[12:13] nt
	v_add_f32_e32 v4, v198, v199
	v_add_f32_e32 v5, v200, v201
	v_add_f32_e32 v4, v4, v5
	v_fmamk_f32 v4, v4, 0x3a800000, v212
	v_rsq_f32_e32 v6, v4
	s_add_u32 s12, s12, 0x2000
	s_addc_u32 s13, s13, 0
	v_pk_fma_f32 v[86:87], v[86:87], v[6:7], v[152:153] op_sel_hi:[1,0,1]
	v_pk_fma_f32 v[84:85], v[84:85], v[6:7], v[150:151] op_sel_hi:[1,0,1]
	v_pk_fma_f32 v[82:83], v[82:83], v[6:7], v[148:149] op_sel_hi:[1,0,1]
	v_pk_fma_f32 v[80:81], v[80:81], v[6:7], v[146:147] op_sel_hi:[1,0,1]
	v_pk_fma_f32 v[78:79], v[78:79], v[6:7], v[144:145] op_sel_hi:[1,0,1]
	v_pk_fma_f32 v[76:77], v[76:77], v[6:7], v[142:143] op_sel_hi:[1,0,1]
	v_pk_fma_f32 v[74:75], v[74:75], v[6:7], v[140:141] op_sel_hi:[1,0,1]
	v_pk_fma_f32 v[72:73], v[72:73], v[6:7], v[138:139] op_sel_hi:[1,0,1]
	v_cvt_pk_bf16_f32 v234, v84, v85
	v_cvt_pk_bf16_f32 v235, v86, v87
	v_cvt_pk_bf16_f32 v236, v80, v81
	v_cvt_pk_bf16_f32 v237, v82, v83
	v_cvt_pk_bf16_f32 v238, v76, v77
	v_cvt_pk_bf16_f32 v239, v78, v79
	v_cvt_pk_bf16_f32 v240, v72, v73
	v_cvt_pk_bf16_f32 v241, v74, v75
	s_mov_b64 vcc, s[6:7]
	v_cndmask_b32_dpp v84, v238, v234, vcc row_ror:8 row_mask:0xf bank_mask:0xf
	v_cndmask_b32_dpp v85, v239, v235, vcc row_ror:8 row_mask:0xf bank_mask:0xf
	v_cndmask_b32_dpp v86, v240, v236, vcc row_ror:8 row_mask:0xf bank_mask:0xf
	v_cndmask_b32_dpp v87, v241, v237, vcc row_ror:8 row_mask:0xf bank_mask:0xf
	s_not_b64 vcc, s[6:7]
	v_cndmask_b32_dpp v80, v234, v238, vcc row_ror:8 row_mask:0xf bank_mask:0xf
	v_cndmask_b32_dpp v81, v235, v239, vcc row_ror:8 row_mask:0xf bank_mask:0xf
	v_cndmask_b32_dpp v82, v236, v240, vcc row_ror:8 row_mask:0xf bank_mask:0xf
	v_cndmask_b32_dpp v83, v237, v241, vcc row_ror:8 row_mask:0xf bank_mask:0xf
	global_store_dwordx4 v246, v[84:87], s[12:13] nt
	global_store_dwordx4 v247, v[80:83], s[12:13] nt
	v_add_f32_e32 v4, v202, v203
	v_add_f32_e32 v5, v204, v205
	v_add_f32_e32 v4, v4, v5
	v_fmamk_f32 v4, v4, 0x3a800000, v212
	v_rsq_f32_e32 v6, v4
	s_add_u32 s12, s12, 0xa000
	s_addc_u32 s13, s13, 0
	v_pk_fma_f32 v[70:71], v[70:71], v[6:7], v[152:153] op_sel_hi:[1,0,1]
	v_pk_fma_f32 v[68:69], v[68:69], v[6:7], v[150:151] op_sel_hi:[1,0,1]
	v_pk_fma_f32 v[66:67], v[66:67], v[6:7], v[148:149] op_sel_hi:[1,0,1]
	v_pk_fma_f32 v[64:65], v[64:65], v[6:7], v[146:147] op_sel_hi:[1,0,1]
	v_pk_fma_f32 v[62:63], v[62:63], v[6:7], v[144:145] op_sel_hi:[1,0,1]
	v_pk_fma_f32 v[60:61], v[60:61], v[6:7], v[142:143] op_sel_hi:[1,0,1]
	v_pk_fma_f32 v[58:59], v[58:59], v[6:7], v[140:141] op_sel_hi:[1,0,1]
	v_pk_fma_f32 v[56:57], v[56:57], v[6:7], v[138:139] op_sel_hi:[1,0,1]
	v_cvt_pk_bf16_f32 v234, v68, v69
	v_cvt_pk_bf16_f32 v235, v70, v71
	v_cvt_pk_bf16_f32 v236, v64, v65
	v_cvt_pk_bf16_f32 v237, v66, v67
	v_cvt_pk_bf16_f32 v238, v60, v61
	v_cvt_pk_bf16_f32 v239, v62, v63
	v_cvt_pk_bf16_f32 v240, v56, v57
	v_cvt_pk_bf16_f32 v241, v58, v59
	s_mov_b64 vcc, s[6:7]
	v_cndmask_b32_dpp v68, v238, v234, vcc row_ror:8 row_mask:0xf bank_mask:0xf
	v_cndmask_b32_dpp v69, v239, v235, vcc row_ror:8 row_mask:0xf bank_mask:0xf
	v_cndmask_b32_dpp v70, v240, v236, vcc row_ror:8 row_mask:0xf bank_mask:0xf
	v_cndmask_b32_dpp v71, v241, v237, vcc row_ror:8 row_mask:0xf bank_mask:0xf
	s_not_b64 vcc, s[6:7]
	v_cndmask_b32_dpp v64, v234, v238, vcc row_ror:8 row_mask:0xf bank_mask:0xf
	v_cndmask_b32_dpp v65, v235, v239, vcc row_ror:8 row_mask:0xf bank_mask:0xf
	v_cndmask_b32_dpp v66, v236, v240, vcc row_ror:8 row_mask:0xf bank_mask:0xf
	v_cndmask_b32_dpp v67, v237, v241, vcc row_ror:8 row_mask:0xf bank_mask:0xf
	global_store_dwordx4 v246, v[68:71], s[12:13] nt
	global_store_dwordx4 v247, v[64:67], s[12:13] nt
	v_add_f32_e32 v4, v222, v223
	v_add_f32_e32 v5, v224, v225
	v_add_f32_e32 v4, v4, v5
	v_fmamk_f32 v4, v4, 0x3a800000, v212
	v_rsq_f32_e32 v6, v4
	s_add_u32 s12, s12, 0x2000
	s_addc_u32 s13, s13, 0
	v_pk_fma_f32 v[54:55], v[54:55], v[6:7], v[152:153] op_sel_hi:[1,0,1]
	v_pk_fma_f32 v[52:53], v[52:53], v[6:7], v[150:151] op_sel_hi:[1,0,1]
	v_pk_fma_f32 v[50:51], v[50:51], v[6:7], v[148:149] op_sel_hi:[1,0,1]
	v_pk_fma_f32 v[48:49], v[48:49], v[6:7], v[146:147] op_sel_hi:[1,0,1]
	v_pk_fma_f32 v[46:47], v[46:47], v[6:7], v[144:145] op_sel_hi:[1,0,1]
	v_pk_fma_f32 v[44:45], v[44:45], v[6:7], v[142:143] op_sel_hi:[1,0,1]
	v_pk_fma_f32 v[42:43], v[42:43], v[6:7], v[140:141] op_sel_hi:[1,0,1]
	v_pk_fma_f32 v[40:41], v[40:41], v[6:7], v[138:139] op_sel_hi:[1,0,1]
	v_cvt_pk_bf16_f32 v234, v52, v53
	v_cvt_pk_bf16_f32 v235, v54, v55
	v_cvt_pk_bf16_f32 v236, v48, v49
	v_cvt_pk_bf16_f32 v237, v50, v51
	v_cvt_pk_bf16_f32 v238, v44, v45
	v_cvt_pk_bf16_f32 v239, v46, v47
	v_cvt_pk_bf16_f32 v240, v40, v41
	v_cvt_pk_bf16_f32 v241, v42, v43
	s_mov_b64 vcc, s[6:7]
	v_cndmask_b32_dpp v52, v238, v234, vcc row_ror:8 row_mask:0xf bank_mask:0xf
	v_cndmask_b32_dpp v53, v239, v235, vcc row_ror:8 row_mask:0xf bank_mask:0xf
	v_cndmask_b32_dpp v54, v240, v236, vcc row_ror:8 row_mask:0xf bank_mask:0xf
	v_cndmask_b32_dpp v55, v241, v237, vcc row_ror:8 row_mask:0xf bank_mask:0xf
	s_not_b64 vcc, s[6:7]
	v_cndmask_b32_dpp v48, v234, v238, vcc row_ror:8 row_mask:0xf bank_mask:0xf
	v_cndmask_b32_dpp v49, v235, v239, vcc row_ror:8 row_mask:0xf bank_mask:0xf
	v_cndmask_b32_dpp v50, v236, v240, vcc row_ror:8 row_mask:0xf bank_mask:0xf
	v_cndmask_b32_dpp v51, v237, v241, vcc row_ror:8 row_mask:0xf bank_mask:0xf
	global_store_dwordx4 v246, v[52:55], s[12:13] nt
	global_store_dwordx4 v247, v[48:51], s[12:13] nt
	v_add_f32_e32 v4, v226, v227
	v_add_f32_e32 v5, v228, v229
	v_add_f32_e32 v4, v4, v5
	v_fmamk_f32 v4, v4, 0x3a800000, v212
	v_rsq_f32_e32 v6, v4
	s_add_u32 s12, s12, 0x2000
	s_addc_u32 s13, s13, 0
	v_pk_fma_f32 v[38:39], v[38:39], v[6:7], v[152:153] op_sel_hi:[1,0,1]
	v_pk_fma_f32 v[36:37], v[36:37], v[6:7], v[150:151] op_sel_hi:[1,0,1]
	v_pk_fma_f32 v[34:35], v[34:35], v[6:7], v[148:149] op_sel_hi:[1,0,1]
	v_pk_fma_f32 v[32:33], v[32:33], v[6:7], v[146:147] op_sel_hi:[1,0,1]
	v_pk_fma_f32 v[30:31], v[30:31], v[6:7], v[144:145] op_sel_hi:[1,0,1]
	v_pk_fma_f32 v[28:29], v[28:29], v[6:7], v[142:143] op_sel_hi:[1,0,1]
	v_pk_fma_f32 v[26:27], v[26:27], v[6:7], v[140:141] op_sel_hi:[1,0,1]
	v_pk_fma_f32 v[24:25], v[24:25], v[6:7], v[138:139] op_sel_hi:[1,0,1]
	v_cvt_pk_bf16_f32 v234, v36, v37
	v_cvt_pk_bf16_f32 v235, v38, v39
	v_cvt_pk_bf16_f32 v236, v32, v33
	v_cvt_pk_bf16_f32 v237, v34, v35
	v_cvt_pk_bf16_f32 v238, v28, v29
	v_cvt_pk_bf16_f32 v239, v30, v31
	v_cvt_pk_bf16_f32 v240, v24, v25
	v_cvt_pk_bf16_f32 v241, v26, v27
	s_mov_b64 vcc, s[6:7]
	v_cndmask_b32_dpp v36, v238, v234, vcc row_ror:8 row_mask:0xf bank_mask:0xf
	v_cndmask_b32_dpp v37, v239, v235, vcc row_ror:8 row_mask:0xf bank_mask:0xf
	v_cndmask_b32_dpp v38, v240, v236, vcc row_ror:8 row_mask:0xf bank_mask:0xf
	v_cndmask_b32_dpp v39, v241, v237, vcc row_ror:8 row_mask:0xf bank_mask:0xf
	s_not_b64 vcc, s[6:7]
	v_cndmask_b32_dpp v32, v234, v238, vcc row_ror:8 row_mask:0xf bank_mask:0xf
	v_cndmask_b32_dpp v33, v235, v239, vcc row_ror:8 row_mask:0xf bank_mask:0xf
	v_cndmask_b32_dpp v34, v236, v240, vcc row_ror:8 row_mask:0xf bank_mask:0xf
	v_cndmask_b32_dpp v35, v237, v241, vcc row_ror:8 row_mask:0xf bank_mask:0xf
	global_store_dwordx4 v246, v[36:39], s[12:13] nt
	global_store_dwordx4 v247, v[32:35], s[12:13] nt
	v_add_f32_e32 v4, v230, v231
	v_add_f32_e32 v5, v232, v233
	v_add_f32_e32 v4, v4, v5
	v_fmamk_f32 v4, v4, 0x3a800000, v212
	v_rsq_f32_e32 v6, v4
	s_add_u32 s12, s12, 0x2000
	s_addc_u32 s13, s13, 0
	v_pk_fma_f32 v[22:23], v[22:23], v[6:7], v[152:153] op_sel_hi:[1,0,1]
	v_pk_fma_f32 v[20:21], v[20:21], v[6:7], v[150:151] op_sel_hi:[1,0,1]
	v_pk_fma_f32 v[18:19], v[18:19], v[6:7], v[148:149] op_sel_hi:[1,0,1]
	v_pk_fma_f32 v[16:17], v[16:17], v[6:7], v[146:147] op_sel_hi:[1,0,1]
	v_pk_fma_f32 v[14:15], v[14:15], v[6:7], v[144:145] op_sel_hi:[1,0,1]
	v_pk_fma_f32 v[12:13], v[12:13], v[6:7], v[142:143] op_sel_hi:[1,0,1]
	v_pk_fma_f32 v[10:11], v[10:11], v[6:7], v[140:141] op_sel_hi:[1,0,1]
	v_pk_fma_f32 v[8:9], v[8:9], v[6:7], v[138:139] op_sel_hi:[1,0,1]
	v_cvt_pk_bf16_f32 v234, v20, v21
	v_cvt_pk_bf16_f32 v235, v22, v23
	v_cvt_pk_bf16_f32 v236, v16, v17
	v_cvt_pk_bf16_f32 v237, v18, v19
	v_cvt_pk_bf16_f32 v238, v12, v13
	v_cvt_pk_bf16_f32 v239, v14, v15
	v_cvt_pk_bf16_f32 v240, v8, v9
	v_cvt_pk_bf16_f32 v241, v10, v11
	s_mov_b64 vcc, s[6:7]
	v_cndmask_b32_dpp v20, v238, v234, vcc row_ror:8 row_mask:0xf bank_mask:0xf
	v_cndmask_b32_dpp v21, v239, v235, vcc row_ror:8 row_mask:0xf bank_mask:0xf
	v_cndmask_b32_dpp v22, v240, v236, vcc row_ror:8 row_mask:0xf bank_mask:0xf
	v_cndmask_b32_dpp v23, v241, v237, vcc row_ror:8 row_mask:0xf bank_mask:0xf
	s_not_b64 vcc, s[6:7]
	v_cndmask_b32_dpp v16, v234, v238, vcc row_ror:8 row_mask:0xf bank_mask:0xf
	v_cndmask_b32_dpp v17, v235, v239, vcc row_ror:8 row_mask:0xf bank_mask:0xf
	v_cndmask_b32_dpp v18, v236, v240, vcc row_ror:8 row_mask:0xf bank_mask:0xf
	v_cndmask_b32_dpp v19, v237, v241, vcc row_ror:8 row_mask:0xf bank_mask:0xf
	global_store_dwordx4 v246, v[20:23], s[12:13] nt
	global_store_dwordx4 v247, v[16:19], s[12:13] nt
	s_mov_b32 s100, 1
	s_branch .LBB0_1422
.Lfi_kv_win:
	v_add_f32_e32 v4, v186, v187
	v_add_f32_e32 v5, v188, v189
	v_add_f32_e32 v4, v4, v5
	v_fmamk_f32 v4, v4, 0x3a800000, v212
	v_rsq_f32_e32 v6, v4
	s_nop 1
	v_pk_fma_f32 v[136:137], v[136:137], v[6:7], v[152:153] op_sel_hi:[1,0,1]
	v_pk_fma_f32 v[134:135], v[134:135], v[6:7], v[150:151] op_sel_hi:[1,0,1]
	v_pk_fma_f32 v[132:133], v[132:133], v[6:7], v[148:149] op_sel_hi:[1,0,1]
	v_pk_fma_f32 v[130:131], v[130:131], v[6:7], v[146:147] op_sel_hi:[1,0,1]
	v_pk_fma_f32 v[128:129], v[128:129], v[6:7], v[144:145] op_sel_hi:[1,0,1]
	v_pk_fma_f32 v[126:127], v[126:127], v[6:7], v[142:143] op_sel_hi:[1,0,1]
	v_pk_fma_f32 v[124:125], v[124:125], v[6:7], v[140:141] op_sel_hi:[1,0,1]
	v_pk_fma_f32 v[122:123], v[122:123], v[6:7], v[138:139] op_sel_hi:[1,0,1]
	v_cvt_pk_bf16_f32 v234, v134, v135
	v_cvt_pk_bf16_f32 v235, v136, v137
	v_cvt_pk_bf16_f32 v236, v130, v131
	v_cvt_pk_bf16_f32 v237, v132, v133
	v_cvt_pk_bf16_f32 v238, v126, v127
	v_cvt_pk_bf16_f32 v239, v128, v129
	v_cvt_pk_bf16_f32 v240, v122, v123
	v_cvt_pk_bf16_f32 v241, v124, v125
	s_mov_b64 vcc, s[6:7]
	v_cndmask_b32_dpp v134, v238, v234, vcc row_ror:8 row_mask:0xf bank_mask:0xf
	v_cndmask_b32_dpp v135, v239, v235, vcc row_ror:8 row_mask:0xf bank_mask:0xf
	v_cndmask_b32_dpp v136, v240, v236, vcc row_ror:8 row_mask:0xf bank_mask:0xf
	v_cndmask_b32_dpp v137, v241, v237, vcc row_ror:8 row_mask:0xf bank_mask:0xf
	s_not_b64 vcc, s[6:7]
	v_cndmask_b32_dpp v130, v234, v238, vcc row_ror:8 row_mask:0xf bank_mask:0xf
	v_cndmask_b32_dpp v131, v235, v239, vcc row_ror:8 row_mask:0xf bank_mask:0xf
	v_cndmask_b32_dpp v132, v236, v240, vcc row_ror:8 row_mask:0xf bank_mask:0xf
	v_cndmask_b32_dpp v133, v237, v241, vcc row_ror:8 row_mask:0xf bank_mask:0xf
	global_store_dwordx4 v246, v[134:137], s[12:13] nt
	global_store_dwordx4 v247, v[130:133], s[12:13] nt
	v_add_f32_e32 v4, v190, v191
	v_add_f32_e32 v5, v192, v193
	v_add_f32_e32 v4, v4, v5
	v_fmamk_f32 v4, v4, 0x3a800000, v212
	v_rsq_f32_e32 v6, v4
	s_add_u32 s12, s12, 0x2000
	s_addc_u32 s13, s13, 0
	v_pk_fma_f32 v[120:121], v[120:121], v[6:7], v[152:153] op_sel_hi:[1,0,1]
	v_pk_fma_f32 v[118:119], v[118:119], v[6:7], v[150:151] op_sel_hi:[1,0,1]
	v_pk_fma_f32 v[116:117], v[116:117], v[6:7], v[148:149] op_sel_hi:[1,0,1]
	v_pk_fma_f32 v[114:115], v[114:115], v[6:7], v[146:147] op_sel_hi:[1,0,1]
	v_pk_fma_f32 v[112:113], v[112:113], v[6:7], v[144:145] op_sel_hi:[1,0,1]
	v_pk_fma_f32 v[110:111], v[110:111], v[6:7], v[142:143] op_sel_hi:[1,0,1]
	v_pk_fma_f32 v[108:109], v[108:109], v[6:7], v[140:141] op_sel_hi:[1,0,1]
	v_pk_fma_f32 v[106:107], v[106:107], v[6:7], v[138:139] op_sel_hi:[1,0,1]
	v_cvt_pk_bf16_f32 v234, v118, v119
	v_cvt_pk_bf16_f32 v235, v120, v121
	v_cvt_pk_bf16_f32 v236, v114, v115
	v_cvt_pk_bf16_f32 v237, v116, v117
	v_cvt_pk_bf16_f32 v238, v110, v111
	v_cvt_pk_bf16_f32 v239, v112, v113
	v_cvt_pk_bf16_f32 v240, v106, v107
	v_cvt_pk_bf16_f32 v241, v108, v109
	s_mov_b64 vcc, s[6:7]
	v_cndmask_b32_dpp v118, v238, v234, vcc row_ror:8 row_mask:0xf bank_mask:0xf
	v_cndmask_b32_dpp v119, v239, v235, vcc row_ror:8 row_mask:0xf bank_mask:0xf
	v_cndmask_b32_dpp v120, v240, v236, vcc row_ror:8 row_mask:0xf bank_mask:0xf
	v_cndmask_b32_dpp v121, v241, v237, vcc row_ror:8 row_mask:0xf bank_mask:0xf
	s_not_b64 vcc, s[6:7]
	v_cndmask_b32_dpp v114, v234, v238, vcc row_ror:8 row_mask:0xf bank_mask:0xf
	v_cndmask_b32_dpp v115, v235, v239, vcc row_ror:8 row_mask:0xf bank_mask:0xf
	v_cndmask_b32_dpp v116, v236, v240, vcc row_ror:8 row_mask:0xf bank_mask:0xf
	v_cndmask_b32_dpp v117, v237, v241, vcc row_ror:8 row_mask:0xf bank_mask:0xf
	global_store_dwordx4 v246, v[118:121], s[12:13] nt
	global_store_dwordx4 v247, v[114:117], s[12:13] nt
	v_add_f32_e32 v4, v194, v195
	v_add_f32_e32 v5, v196, v197
	v_add_f32_e32 v4, v4, v5
	v_fmamk_f32 v4, v4, 0x3a800000, v212
	v_rsq_f32_e32 v6, v4
	s_add_u32 s12, s12, 0x2000
	s_addc_u32 s13, s13, 0
	v_pk_fma_f32 v[104:105], v[104:105], v[6:7], v[152:153] op_sel_hi:[1,0,1]
	v_pk_fma_f32 v[102:103], v[102:103], v[6:7], v[150:151] op_sel_hi:[1,0,1]
	v_pk_fma_f32 v[100:101], v[100:101], v[6:7], v[148:149] op_sel_hi:[1,0,1]
	v_pk_fma_f32 v[98:99], v[98:99], v[6:7], v[146:147] op_sel_hi:[1,0,1]
	v_pk_fma_f32 v[94:95], v[94:95], v[6:7], v[144:145] op_sel_hi:[1,0,1]
	v_pk_fma_f32 v[92:93], v[92:93], v[6:7], v[142:143] op_sel_hi:[1,0,1]
	v_pk_fma_f32 v[90:91], v[90:91], v[6:7], v[140:141] op_sel_hi:[1,0,1]
	v_pk_fma_f32 v[88:89], v[88:89], v[6:7], v[138:139] op_sel_hi:[1,0,1]
	v_cvt_pk_bf16_f32 v234, v102, v103
	v_cvt_pk_bf16_f32 v235, v104, v105
	v_cvt_pk_bf16_f32 v236, v98, v99
	v_cvt_pk_bf16_f32 v237, v100, v101
	v_cvt_pk_bf16_f32 v238, v92, v93
	v_cvt_pk_bf16_f32 v239, v94, v95
	v_cvt_pk_bf16_f32 v240, v88, v89
	v_cvt_pk_bf16_f32 v241, v90, v91
	s_mov_b64 vcc, s[6:7]
	v_cndmask_b32_dpp v102, v238, v234, vcc row_ror:8 row_mask:0xf bank_mask:0xf
	v_cndmask_b32_dpp v103, v239, v235, vcc row_ror:8 row_mask:0xf bank_mask:0xf
	v_cndmask_b32_dpp v104, v240, v236, vcc row_ror:8 row_mask:0xf bank_mask:0xf
	v_cndmask_b32_dpp v105, v241, v237, vcc row_ror:8 row_mask:0xf bank_mask:0xf
	s_not_b64 vcc, s[6:7]
	v_cndmask_b32_dpp v98, v234, v238, vcc row_ror:8 row_mask:0xf bank_mask:0xf
	v_cndmask_b32_dpp v99, v235, v239, vcc row_ror:8 row_mask:0xf bank_mask:0xf
	v_cndmask_b32_dpp v100, v236, v240, vcc row_ror:8 row_mask:0xf bank_mask:0xf
	v_cndmask_b32_dpp v101, v237, v241, vcc row_ror:8 row_mask:0xf bank_mask:0xf
	global_store_dwordx4 v246, v[102:105], s[12:13] nt
	global_store_dwordx4 v247, v[98:101], s[12:13] nt
	v_add_f32_e32 v4, v198, v199
	v_add_f32_e32 v5, v200, v201
	v_add_f32_e32 v4, v4, v5
	v_fmamk_f32 v4, v4, 0x3a800000, v212
	v_rsq_f32_e32 v6, v4
	s_add_u32 s12, s12, 0x2000
	s_addc_u32 s13, s13, 0
	v_pk_fma_f32 v[86:87], v[86:87], v[6:7], v[152:153] op_sel_hi:[1,0,1]
	v_pk_fma_f32 v[84:85], v[84:85], v[6:7], v[150:151] op_sel_hi:[1,0,1]
	v_pk_fma_f32 v[82:83], v[82:83], v[6:7], v[148:149] op_sel_hi:[1,0,1]
	v_pk_fma_f32 v[80:81], v[80:81], v[6:7], v[146:147] op_sel_hi:[1,0,1]
	v_pk_fma_f32 v[78:79], v[78:79], v[6:7], v[144:145] op_sel_hi:[1,0,1]
	v_pk_fma_f32 v[76:77], v[76:77], v[6:7], v[142:143] op_sel_hi:[1,0,1]
	v_pk_fma_f32 v[74:75], v[74:75], v[6:7], v[140:141] op_sel_hi:[1,0,1]
	v_pk_fma_f32 v[72:73], v[72:73], v[6:7], v[138:139] op_sel_hi:[1,0,1]
	v_cvt_pk_bf16_f32 v234, v84, v85
	v_cvt_pk_bf16_f32 v235, v86, v87
	v_cvt_pk_bf16_f32 v236, v80, v81
	v_cvt_pk_bf16_f32 v237, v82, v83
	v_cvt_pk_bf16_f32 v238, v76, v77
	v_cvt_pk_bf16_f32 v239, v78, v79
	v_cvt_pk_bf16_f32 v240, v72, v73
	v_cvt_pk_bf16_f32 v241, v74, v75
	s_mov_b64 vcc, s[6:7]
	v_cndmask_b32_dpp v84, v238, v234, vcc row_ror:8 row_mask:0xf bank_mask:0xf
	v_cndmask_b32_dpp v85, v239, v235, vcc row_ror:8 row_mask:0xf bank_mask:0xf
	v_cndmask_b32_dpp v86, v240, v236, vcc row_ror:8 row_mask:0xf bank_mask:0xf
	v_cndmask_b32_dpp v87, v241, v237, vcc row_ror:8 row_mask:0xf bank_mask:0xf
	s_not_b64 vcc, s[6:7]
	v_cndmask_b32_dpp v80, v234, v238, vcc row_ror:8 row_mask:0xf bank_mask:0xf
	v_cndmask_b32_dpp v81, v235, v239, vcc row_ror:8 row_mask:0xf bank_mask:0xf
	v_cndmask_b32_dpp v82, v236, v240, vcc row_ror:8 row_mask:0xf bank_mask:0xf
	v_cndmask_b32_dpp v83, v237, v241, vcc row_ror:8 row_mask:0xf bank_mask:0xf
	global_store_dwordx4 v246, v[84:87], s[12:13] nt
	global_store_dwordx4 v247, v[80:83], s[12:13] nt
	v_add_f32_e32 v4, v202, v203
	v_add_f32_e32 v5, v204, v205
	v_add_f32_e32 v4, v4, v5
	v_fmamk_f32 v4, v4, 0x3a800000, v212
	v_rsq_f32_e32 v6, v4
	s_add_u32 s12, s12, 0xa000
	s_addc_u32 s13, s13, 0
	v_pk_fma_f32 v[70:71], v[70:71], v[6:7], v[152:153] op_sel_hi:[1,0,1]
	v_pk_fma_f32 v[68:69], v[68:69], v[6:7], v[150:151] op_sel_hi:[1,0,1]
	v_pk_fma_f32 v[66:67], v[66:67], v[6:7], v[148:149] op_sel_hi:[1,0,1]
	v_pk_fma_f32 v[64:65], v[64:65], v[6:7], v[146:147] op_sel_hi:[1,0,1]
	v_pk_fma_f32 v[62:63], v[62:63], v[6:7], v[144:145] op_sel_hi:[1,0,1]
	v_pk_fma_f32 v[60:61], v[60:61], v[6:7], v[142:143] op_sel_hi:[1,0,1]
	v_pk_fma_f32 v[58:59], v[58:59], v[6:7], v[140:141] op_sel_hi:[1,0,1]
	v_pk_fma_f32 v[56:57], v[56:57], v[6:7], v[138:139] op_sel_hi:[1,0,1]
	global_store_dwordx4 v3, v[68:71], s[18:19]
	global_store_dwordx4 v3, v[64:67], s[18:19] offset:16
	global_store_dwordx4 v3, v[60:63], s[18:19] offset:128
	global_store_dwordx4 v3, v[56:59], s[18:19] offset:144
	v_cvt_pk_bf16_f32 v234, v68, v69
	v_cvt_pk_bf16_f32 v235, v70, v71
	v_cvt_pk_bf16_f32 v236, v64, v65
	v_cvt_pk_bf16_f32 v237, v66, v67
	v_cvt_pk_bf16_f32 v238, v60, v61
	v_cvt_pk_bf16_f32 v239, v62, v63
	v_cvt_pk_bf16_f32 v240, v56, v57
	v_cvt_pk_bf16_f32 v241, v58, v59
	s_mov_b64 vcc, s[6:7]
	v_cndmask_b32_dpp v68, v238, v234, vcc row_ror:8 row_mask:0xf bank_mask:0xf
	v_cndmask_b32_dpp v69, v239, v235, vcc row_ror:8 row_mask:0xf bank_mask:0xf
	v_cndmask_b32_dpp v70, v240, v236, vcc row_ror:8 row_mask:0xf bank_mask:0xf
	v_cndmask_b32_dpp v71, v241, v237, vcc row_ror:8 row_mask:0xf bank_mask:0xf
	s_not_b64 vcc, s[6:7]
	v_cndmask_b32_dpp v64, v234, v238, vcc row_ror:8 row_mask:0xf bank_mask:0xf
	v_cndmask_b32_dpp v65, v235, v239, vcc row_ror:8 row_mask:0xf bank_mask:0xf
	v_cndmask_b32_dpp v66, v236, v240, vcc row_ror:8 row_mask:0xf bank_mask:0xf
	v_cndmask_b32_dpp v67, v237, v241, vcc row_ror:8 row_mask:0xf bank_mask:0xf
	global_store_dwordx4 v246, v[68:71], s[12:13] nt
	global_store_dwordx4 v247, v[64:67], s[12:13] nt
	v_add_f32_e32 v4, v222, v223
	v_add_f32_e32 v5, v224, v225
	v_add_f32_e32 v4, v4, v5
	v_fmamk_f32 v4, v4, 0x3a800000, v212
	v_rsq_f32_e32 v6, v4
	s_add_u32 s12, s12, 0x2000
	s_addc_u32 s13, s13, 0
	v_pk_fma_f32 v[54:55], v[54:55], v[6:7], v[152:153] op_sel_hi:[1,0,1]
	v_pk_fma_f32 v[52:53], v[52:53], v[6:7], v[150:151] op_sel_hi:[1,0,1]
	v_pk_fma_f32 v[50:51], v[50:51], v[6:7], v[148:149] op_sel_hi:[1,0,1]
	v_pk_fma_f32 v[48:49], v[48:49], v[6:7], v[146:147] op_sel_hi:[1,0,1]
	v_pk_fma_f32 v[46:47], v[46:47], v[6:7], v[144:145] op_sel_hi:[1,0,1]
	v_pk_fma_f32 v[44:45], v[44:45], v[6:7], v[142:143] op_sel_hi:[1,0,1]
	v_pk_fma_f32 v[42:43], v[42:43], v[6:7], v[140:141] op_sel_hi:[1,0,1]
	v_pk_fma_f32 v[40:41], v[40:41], v[6:7], v[138:139] op_sel_hi:[1,0,1]
	s_add_u32 s18, s18, 0x4000
	s_addc_u32 s19, s19, 0
	global_store_dwordx4 v3, v[52:55], s[18:19]
	global_store_dwordx4 v3, v[48:51], s[18:19] offset:16
	global_store_dwordx4 v3, v[44:47], s[18:19] offset:128
	global_store_dwordx4 v3, v[40:43], s[18:19] offset:144
	v_cvt_pk_bf16_f32 v234, v52, v53
	v_cvt_pk_bf16_f32 v235, v54, v55
	v_cvt_pk_bf16_f32 v236, v48, v49
	v_cvt_pk_bf16_f32 v237, v50, v51
	v_cvt_pk_bf16_f32 v238, v44, v45
	v_cvt_pk_bf16_f32 v239, v46, v47
	v_cvt_pk_bf16_f32 v240, v40, v41
	v_cvt_pk_bf16_f32 v241, v42, v43
	s_mov_b64 vcc, s[6:7]
	v_cndmask_b32_dpp v52, v238, v234, vcc row_ror:8 row_mask:0xf bank_mask:0xf
	v_cndmask_b32_dpp v53, v239, v235, vcc row_ror:8 row_mask:0xf bank_mask:0xf
	v_cndmask_b32_dpp v54, v240, v236, vcc row_ror:8 row_mask:0xf bank_mask:0xf
	v_cndmask_b32_dpp v55, v241, v237, vcc row_ror:8 row_mask:0xf bank_mask:0xf
	s_not_b64 vcc, s[6:7]
	v_cndmask_b32_dpp v48, v234, v238, vcc row_ror:8 row_mask:0xf bank_mask:0xf
	v_cndmask_b32_dpp v49, v235, v239, vcc row_ror:8 row_mask:0xf bank_mask:0xf
	v_cndmask_b32_dpp v50, v236, v240, vcc row_ror:8 row_mask:0xf bank_mask:0xf
	v_cndmask_b32_dpp v51, v237, v241, vcc row_ror:8 row_mask:0xf bank_mask:0xf
	global_store_dwordx4 v246, v[52:55], s[12:13] nt
	global_store_dwordx4 v247, v[48:51], s[12:13] nt
	v_add_f32_e32 v4, v226, v227
	v_add_f32_e32 v5, v228, v229
	v_add_f32_e32 v4, v4, v5
	v_fmamk_f32 v4, v4, 0x3a800000, v212
	v_rsq_f32_e32 v6, v4
	s_add_u32 s12, s12, 0x2000
	s_addc_u32 s13, s13, 0
	v_pk_fma_f32 v[38:39], v[38:39], v[6:7], v[152:153] op_sel_hi:[1,0,1]
	v_pk_fma_f32 v[36:37], v[36:37], v[6:7], v[150:151] op_sel_hi:[1,0,1]
	v_pk_fma_f32 v[34:35], v[34:35], v[6:7], v[148:149] op_sel_hi:[1,0,1]
	v_pk_fma_f32 v[32:33], v[32:33], v[6:7], v[146:147] op_sel_hi:[1,0,1]
	v_pk_fma_f32 v[30:31], v[30:31], v[6:7], v[144:145] op_sel_hi:[1,0,1]
	v_pk_fma_f32 v[28:29], v[28:29], v[6:7], v[142:143] op_sel_hi:[1,0,1]
	v_pk_fma_f32 v[26:27], v[26:27], v[6:7], v[140:141] op_sel_hi:[1,0,1]
	v_pk_fma_f32 v[24:25], v[24:25], v[6:7], v[138:139] op_sel_hi:[1,0,1]
	s_add_u32 s18, s18, 0x4000
	s_addc_u32 s19, s19, 0
	global_store_dwordx4 v3, v[36:39], s[18:19]
	global_store_dwordx4 v3, v[32:35], s[18:19] offset:16
	global_store_dwordx4 v3, v[28:31], s[18:19] offset:128
	global_store_dwordx4 v3, v[24:27], s[18:19] offset:144
	v_cvt_pk_bf16_f32 v234, v36, v37
	v_cvt_pk_bf16_f32 v235, v38, v39
	v_cvt_pk_bf16_f32 v236, v32, v33
	v_cvt_pk_bf16_f32 v237, v34, v35
	v_cvt_pk_bf16_f32 v238, v28, v29
	v_cvt_pk_bf16_f32 v239, v30, v31
	v_cvt_pk_bf16_f32 v240, v24, v25
	v_cvt_pk_bf16_f32 v241, v26, v27
	s_mov_b64 vcc, s[6:7]
	v_cndmask_b32_dpp v36, v238, v234, vcc row_ror:8 row_mask:0xf bank_mask:0xf
	v_cndmask_b32_dpp v37, v239, v235, vcc row_ror:8 row_mask:0xf bank_mask:0xf
	v_cndmask_b32_dpp v38, v240, v236, vcc row_ror:8 row_mask:0xf bank_mask:0xf
	v_cndmask_b32_dpp v39, v241, v237, vcc row_ror:8 row_mask:0xf bank_mask:0xf
	s_not_b64 vcc, s[6:7]
	v_cndmask_b32_dpp v32, v234, v238, vcc row_ror:8 row_mask:0xf bank_mask:0xf
	v_cndmask_b32_dpp v33, v235, v239, vcc row_ror:8 row_mask:0xf bank_mask:0xf
	v_cndmask_b32_dpp v34, v236, v240, vcc row_ror:8 row_mask:0xf bank_mask:0xf
	v_cndmask_b32_dpp v35, v237, v241, vcc row_ror:8 row_mask:0xf bank_mask:0xf
	global_store_dwordx4 v246, v[36:39], s[12:13] nt
	global_store_dwordx4 v247, v[32:35], s[12:13] nt
	v_add_f32_e32 v4, v230, v231
	v_add_f32_e32 v5, v232, v233
	v_add_f32_e32 v4, v4, v5
	v_fmamk_f32 v4, v4, 0x3a800000, v212
	v_rsq_f32_e32 v6, v4
	s_add_u32 s12, s12, 0x2000
	s_addc_u32 s13, s13, 0
	v_pk_fma_f32 v[22:23], v[22:23], v[6:7], v[152:153] op_sel_hi:[1,0,1]
	v_pk_fma_f32 v[20:21], v[20:21], v[6:7], v[150:151] op_sel_hi:[1,0,1]
	v_pk_fma_f32 v[18:19], v[18:19], v[6:7], v[148:149] op_sel_hi:[1,0,1]
	v_pk_fma_f32 v[16:17], v[16:17], v[6:7], v[146:147] op_sel_hi:[1,0,1]
	v_pk_fma_f32 v[14:15], v[14:15], v[6:7], v[144:145] op_sel_hi:[1,0,1]
	v_pk_fma_f32 v[12:13], v[12:13], v[6:7], v[142:143] op_sel_hi:[1,0,1]
	v_pk_fma_f32 v[10:11], v[10:11], v[6:7], v[140:141] op_sel_hi:[1,0,1]
	v_pk_fma_f32 v[8:9], v[8:9], v[6:7], v[138:139] op_sel_hi:[1,0,1]
	s_add_u32 s18, s18, 0x4000
	s_addc_u32 s19, s19, 0
	global_store_dwordx4 v3, v[20:23], s[18:19]
	global_store_dwordx4 v3, v[16:19], s[18:19] offset:16
	global_store_dwordx4 v3, v[12:15], s[18:19] offset:128
	global_store_dwordx4 v3, v[8:11], s[18:19] offset:144
	v_cvt_pk_bf16_f32 v234, v20, v21
	v_cvt_pk_bf16_f32 v235, v22, v23
	v_cvt_pk_bf16_f32 v236, v16, v17
	v_cvt_pk_bf16_f32 v237, v18, v19
	v_cvt_pk_bf16_f32 v238, v12, v13
	v_cvt_pk_bf16_f32 v239, v14, v15
	v_cvt_pk_bf16_f32 v240, v8, v9
	v_cvt_pk_bf16_f32 v241, v10, v11
	s_mov_b64 vcc, s[6:7]
	v_cndmask_b32_dpp v20, v238, v234, vcc row_ror:8 row_mask:0xf bank_mask:0xf
	v_cndmask_b32_dpp v21, v239, v235, vcc row_ror:8 row_mask:0xf bank_mask:0xf
	v_cndmask_b32_dpp v22, v240, v236, vcc row_ror:8 row_mask:0xf bank_mask:0xf
	v_cndmask_b32_dpp v23, v241, v237, vcc row_ror:8 row_mask:0xf bank_mask:0xf
	s_not_b64 vcc, s[6:7]
	v_cndmask_b32_dpp v16, v234, v238, vcc row_ror:8 row_mask:0xf bank_mask:0xf
	v_cndmask_b32_dpp v17, v235, v239, vcc row_ror:8 row_mask:0xf bank_mask:0xf
	v_cndmask_b32_dpp v18, v236, v240, vcc row_ror:8 row_mask:0xf bank_mask:0xf
	v_cndmask_b32_dpp v19, v237, v241, vcc row_ror:8 row_mask:0xf bank_mask:0xf
	global_store_dwordx4 v246, v[20:23], s[12:13] nt
	global_store_dwordx4 v247, v[16:19], s[12:13] nt
	s_branch .LBB0_1422
